# 2x s_nop 15 before the wait in the six-DMA load segments of all nine GEMM K-loops
# speedup vs baseline: 1.0076x; 1.0076x over previous
; #define PG8_STAGE(bufoff, gbase, voff) do { _Pragma("unroll") for (int _i = 0; _i < 2; ++_i) \
;         __builtin_amdgcn_global_load_lds((const unsigned*)((const char*)(gbase) + (voff)[_i]), (LAS unsigned*)(lds + (bufoff) + ldsw + _i * 8192), 16, 0, 0); } while (0)
; #define PG8_LDA(dst, b, h) do { _Pragma("unroll") for (int m = 0; m < 4; ++m) _Pragma("unroll") for (int k = 0; k < 2; ++k) dst[m][k] = *(const LAS bf16x8*)(lds + PG8_SA(b, h) + aoff + m * 2048 + k * 1024); } while (0)
; #define PG8_LDB(dst, b, h) do { _Pragma("unroll") for (int n = 0; n < 2; ++n) _Pragma("unroll") for (int k = 0; k < 2; ++k) dst[n][k] = *(const LAS bf16x8*)(lds + PG8_SB(b, h) + boff + n * 2048 + k * 1024); } while (0)
; #define PG8_MMA(ai, bj, At, Bt) do { __builtin_amdgcn_s_setprio(1); _Pragma("unroll") for (int m = 0; m < 4; ++m) _Pragma("unroll") for (int n = 0; n < 2; ++n) _Pragma("unroll") for (int k = 0; k < 2; ++k) \
;         acc[ai][bj][m][n] = __builtin_amdgcn_mfma_f32_16x16x32_bf16(Bt[n][k], At[m][k], acc[ai][bj][m][n], 0, 0, 0); __builtin_amdgcn_s_setprio(0); } while (0)
; #define PG8_WAIT_V(n) asm volatile("s_waitcnt vmcnt(" #n ")" ::: "memory")
; #define PG8_WAIT_L(n) asm volatile("s_waitcnt lgkmcnt(" #n ")" ::: "memory")
; #define PG8_BAR __builtin_amdgcn_s_barrier()
; #define PG8_SCHED __builtin_amdgcn_sched_barrier(0)
; template <class Epi, bool ALIGN_EPI = PG8_ALIGN>
; __device__ __forceinline__ void gemm_phase(LAS unsigned char* lds, const Gemm g, const StaticOrder& S, const Epi& E) {
;     ...
;         for (int t = 0; t < nt; t += 2) {
;             const bool last = (t == nt - 2);
;             const char* a1 = cA + (size_t)(t + 1) * kstep;
;             const char* a2 = last ? nA : cA + (size_t)(t + 2) * kstep; const char* b2 = last ? nB : cB + (size_t)(t + 2) * kstep;
;             const char* a3 = a2 + kstep; const char* b3 = b2 + kstep;
;             PG8_LDB(B0, 0, 0); PG8_LDB(B1, 0, 1); PG8_SCHED; PG8_LDA(At, 0, 0); PG8_STAGE(PG8_SA(1, 1), a1 + hstepA, voffA);
;             PG8_WAIT_V(8); PG8_WAIT_L(0); PG8_BAR; PG8_MMA(0, 0, At, B0); PG8_MMA(0, 1, At, B1); PG8_BAR; PG8_SCHED;
;             PG8_LDA(At, 0, 1); PG8_STAGE(PG8_SB(0, 0), b2, voffB); PG8_STAGE(PG8_SB(0, 1), b2 + hstepB, voffB); PG8_STAGE(PG8_SA(0, 0), a2, voffA);
.LBB0_219:
	s_add_i32 s49, s24, 2
	s_add_u32 s20, s2, 0xfff80080
	s_addc_u32 s21, s3, -1
	s_add_i32 s22, 16, 0x10000
	s_cmp_eq_u32 s46, s24
	s_cselect_b32 s25, s15, s21
	s_cselect_b32 s24, s34, s20
	s_cselect_b32 s51, s17, s37
	s_cselect_b32 s50, s16, s36
	s_add_i32 s20, 16, 0x14000
	v_add_u32_e32 v154, s22, v139
	v_add_u32_e32 v170, s20, v139
	ds_read_b128 v[142:145], v154
	ds_read_b128 v[146:149], v154 offset:1024
	ds_read_b128 v[150:153], v154 offset:2048
	ds_read_b128 v[154:157], v154 offset:3072
	ds_read_b128 v[158:161], v170
	ds_read_b128 v[162:165], v170 offset:1024
	ds_read_b128 v[166:169], v170 offset:2048
	ds_read_b128 v[170:173], v170 offset:3072
	v_lshl_add_u64 v[174:175], s[2:3], 0, v[134:135]
	s_add_i32 m0, s29, 0xc000
	ds_read_b128 v[184:187], v141
	ds_read_b128 v[188:191], v141 offset:1024
	ds_read_b128 v[192:195], v141 offset:2048
	ds_read_b128 v[196:199], v141 offset:3072
	ds_read_b128 v[200:203], v141 offset:4096
	ds_read_b128 v[204:207], v141 offset:5120
	ds_read_b128 v[208:211], v141 offset:6144
	ds_read_b128 v[212:215], v141 offset:7168
	global_load_lds_dwordx4 v[174:175], off
	v_lshl_add_u64 v[174:175], s[2:3], 0, v[136:137]
	s_add_i32 m0, s29, 0xe000
	s_nop 0
	global_load_lds_dwordx4 v[174:175], off
	s_waitcnt vmcnt(8)
	s_waitcnt lgkmcnt(0)
	s_barrier
	s_setprio 1
	s_waitcnt lgkmcnt(0)
	v_mfma_f32_16x16x32_bf16 v[124:127], v[142:145], v[184:187], v[124:127]
	v_mfma_f32_16x16x32_bf16 v[116:119], v[150:153], v[184:187], v[116:119]
	v_mfma_f32_16x16x32_bf16 v[108:111], v[142:145], v[192:195], v[108:111]
	v_mfma_f32_16x16x32_bf16 v[100:103], v[150:153], v[192:195], v[100:103]
	v_mfma_f32_16x16x32_bf16 v[92:95], v[142:145], v[200:203], v[92:95]
	v_mfma_f32_16x16x32_bf16 v[84:87], v[150:153], v[200:203], v[84:87]
	v_mfma_f32_16x16x32_bf16 v[76:79], v[142:145], v[208:211], v[76:79]
	v_mfma_f32_16x16x32_bf16 v[68:71], v[150:153], v[208:211], v[68:71]
	v_mfma_f32_16x16x32_bf16 v[124:127], v[146:149], v[188:191], v[124:127]
	v_mfma_f32_16x16x32_bf16 v[116:119], v[154:157], v[188:191], v[116:119]
	v_mfma_f32_16x16x32_bf16 v[108:111], v[146:149], v[196:199], v[108:111]
	v_mfma_f32_16x16x32_bf16 v[100:103], v[154:157], v[196:199], v[100:103]
	v_mfma_f32_16x16x32_bf16 v[92:95], v[146:149], v[204:207], v[92:95]
	v_mfma_f32_16x16x32_bf16 v[84:87], v[154:157], v[204:207], v[84:87]
	v_mfma_f32_16x16x32_bf16 v[76:79], v[146:149], v[212:215], v[76:79]
	v_mfma_f32_16x16x32_bf16 v[68:71], v[154:157], v[212:215], v[68:71]
	s_setprio 0
	s_setprio 1
	v_mfma_f32_16x16x32_bf16 v[120:123], v[158:161], v[184:187], v[120:123]
	v_mfma_f32_16x16x32_bf16 v[112:115], v[166:169], v[184:187], v[112:115]
	v_mfma_f32_16x16x32_bf16 v[104:107], v[158:161], v[192:195], v[104:107]
	v_mfma_f32_16x16x32_bf16 v[96:99], v[166:169], v[192:195], v[96:99]
	v_mfma_f32_16x16x32_bf16 v[88:91], v[158:161], v[200:203], v[88:91]
	v_mfma_f32_16x16x32_bf16 v[80:83], v[166:169], v[200:203], v[80:83]
	v_mfma_f32_16x16x32_bf16 v[72:75], v[158:161], v[208:211], v[72:75]
	v_mfma_f32_16x16x32_bf16 v[64:67], v[166:169], v[208:211], v[64:67]
	v_mfma_f32_16x16x32_bf16 v[120:123], v[162:165], v[188:191], v[120:123]
	v_mfma_f32_16x16x32_bf16 v[112:115], v[170:173], v[188:191], v[112:115]
	v_mfma_f32_16x16x32_bf16 v[104:107], v[162:165], v[196:199], v[104:107]
	v_mfma_f32_16x16x32_bf16 v[96:99], v[170:173], v[196:199], v[96:99]
	v_mfma_f32_16x16x32_bf16 v[88:91], v[162:165], v[204:207], v[88:91]
	v_mfma_f32_16x16x32_bf16 v[80:83], v[170:173], v[204:207], v[80:83]
	v_mfma_f32_16x16x32_bf16 v[72:75], v[162:165], v[212:215], v[72:75]
	v_mfma_f32_16x16x32_bf16 v[64:67], v[170:173], v[212:215], v[64:67]
	s_setprio 0
	s_barrier
	s_add_i32 s21, s22, s18
	v_lshl_add_u64 v[174:175], s[50:51], 0, v[176:177]
	s_mov_b32 m0, s21
	ds_read_b128 v[184:187], v141 offset:16384
	ds_read_b128 v[188:191], v141 offset:17408
	ds_read_b128 v[192:195], v141 offset:18432
	ds_read_b128 v[196:199], v141 offset:19456
	ds_read_b128 v[200:203], v141 offset:20480
	ds_read_b128 v[204:207], v141 offset:21504
	ds_read_b128 v[208:211], v141 offset:22528
	ds_read_b128 v[212:215], v141 offset:23552
	global_load_lds_dwordx4 v[174:175], off
	s_add_i32 m0, s21, 0x2000
	v_lshl_add_u64 v[216:217], s[50:51], 0, v[128:129]
	s_add_u32 s50, s50, s4
	s_addc_u32 s51, s51, s5
	s_add_i32 s20, s20, s18
	global_load_lds_dwordx4 v[216:217], off
	v_lshl_add_u64 v[218:219], s[50:51], 0, v[176:177]
	s_mov_b32 m0, s20
	v_lshl_add_u64 v[220:221], s[50:51], 0, v[128:129]
	global_load_lds_dwordx4 v[218:219], off
	s_add_i32 m0, s20, 0x2000
	v_lshl_add_u64 v[222:223], s[24:25], 0, v[132:133]
	global_load_lds_dwordx4 v[220:221], off
	s_mov_b32 m0, s29
	v_lshl_add_u64 v[224:225], s[24:25], 0, v[130:131]
	global_load_lds_dwordx4 v[222:223], off
	s_mov_b32 m0, s30
	s_nop 0
	global_load_lds_dwordx4 v[224:225], off
	s_nop 15
	s_nop 15
	s_waitcnt vmcnt(8)
	s_waitcnt lgkmcnt(0)
	s_barrier
; #define PG8_STAGE(bufoff, gbase, voff) do { _Pragma("unroll") for (int _i = 0; _i < 2; ++_i) \
;         __builtin_amdgcn_global_load_lds((const unsigned*)((const char*)(gbase) + (voff)[_i]), (LAS unsigned*)(lds + (bufoff) + ldsw + _i * 8192), 16, 0, 0); } while (0)
; #define PG8_LDA(dst, b, h) do { _Pragma("unroll") for (int m = 0; m < 4; ++m) _Pragma("unroll") for (int k = 0; k < 2; ++k) dst[m][k] = *(const LAS bf16x8*)(lds + PG8_SA(b, h) + aoff + m * 2048 + k * 1024); } while (0)
; #define PG8_LDB(dst, b, h) do { _Pragma("unroll") for (int n = 0; n < 2; ++n) _Pragma("unroll") for (int k = 0; k < 2; ++k) dst[n][k] = *(const LAS bf16x8*)(lds + PG8_SB(b, h) + boff + n * 2048 + k * 1024); } while (0)
; #define PG8_MMA(ai, bj, At, Bt) do { __builtin_amdgcn_s_setprio(1); _Pragma("unroll") for (int m = 0; m < 4; ++m) _Pragma("unroll") for (int n = 0; n < 2; ++n) _Pragma("unroll") for (int k = 0; k < 2; ++k) \
;         acc[ai][bj][m][n] = __builtin_amdgcn_mfma_f32_16x16x32_bf16(Bt[n][k], At[m][k], acc[ai][bj][m][n], 0, 0, 0); __builtin_amdgcn_s_setprio(0); } while (0)
; #define PG8_WAIT_V(n) asm volatile("s_waitcnt vmcnt(" #n ")" ::: "memory")
; #define PG8_WAIT_L(n) asm volatile("s_waitcnt lgkmcnt(" #n ")" ::: "memory")
; #define PG8_BAR __builtin_amdgcn_s_barrier()
; #define PG8_SCHED __builtin_amdgcn_sched_barrier(0)
; template <class Epi, bool ALIGN_EPI = PG8_ALIGN>
; __device__ __forceinline__ void gemm_phase(LAS unsigned char* lds, const Gemm g, const StaticOrder& S, const Epi& E) {
;     ...
;             PG8_WAIT_V(8); PG8_WAIT_L(0); PG8_BAR; PG8_MMA(1, 0, At, B0); PG8_MMA(1, 1, At, B1); PG8_BAR; PG8_SCHED;
;             PG8_LDB(B0, 1, 0); PG8_LDB(B1, 1, 1); PG8_SCHED; PG8_LDA(At, 1, 0); PG8_STAGE(PG8_SA(0, 1), a2 + hstepA, voffA);
;             PG8_WAIT_V(8); PG8_WAIT_L(0); PG8_BAR; PG8_MMA(0, 0, At, B0); PG8_MMA(0, 1, At, B1); PG8_BAR; PG8_SCHED;
	s_setprio 1
	s_waitcnt lgkmcnt(0)
	v_mfma_f32_16x16x32_bf16 v[60:63], v[142:145], v[184:187], v[60:63]
	v_mfma_f32_16x16x32_bf16 v[52:55], v[150:153], v[184:187], v[52:55]
	v_mfma_f32_16x16x32_bf16 v[44:47], v[142:145], v[192:195], v[44:47]
	v_mfma_f32_16x16x32_bf16 v[36:39], v[150:153], v[192:195], v[36:39]
	v_mfma_f32_16x16x32_bf16 v[28:31], v[142:145], v[200:203], v[28:31]
	v_mfma_f32_16x16x32_bf16 v[20:23], v[150:153], v[200:203], v[20:23]
	v_mfma_f32_16x16x32_bf16 v[12:15], v[142:145], v[208:211], v[12:15]
	v_mfma_f32_16x16x32_bf16 v[4:7], v[150:153], v[208:211], v[4:7]
	v_mfma_f32_16x16x32_bf16 v[60:63], v[146:149], v[188:191], v[60:63]
	v_mfma_f32_16x16x32_bf16 v[52:55], v[154:157], v[188:191], v[52:55]
	v_mfma_f32_16x16x32_bf16 v[44:47], v[146:149], v[196:199], v[44:47]
	v_mfma_f32_16x16x32_bf16 v[36:39], v[154:157], v[196:199], v[36:39]
	v_mfma_f32_16x16x32_bf16 v[28:31], v[146:149], v[204:207], v[28:31]
	v_mfma_f32_16x16x32_bf16 v[20:23], v[154:157], v[204:207], v[20:23]
	v_mfma_f32_16x16x32_bf16 v[12:15], v[146:149], v[212:215], v[12:15]
	v_mfma_f32_16x16x32_bf16 v[4:7], v[154:157], v[212:215], v[4:7]
	s_setprio 0
	s_setprio 1
	v_mfma_f32_16x16x32_bf16 v[56:59], v[158:161], v[184:187], v[56:59]
	v_mfma_f32_16x16x32_bf16 v[48:51], v[166:169], v[184:187], v[48:51]
	v_mfma_f32_16x16x32_bf16 v[40:43], v[158:161], v[192:195], v[40:43]
	v_mfma_f32_16x16x32_bf16 v[32:35], v[166:169], v[192:195], v[32:35]
	v_mfma_f32_16x16x32_bf16 v[24:27], v[158:161], v[200:203], v[24:27]
	v_mfma_f32_16x16x32_bf16 v[16:19], v[166:169], v[200:203], v[16:19]
	v_mfma_f32_16x16x32_bf16 v[8:11], v[158:161], v[208:211], v[8:11]
	v_mfma_f32_16x16x32_bf16 v[0:3], v[166:169], v[208:211], v[0:3]
	v_mfma_f32_16x16x32_bf16 v[56:59], v[162:165], v[188:191], v[56:59]
	v_mfma_f32_16x16x32_bf16 v[48:51], v[170:173], v[188:191], v[48:51]
	v_mfma_f32_16x16x32_bf16 v[40:43], v[162:165], v[196:199], v[40:43]
	v_mfma_f32_16x16x32_bf16 v[32:35], v[170:173], v[196:199], v[32:35]
	v_mfma_f32_16x16x32_bf16 v[24:27], v[162:165], v[204:207], v[24:27]
	v_mfma_f32_16x16x32_bf16 v[16:19], v[170:173], v[204:207], v[16:19]
	v_mfma_f32_16x16x32_bf16 v[8:11], v[162:165], v[212:215], v[8:11]
	v_mfma_f32_16x16x32_bf16 v[0:3], v[170:173], v[212:215], v[0:3]
	s_setprio 0
	s_barrier
	s_add_i32 s20, 16, 0x18000
	s_add_i32 s21, 16, 0x1c000
	v_add_u32_e32 v154, s20, v139
	v_add_u32_e32 v170, s21, v139
	ds_read_b128 v[142:145], v154
	ds_read_b128 v[146:149], v154 offset:1024
	ds_read_b128 v[150:153], v154 offset:2048
	ds_read_b128 v[154:157], v154 offset:3072
	ds_read_b128 v[158:161], v170
	ds_read_b128 v[162:165], v170 offset:1024
	ds_read_b128 v[166:169], v170 offset:2048
	ds_read_b128 v[170:173], v170 offset:3072
	s_add_u32 s24, s24, 0x80000
	s_addc_u32 s25, s25, 0
	s_mov_b32 m0, s31
	v_lshl_add_u64 v[226:227], s[24:25], 0, v[132:133]
	ds_read_b128 v[184:187], v141 offset:32768
	ds_read_b128 v[188:191], v141 offset:33792
	ds_read_b128 v[192:195], v141 offset:34816
	ds_read_b128 v[196:199], v141 offset:35840
	ds_read_b128 v[200:203], v141 offset:36864
	ds_read_b128 v[204:207], v141 offset:37888
	ds_read_b128 v[208:211], v141 offset:38912
	ds_read_b128 v[212:215], v141 offset:39936
	global_load_lds_dwordx4 v[226:227], off
	v_lshl_add_u64 v[226:227], s[24:25], 0, v[130:131]
	s_mov_b32 m0, s42
	s_nop 0
	global_load_lds_dwordx4 v[226:227], off
	s_waitcnt vmcnt(8)
	s_waitcnt lgkmcnt(0)
	s_barrier
	s_setprio 1
	s_waitcnt lgkmcnt(0)
	v_mfma_f32_16x16x32_bf16 v[124:127], v[142:145], v[184:187], v[124:127]
	v_mfma_f32_16x16x32_bf16 v[116:119], v[150:153], v[184:187], v[116:119]
	v_mfma_f32_16x16x32_bf16 v[108:111], v[142:145], v[192:195], v[108:111]
	v_mfma_f32_16x16x32_bf16 v[100:103], v[150:153], v[192:195], v[100:103]
	v_mfma_f32_16x16x32_bf16 v[92:95], v[142:145], v[200:203], v[92:95]
	v_mfma_f32_16x16x32_bf16 v[84:87], v[150:153], v[200:203], v[84:87]
	v_mfma_f32_16x16x32_bf16 v[76:79], v[142:145], v[208:211], v[76:79]
	v_mfma_f32_16x16x32_bf16 v[68:71], v[150:153], v[208:211], v[68:71]
	v_mfma_f32_16x16x32_bf16 v[124:127], v[146:149], v[188:191], v[124:127]
	v_mfma_f32_16x16x32_bf16 v[116:119], v[154:157], v[188:191], v[116:119]
	v_mfma_f32_16x16x32_bf16 v[108:111], v[146:149], v[196:199], v[108:111]
	v_mfma_f32_16x16x32_bf16 v[100:103], v[154:157], v[196:199], v[100:103]
	v_mfma_f32_16x16x32_bf16 v[92:95], v[146:149], v[204:207], v[92:95]
	v_mfma_f32_16x16x32_bf16 v[84:87], v[154:157], v[204:207], v[84:87]
	v_mfma_f32_16x16x32_bf16 v[76:79], v[146:149], v[212:215], v[76:79]
	v_mfma_f32_16x16x32_bf16 v[68:71], v[154:157], v[212:215], v[68:71]
	s_setprio 0
	s_setprio 1
	v_mfma_f32_16x16x32_bf16 v[120:123], v[158:161], v[184:187], v[120:123]
	v_mfma_f32_16x16x32_bf16 v[112:115], v[166:169], v[184:187], v[112:115]
	v_mfma_f32_16x16x32_bf16 v[104:107], v[158:161], v[192:195], v[104:107]
	v_mfma_f32_16x16x32_bf16 v[96:99], v[166:169], v[192:195], v[96:99]
	v_mfma_f32_16x16x32_bf16 v[88:91], v[158:161], v[200:203], v[88:91]
	v_mfma_f32_16x16x32_bf16 v[80:83], v[166:169], v[200:203], v[80:83]
	v_mfma_f32_16x16x32_bf16 v[72:75], v[158:161], v[208:211], v[72:75]
	v_mfma_f32_16x16x32_bf16 v[64:67], v[166:169], v[208:211], v[64:67]
	v_mfma_f32_16x16x32_bf16 v[120:123], v[162:165], v[188:191], v[120:123]
	v_mfma_f32_16x16x32_bf16 v[112:115], v[170:173], v[188:191], v[112:115]
	v_mfma_f32_16x16x32_bf16 v[104:107], v[162:165], v[196:199], v[104:107]
	v_mfma_f32_16x16x32_bf16 v[96:99], v[170:173], v[196:199], v[96:99]
	v_mfma_f32_16x16x32_bf16 v[88:91], v[162:165], v[204:207], v[88:91]
	v_mfma_f32_16x16x32_bf16 v[80:83], v[170:173], v[204:207], v[80:83]
	v_mfma_f32_16x16x32_bf16 v[72:75], v[162:165], v[212:215], v[72:75]
	v_mfma_f32_16x16x32_bf16 v[64:67], v[170:173], v[212:215], v[64:67]
	s_setprio 0
	s_barrier
; #define PG8_STAGE(bufoff, gbase, voff) do { _Pragma("unroll") for (int _i = 0; _i < 2; ++_i) \
;         __builtin_amdgcn_global_load_lds((const unsigned*)((const char*)(gbase) + (voff)[_i]), (LAS unsigned*)(lds + (bufoff) + ldsw + _i * 8192), 16, 0, 0); } while (0)
; #define PG8_LDA(dst, b, h) do { _Pragma("unroll") for (int m = 0; m < 4; ++m) _Pragma("unroll") for (int k = 0; k < 2; ++k) dst[m][k] = *(const LAS bf16x8*)(lds + PG8_SA(b, h) + aoff + m * 2048 + k * 1024); } while (0)
; #define PG8_MMA(ai, bj, At, Bt) do { __builtin_amdgcn_s_setprio(1); _Pragma("unroll") for (int m = 0; m < 4; ++m) _Pragma("unroll") for (int n = 0; n < 2; ++n) _Pragma("unroll") for (int k = 0; k < 2; ++k) \
;         acc[ai][bj][m][n] = __builtin_amdgcn_mfma_f32_16x16x32_bf16(Bt[n][k], At[m][k], acc[ai][bj][m][n], 0, 0, 0); __builtin_amdgcn_s_setprio(0); } while (0)
; #define PG8_WAIT_V(n) asm volatile("s_waitcnt vmcnt(" #n ")" ::: "memory")
; #define PG8_WAIT_L(n) asm volatile("s_waitcnt lgkmcnt(" #n ")" ::: "memory")
; #define PG8_BAR __builtin_amdgcn_s_barrier()
; #define PG8_SCHED __builtin_amdgcn_sched_barrier(0)
; template <class Epi, bool ALIGN_EPI = PG8_ALIGN>
; __device__ __forceinline__ void gemm_phase(LAS unsigned char* lds, const Gemm g, const StaticOrder& S, const Epi& E) {
;     ...
;             PG8_LDA(At, 1, 1); PG8_STAGE(PG8_SB(1, 0), b3, voffB); PG8_STAGE(PG8_SB(1, 1), b3 + hstepB, voffB); PG8_STAGE(PG8_SA(1, 0), a3, voffA);
;             PG8_WAIT_V(8); PG8_WAIT_L(0); PG8_BAR; PG8_MMA(1, 0, At, B0); PG8_MMA(1, 1, At, B1); PG8_BAR; PG8_SCHED;
;         }
	s_add_i32 s20, s20, s18
	v_lshl_add_u64 v[174:175], v[174:175], 0, s[0:1]
	s_mov_b32 m0, s20
	ds_read_b128 v[184:187], v141 offset:49152
	ds_read_b128 v[188:191], v141 offset:50176
	ds_read_b128 v[192:195], v141 offset:51200
	ds_read_b128 v[196:199], v141 offset:52224
	ds_read_b128 v[200:203], v141 offset:53248
	ds_read_b128 v[204:207], v141 offset:54272
	ds_read_b128 v[208:211], v141 offset:55296
	ds_read_b128 v[212:215], v141 offset:56320
	global_load_lds_dwordx4 v[174:175], off
	v_lshl_add_u64 v[174:175], v[216:217], 0, s[0:1]
	s_add_i32 m0, s20, 0x2000
	s_add_i32 s20, s21, s18
	global_load_lds_dwordx4 v[174:175], off
	v_lshl_add_u64 v[174:175], v[218:219], 0, s[0:1]
	s_mov_b32 m0, s20
	s_nop 0
	global_load_lds_dwordx4 v[174:175], off
	v_lshl_add_u64 v[174:175], v[220:221], 0, s[0:1]
	s_add_i32 m0, s20, 0x2000
	s_nop 0
	global_load_lds_dwordx4 v[174:175], off
	v_lshl_add_u64 v[174:175], v[222:223], 0, s[0:1]
	s_mov_b32 m0, s43
	s_nop 0
	global_load_lds_dwordx4 v[174:175], off
	v_lshl_add_u64 v[174:175], v[224:225], 0, s[0:1]
	s_mov_b32 m0, s44
	s_nop 0
	global_load_lds_dwordx4 v[174:175], off
	s_nop 15
	s_nop 15
	s_waitcnt vmcnt(8)
	s_waitcnt lgkmcnt(0)
	s_barrier
	s_setprio 1
	s_waitcnt lgkmcnt(0)
	v_mfma_f32_16x16x32_bf16 v[60:63], v[142:145], v[184:187], v[60:63]
	v_mfma_f32_16x16x32_bf16 v[52:55], v[150:153], v[184:187], v[52:55]
	v_mfma_f32_16x16x32_bf16 v[44:47], v[142:145], v[192:195], v[44:47]
	v_mfma_f32_16x16x32_bf16 v[36:39], v[150:153], v[192:195], v[36:39]
	v_mfma_f32_16x16x32_bf16 v[28:31], v[142:145], v[200:203], v[28:31]
	v_mfma_f32_16x16x32_bf16 v[20:23], v[150:153], v[200:203], v[20:23]
	v_mfma_f32_16x16x32_bf16 v[12:15], v[142:145], v[208:211], v[12:15]
	v_mfma_f32_16x16x32_bf16 v[4:7], v[150:153], v[208:211], v[4:7]
	v_mfma_f32_16x16x32_bf16 v[60:63], v[146:149], v[188:191], v[60:63]
	v_mfma_f32_16x16x32_bf16 v[52:55], v[154:157], v[188:191], v[52:55]
	v_mfma_f32_16x16x32_bf16 v[44:47], v[146:149], v[196:199], v[44:47]
	v_mfma_f32_16x16x32_bf16 v[36:39], v[154:157], v[196:199], v[36:39]
	v_mfma_f32_16x16x32_bf16 v[28:31], v[146:149], v[204:207], v[28:31]
	v_mfma_f32_16x16x32_bf16 v[20:23], v[154:157], v[204:207], v[20:23]
	v_mfma_f32_16x16x32_bf16 v[12:15], v[146:149], v[212:215], v[12:15]
	v_mfma_f32_16x16x32_bf16 v[4:7], v[154:157], v[212:215], v[4:7]
	s_setprio 0
	s_setprio 1
	v_mfma_f32_16x16x32_bf16 v[56:59], v[158:161], v[184:187], v[56:59]
	v_mfma_f32_16x16x32_bf16 v[48:51], v[166:169], v[184:187], v[48:51]
	v_mfma_f32_16x16x32_bf16 v[40:43], v[158:161], v[192:195], v[40:43]
	v_mfma_f32_16x16x32_bf16 v[32:35], v[166:169], v[192:195], v[32:35]
	v_mfma_f32_16x16x32_bf16 v[24:27], v[158:161], v[200:203], v[24:27]
	v_mfma_f32_16x16x32_bf16 v[16:19], v[166:169], v[200:203], v[16:19]
	v_mfma_f32_16x16x32_bf16 v[8:11], v[158:161], v[208:211], v[8:11]
	v_mfma_f32_16x16x32_bf16 v[0:3], v[166:169], v[208:211], v[0:3]
	v_mfma_f32_16x16x32_bf16 v[56:59], v[162:165], v[188:191], v[56:59]
	v_mfma_f32_16x16x32_bf16 v[48:51], v[170:173], v[188:191], v[48:51]
	v_mfma_f32_16x16x32_bf16 v[40:43], v[162:165], v[196:199], v[40:43]
	v_mfma_f32_16x16x32_bf16 v[32:35], v[170:173], v[196:199], v[32:35]
	v_mfma_f32_16x16x32_bf16 v[24:27], v[162:165], v[204:207], v[24:27]
	v_mfma_f32_16x16x32_bf16 v[16:19], v[170:173], v[204:207], v[16:19]
	v_mfma_f32_16x16x32_bf16 v[8:11], v[162:165], v[212:215], v[8:11]
	v_mfma_f32_16x16x32_bf16 v[0:3], v[170:173], v[212:215], v[0:3]
	s_setprio 0
	s_barrier
	s_add_u32 s2, s2, 0x100
	s_addc_u32 s3, s3, 0
	s_add_u32 s36, s36, 0x100
	s_addc_u32 s37, s37, 0
	s_cmp_ge_i32 s49, s45
	s_mov_b32 s24, s49
	s_cbranch_scc0 .LBB0_219

; #define PG8_STAGE(bufoff, gbase, voff) do { _Pragma("unroll") for (int _i = 0; _i < 2; ++_i) \
;         __builtin_amdgcn_global_load_lds((const unsigned*)((const char*)(gbase) + (voff)[_i]), (LAS unsigned*)(lds + (bufoff) + ldsw + _i * 8192), 16, 0, 0); } while (0)
; #define PG8_LDA(dst, b, h) do { _Pragma("unroll") for (int m = 0; m < 4; ++m) _Pragma("unroll") for (int k = 0; k < 2; ++k) dst[m][k] = *(const LAS bf16x8*)(lds + PG8_SA(b, h) + aoff + m * 2048 + k * 1024); } while (0)
; #define PG8_LDB(dst, b, h) do { _Pragma("unroll") for (int n = 0; n < 2; ++n) _Pragma("unroll") for (int k = 0; k < 2; ++k) dst[n][k] = *(const LAS bf16x8*)(lds + PG8_SB(b, h) + boff + n * 2048 + k * 1024); } while (0)
; #define PG8_MMA(ai, bj, At, Bt) do { __builtin_amdgcn_s_setprio(1); _Pragma("unroll") for (int m = 0; m < 4; ++m) _Pragma("unroll") for (int n = 0; n < 2; ++n) _Pragma("unroll") for (int k = 0; k < 2; ++k) \
;         acc[ai][bj][m][n] = __builtin_amdgcn_mfma_f32_16x16x32_bf16(Bt[n][k], At[m][k], acc[ai][bj][m][n], 0, 0, 0); __builtin_amdgcn_s_setprio(0); } while (0)
; #define PG8_WAIT_V(n) asm volatile("s_waitcnt vmcnt(" #n ")" ::: "memory")
; #define PG8_WAIT_L(n) asm volatile("s_waitcnt lgkmcnt(" #n ")" ::: "memory")
; #define PG8_BAR __builtin_amdgcn_s_barrier()
; #define PG8_SCHED __builtin_amdgcn_sched_barrier(0)
; template <class Epi, bool ALIGN_EPI = PG8_ALIGN>
; __device__ __forceinline__ void gemm_phase(LAS unsigned char* lds, const Gemm g, const StaticOrder& S, const Epi& E) {
;     ...
;         for (int t = 0; t < nt; t += 2) {
;             const bool last = (t == nt - 2);
;             const char* a1 = cA + (size_t)(t + 1) * kstep;
;             const char* a2 = last ? nA : cA + (size_t)(t + 2) * kstep; const char* b2 = last ? nB : cB + (size_t)(t + 2) * kstep;
;             const char* a3 = a2 + kstep; const char* b3 = b2 + kstep;
;             PG8_LDB(B0, 0, 0); PG8_LDB(B1, 0, 1); PG8_SCHED; PG8_LDA(At, 0, 0); PG8_STAGE(PG8_SA(1, 1), a1 + hstepA, voffA);
;             PG8_WAIT_V(8); PG8_WAIT_L(0); PG8_BAR; PG8_MMA(0, 0, At, B0); PG8_MMA(0, 1, At, B1); PG8_BAR; PG8_SCHED;
;             PG8_LDA(At, 0, 1); PG8_STAGE(PG8_SB(0, 0), b2, voffB); PG8_STAGE(PG8_SB(0, 1), b2 + hstepB, voffB); PG8_STAGE(PG8_SA(0, 0), a2, voffA);
.LBB0_295:
	s_add_i32 s53, s38, 2
	s_add_u32 s36, s24, 0x100
	s_addc_u32 s37, s25, 0
	s_add_i32 s20, 16, 0x10000
	s_cmp_eq_u32 s26, s38
	s_cselect_b32 s39, s3, s37
	s_cselect_b32 s38, s2, s36
	s_cselect_b32 s55, s17, s52
	s_cselect_b32 s54, s16, s51
	s_add_i32 s21, 16, 0x14000
	v_add_u32_e32 v154, s20, v147
	v_add_u32_e32 v170, s21, v147
	ds_read_b128 v[138:141], v154
	ds_read_b128 v[142:145], v154 offset:1024
	ds_read_b128 v[150:153], v154 offset:2048
	ds_read_b128 v[154:157], v154 offset:3072
	ds_read_b128 v[158:161], v170
	ds_read_b128 v[162:165], v170 offset:1024
	ds_read_b128 v[166:169], v170 offset:2048
	ds_read_b128 v[170:173], v170 offset:3072
	v_lshl_add_u64 v[174:175], s[24:25], 0, v[134:135]
	s_add_i32 m0, s31, 0xc000
	ds_read_b128 v[184:187], v149
	ds_read_b128 v[188:191], v149 offset:1024
	ds_read_b128 v[192:195], v149 offset:2048
	ds_read_b128 v[196:199], v149 offset:3072
	ds_read_b128 v[200:203], v149 offset:4096
	ds_read_b128 v[204:207], v149 offset:5120
	ds_read_b128 v[208:211], v149 offset:6144
	ds_read_b128 v[212:215], v149 offset:7168
	global_load_lds_dwordx4 v[174:175], off
	v_lshl_add_u64 v[174:175], s[24:25], 0, v[136:137]
	s_add_i32 m0, s31, 0xe000
	s_nop 0
	global_load_lds_dwordx4 v[174:175], off
	s_waitcnt vmcnt(8)
	s_waitcnt lgkmcnt(0)
	s_barrier
	s_setprio 1
	s_waitcnt lgkmcnt(0)
	v_mfma_f32_16x16x32_bf16 v[124:127], v[138:141], v[184:187], v[124:127]
	v_mfma_f32_16x16x32_bf16 v[120:123], v[150:153], v[184:187], v[120:123]
	v_mfma_f32_16x16x32_bf16 v[116:119], v[138:141], v[192:195], v[116:119]
	v_mfma_f32_16x16x32_bf16 v[112:115], v[150:153], v[192:195], v[112:115]
	v_mfma_f32_16x16x32_bf16 v[104:107], v[138:141], v[200:203], v[104:107]
	v_mfma_f32_16x16x32_bf16 v[96:99], v[150:153], v[200:203], v[96:99]
	v_mfma_f32_16x16x32_bf16 v[88:91], v[138:141], v[208:211], v[88:91]
	v_mfma_f32_16x16x32_bf16 v[80:83], v[150:153], v[208:211], v[80:83]
	v_mfma_f32_16x16x32_bf16 v[124:127], v[142:145], v[188:191], v[124:127]
	v_mfma_f32_16x16x32_bf16 v[120:123], v[154:157], v[188:191], v[120:123]
	v_mfma_f32_16x16x32_bf16 v[116:119], v[142:145], v[196:199], v[116:119]
	v_mfma_f32_16x16x32_bf16 v[112:115], v[154:157], v[196:199], v[112:115]
	v_mfma_f32_16x16x32_bf16 v[104:107], v[142:145], v[204:207], v[104:107]
	v_mfma_f32_16x16x32_bf16 v[96:99], v[154:157], v[204:207], v[96:99]
	v_mfma_f32_16x16x32_bf16 v[88:91], v[142:145], v[212:215], v[88:91]
	v_mfma_f32_16x16x32_bf16 v[80:83], v[154:157], v[212:215], v[80:83]
	s_setprio 0
	s_setprio 1
	v_mfma_f32_16x16x32_bf16 v[108:111], v[158:161], v[184:187], v[108:111]
	v_mfma_f32_16x16x32_bf16 v[100:103], v[166:169], v[184:187], v[100:103]
	v_mfma_f32_16x16x32_bf16 v[92:95], v[158:161], v[192:195], v[92:95]
	v_mfma_f32_16x16x32_bf16 v[84:87], v[166:169], v[192:195], v[84:87]
	v_mfma_f32_16x16x32_bf16 v[76:79], v[158:161], v[200:203], v[76:79]
	v_mfma_f32_16x16x32_bf16 v[72:75], v[166:169], v[200:203], v[72:75]
	v_mfma_f32_16x16x32_bf16 v[68:71], v[158:161], v[208:211], v[68:71]
	v_mfma_f32_16x16x32_bf16 v[64:67], v[166:169], v[208:211], v[64:67]
	v_mfma_f32_16x16x32_bf16 v[108:111], v[162:165], v[188:191], v[108:111]
	v_mfma_f32_16x16x32_bf16 v[100:103], v[170:173], v[188:191], v[100:103]
	v_mfma_f32_16x16x32_bf16 v[92:95], v[162:165], v[196:199], v[92:95]
	v_mfma_f32_16x16x32_bf16 v[84:87], v[170:173], v[196:199], v[84:87]
	v_mfma_f32_16x16x32_bf16 v[76:79], v[162:165], v[204:207], v[76:79]
	v_mfma_f32_16x16x32_bf16 v[72:75], v[170:173], v[204:207], v[72:75]
	v_mfma_f32_16x16x32_bf16 v[68:71], v[162:165], v[212:215], v[68:71]
	v_mfma_f32_16x16x32_bf16 v[64:67], v[170:173], v[212:215], v[64:67]
	s_setprio 0
	s_barrier
	s_add_i32 s20, s20, s18
	v_lshl_add_u64 v[174:175], s[54:55], 0, v[176:177]
	s_mov_b32 m0, s20
	ds_read_b128 v[184:187], v149 offset:16384
	ds_read_b128 v[188:191], v149 offset:17408
	ds_read_b128 v[192:195], v149 offset:18432
	ds_read_b128 v[196:199], v149 offset:19456
	ds_read_b128 v[200:203], v149 offset:20480
	ds_read_b128 v[204:207], v149 offset:21504
	ds_read_b128 v[208:211], v149 offset:22528
	ds_read_b128 v[212:215], v149 offset:23552
	global_load_lds_dwordx4 v[174:175], off
	s_add_i32 m0, s20, 0x2000
	s_add_u32 s24, s54, s6
	v_lshl_add_u64 v[216:217], s[54:55], 0, v[128:129]
	s_addc_u32 s25, s55, s7
	s_add_i32 s20, s21, s18
	global_load_lds_dwordx4 v[216:217], off
	v_lshl_add_u64 v[218:219], s[24:25], 0, v[176:177]
	s_mov_b32 m0, s20
	v_lshl_add_u64 v[220:221], s[24:25], 0, v[128:129]
	global_load_lds_dwordx4 v[218:219], off
	s_add_i32 m0, s20, 0x2000
	v_lshl_add_u64 v[222:223], s[38:39], 0, v[132:133]
	global_load_lds_dwordx4 v[220:221], off
	s_mov_b32 m0, s31
	v_lshl_add_u64 v[224:225], s[38:39], 0, v[130:131]
	global_load_lds_dwordx4 v[222:223], off
	s_mov_b32 m0, s40
	s_nop 0
	global_load_lds_dwordx4 v[224:225], off
	s_nop 15
	s_nop 15
	s_waitcnt vmcnt(8)
	s_waitcnt lgkmcnt(0)
	s_barrier
; #define PG8_STAGE(bufoff, gbase, voff) do { _Pragma("unroll") for (int _i = 0; _i < 2; ++_i) \
;         __builtin_amdgcn_global_load_lds((const unsigned*)((const char*)(gbase) + (voff)[_i]), (LAS unsigned*)(lds + (bufoff) + ldsw + _i * 8192), 16, 0, 0); } while (0)
; #define PG8_LDA(dst, b, h) do { _Pragma("unroll") for (int m = 0; m < 4; ++m) _Pragma("unroll") for (int k = 0; k < 2; ++k) dst[m][k] = *(const LAS bf16x8*)(lds + PG8_SA(b, h) + aoff + m * 2048 + k * 1024); } while (0)
; #define PG8_LDB(dst, b, h) do { _Pragma("unroll") for (int n = 0; n < 2; ++n) _Pragma("unroll") for (int k = 0; k < 2; ++k) dst[n][k] = *(const LAS bf16x8*)(lds + PG8_SB(b, h) + boff + n * 2048 + k * 1024); } while (0)
; #define PG8_MMA(ai, bj, At, Bt) do { __builtin_amdgcn_s_setprio(1); _Pragma("unroll") for (int m = 0; m < 4; ++m) _Pragma("unroll") for (int n = 0; n < 2; ++n) _Pragma("unroll") for (int k = 0; k < 2; ++k) \
;         acc[ai][bj][m][n] = __builtin_amdgcn_mfma_f32_16x16x32_bf16(Bt[n][k], At[m][k], acc[ai][bj][m][n], 0, 0, 0); __builtin_amdgcn_s_setprio(0); } while (0)
; #define PG8_WAIT_V(n) asm volatile("s_waitcnt vmcnt(" #n ")" ::: "memory")
; #define PG8_WAIT_L(n) asm volatile("s_waitcnt lgkmcnt(" #n ")" ::: "memory")
; #define PG8_BAR __builtin_amdgcn_s_barrier()
; #define PG8_SCHED __builtin_amdgcn_sched_barrier(0)
; template <class Epi, bool ALIGN_EPI = PG8_ALIGN>
; __device__ __forceinline__ void gemm_phase(LAS unsigned char* lds, const Gemm g, const StaticOrder& S, const Epi& E) {
;     ...
;             PG8_WAIT_V(8); PG8_WAIT_L(0); PG8_BAR; PG8_MMA(1, 0, At, B0); PG8_MMA(1, 1, At, B1); PG8_BAR; PG8_SCHED;
;             PG8_LDB(B0, 1, 0); PG8_LDB(B1, 1, 1); PG8_SCHED; PG8_LDA(At, 1, 0); PG8_STAGE(PG8_SA(0, 1), a2 + hstepA, voffA);
;             PG8_WAIT_V(8); PG8_WAIT_L(0); PG8_BAR; PG8_MMA(0, 0, At, B0); PG8_MMA(0, 1, At, B1); PG8_BAR; PG8_SCHED;
	s_setprio 1
	s_waitcnt lgkmcnt(0)
	v_mfma_f32_16x16x32_bf16 v[60:63], v[138:141], v[184:187], v[60:63]
	v_mfma_f32_16x16x32_bf16 v[56:59], v[150:153], v[184:187], v[56:59]
	v_mfma_f32_16x16x32_bf16 v[52:55], v[138:141], v[192:195], v[52:55]
	v_mfma_f32_16x16x32_bf16 v[48:51], v[150:153], v[192:195], v[48:51]
	v_mfma_f32_16x16x32_bf16 v[40:43], v[138:141], v[200:203], v[40:43]
	v_mfma_f32_16x16x32_bf16 v[32:35], v[150:153], v[200:203], v[32:35]
	v_mfma_f32_16x16x32_bf16 v[24:27], v[138:141], v[208:211], v[24:27]
	v_mfma_f32_16x16x32_bf16 v[16:19], v[150:153], v[208:211], v[16:19]
	v_mfma_f32_16x16x32_bf16 v[60:63], v[142:145], v[188:191], v[60:63]
	v_mfma_f32_16x16x32_bf16 v[56:59], v[154:157], v[188:191], v[56:59]
	v_mfma_f32_16x16x32_bf16 v[52:55], v[142:145], v[196:199], v[52:55]
	v_mfma_f32_16x16x32_bf16 v[48:51], v[154:157], v[196:199], v[48:51]
	v_mfma_f32_16x16x32_bf16 v[40:43], v[142:145], v[204:207], v[40:43]
	v_mfma_f32_16x16x32_bf16 v[32:35], v[154:157], v[204:207], v[32:35]
	v_mfma_f32_16x16x32_bf16 v[24:27], v[142:145], v[212:215], v[24:27]
	v_mfma_f32_16x16x32_bf16 v[16:19], v[154:157], v[212:215], v[16:19]
	s_setprio 0
	s_setprio 1
	v_mfma_f32_16x16x32_bf16 v[44:47], v[158:161], v[184:187], v[44:47]
	v_mfma_f32_16x16x32_bf16 v[36:39], v[166:169], v[184:187], v[36:39]
	v_mfma_f32_16x16x32_bf16 v[28:31], v[158:161], v[192:195], v[28:31]
	v_mfma_f32_16x16x32_bf16 v[20:23], v[166:169], v[192:195], v[20:23]
	v_mfma_f32_16x16x32_bf16 v[12:15], v[158:161], v[200:203], v[12:15]
	v_mfma_f32_16x16x32_bf16 v[8:11], v[166:169], v[200:203], v[8:11]
	v_mfma_f32_16x16x32_bf16 v[4:7], v[158:161], v[208:211], v[4:7]
	v_mfma_f32_16x16x32_bf16 v[0:3], v[166:169], v[208:211], v[0:3]
	v_mfma_f32_16x16x32_bf16 v[44:47], v[162:165], v[188:191], v[44:47]
	v_mfma_f32_16x16x32_bf16 v[36:39], v[170:173], v[188:191], v[36:39]
	v_mfma_f32_16x16x32_bf16 v[28:31], v[162:165], v[196:199], v[28:31]
	v_mfma_f32_16x16x32_bf16 v[20:23], v[170:173], v[196:199], v[20:23]
	v_mfma_f32_16x16x32_bf16 v[12:15], v[162:165], v[204:207], v[12:15]
	v_mfma_f32_16x16x32_bf16 v[8:11], v[170:173], v[204:207], v[8:11]
	v_mfma_f32_16x16x32_bf16 v[4:7], v[162:165], v[212:215], v[4:7]
	v_mfma_f32_16x16x32_bf16 v[0:3], v[170:173], v[212:215], v[0:3]
	s_setprio 0
	s_barrier
	s_add_i32 s20, 16, 0x18000
	s_add_i32 s21, 16, 0x1c000
	v_add_u32_e32 v154, s20, v147
	v_add_u32_e32 v170, s21, v147
	ds_read_b128 v[138:141], v154
	ds_read_b128 v[142:145], v154 offset:1024
	ds_read_b128 v[150:153], v154 offset:2048
	ds_read_b128 v[154:157], v154 offset:3072
	ds_read_b128 v[158:161], v170
	ds_read_b128 v[162:165], v170 offset:1024
	ds_read_b128 v[166:169], v170 offset:2048
	ds_read_b128 v[170:173], v170 offset:3072
	s_add_u32 s24, s38, 0x160000
	s_addc_u32 s25, s39, 0
	s_mov_b32 m0, s41
	v_lshl_add_u64 v[226:227], s[24:25], 0, v[132:133]
	ds_read_b128 v[184:187], v149 offset:32768
	ds_read_b128 v[188:191], v149 offset:33792
	ds_read_b128 v[192:195], v149 offset:34816
	ds_read_b128 v[196:199], v149 offset:35840
	ds_read_b128 v[200:203], v149 offset:36864
	ds_read_b128 v[204:207], v149 offset:37888
	ds_read_b128 v[208:211], v149 offset:38912
	ds_read_b128 v[212:215], v149 offset:39936
	global_load_lds_dwordx4 v[226:227], off
	v_lshl_add_u64 v[226:227], s[24:25], 0, v[130:131]
	s_mov_b32 m0, s44
	s_nop 0
	global_load_lds_dwordx4 v[226:227], off
	s_waitcnt vmcnt(8)
	s_waitcnt lgkmcnt(0)
	s_barrier
	s_setprio 1
	s_waitcnt lgkmcnt(0)
	v_mfma_f32_16x16x32_bf16 v[124:127], v[138:141], v[184:187], v[124:127]
	v_mfma_f32_16x16x32_bf16 v[120:123], v[150:153], v[184:187], v[120:123]
	v_mfma_f32_16x16x32_bf16 v[116:119], v[138:141], v[192:195], v[116:119]
	v_mfma_f32_16x16x32_bf16 v[112:115], v[150:153], v[192:195], v[112:115]
	v_mfma_f32_16x16x32_bf16 v[104:107], v[138:141], v[200:203], v[104:107]
	v_mfma_f32_16x16x32_bf16 v[96:99], v[150:153], v[200:203], v[96:99]
	v_mfma_f32_16x16x32_bf16 v[88:91], v[138:141], v[208:211], v[88:91]
	v_mfma_f32_16x16x32_bf16 v[80:83], v[150:153], v[208:211], v[80:83]
	v_mfma_f32_16x16x32_bf16 v[124:127], v[142:145], v[188:191], v[124:127]
	v_mfma_f32_16x16x32_bf16 v[120:123], v[154:157], v[188:191], v[120:123]
	v_mfma_f32_16x16x32_bf16 v[116:119], v[142:145], v[196:199], v[116:119]
	v_mfma_f32_16x16x32_bf16 v[112:115], v[154:157], v[196:199], v[112:115]
	v_mfma_f32_16x16x32_bf16 v[104:107], v[142:145], v[204:207], v[104:107]
	v_mfma_f32_16x16x32_bf16 v[96:99], v[154:157], v[204:207], v[96:99]
	v_mfma_f32_16x16x32_bf16 v[88:91], v[142:145], v[212:215], v[88:91]
	v_mfma_f32_16x16x32_bf16 v[80:83], v[154:157], v[212:215], v[80:83]
	s_setprio 0
	s_setprio 1
	v_mfma_f32_16x16x32_bf16 v[108:111], v[158:161], v[184:187], v[108:111]
	v_mfma_f32_16x16x32_bf16 v[100:103], v[166:169], v[184:187], v[100:103]
	v_mfma_f32_16x16x32_bf16 v[92:95], v[158:161], v[192:195], v[92:95]
	v_mfma_f32_16x16x32_bf16 v[84:87], v[166:169], v[192:195], v[84:87]
	v_mfma_f32_16x16x32_bf16 v[76:79], v[158:161], v[200:203], v[76:79]
	v_mfma_f32_16x16x32_bf16 v[72:75], v[166:169], v[200:203], v[72:75]
	v_mfma_f32_16x16x32_bf16 v[68:71], v[158:161], v[208:211], v[68:71]
	v_mfma_f32_16x16x32_bf16 v[64:67], v[166:169], v[208:211], v[64:67]
	v_mfma_f32_16x16x32_bf16 v[108:111], v[162:165], v[188:191], v[108:111]
	v_mfma_f32_16x16x32_bf16 v[100:103], v[170:173], v[188:191], v[100:103]
	v_mfma_f32_16x16x32_bf16 v[92:95], v[162:165], v[196:199], v[92:95]
	v_mfma_f32_16x16x32_bf16 v[84:87], v[170:173], v[196:199], v[84:87]
	v_mfma_f32_16x16x32_bf16 v[76:79], v[162:165], v[204:207], v[76:79]
	v_mfma_f32_16x16x32_bf16 v[72:75], v[170:173], v[204:207], v[72:75]
	v_mfma_f32_16x16x32_bf16 v[68:71], v[162:165], v[212:215], v[68:71]
	v_mfma_f32_16x16x32_bf16 v[64:67], v[170:173], v[212:215], v[64:67]
	s_setprio 0
	s_barrier
; #define PG8_STAGE(bufoff, gbase, voff) do { _Pragma("unroll") for (int _i = 0; _i < 2; ++_i) \
;         __builtin_amdgcn_global_load_lds((const unsigned*)((const char*)(gbase) + (voff)[_i]), (LAS unsigned*)(lds + (bufoff) + ldsw + _i * 8192), 16, 0, 0); } while (0)
; #define PG8_LDA(dst, b, h) do { _Pragma("unroll") for (int m = 0; m < 4; ++m) _Pragma("unroll") for (int k = 0; k < 2; ++k) dst[m][k] = *(const LAS bf16x8*)(lds + PG8_SA(b, h) + aoff + m * 2048 + k * 1024); } while (0)
; #define PG8_MMA(ai, bj, At, Bt) do { __builtin_amdgcn_s_setprio(1); _Pragma("unroll") for (int m = 0; m < 4; ++m) _Pragma("unroll") for (int n = 0; n < 2; ++n) _Pragma("unroll") for (int k = 0; k < 2; ++k) \
;         acc[ai][bj][m][n] = __builtin_amdgcn_mfma_f32_16x16x32_bf16(Bt[n][k], At[m][k], acc[ai][bj][m][n], 0, 0, 0); __builtin_amdgcn_s_setprio(0); } while (0)
; #define PG8_WAIT_V(n) asm volatile("s_waitcnt vmcnt(" #n ")" ::: "memory")
; #define PG8_WAIT_L(n) asm volatile("s_waitcnt lgkmcnt(" #n ")" ::: "memory")
; #define PG8_BAR __builtin_amdgcn_s_barrier()
; #define PG8_SCHED __builtin_amdgcn_sched_barrier(0)
; template <class Epi, bool ALIGN_EPI = PG8_ALIGN>
; __device__ __forceinline__ void gemm_phase(LAS unsigned char* lds, const Gemm g, const StaticOrder& S, const Epi& E) {
;     ...
;             PG8_LDA(At, 1, 1); PG8_STAGE(PG8_SB(1, 0), b3, voffB); PG8_STAGE(PG8_SB(1, 1), b3 + hstepB, voffB); PG8_STAGE(PG8_SA(1, 0), a3, voffA);
;             PG8_WAIT_V(8); PG8_WAIT_L(0); PG8_BAR; PG8_MMA(1, 0, At, B0); PG8_MMA(1, 1, At, B1); PG8_BAR; PG8_SCHED;
;         }
	s_add_i32 s20, s20, s18
	v_lshl_add_u64 v[174:175], v[174:175], 0, s[0:1]
	s_mov_b32 m0, s20
	ds_read_b128 v[184:187], v149 offset:49152
	ds_read_b128 v[188:191], v149 offset:50176
	ds_read_b128 v[192:195], v149 offset:51200
	ds_read_b128 v[196:199], v149 offset:52224
	ds_read_b128 v[200:203], v149 offset:53248
	ds_read_b128 v[204:207], v149 offset:54272
	ds_read_b128 v[208:211], v149 offset:55296
	ds_read_b128 v[212:215], v149 offset:56320
	global_load_lds_dwordx4 v[174:175], off
	v_lshl_add_u64 v[174:175], v[216:217], 0, s[0:1]
	s_add_i32 m0, s20, 0x2000
	s_add_i32 s20, s21, s18
	global_load_lds_dwordx4 v[174:175], off
	v_lshl_add_u64 v[174:175], v[218:219], 0, s[0:1]
	s_mov_b32 m0, s20
	s_nop 0
	global_load_lds_dwordx4 v[174:175], off
	v_lshl_add_u64 v[174:175], v[220:221], 0, s[0:1]
	s_add_i32 m0, s20, 0x2000
	s_nop 0
	global_load_lds_dwordx4 v[174:175], off
	v_lshl_add_u64 v[174:175], v[222:223], 0, s[0:1]
	s_mov_b32 m0, s45
	s_nop 0
	global_load_lds_dwordx4 v[174:175], off
	v_lshl_add_u64 v[174:175], v[224:225], 0, s[0:1]
	s_mov_b32 m0, s46
	s_nop 0
	global_load_lds_dwordx4 v[174:175], off
	s_nop 15
	s_nop 15
	s_waitcnt vmcnt(8)
	s_waitcnt lgkmcnt(0)
	s_barrier
	s_setprio 1
	s_waitcnt lgkmcnt(0)
	v_mfma_f32_16x16x32_bf16 v[60:63], v[138:141], v[184:187], v[60:63]
	v_mfma_f32_16x16x32_bf16 v[56:59], v[150:153], v[184:187], v[56:59]
	v_mfma_f32_16x16x32_bf16 v[52:55], v[138:141], v[192:195], v[52:55]
	v_mfma_f32_16x16x32_bf16 v[48:51], v[150:153], v[192:195], v[48:51]
	v_mfma_f32_16x16x32_bf16 v[40:43], v[138:141], v[200:203], v[40:43]
	v_mfma_f32_16x16x32_bf16 v[32:35], v[150:153], v[200:203], v[32:35]
	v_mfma_f32_16x16x32_bf16 v[24:27], v[138:141], v[208:211], v[24:27]
	v_mfma_f32_16x16x32_bf16 v[16:19], v[150:153], v[208:211], v[16:19]
	v_mfma_f32_16x16x32_bf16 v[60:63], v[142:145], v[188:191], v[60:63]
	v_mfma_f32_16x16x32_bf16 v[56:59], v[154:157], v[188:191], v[56:59]
	v_mfma_f32_16x16x32_bf16 v[52:55], v[142:145], v[196:199], v[52:55]
	v_mfma_f32_16x16x32_bf16 v[48:51], v[154:157], v[196:199], v[48:51]
	v_mfma_f32_16x16x32_bf16 v[40:43], v[142:145], v[204:207], v[40:43]
	v_mfma_f32_16x16x32_bf16 v[32:35], v[154:157], v[204:207], v[32:35]
	v_mfma_f32_16x16x32_bf16 v[24:27], v[142:145], v[212:215], v[24:27]
	v_mfma_f32_16x16x32_bf16 v[16:19], v[154:157], v[212:215], v[16:19]
	s_setprio 0
	s_setprio 1
	v_mfma_f32_16x16x32_bf16 v[44:47], v[158:161], v[184:187], v[44:47]
	v_mfma_f32_16x16x32_bf16 v[36:39], v[166:169], v[184:187], v[36:39]
	v_mfma_f32_16x16x32_bf16 v[28:31], v[158:161], v[192:195], v[28:31]
	v_mfma_f32_16x16x32_bf16 v[20:23], v[166:169], v[192:195], v[20:23]
	v_mfma_f32_16x16x32_bf16 v[12:15], v[158:161], v[200:203], v[12:15]
	v_mfma_f32_16x16x32_bf16 v[8:11], v[166:169], v[200:203], v[8:11]
	v_mfma_f32_16x16x32_bf16 v[4:7], v[158:161], v[208:211], v[4:7]
	v_mfma_f32_16x16x32_bf16 v[0:3], v[166:169], v[208:211], v[0:3]
	v_mfma_f32_16x16x32_bf16 v[44:47], v[162:165], v[188:191], v[44:47]
	v_mfma_f32_16x16x32_bf16 v[36:39], v[170:173], v[188:191], v[36:39]
	v_mfma_f32_16x16x32_bf16 v[28:31], v[162:165], v[196:199], v[28:31]
	v_mfma_f32_16x16x32_bf16 v[20:23], v[170:173], v[196:199], v[20:23]
	v_mfma_f32_16x16x32_bf16 v[12:15], v[162:165], v[204:207], v[12:15]
	v_mfma_f32_16x16x32_bf16 v[8:11], v[170:173], v[204:207], v[8:11]
	v_mfma_f32_16x16x32_bf16 v[4:7], v[162:165], v[212:215], v[4:7]
	v_mfma_f32_16x16x32_bf16 v[0:3], v[170:173], v[212:215], v[0:3]
	s_setprio 0
	s_barrier
	s_add_u32 s51, s51, 0x100
	s_addc_u32 s52, s52, 0
	s_cmp_ge_i32 s53, s47
	s_mov_b64 s[24:25], s[36:37]
	s_mov_b32 s38, s53
	s_cbranch_scc0 .LBB0_295
;     __device__ __forceinline__ void operator()(const f32x4 (&acc)[2][2][4][2], const Unit& u, int wr, int wc, int fr, int fq) const {
;     ...
;                 for (int bj = 0; bj < 2; ++bj) { const f32x4 v0 = acc[ai][bj][m][0] * sc, v1 = acc[ai][bj][m][1] * sc;
	v_pk_mul_f32 v[126:127], v[126:127], 0.5 op_sel_hi:[1,0]
	v_pk_mul_f32 v[124:125], v[124:125], 0.5 op_sel_hi:[1,0]
	v_pk_mul_f32 v[122:123], v[122:123], 0.5 op_sel_hi:[1,0]
	v_pk_mul_f32 v[120:121], v[120:121], 0.5 op_sel_hi:[1,0]
	v_pk_mul_f32 v[138:139], v[110:111], 0.5 op_sel_hi:[1,0]
	v_pk_mul_f32 v[140:141], v[108:109], 0.5 op_sel_hi:[1,0]
	v_pk_mul_f32 v[142:143], v[102:103], 0.5 op_sel_hi:[1,0]
	v_pk_mul_f32 v[144:145], v[100:101], 0.5 op_sel_hi:[1,0]
	v_pk_mul_f32 v[100:101], v[118:119], 0.5 op_sel_hi:[1,0]
	v_pk_mul_f32 v[102:103], v[116:117], 0.5 op_sel_hi:[1,0]
	v_pk_mul_f32 v[108:109], v[114:115], 0.5 op_sel_hi:[1,0]
	v_pk_mul_f32 v[110:111], v[112:113], 0.5 op_sel_hi:[1,0]
	v_pk_mul_f32 v[112:113], v[94:95], 0.5 op_sel_hi:[1,0]
	v_pk_mul_f32 v[114:115], v[92:93], 0.5 op_sel_hi:[1,0]
	v_pk_mul_f32 v[116:117], v[86:87], 0.5 op_sel_hi:[1,0]
	v_pk_mul_f32 v[118:119], v[84:85], 0.5 op_sel_hi:[1,0]
	v_pk_mul_f32 v[84:85], v[106:107], 0.5 op_sel_hi:[1,0]
	v_pk_mul_f32 v[86:87], v[104:105], 0.5 op_sel_hi:[1,0]
	v_pk_mul_f32 v[92:93], v[98:99], 0.5 op_sel_hi:[1,0]
	v_pk_mul_f32 v[94:95], v[96:97], 0.5 op_sel_hi:[1,0]
	v_pk_mul_f32 v[96:97], v[78:79], 0.5 op_sel_hi:[1,0]
	v_pk_mul_f32 v[98:99], v[76:77], 0.5 op_sel_hi:[1,0]
	v_pk_mul_f32 v[104:105], v[74:75], 0.5 op_sel_hi:[1,0]
	v_pk_mul_f32 v[106:107], v[72:73], 0.5 op_sel_hi:[1,0]
	v_pk_mul_f32 v[72:73], v[90:91], 0.5 op_sel_hi:[1,0]
	v_pk_mul_f32 v[74:75], v[88:89], 0.5 op_sel_hi:[1,0]
	v_pk_mul_f32 v[76:77], v[82:83], 0.5 op_sel_hi:[1,0]
	v_pk_mul_f32 v[78:79], v[80:81], 0.5 op_sel_hi:[1,0]
	v_pk_mul_f32 v[70:71], v[70:71], 0.5 op_sel_hi:[1,0]
	v_pk_mul_f32 v[68:69], v[68:69], 0.5 op_sel_hi:[1,0]
	v_pk_mul_f32 v[66:67], v[66:67], 0.5 op_sel_hi:[1,0]
	v_pk_mul_f32 v[64:65], v[64:65], 0.5 op_sel_hi:[1,0]
	v_pk_mul_f32 v[62:63], v[62:63], 0.5 op_sel_hi:[1,0]
	v_pk_mul_f32 v[60:61], v[60:61], 0.5 op_sel_hi:[1,0]
	v_pk_mul_f32 v[58:59], v[58:59], 0.5 op_sel_hi:[1,0]
	v_pk_mul_f32 v[56:57], v[56:57], 0.5 op_sel_hi:[1,0]
	v_pk_mul_f32 v[80:81], v[46:47], 0.5 op_sel_hi:[1,0]
	v_pk_mul_f32 v[82:83], v[44:45], 0.5 op_sel_hi:[1,0]
	v_pk_mul_f32 v[88:89], v[38:39], 0.5 op_sel_hi:[1,0]
	v_pk_mul_f32 v[90:91], v[36:37], 0.5 op_sel_hi:[1,0]
	v_pk_mul_f32 v[36:37], v[54:55], 0.5 op_sel_hi:[1,0]
	v_pk_mul_f32 v[38:39], v[52:53], 0.5 op_sel_hi:[1,0]
	v_pk_mul_f32 v[44:45], v[50:51], 0.5 op_sel_hi:[1,0]
	v_pk_mul_f32 v[46:47], v[48:49], 0.5 op_sel_hi:[1,0]
	v_pk_mul_f32 v[48:49], v[30:31], 0.5 op_sel_hi:[1,0]
	v_pk_mul_f32 v[50:51], v[28:29], 0.5 op_sel_hi:[1,0]
	v_pk_mul_f32 v[52:53], v[22:23], 0.5 op_sel_hi:[1,0]
	v_pk_mul_f32 v[54:55], v[20:21], 0.5 op_sel_hi:[1,0]
	v_pk_mul_f32 v[20:21], v[42:43], 0.5 op_sel_hi:[1,0]
	v_pk_mul_f32 v[22:23], v[40:41], 0.5 op_sel_hi:[1,0]
	v_pk_mul_f32 v[28:29], v[34:35], 0.5 op_sel_hi:[1,0]
	v_pk_mul_f32 v[30:31], v[32:33], 0.5 op_sel_hi:[1,0]
	v_pk_mul_f32 v[32:33], v[14:15], 0.5 op_sel_hi:[1,0]
	v_pk_mul_f32 v[34:35], v[12:13], 0.5 op_sel_hi:[1,0]
	v_pk_mul_f32 v[40:41], v[10:11], 0.5 op_sel_hi:[1,0]
	v_pk_mul_f32 v[42:43], v[8:9], 0.5 op_sel_hi:[1,0]
	v_pk_mul_f32 v[8:9], v[26:27], 0.5 op_sel_hi:[1,0]
	v_pk_mul_f32 v[10:11], v[24:25], 0.5 op_sel_hi:[1,0]
	v_pk_mul_f32 v[12:13], v[18:19], 0.5 op_sel_hi:[1,0]
	v_pk_mul_f32 v[14:15], v[16:17], 0.5 op_sel_hi:[1,0]
	v_pk_mul_f32 v[6:7], v[6:7], 0.5 op_sel_hi:[1,0]
	v_pk_mul_f32 v[4:5], v[4:5], 0.5 op_sel_hi:[1,0]
	v_pk_mul_f32 v[2:3], v[2:3], 0.5 op_sel_hi:[1,0]
	v_pk_mul_f32 v[0:1], v[0:1], 0.5 op_sel_hi:[1,0]

; #define PG8_STAGE(bufoff, gbase, voff) do { _Pragma("unroll") for (int _i = 0; _i < 2; ++_i) \
;         __builtin_amdgcn_global_load_lds((const unsigned*)((const char*)(gbase) + (voff)[_i]), (LAS unsigned*)(lds + (bufoff) + ldsw + _i * 8192), 16, 0, 0); } while (0)
; #define PG8_LDA(dst, b, h) do { _Pragma("unroll") for (int m = 0; m < 4; ++m) _Pragma("unroll") for (int k = 0; k < 2; ++k) dst[m][k] = *(const LAS bf16x8*)(lds + PG8_SA(b, h) + aoff + m * 2048 + k * 1024); } while (0)
; #define PG8_LDB(dst, b, h) do { _Pragma("unroll") for (int n = 0; n < 2; ++n) _Pragma("unroll") for (int k = 0; k < 2; ++k) dst[n][k] = *(const LAS bf16x8*)(lds + PG8_SB(b, h) + boff + n * 2048 + k * 1024); } while (0)
; #define PG8_MMA(ai, bj, At, Bt) do { __builtin_amdgcn_s_setprio(1); _Pragma("unroll") for (int m = 0; m < 4; ++m) _Pragma("unroll") for (int n = 0; n < 2; ++n) _Pragma("unroll") for (int k = 0; k < 2; ++k) \
;         acc[ai][bj][m][n] = __builtin_amdgcn_mfma_f32_16x16x32_bf16(Bt[n][k], At[m][k], acc[ai][bj][m][n], 0, 0, 0); __builtin_amdgcn_s_setprio(0); } while (0)
; #define PG8_WAIT_V(n) asm volatile("s_waitcnt vmcnt(" #n ")" ::: "memory")
; #define PG8_WAIT_L(n) asm volatile("s_waitcnt lgkmcnt(" #n ")" ::: "memory")
; #define PG8_BAR __builtin_amdgcn_s_barrier()
; #define PG8_SCHED __builtin_amdgcn_sched_barrier(0)
; template <class Epi, bool ALIGN_EPI = PG8_ALIGN>
; __device__ __forceinline__ void gemm_phase(LAS unsigned char* lds, const Gemm g, const StaticOrder& S, const Epi& E) {
;     ...
;         for (int t = 0; t < nt; t += 2) {
;             const bool last = (t == nt - 2);
;             const char* a1 = cA + (size_t)(t + 1) * kstep;
;             const char* a2 = last ? nA : cA + (size_t)(t + 2) * kstep; const char* b2 = last ? nB : cB + (size_t)(t + 2) * kstep;
;             const char* a3 = a2 + kstep; const char* b3 = b2 + kstep;
;             PG8_LDB(B0, 0, 0); PG8_LDB(B1, 0, 1); PG8_SCHED; PG8_LDA(At, 0, 0); PG8_STAGE(PG8_SA(1, 1), a1 + hstepA, voffA);
;             PG8_WAIT_V(8); PG8_WAIT_L(0); PG8_BAR; PG8_MMA(0, 0, At, B0); PG8_MMA(0, 1, At, B1); PG8_BAR; PG8_SCHED;
;             PG8_LDA(At, 0, 1); PG8_STAGE(PG8_SB(0, 0), b2, voffB); PG8_STAGE(PG8_SB(0, 1), b2 + hstepB, voffB); PG8_STAGE(PG8_SA(0, 0), a2, voffA);
.LBB0_458:
	s_add_i32 s51, s38, 2
	s_add_u32 s20, s4, 0xfff80080
	s_addc_u32 s21, s5, -1
	s_add_i32 s22, 16, 0x10000
	s_cmp_eq_u32 s45, s38
	s_cselect_b32 s39, s17, s21
	s_cselect_b32 s38, s50, s20
	s_cselect_b32 s53, s25, s41
	s_cselect_b32 s52, s24, s40
	s_add_i32 s20, 16, 0x14000
	v_add_u32_e32 v154, s22, v139
	v_add_u32_e32 v170, s20, v139
	ds_read_b128 v[142:145], v154
	ds_read_b128 v[146:149], v154 offset:1024
	ds_read_b128 v[150:153], v154 offset:2048
	ds_read_b128 v[154:157], v154 offset:3072
	ds_read_b128 v[158:161], v170
	ds_read_b128 v[162:165], v170 offset:1024
	ds_read_b128 v[166:169], v170 offset:2048
	ds_read_b128 v[170:173], v170 offset:3072
	v_lshl_add_u64 v[174:175], s[4:5], 0, v[134:135]
	s_add_i32 m0, s29, 0xc000
	ds_read_b128 v[184:187], v141
	ds_read_b128 v[188:191], v141 offset:1024
	ds_read_b128 v[192:195], v141 offset:2048
	ds_read_b128 v[196:199], v141 offset:3072
	ds_read_b128 v[200:203], v141 offset:4096
	ds_read_b128 v[204:207], v141 offset:5120
	ds_read_b128 v[208:211], v141 offset:6144
	ds_read_b128 v[212:215], v141 offset:7168
	global_load_lds_dwordx4 v[174:175], off
	v_lshl_add_u64 v[174:175], s[4:5], 0, v[136:137]
	s_add_i32 m0, s29, 0xe000
	s_nop 0
	global_load_lds_dwordx4 v[174:175], off
	s_waitcnt vmcnt(8)
	s_waitcnt lgkmcnt(0)
	s_barrier
	s_setprio 1
	s_waitcnt lgkmcnt(0)
	v_mfma_f32_16x16x32_bf16 v[120:123], v[142:145], v[184:187], v[120:123]
	v_mfma_f32_16x16x32_bf16 v[124:127], v[150:153], v[184:187], v[124:127]
	v_mfma_f32_16x16x32_bf16 v[108:111], v[142:145], v[192:195], v[108:111]
	v_mfma_f32_16x16x32_bf16 v[104:107], v[150:153], v[192:195], v[104:107]
	v_mfma_f32_16x16x32_bf16 v[92:95], v[142:145], v[200:203], v[92:95]
	v_mfma_f32_16x16x32_bf16 v[88:91], v[150:153], v[200:203], v[88:91]
	v_mfma_f32_16x16x32_bf16 v[76:79], v[142:145], v[208:211], v[76:79]
	v_mfma_f32_16x16x32_bf16 v[72:75], v[150:153], v[208:211], v[72:75]
	v_mfma_f32_16x16x32_bf16 v[120:123], v[146:149], v[188:191], v[120:123]
	v_mfma_f32_16x16x32_bf16 v[124:127], v[154:157], v[188:191], v[124:127]
	v_mfma_f32_16x16x32_bf16 v[108:111], v[146:149], v[196:199], v[108:111]
	v_mfma_f32_16x16x32_bf16 v[104:107], v[154:157], v[196:199], v[104:107]
	v_mfma_f32_16x16x32_bf16 v[92:95], v[146:149], v[204:207], v[92:95]
	v_mfma_f32_16x16x32_bf16 v[88:91], v[154:157], v[204:207], v[88:91]
	v_mfma_f32_16x16x32_bf16 v[76:79], v[146:149], v[212:215], v[76:79]
	v_mfma_f32_16x16x32_bf16 v[72:75], v[154:157], v[212:215], v[72:75]
	s_setprio 0
	s_setprio 1
	v_mfma_f32_16x16x32_bf16 v[116:119], v[158:161], v[184:187], v[116:119]
	v_mfma_f32_16x16x32_bf16 v[112:115], v[166:169], v[184:187], v[112:115]
	v_mfma_f32_16x16x32_bf16 v[100:103], v[158:161], v[192:195], v[100:103]
	v_mfma_f32_16x16x32_bf16 v[96:99], v[166:169], v[192:195], v[96:99]
	v_mfma_f32_16x16x32_bf16 v[84:87], v[158:161], v[200:203], v[84:87]
	v_mfma_f32_16x16x32_bf16 v[80:83], v[166:169], v[200:203], v[80:83]
	v_mfma_f32_16x16x32_bf16 v[68:71], v[158:161], v[208:211], v[68:71]
	v_mfma_f32_16x16x32_bf16 v[64:67], v[166:169], v[208:211], v[64:67]
	v_mfma_f32_16x16x32_bf16 v[116:119], v[162:165], v[188:191], v[116:119]
	v_mfma_f32_16x16x32_bf16 v[112:115], v[170:173], v[188:191], v[112:115]
	v_mfma_f32_16x16x32_bf16 v[100:103], v[162:165], v[196:199], v[100:103]
	v_mfma_f32_16x16x32_bf16 v[96:99], v[170:173], v[196:199], v[96:99]
	v_mfma_f32_16x16x32_bf16 v[84:87], v[162:165], v[204:207], v[84:87]
	v_mfma_f32_16x16x32_bf16 v[80:83], v[170:173], v[204:207], v[80:83]
	v_mfma_f32_16x16x32_bf16 v[68:71], v[162:165], v[212:215], v[68:71]
	v_mfma_f32_16x16x32_bf16 v[64:67], v[170:173], v[212:215], v[64:67]
	s_setprio 0
	s_barrier
	s_add_i32 s21, s22, s18
	v_lshl_add_u64 v[174:175], s[52:53], 0, v[176:177]
	s_mov_b32 m0, s21
	ds_read_b128 v[184:187], v141 offset:16384
	ds_read_b128 v[188:191], v141 offset:17408
	ds_read_b128 v[192:195], v141 offset:18432
	ds_read_b128 v[196:199], v141 offset:19456
	ds_read_b128 v[200:203], v141 offset:20480
	ds_read_b128 v[204:207], v141 offset:21504
	ds_read_b128 v[208:211], v141 offset:22528
	ds_read_b128 v[212:215], v141 offset:23552
	global_load_lds_dwordx4 v[174:175], off
	s_add_i32 m0, s21, 0x2000
	v_lshl_add_u64 v[216:217], s[52:53], 0, v[128:129]
	s_add_u32 s52, s52, s6
	s_addc_u32 s53, s53, s7
	s_add_i32 s20, s20, s18
	global_load_lds_dwordx4 v[216:217], off
	v_lshl_add_u64 v[218:219], s[52:53], 0, v[176:177]
	s_mov_b32 m0, s20
	v_lshl_add_u64 v[220:221], s[52:53], 0, v[128:129]
	global_load_lds_dwordx4 v[218:219], off
	s_add_i32 m0, s20, 0x2000
	v_lshl_add_u64 v[222:223], s[38:39], 0, v[132:133]
	global_load_lds_dwordx4 v[220:221], off
	s_mov_b32 m0, s29
	v_lshl_add_u64 v[224:225], s[38:39], 0, v[130:131]
	global_load_lds_dwordx4 v[222:223], off
	s_mov_b32 m0, s30
	s_nop 0
	global_load_lds_dwordx4 v[224:225], off
	s_nop 15
	s_nop 15
	s_waitcnt vmcnt(8)
	s_waitcnt lgkmcnt(0)
	s_barrier
; #define PG8_STAGE(bufoff, gbase, voff) do { _Pragma("unroll") for (int _i = 0; _i < 2; ++_i) \
;         __builtin_amdgcn_global_load_lds((const unsigned*)((const char*)(gbase) + (voff)[_i]), (LAS unsigned*)(lds + (bufoff) + ldsw + _i * 8192), 16, 0, 0); } while (0)
; #define PG8_LDA(dst, b, h) do { _Pragma("unroll") for (int m = 0; m < 4; ++m) _Pragma("unroll") for (int k = 0; k < 2; ++k) dst[m][k] = *(const LAS bf16x8*)(lds + PG8_SA(b, h) + aoff + m * 2048 + k * 1024); } while (0)
; #define PG8_LDB(dst, b, h) do { _Pragma("unroll") for (int n = 0; n < 2; ++n) _Pragma("unroll") for (int k = 0; k < 2; ++k) dst[n][k] = *(const LAS bf16x8*)(lds + PG8_SB(b, h) + boff + n * 2048 + k * 1024); } while (0)
; #define PG8_MMA(ai, bj, At, Bt) do { __builtin_amdgcn_s_setprio(1); _Pragma("unroll") for (int m = 0; m < 4; ++m) _Pragma("unroll") for (int n = 0; n < 2; ++n) _Pragma("unroll") for (int k = 0; k < 2; ++k) \
;         acc[ai][bj][m][n] = __builtin_amdgcn_mfma_f32_16x16x32_bf16(Bt[n][k], At[m][k], acc[ai][bj][m][n], 0, 0, 0); __builtin_amdgcn_s_setprio(0); } while (0)
; #define PG8_WAIT_V(n) asm volatile("s_waitcnt vmcnt(" #n ")" ::: "memory")
; #define PG8_WAIT_L(n) asm volatile("s_waitcnt lgkmcnt(" #n ")" ::: "memory")
; #define PG8_BAR __builtin_amdgcn_s_barrier()
; #define PG8_SCHED __builtin_amdgcn_sched_barrier(0)
; template <class Epi, bool ALIGN_EPI = PG8_ALIGN>
; __device__ __forceinline__ void gemm_phase(LAS unsigned char* lds, const Gemm g, const StaticOrder& S, const Epi& E) {
;     ...
;             PG8_WAIT_V(8); PG8_WAIT_L(0); PG8_BAR; PG8_MMA(1, 0, At, B0); PG8_MMA(1, 1, At, B1); PG8_BAR; PG8_SCHED;
;             PG8_LDB(B0, 1, 0); PG8_LDB(B1, 1, 1); PG8_SCHED; PG8_LDA(At, 1, 0); PG8_STAGE(PG8_SA(0, 1), a2 + hstepA, voffA);
;             PG8_WAIT_V(8); PG8_WAIT_L(0); PG8_BAR; PG8_MMA(0, 0, At, B0); PG8_MMA(0, 1, At, B1); PG8_BAR; PG8_SCHED;
	s_setprio 1
	s_waitcnt lgkmcnt(0)
	v_mfma_f32_16x16x32_bf16 v[60:63], v[142:145], v[184:187], v[60:63]
	v_mfma_f32_16x16x32_bf16 v[56:59], v[150:153], v[184:187], v[56:59]
	v_mfma_f32_16x16x32_bf16 v[44:47], v[142:145], v[192:195], v[44:47]
	v_mfma_f32_16x16x32_bf16 v[40:43], v[150:153], v[192:195], v[40:43]
	v_mfma_f32_16x16x32_bf16 v[28:31], v[142:145], v[200:203], v[28:31]
	v_mfma_f32_16x16x32_bf16 v[24:27], v[150:153], v[200:203], v[24:27]
	v_mfma_f32_16x16x32_bf16 v[12:15], v[142:145], v[208:211], v[12:15]
	v_mfma_f32_16x16x32_bf16 v[8:11], v[150:153], v[208:211], v[8:11]
	v_mfma_f32_16x16x32_bf16 v[60:63], v[146:149], v[188:191], v[60:63]
	v_mfma_f32_16x16x32_bf16 v[56:59], v[154:157], v[188:191], v[56:59]
	v_mfma_f32_16x16x32_bf16 v[44:47], v[146:149], v[196:199], v[44:47]
	v_mfma_f32_16x16x32_bf16 v[40:43], v[154:157], v[196:199], v[40:43]
	v_mfma_f32_16x16x32_bf16 v[28:31], v[146:149], v[204:207], v[28:31]
	v_mfma_f32_16x16x32_bf16 v[24:27], v[154:157], v[204:207], v[24:27]
	v_mfma_f32_16x16x32_bf16 v[12:15], v[146:149], v[212:215], v[12:15]
	v_mfma_f32_16x16x32_bf16 v[8:11], v[154:157], v[212:215], v[8:11]
	s_setprio 0
	s_setprio 1
	v_mfma_f32_16x16x32_bf16 v[52:55], v[158:161], v[184:187], v[52:55]
	v_mfma_f32_16x16x32_bf16 v[48:51], v[166:169], v[184:187], v[48:51]
	v_mfma_f32_16x16x32_bf16 v[36:39], v[158:161], v[192:195], v[36:39]
	v_mfma_f32_16x16x32_bf16 v[32:35], v[166:169], v[192:195], v[32:35]
	v_mfma_f32_16x16x32_bf16 v[20:23], v[158:161], v[200:203], v[20:23]
	v_mfma_f32_16x16x32_bf16 v[16:19], v[166:169], v[200:203], v[16:19]
	v_mfma_f32_16x16x32_bf16 v[4:7], v[158:161], v[208:211], v[4:7]
	v_mfma_f32_16x16x32_bf16 v[0:3], v[166:169], v[208:211], v[0:3]
	v_mfma_f32_16x16x32_bf16 v[52:55], v[162:165], v[188:191], v[52:55]
	v_mfma_f32_16x16x32_bf16 v[48:51], v[170:173], v[188:191], v[48:51]
	v_mfma_f32_16x16x32_bf16 v[36:39], v[162:165], v[196:199], v[36:39]
	v_mfma_f32_16x16x32_bf16 v[32:35], v[170:173], v[196:199], v[32:35]
	v_mfma_f32_16x16x32_bf16 v[20:23], v[162:165], v[204:207], v[20:23]
	v_mfma_f32_16x16x32_bf16 v[16:19], v[170:173], v[204:207], v[16:19]
	v_mfma_f32_16x16x32_bf16 v[4:7], v[162:165], v[212:215], v[4:7]
	v_mfma_f32_16x16x32_bf16 v[0:3], v[170:173], v[212:215], v[0:3]
	s_setprio 0
	s_barrier
	s_add_i32 s20, 16, 0x18000
	s_add_i32 s21, 16, 0x1c000
	v_add_u32_e32 v154, s20, v139
	v_add_u32_e32 v170, s21, v139
	ds_read_b128 v[142:145], v154
	ds_read_b128 v[146:149], v154 offset:1024
	ds_read_b128 v[150:153], v154 offset:2048
	ds_read_b128 v[154:157], v154 offset:3072
	ds_read_b128 v[158:161], v170
	ds_read_b128 v[162:165], v170 offset:1024
	ds_read_b128 v[166:169], v170 offset:2048
	ds_read_b128 v[170:173], v170 offset:3072
	s_add_u32 s38, s38, 0x80000
	s_addc_u32 s39, s39, 0
	s_mov_b32 m0, s31
	v_lshl_add_u64 v[226:227], s[38:39], 0, v[132:133]
	ds_read_b128 v[184:187], v141 offset:32768
	ds_read_b128 v[188:191], v141 offset:33792
	ds_read_b128 v[192:195], v141 offset:34816
	ds_read_b128 v[196:199], v141 offset:35840
	ds_read_b128 v[200:203], v141 offset:36864
	ds_read_b128 v[204:207], v141 offset:37888
	ds_read_b128 v[208:211], v141 offset:38912
	ds_read_b128 v[212:215], v141 offset:39936
	global_load_lds_dwordx4 v[226:227], off
	v_lshl_add_u64 v[226:227], s[38:39], 0, v[130:131]
	s_mov_b32 m0, s42
	s_nop 0
	global_load_lds_dwordx4 v[226:227], off
	s_waitcnt vmcnt(8)
	s_waitcnt lgkmcnt(0)
	s_barrier
	s_setprio 1
	s_waitcnt lgkmcnt(0)
	v_mfma_f32_16x16x32_bf16 v[120:123], v[142:145], v[184:187], v[120:123]
	v_mfma_f32_16x16x32_bf16 v[124:127], v[150:153], v[184:187], v[124:127]
	v_mfma_f32_16x16x32_bf16 v[108:111], v[142:145], v[192:195], v[108:111]
	v_mfma_f32_16x16x32_bf16 v[104:107], v[150:153], v[192:195], v[104:107]
	v_mfma_f32_16x16x32_bf16 v[92:95], v[142:145], v[200:203], v[92:95]
	v_mfma_f32_16x16x32_bf16 v[88:91], v[150:153], v[200:203], v[88:91]
	v_mfma_f32_16x16x32_bf16 v[76:79], v[142:145], v[208:211], v[76:79]
	v_mfma_f32_16x16x32_bf16 v[72:75], v[150:153], v[208:211], v[72:75]
	v_mfma_f32_16x16x32_bf16 v[120:123], v[146:149], v[188:191], v[120:123]
	v_mfma_f32_16x16x32_bf16 v[124:127], v[154:157], v[188:191], v[124:127]
	v_mfma_f32_16x16x32_bf16 v[108:111], v[146:149], v[196:199], v[108:111]
	v_mfma_f32_16x16x32_bf16 v[104:107], v[154:157], v[196:199], v[104:107]
	v_mfma_f32_16x16x32_bf16 v[92:95], v[146:149], v[204:207], v[92:95]
	v_mfma_f32_16x16x32_bf16 v[88:91], v[154:157], v[204:207], v[88:91]
	v_mfma_f32_16x16x32_bf16 v[76:79], v[146:149], v[212:215], v[76:79]
	v_mfma_f32_16x16x32_bf16 v[72:75], v[154:157], v[212:215], v[72:75]
	s_setprio 0
	s_setprio 1
	v_mfma_f32_16x16x32_bf16 v[116:119], v[158:161], v[184:187], v[116:119]
	v_mfma_f32_16x16x32_bf16 v[112:115], v[166:169], v[184:187], v[112:115]
	v_mfma_f32_16x16x32_bf16 v[100:103], v[158:161], v[192:195], v[100:103]
	v_mfma_f32_16x16x32_bf16 v[96:99], v[166:169], v[192:195], v[96:99]
	v_mfma_f32_16x16x32_bf16 v[84:87], v[158:161], v[200:203], v[84:87]
	v_mfma_f32_16x16x32_bf16 v[80:83], v[166:169], v[200:203], v[80:83]
	v_mfma_f32_16x16x32_bf16 v[68:71], v[158:161], v[208:211], v[68:71]
	v_mfma_f32_16x16x32_bf16 v[64:67], v[166:169], v[208:211], v[64:67]
	v_mfma_f32_16x16x32_bf16 v[116:119], v[162:165], v[188:191], v[116:119]
	v_mfma_f32_16x16x32_bf16 v[112:115], v[170:173], v[188:191], v[112:115]
	v_mfma_f32_16x16x32_bf16 v[100:103], v[162:165], v[196:199], v[100:103]
	v_mfma_f32_16x16x32_bf16 v[96:99], v[170:173], v[196:199], v[96:99]
	v_mfma_f32_16x16x32_bf16 v[84:87], v[162:165], v[204:207], v[84:87]
	v_mfma_f32_16x16x32_bf16 v[80:83], v[170:173], v[204:207], v[80:83]
	v_mfma_f32_16x16x32_bf16 v[68:71], v[162:165], v[212:215], v[68:71]
	v_mfma_f32_16x16x32_bf16 v[64:67], v[170:173], v[212:215], v[64:67]
	s_setprio 0
	s_barrier
; #define PG8_STAGE(bufoff, gbase, voff) do { _Pragma("unroll") for (int _i = 0; _i < 2; ++_i) \
;         __builtin_amdgcn_global_load_lds((const unsigned*)((const char*)(gbase) + (voff)[_i]), (LAS unsigned*)(lds + (bufoff) + ldsw + _i * 8192), 16, 0, 0); } while (0)
; #define PG8_LDA(dst, b, h) do { _Pragma("unroll") for (int m = 0; m < 4; ++m) _Pragma("unroll") for (int k = 0; k < 2; ++k) dst[m][k] = *(const LAS bf16x8*)(lds + PG8_SA(b, h) + aoff + m * 2048 + k * 1024); } while (0)
; #define PG8_MMA(ai, bj, At, Bt) do { __builtin_amdgcn_s_setprio(1); _Pragma("unroll") for (int m = 0; m < 4; ++m) _Pragma("unroll") for (int n = 0; n < 2; ++n) _Pragma("unroll") for (int k = 0; k < 2; ++k) \
;         acc[ai][bj][m][n] = __builtin_amdgcn_mfma_f32_16x16x32_bf16(Bt[n][k], At[m][k], acc[ai][bj][m][n], 0, 0, 0); __builtin_amdgcn_s_setprio(0); } while (0)
; #define PG8_WAIT_V(n) asm volatile("s_waitcnt vmcnt(" #n ")" ::: "memory")
; #define PG8_WAIT_L(n) asm volatile("s_waitcnt lgkmcnt(" #n ")" ::: "memory")
; #define PG8_BAR __builtin_amdgcn_s_barrier()
; #define PG8_SCHED __builtin_amdgcn_sched_barrier(0)
; template <class Epi, bool ALIGN_EPI = PG8_ALIGN>
; __device__ __forceinline__ void gemm_phase(LAS unsigned char* lds, const Gemm g, const StaticOrder& S, const Epi& E) {
;     ...
;             PG8_LDA(At, 1, 1); PG8_STAGE(PG8_SB(1, 0), b3, voffB); PG8_STAGE(PG8_SB(1, 1), b3 + hstepB, voffB); PG8_STAGE(PG8_SA(1, 0), a3, voffA);
;             PG8_WAIT_V(8); PG8_WAIT_L(0); PG8_BAR; PG8_MMA(1, 0, At, B0); PG8_MMA(1, 1, At, B1); PG8_BAR; PG8_SCHED;
;         }
	s_add_i32 s20, s20, s18
	v_lshl_add_u64 v[174:175], v[174:175], 0, s[0:1]
	s_mov_b32 m0, s20
	ds_read_b128 v[184:187], v141 offset:49152
	ds_read_b128 v[188:191], v141 offset:50176
	ds_read_b128 v[192:195], v141 offset:51200
	ds_read_b128 v[196:199], v141 offset:52224
	ds_read_b128 v[200:203], v141 offset:53248
	ds_read_b128 v[204:207], v141 offset:54272
	ds_read_b128 v[208:211], v141 offset:55296
	ds_read_b128 v[212:215], v141 offset:56320
	global_load_lds_dwordx4 v[174:175], off
	v_lshl_add_u64 v[174:175], v[216:217], 0, s[0:1]
	s_add_i32 m0, s20, 0x2000
	s_add_i32 s20, s21, s18
	global_load_lds_dwordx4 v[174:175], off
	v_lshl_add_u64 v[174:175], v[218:219], 0, s[0:1]
	s_mov_b32 m0, s20
	s_nop 0
	global_load_lds_dwordx4 v[174:175], off
	v_lshl_add_u64 v[174:175], v[220:221], 0, s[0:1]
	s_add_i32 m0, s20, 0x2000
	s_nop 0
	global_load_lds_dwordx4 v[174:175], off
	v_lshl_add_u64 v[174:175], v[222:223], 0, s[0:1]
	s_mov_b32 m0, s34
	s_nop 0
	global_load_lds_dwordx4 v[174:175], off
	v_lshl_add_u64 v[174:175], v[224:225], 0, s[0:1]
	s_mov_b32 m0, s43
	s_nop 0
	global_load_lds_dwordx4 v[174:175], off
	s_nop 15
	s_nop 15
	s_waitcnt vmcnt(8)
	s_waitcnt lgkmcnt(0)
	s_barrier
	s_setprio 1
	s_waitcnt lgkmcnt(0)
	v_mfma_f32_16x16x32_bf16 v[60:63], v[142:145], v[184:187], v[60:63]
	v_mfma_f32_16x16x32_bf16 v[56:59], v[150:153], v[184:187], v[56:59]
	v_mfma_f32_16x16x32_bf16 v[44:47], v[142:145], v[192:195], v[44:47]
	v_mfma_f32_16x16x32_bf16 v[40:43], v[150:153], v[192:195], v[40:43]
	v_mfma_f32_16x16x32_bf16 v[28:31], v[142:145], v[200:203], v[28:31]
	v_mfma_f32_16x16x32_bf16 v[24:27], v[150:153], v[200:203], v[24:27]
	v_mfma_f32_16x16x32_bf16 v[12:15], v[142:145], v[208:211], v[12:15]
	v_mfma_f32_16x16x32_bf16 v[8:11], v[150:153], v[208:211], v[8:11]
	v_mfma_f32_16x16x32_bf16 v[60:63], v[146:149], v[188:191], v[60:63]
	v_mfma_f32_16x16x32_bf16 v[56:59], v[154:157], v[188:191], v[56:59]
	v_mfma_f32_16x16x32_bf16 v[44:47], v[146:149], v[196:199], v[44:47]
	v_mfma_f32_16x16x32_bf16 v[40:43], v[154:157], v[196:199], v[40:43]
	v_mfma_f32_16x16x32_bf16 v[28:31], v[146:149], v[204:207], v[28:31]
	v_mfma_f32_16x16x32_bf16 v[24:27], v[154:157], v[204:207], v[24:27]
	v_mfma_f32_16x16x32_bf16 v[12:15], v[146:149], v[212:215], v[12:15]
	v_mfma_f32_16x16x32_bf16 v[8:11], v[154:157], v[212:215], v[8:11]
	s_setprio 0
	s_setprio 1
	v_mfma_f32_16x16x32_bf16 v[52:55], v[158:161], v[184:187], v[52:55]
	v_mfma_f32_16x16x32_bf16 v[48:51], v[166:169], v[184:187], v[48:51]
	v_mfma_f32_16x16x32_bf16 v[36:39], v[158:161], v[192:195], v[36:39]
	v_mfma_f32_16x16x32_bf16 v[32:35], v[166:169], v[192:195], v[32:35]
	v_mfma_f32_16x16x32_bf16 v[20:23], v[158:161], v[200:203], v[20:23]
	v_mfma_f32_16x16x32_bf16 v[16:19], v[166:169], v[200:203], v[16:19]
	v_mfma_f32_16x16x32_bf16 v[4:7], v[158:161], v[208:211], v[4:7]
	v_mfma_f32_16x16x32_bf16 v[0:3], v[166:169], v[208:211], v[0:3]
	v_mfma_f32_16x16x32_bf16 v[52:55], v[162:165], v[188:191], v[52:55]
	v_mfma_f32_16x16x32_bf16 v[48:51], v[170:173], v[188:191], v[48:51]
	v_mfma_f32_16x16x32_bf16 v[36:39], v[162:165], v[196:199], v[36:39]
	v_mfma_f32_16x16x32_bf16 v[32:35], v[170:173], v[196:199], v[32:35]
	v_mfma_f32_16x16x32_bf16 v[20:23], v[162:165], v[204:207], v[20:23]
	v_mfma_f32_16x16x32_bf16 v[16:19], v[170:173], v[204:207], v[16:19]
	v_mfma_f32_16x16x32_bf16 v[4:7], v[162:165], v[212:215], v[4:7]
	v_mfma_f32_16x16x32_bf16 v[0:3], v[170:173], v[212:215], v[0:3]
	s_setprio 0
	s_barrier
	s_add_u32 s4, s4, 0x100
	s_addc_u32 s5, s5, 0
	s_add_u32 s40, s40, 0x100
	s_addc_u32 s41, s41, 0
	s_cmp_ge_i32 s51, s44
	s_mov_b32 s38, s51
	s_cbranch_scc0 .LBB0_458

; #define PG8_STAGE(bufoff, gbase, voff) do { _Pragma("unroll") for (int _i = 0; _i < 2; ++_i) \
;         __builtin_amdgcn_global_load_lds((const unsigned*)((const char*)(gbase) + (voff)[_i]), (LAS unsigned*)(lds + (bufoff) + ldsw + _i * 8192), 16, 0, 0); } while (0)
; #define PG8_LDA(dst, b, h) do { _Pragma("unroll") for (int m = 0; m < 4; ++m) _Pragma("unroll") for (int k = 0; k < 2; ++k) dst[m][k] = *(const LAS bf16x8*)(lds + PG8_SA(b, h) + aoff + m * 2048 + k * 1024); } while (0)
; #define PG8_LDB(dst, b, h) do { _Pragma("unroll") for (int n = 0; n < 2; ++n) _Pragma("unroll") for (int k = 0; k < 2; ++k) dst[n][k] = *(const LAS bf16x8*)(lds + PG8_SB(b, h) + boff + n * 2048 + k * 1024); } while (0)
; #define PG8_MMA(ai, bj, At, Bt) do { __builtin_amdgcn_s_setprio(1); _Pragma("unroll") for (int m = 0; m < 4; ++m) _Pragma("unroll") for (int n = 0; n < 2; ++n) _Pragma("unroll") for (int k = 0; k < 2; ++k) \
;         acc[ai][bj][m][n] = __builtin_amdgcn_mfma_f32_16x16x32_bf16(Bt[n][k], At[m][k], acc[ai][bj][m][n], 0, 0, 0); __builtin_amdgcn_s_setprio(0); } while (0)
; #define PG8_WAIT_V(n) asm volatile("s_waitcnt vmcnt(" #n ")" ::: "memory")
; #define PG8_WAIT_L(n) asm volatile("s_waitcnt lgkmcnt(" #n ")" ::: "memory")
; #define PG8_BAR __builtin_amdgcn_s_barrier()
; #define PG8_SCHED __builtin_amdgcn_sched_barrier(0)
; template <class Epi, bool ALIGN_EPI = PG8_ALIGN>
; __device__ __forceinline__ void gemm_phase(LAS unsigned char* lds, const Gemm g, const StaticOrder& S, const Epi& E) {
;     ...
;         for (int t = 0; t < nt; t += 2) {
;             const bool last = (t == nt - 2);
;             const char* a1 = cA + (size_t)(t + 1) * kstep;
;             const char* a2 = last ? nA : cA + (size_t)(t + 2) * kstep; const char* b2 = last ? nB : cB + (size_t)(t + 2) * kstep;
;             const char* a3 = a2 + kstep; const char* b3 = b2 + kstep;
;             PG8_LDB(B0, 0, 0); PG8_LDB(B1, 0, 1); PG8_SCHED; PG8_LDA(At, 0, 0); PG8_STAGE(PG8_SA(1, 1), a1 + hstepA, voffA);
;             PG8_WAIT_V(8); PG8_WAIT_L(0); PG8_BAR; PG8_MMA(0, 0, At, B0); PG8_MMA(0, 1, At, B1); PG8_BAR; PG8_SCHED;
;             PG8_LDA(At, 0, 1); PG8_STAGE(PG8_SB(0, 0), b2, voffB); PG8_STAGE(PG8_SB(0, 1), b2 + hstepB, voffB); PG8_STAGE(PG8_SA(0, 0), a2, voffA);
.LBB0_481:
	s_add_i32 s53, s38, 2
	s_add_u32 s20, s4, 0xffff0080
	s_addc_u32 s21, s5, -1
	s_add_i32 s22, 16, 0x10000
	s_cmp_eq_u32 s47, s38
	s_cselect_b32 s39, s17, s21
	s_cselect_b32 s38, s52, s20
	s_cselect_b32 s55, s25, s41
	s_cselect_b32 s54, s24, s40
	s_add_i32 s20, 16, 0x14000
	v_add_u32_e32 v154, s22, v139
	v_add_u32_e32 v170, s20, v139
	ds_read_b128 v[142:145], v154
	ds_read_b128 v[146:149], v154 offset:1024
	ds_read_b128 v[150:153], v154 offset:2048
	ds_read_b128 v[154:157], v154 offset:3072
	ds_read_b128 v[158:161], v170
	ds_read_b128 v[162:165], v170 offset:1024
	ds_read_b128 v[166:169], v170 offset:2048
	ds_read_b128 v[170:173], v170 offset:3072
	v_lshl_add_u64 v[174:175], s[4:5], 0, v[134:135]
	s_add_i32 m0, s26, 0xc000
	ds_read_b128 v[184:187], v141
	ds_read_b128 v[188:191], v141 offset:1024
	ds_read_b128 v[192:195], v141 offset:2048
	ds_read_b128 v[196:199], v141 offset:3072
	ds_read_b128 v[200:203], v141 offset:4096
	ds_read_b128 v[204:207], v141 offset:5120
	ds_read_b128 v[208:211], v141 offset:6144
	ds_read_b128 v[212:215], v141 offset:7168
	global_load_lds_dwordx4 v[174:175], off
	v_lshl_add_u64 v[174:175], s[4:5], 0, v[136:137]
	s_add_i32 m0, s26, 0xe000
	s_nop 0
	global_load_lds_dwordx4 v[174:175], off
	s_waitcnt vmcnt(8)
	s_waitcnt lgkmcnt(0)
	s_barrier
	s_setprio 1
	s_waitcnt lgkmcnt(0)
	v_mfma_f32_16x16x32_bf16 v[120:123], v[142:145], v[184:187], v[120:123]
	v_mfma_f32_16x16x32_bf16 v[124:127], v[150:153], v[184:187], v[124:127]
	v_mfma_f32_16x16x32_bf16 v[108:111], v[142:145], v[192:195], v[108:111]
	v_mfma_f32_16x16x32_bf16 v[104:107], v[150:153], v[192:195], v[104:107]
	v_mfma_f32_16x16x32_bf16 v[92:95], v[142:145], v[200:203], v[92:95]
	v_mfma_f32_16x16x32_bf16 v[88:91], v[150:153], v[200:203], v[88:91]
	v_mfma_f32_16x16x32_bf16 v[76:79], v[142:145], v[208:211], v[76:79]
	v_mfma_f32_16x16x32_bf16 v[72:75], v[150:153], v[208:211], v[72:75]
	v_mfma_f32_16x16x32_bf16 v[120:123], v[146:149], v[188:191], v[120:123]
	v_mfma_f32_16x16x32_bf16 v[124:127], v[154:157], v[188:191], v[124:127]
	v_mfma_f32_16x16x32_bf16 v[108:111], v[146:149], v[196:199], v[108:111]
	v_mfma_f32_16x16x32_bf16 v[104:107], v[154:157], v[196:199], v[104:107]
	v_mfma_f32_16x16x32_bf16 v[92:95], v[146:149], v[204:207], v[92:95]
	v_mfma_f32_16x16x32_bf16 v[88:91], v[154:157], v[204:207], v[88:91]
	v_mfma_f32_16x16x32_bf16 v[76:79], v[146:149], v[212:215], v[76:79]
	v_mfma_f32_16x16x32_bf16 v[72:75], v[154:157], v[212:215], v[72:75]
	s_setprio 0
	s_setprio 1
	v_mfma_f32_16x16x32_bf16 v[116:119], v[158:161], v[184:187], v[116:119]
	v_mfma_f32_16x16x32_bf16 v[112:115], v[166:169], v[184:187], v[112:115]
	v_mfma_f32_16x16x32_bf16 v[100:103], v[158:161], v[192:195], v[100:103]
	v_mfma_f32_16x16x32_bf16 v[96:99], v[166:169], v[192:195], v[96:99]
	v_mfma_f32_16x16x32_bf16 v[84:87], v[158:161], v[200:203], v[84:87]
	v_mfma_f32_16x16x32_bf16 v[80:83], v[166:169], v[200:203], v[80:83]
	v_mfma_f32_16x16x32_bf16 v[68:71], v[158:161], v[208:211], v[68:71]
	v_mfma_f32_16x16x32_bf16 v[64:67], v[166:169], v[208:211], v[64:67]
	v_mfma_f32_16x16x32_bf16 v[116:119], v[162:165], v[188:191], v[116:119]
	v_mfma_f32_16x16x32_bf16 v[112:115], v[170:173], v[188:191], v[112:115]
	v_mfma_f32_16x16x32_bf16 v[100:103], v[162:165], v[196:199], v[100:103]
	v_mfma_f32_16x16x32_bf16 v[96:99], v[170:173], v[196:199], v[96:99]
	v_mfma_f32_16x16x32_bf16 v[84:87], v[162:165], v[204:207], v[84:87]
	v_mfma_f32_16x16x32_bf16 v[80:83], v[170:173], v[204:207], v[80:83]
	v_mfma_f32_16x16x32_bf16 v[68:71], v[162:165], v[212:215], v[68:71]
	v_mfma_f32_16x16x32_bf16 v[64:67], v[170:173], v[212:215], v[64:67]
	s_setprio 0
	s_barrier
	s_add_i32 s21, s22, s42
	v_lshl_add_u64 v[174:175], s[54:55], 0, v[176:177]
	s_mov_b32 m0, s21
	ds_read_b128 v[184:187], v141 offset:16384
	ds_read_b128 v[188:191], v141 offset:17408
	ds_read_b128 v[192:195], v141 offset:18432
	ds_read_b128 v[196:199], v141 offset:19456
	ds_read_b128 v[200:203], v141 offset:20480
	ds_read_b128 v[204:207], v141 offset:21504
	ds_read_b128 v[208:211], v141 offset:22528
	ds_read_b128 v[212:215], v141 offset:23552
	global_load_lds_dwordx4 v[174:175], off
	s_add_i32 m0, s21, 0x2000
	v_lshl_add_u64 v[216:217], s[54:55], 0, v[128:129]
	s_add_u32 s54, s54, s6
	s_addc_u32 s55, s55, s7
	s_add_i32 s20, s20, s42
	global_load_lds_dwordx4 v[216:217], off
	v_lshl_add_u64 v[218:219], s[54:55], 0, v[176:177]
	s_mov_b32 m0, s20
	v_lshl_add_u64 v[220:221], s[54:55], 0, v[128:129]
	global_load_lds_dwordx4 v[218:219], off
	s_add_i32 m0, s20, 0x2000
	v_lshl_add_u64 v[222:223], s[38:39], 0, v[132:133]
	global_load_lds_dwordx4 v[220:221], off
	s_mov_b32 m0, s26
	v_lshl_add_u64 v[224:225], s[38:39], 0, v[130:131]
	global_load_lds_dwordx4 v[222:223], off
	s_mov_b32 m0, s27
	s_nop 0
	global_load_lds_dwordx4 v[224:225], off
	s_nop 15
	s_nop 15
	s_waitcnt vmcnt(8)
	s_waitcnt lgkmcnt(0)
	s_barrier
; #define PG8_STAGE(bufoff, gbase, voff) do { _Pragma("unroll") for (int _i = 0; _i < 2; ++_i) \
;         __builtin_amdgcn_global_load_lds((const unsigned*)((const char*)(gbase) + (voff)[_i]), (LAS unsigned*)(lds + (bufoff) + ldsw + _i * 8192), 16, 0, 0); } while (0)
; #define PG8_LDA(dst, b, h) do { _Pragma("unroll") for (int m = 0; m < 4; ++m) _Pragma("unroll") for (int k = 0; k < 2; ++k) dst[m][k] = *(const LAS bf16x8*)(lds + PG8_SA(b, h) + aoff + m * 2048 + k * 1024); } while (0)
; #define PG8_LDB(dst, b, h) do { _Pragma("unroll") for (int n = 0; n < 2; ++n) _Pragma("unroll") for (int k = 0; k < 2; ++k) dst[n][k] = *(const LAS bf16x8*)(lds + PG8_SB(b, h) + boff + n * 2048 + k * 1024); } while (0)
; #define PG8_MMA(ai, bj, At, Bt) do { __builtin_amdgcn_s_setprio(1); _Pragma("unroll") for (int m = 0; m < 4; ++m) _Pragma("unroll") for (int n = 0; n < 2; ++n) _Pragma("unroll") for (int k = 0; k < 2; ++k) \
;         acc[ai][bj][m][n] = __builtin_amdgcn_mfma_f32_16x16x32_bf16(Bt[n][k], At[m][k], acc[ai][bj][m][n], 0, 0, 0); __builtin_amdgcn_s_setprio(0); } while (0)
; #define PG8_WAIT_V(n) asm volatile("s_waitcnt vmcnt(" #n ")" ::: "memory")
; #define PG8_WAIT_L(n) asm volatile("s_waitcnt lgkmcnt(" #n ")" ::: "memory")
; #define PG8_BAR __builtin_amdgcn_s_barrier()
; #define PG8_SCHED __builtin_amdgcn_sched_barrier(0)
; template <class Epi, bool ALIGN_EPI = PG8_ALIGN>
; __device__ __forceinline__ void gemm_phase(LAS unsigned char* lds, const Gemm g, const StaticOrder& S, const Epi& E) {
;     ...
;             PG8_WAIT_V(8); PG8_WAIT_L(0); PG8_BAR; PG8_MMA(1, 0, At, B0); PG8_MMA(1, 1, At, B1); PG8_BAR; PG8_SCHED;
;             PG8_LDB(B0, 1, 0); PG8_LDB(B1, 1, 1); PG8_SCHED; PG8_LDA(At, 1, 0); PG8_STAGE(PG8_SA(0, 1), a2 + hstepA, voffA);
;             PG8_WAIT_V(8); PG8_WAIT_L(0); PG8_BAR; PG8_MMA(0, 0, At, B0); PG8_MMA(0, 1, At, B1); PG8_BAR; PG8_SCHED;
	s_setprio 1
	s_waitcnt lgkmcnt(0)
	v_mfma_f32_16x16x32_bf16 v[60:63], v[142:145], v[184:187], v[60:63]
	v_mfma_f32_16x16x32_bf16 v[56:59], v[150:153], v[184:187], v[56:59]
	v_mfma_f32_16x16x32_bf16 v[44:47], v[142:145], v[192:195], v[44:47]
	v_mfma_f32_16x16x32_bf16 v[40:43], v[150:153], v[192:195], v[40:43]
	v_mfma_f32_16x16x32_bf16 v[28:31], v[142:145], v[200:203], v[28:31]
	v_mfma_f32_16x16x32_bf16 v[24:27], v[150:153], v[200:203], v[24:27]
	v_mfma_f32_16x16x32_bf16 v[12:15], v[142:145], v[208:211], v[12:15]
	v_mfma_f32_16x16x32_bf16 v[8:11], v[150:153], v[208:211], v[8:11]
	v_mfma_f32_16x16x32_bf16 v[60:63], v[146:149], v[188:191], v[60:63]
	v_mfma_f32_16x16x32_bf16 v[56:59], v[154:157], v[188:191], v[56:59]
	v_mfma_f32_16x16x32_bf16 v[44:47], v[146:149], v[196:199], v[44:47]
	v_mfma_f32_16x16x32_bf16 v[40:43], v[154:157], v[196:199], v[40:43]
	v_mfma_f32_16x16x32_bf16 v[28:31], v[146:149], v[204:207], v[28:31]
	v_mfma_f32_16x16x32_bf16 v[24:27], v[154:157], v[204:207], v[24:27]
	v_mfma_f32_16x16x32_bf16 v[12:15], v[146:149], v[212:215], v[12:15]
	v_mfma_f32_16x16x32_bf16 v[8:11], v[154:157], v[212:215], v[8:11]
	s_setprio 0
	s_setprio 1
	v_mfma_f32_16x16x32_bf16 v[52:55], v[158:161], v[184:187], v[52:55]
	v_mfma_f32_16x16x32_bf16 v[48:51], v[166:169], v[184:187], v[48:51]
	v_mfma_f32_16x16x32_bf16 v[36:39], v[158:161], v[192:195], v[36:39]
	v_mfma_f32_16x16x32_bf16 v[32:35], v[166:169], v[192:195], v[32:35]
	v_mfma_f32_16x16x32_bf16 v[20:23], v[158:161], v[200:203], v[20:23]
	v_mfma_f32_16x16x32_bf16 v[16:19], v[166:169], v[200:203], v[16:19]
	v_mfma_f32_16x16x32_bf16 v[4:7], v[158:161], v[208:211], v[4:7]
	v_mfma_f32_16x16x32_bf16 v[0:3], v[166:169], v[208:211], v[0:3]
	v_mfma_f32_16x16x32_bf16 v[52:55], v[162:165], v[188:191], v[52:55]
	v_mfma_f32_16x16x32_bf16 v[48:51], v[170:173], v[188:191], v[48:51]
	v_mfma_f32_16x16x32_bf16 v[36:39], v[162:165], v[196:199], v[36:39]
	v_mfma_f32_16x16x32_bf16 v[32:35], v[170:173], v[196:199], v[32:35]
	v_mfma_f32_16x16x32_bf16 v[20:23], v[162:165], v[204:207], v[20:23]
	v_mfma_f32_16x16x32_bf16 v[16:19], v[170:173], v[204:207], v[16:19]
	v_mfma_f32_16x16x32_bf16 v[4:7], v[162:165], v[212:215], v[4:7]
	v_mfma_f32_16x16x32_bf16 v[0:3], v[170:173], v[212:215], v[0:3]
	s_setprio 0
	s_barrier
	s_add_i32 s20, 16, 0x18000
	s_add_i32 s21, 16, 0x1c000
	v_add_u32_e32 v154, s20, v139
	v_add_u32_e32 v170, s21, v139
	ds_read_b128 v[142:145], v154
	ds_read_b128 v[146:149], v154 offset:1024
	ds_read_b128 v[150:153], v154 offset:2048
	ds_read_b128 v[154:157], v154 offset:3072
	ds_read_b128 v[158:161], v170
	ds_read_b128 v[162:165], v170 offset:1024
	ds_read_b128 v[166:169], v170 offset:2048
	ds_read_b128 v[170:173], v170 offset:3072
	s_add_u32 s38, s38, 0x10000
	s_addc_u32 s39, s39, 0
	s_mov_b32 m0, s43
	v_lshl_add_u64 v[226:227], s[38:39], 0, v[132:133]
	ds_read_b128 v[184:187], v141 offset:32768
	ds_read_b128 v[188:191], v141 offset:33792
	ds_read_b128 v[192:195], v141 offset:34816
	ds_read_b128 v[196:199], v141 offset:35840
	ds_read_b128 v[200:203], v141 offset:36864
	ds_read_b128 v[204:207], v141 offset:37888
	ds_read_b128 v[208:211], v141 offset:38912
	ds_read_b128 v[212:215], v141 offset:39936
	global_load_lds_dwordx4 v[226:227], off
	v_lshl_add_u64 v[226:227], s[38:39], 0, v[130:131]
	s_mov_b32 m0, s44
	s_nop 0
	global_load_lds_dwordx4 v[226:227], off
	s_waitcnt vmcnt(8)
	s_waitcnt lgkmcnt(0)
	s_barrier
	s_setprio 1
	s_waitcnt lgkmcnt(0)
	v_mfma_f32_16x16x32_bf16 v[120:123], v[142:145], v[184:187], v[120:123]
	v_mfma_f32_16x16x32_bf16 v[124:127], v[150:153], v[184:187], v[124:127]
	v_mfma_f32_16x16x32_bf16 v[108:111], v[142:145], v[192:195], v[108:111]
	v_mfma_f32_16x16x32_bf16 v[104:107], v[150:153], v[192:195], v[104:107]
	v_mfma_f32_16x16x32_bf16 v[92:95], v[142:145], v[200:203], v[92:95]
	v_mfma_f32_16x16x32_bf16 v[88:91], v[150:153], v[200:203], v[88:91]
	v_mfma_f32_16x16x32_bf16 v[76:79], v[142:145], v[208:211], v[76:79]
	v_mfma_f32_16x16x32_bf16 v[72:75], v[150:153], v[208:211], v[72:75]
	v_mfma_f32_16x16x32_bf16 v[120:123], v[146:149], v[188:191], v[120:123]
	v_mfma_f32_16x16x32_bf16 v[124:127], v[154:157], v[188:191], v[124:127]
	v_mfma_f32_16x16x32_bf16 v[108:111], v[146:149], v[196:199], v[108:111]
	v_mfma_f32_16x16x32_bf16 v[104:107], v[154:157], v[196:199], v[104:107]
	v_mfma_f32_16x16x32_bf16 v[92:95], v[146:149], v[204:207], v[92:95]
	v_mfma_f32_16x16x32_bf16 v[88:91], v[154:157], v[204:207], v[88:91]
	v_mfma_f32_16x16x32_bf16 v[76:79], v[146:149], v[212:215], v[76:79]
	v_mfma_f32_16x16x32_bf16 v[72:75], v[154:157], v[212:215], v[72:75]
	s_setprio 0
	s_setprio 1
	v_mfma_f32_16x16x32_bf16 v[116:119], v[158:161], v[184:187], v[116:119]
	v_mfma_f32_16x16x32_bf16 v[112:115], v[166:169], v[184:187], v[112:115]
	v_mfma_f32_16x16x32_bf16 v[100:103], v[158:161], v[192:195], v[100:103]
	v_mfma_f32_16x16x32_bf16 v[96:99], v[166:169], v[192:195], v[96:99]
	v_mfma_f32_16x16x32_bf16 v[84:87], v[158:161], v[200:203], v[84:87]
	v_mfma_f32_16x16x32_bf16 v[80:83], v[166:169], v[200:203], v[80:83]
	v_mfma_f32_16x16x32_bf16 v[68:71], v[158:161], v[208:211], v[68:71]
	v_mfma_f32_16x16x32_bf16 v[64:67], v[166:169], v[208:211], v[64:67]
	v_mfma_f32_16x16x32_bf16 v[116:119], v[162:165], v[188:191], v[116:119]
	v_mfma_f32_16x16x32_bf16 v[112:115], v[170:173], v[188:191], v[112:115]
	v_mfma_f32_16x16x32_bf16 v[100:103], v[162:165], v[196:199], v[100:103]
	v_mfma_f32_16x16x32_bf16 v[96:99], v[170:173], v[196:199], v[96:99]
	v_mfma_f32_16x16x32_bf16 v[84:87], v[162:165], v[204:207], v[84:87]
	v_mfma_f32_16x16x32_bf16 v[80:83], v[170:173], v[204:207], v[80:83]
	v_mfma_f32_16x16x32_bf16 v[68:71], v[162:165], v[212:215], v[68:71]
	v_mfma_f32_16x16x32_bf16 v[64:67], v[170:173], v[212:215], v[64:67]
	s_setprio 0
	s_barrier
; #define PG8_STAGE(bufoff, gbase, voff) do { _Pragma("unroll") for (int _i = 0; _i < 2; ++_i) \
;         __builtin_amdgcn_global_load_lds((const unsigned*)((const char*)(gbase) + (voff)[_i]), (LAS unsigned*)(lds + (bufoff) + ldsw + _i * 8192), 16, 0, 0); } while (0)
; #define PG8_LDA(dst, b, h) do { _Pragma("unroll") for (int m = 0; m < 4; ++m) _Pragma("unroll") for (int k = 0; k < 2; ++k) dst[m][k] = *(const LAS bf16x8*)(lds + PG8_SA(b, h) + aoff + m * 2048 + k * 1024); } while (0)
; #define PG8_MMA(ai, bj, At, Bt) do { __builtin_amdgcn_s_setprio(1); _Pragma("unroll") for (int m = 0; m < 4; ++m) _Pragma("unroll") for (int n = 0; n < 2; ++n) _Pragma("unroll") for (int k = 0; k < 2; ++k) \
;         acc[ai][bj][m][n] = __builtin_amdgcn_mfma_f32_16x16x32_bf16(Bt[n][k], At[m][k], acc[ai][bj][m][n], 0, 0, 0); __builtin_amdgcn_s_setprio(0); } while (0)
; #define PG8_WAIT_V(n) asm volatile("s_waitcnt vmcnt(" #n ")" ::: "memory")
; #define PG8_WAIT_L(n) asm volatile("s_waitcnt lgkmcnt(" #n ")" ::: "memory")
; #define PG8_BAR __builtin_amdgcn_s_barrier()
; #define PG8_SCHED __builtin_amdgcn_sched_barrier(0)
; template <class Epi, bool ALIGN_EPI = PG8_ALIGN>
; __device__ __forceinline__ void gemm_phase(LAS unsigned char* lds, const Gemm g, const StaticOrder& S, const Epi& E) {
;     ...
;             PG8_LDA(At, 1, 1); PG8_STAGE(PG8_SB(1, 0), b3, voffB); PG8_STAGE(PG8_SB(1, 1), b3 + hstepB, voffB); PG8_STAGE(PG8_SA(1, 0), a3, voffA);
;             PG8_WAIT_V(8); PG8_WAIT_L(0); PG8_BAR; PG8_MMA(1, 0, At, B0); PG8_MMA(1, 1, At, B1); PG8_BAR; PG8_SCHED;
;         }
	s_add_i32 s20, s20, s42
	v_lshl_add_u64 v[174:175], v[174:175], 0, s[0:1]
	s_mov_b32 m0, s20
	ds_read_b128 v[184:187], v141 offset:49152
	ds_read_b128 v[188:191], v141 offset:50176
	ds_read_b128 v[192:195], v141 offset:51200
	ds_read_b128 v[196:199], v141 offset:52224
	ds_read_b128 v[200:203], v141 offset:53248
	ds_read_b128 v[204:207], v141 offset:54272
	ds_read_b128 v[208:211], v141 offset:55296
	ds_read_b128 v[212:215], v141 offset:56320
	global_load_lds_dwordx4 v[174:175], off
	v_lshl_add_u64 v[174:175], v[216:217], 0, s[0:1]
	s_add_i32 m0, s20, 0x2000
	s_add_i32 s20, s21, s42
	global_load_lds_dwordx4 v[174:175], off
	v_lshl_add_u64 v[174:175], v[218:219], 0, s[0:1]
	s_mov_b32 m0, s20
	s_nop 0
	global_load_lds_dwordx4 v[174:175], off
	v_lshl_add_u64 v[174:175], v[220:221], 0, s[0:1]
	s_add_i32 m0, s20, 0x2000
	s_nop 0
	global_load_lds_dwordx4 v[174:175], off
	v_lshl_add_u64 v[174:175], v[222:223], 0, s[0:1]
	s_mov_b32 m0, s45
	s_nop 0
	global_load_lds_dwordx4 v[174:175], off
	v_lshl_add_u64 v[174:175], v[224:225], 0, s[0:1]
	s_mov_b32 m0, s46
	s_nop 0
	global_load_lds_dwordx4 v[174:175], off
	s_nop 15
	s_nop 15
	s_waitcnt vmcnt(8)
	s_waitcnt lgkmcnt(0)
	s_barrier
	s_setprio 1
	s_waitcnt lgkmcnt(0)
	v_mfma_f32_16x16x32_bf16 v[60:63], v[142:145], v[184:187], v[60:63]
	v_mfma_f32_16x16x32_bf16 v[56:59], v[150:153], v[184:187], v[56:59]
	v_mfma_f32_16x16x32_bf16 v[44:47], v[142:145], v[192:195], v[44:47]
	v_mfma_f32_16x16x32_bf16 v[40:43], v[150:153], v[192:195], v[40:43]
	v_mfma_f32_16x16x32_bf16 v[28:31], v[142:145], v[200:203], v[28:31]
	v_mfma_f32_16x16x32_bf16 v[24:27], v[150:153], v[200:203], v[24:27]
	v_mfma_f32_16x16x32_bf16 v[12:15], v[142:145], v[208:211], v[12:15]
	v_mfma_f32_16x16x32_bf16 v[8:11], v[150:153], v[208:211], v[8:11]
	v_mfma_f32_16x16x32_bf16 v[60:63], v[146:149], v[188:191], v[60:63]
	v_mfma_f32_16x16x32_bf16 v[56:59], v[154:157], v[188:191], v[56:59]
	v_mfma_f32_16x16x32_bf16 v[44:47], v[146:149], v[196:199], v[44:47]
	v_mfma_f32_16x16x32_bf16 v[40:43], v[154:157], v[196:199], v[40:43]
	v_mfma_f32_16x16x32_bf16 v[28:31], v[146:149], v[204:207], v[28:31]
	v_mfma_f32_16x16x32_bf16 v[24:27], v[154:157], v[204:207], v[24:27]
	v_mfma_f32_16x16x32_bf16 v[12:15], v[146:149], v[212:215], v[12:15]
	v_mfma_f32_16x16x32_bf16 v[8:11], v[154:157], v[212:215], v[8:11]
	s_setprio 0
	s_setprio 1
	v_mfma_f32_16x16x32_bf16 v[52:55], v[158:161], v[184:187], v[52:55]
	v_mfma_f32_16x16x32_bf16 v[48:51], v[166:169], v[184:187], v[48:51]
	v_mfma_f32_16x16x32_bf16 v[36:39], v[158:161], v[192:195], v[36:39]
	v_mfma_f32_16x16x32_bf16 v[32:35], v[166:169], v[192:195], v[32:35]
	v_mfma_f32_16x16x32_bf16 v[20:23], v[158:161], v[200:203], v[20:23]
	v_mfma_f32_16x16x32_bf16 v[16:19], v[166:169], v[200:203], v[16:19]
	v_mfma_f32_16x16x32_bf16 v[4:7], v[158:161], v[208:211], v[4:7]
	v_mfma_f32_16x16x32_bf16 v[0:3], v[166:169], v[208:211], v[0:3]
	v_mfma_f32_16x16x32_bf16 v[52:55], v[162:165], v[188:191], v[52:55]
	v_mfma_f32_16x16x32_bf16 v[48:51], v[170:173], v[188:191], v[48:51]
	v_mfma_f32_16x16x32_bf16 v[36:39], v[162:165], v[196:199], v[36:39]
	v_mfma_f32_16x16x32_bf16 v[32:35], v[170:173], v[196:199], v[32:35]
	v_mfma_f32_16x16x32_bf16 v[20:23], v[162:165], v[204:207], v[20:23]
	v_mfma_f32_16x16x32_bf16 v[16:19], v[170:173], v[204:207], v[16:19]
	v_mfma_f32_16x16x32_bf16 v[4:7], v[162:165], v[212:215], v[4:7]
	v_mfma_f32_16x16x32_bf16 v[0:3], v[170:173], v[212:215], v[0:3]
	s_setprio 0
	s_barrier
	s_add_u32 s4, s4, 0x100
	s_addc_u32 s5, s5, 0
	s_add_u32 s40, s40, 0x100
	s_addc_u32 s41, s41, 0
	s_cmp_ge_i32 s53, s34
	s_mov_b32 s38, s53
	s_cbranch_scc0 .LBB0_481

; #define PG8_STAGE(bufoff, gbase, voff) do { _Pragma("unroll") for (int _i = 0; _i < 2; ++_i) \
;         __builtin_amdgcn_global_load_lds((const unsigned*)((const char*)(gbase) + (voff)[_i]), (LAS unsigned*)(lds + (bufoff) + ldsw + _i * 8192), 16, 0, 0); } while (0)
; #define PG8_LDA(dst, b, h) do { _Pragma("unroll") for (int m = 0; m < 4; ++m) _Pragma("unroll") for (int k = 0; k < 2; ++k) dst[m][k] = *(const LAS bf16x8*)(lds + PG8_SA(b, h) + aoff + m * 2048 + k * 1024); } while (0)
; #define PG8_LDB(dst, b, h) do { _Pragma("unroll") for (int n = 0; n < 2; ++n) _Pragma("unroll") for (int k = 0; k < 2; ++k) dst[n][k] = *(const LAS bf16x8*)(lds + PG8_SB(b, h) + boff + n * 2048 + k * 1024); } while (0)
; #define PG8_MMA(ai, bj, At, Bt) do { __builtin_amdgcn_s_setprio(1); _Pragma("unroll") for (int m = 0; m < 4; ++m) _Pragma("unroll") for (int n = 0; n < 2; ++n) _Pragma("unroll") for (int k = 0; k < 2; ++k) \
;         acc[ai][bj][m][n] = __builtin_amdgcn_mfma_f32_16x16x32_bf16(Bt[n][k], At[m][k], acc[ai][bj][m][n], 0, 0, 0); __builtin_amdgcn_s_setprio(0); } while (0)
; #define PG8_WAIT_V(n) asm volatile("s_waitcnt vmcnt(" #n ")" ::: "memory")
; #define PG8_WAIT_L(n) asm volatile("s_waitcnt lgkmcnt(" #n ")" ::: "memory")
; #define PG8_BAR __builtin_amdgcn_s_barrier()
; #define PG8_SCHED __builtin_amdgcn_sched_barrier(0)
; template <class Epi, bool ALIGN_EPI = PG8_ALIGN>
; __device__ __forceinline__ void gemm_phase(LAS unsigned char* lds, const Gemm g, const StaticOrder& S, const Epi& E) {
;     ...
;         for (int t = 0; t < nt; t += 2) {
;             const bool last = (t == nt - 2);
;             const char* a1 = cA + (size_t)(t + 1) * kstep;
;             const char* a2 = last ? nA : cA + (size_t)(t + 2) * kstep; const char* b2 = last ? nB : cB + (size_t)(t + 2) * kstep;
;             const char* a3 = a2 + kstep; const char* b3 = b2 + kstep;
;             PG8_LDB(B0, 0, 0); PG8_LDB(B1, 0, 1); PG8_SCHED; PG8_LDA(At, 0, 0); PG8_STAGE(PG8_SA(1, 1), a1 + hstepA, voffA);
;             PG8_WAIT_V(8); PG8_WAIT_L(0); PG8_BAR; PG8_MMA(0, 0, At, B0); PG8_MMA(0, 1, At, B1); PG8_BAR; PG8_SCHED;
;             PG8_LDA(At, 0, 1); PG8_STAGE(PG8_SB(0, 0), b2, voffB); PG8_STAGE(PG8_SB(0, 1), b2 + hstepB, voffB); PG8_STAGE(PG8_SA(0, 0), a2, voffA);
.LBB0_642:
	s_add_i32 s53, s38, 2
	s_add_u32 s36, s24, 0x100
	s_addc_u32 s37, s25, 0
	s_add_i32 s20, 16, 0x10000
	s_cmp_eq_u32 s48, s38
	s_cselect_b32 s39, s3, s37
	s_cselect_b32 s38, s2, s36
	v_add_u32_e32 v142, s20, v149
	s_cselect_b32 s55, s17, s52
	s_cselect_b32 s54, s16, s51
	s_add_i32 s21, 16, 0x14000
	ds_read_b128 v[138:141], v142
	ds_read_b128 v[152:155], v142 offset:1024
	ds_read_b128 v[156:159], v142 offset:2048
	ds_read_b128 v[160:163], v142 offset:3072
	v_add_u32_e32 v142, s21, v149
	ds_read_b128 v[164:167], v142
	ds_read_b128 v[168:171], v142 offset:1024
	ds_read_b128 v[172:175], v142 offset:2048
	ds_read_b128 v[184:187], v142 offset:3072
	v_lshl_add_u64 v[142:143], s[24:25], 0, v[134:135]
	s_add_i32 m0, s31, 0xc000
	ds_read_b128 v[188:191], v151
	ds_read_b128 v[192:195], v151 offset:1024
	ds_read_b128 v[196:199], v151 offset:2048
	ds_read_b128 v[200:203], v151 offset:3072
	ds_read_b128 v[204:207], v151 offset:4096
	ds_read_b128 v[208:211], v151 offset:5120
	ds_read_b128 v[212:215], v151 offset:6144
	ds_read_b128 v[216:219], v151 offset:7168
	global_load_lds_dwordx4 v[142:143], off
	v_lshl_add_u64 v[142:143], s[24:25], 0, v[136:137]
	s_add_i32 m0, s31, 0xe000
	s_nop 0
	global_load_lds_dwordx4 v[142:143], off
	s_waitcnt vmcnt(8)
	s_waitcnt lgkmcnt(0)
	s_barrier
	s_setprio 1
	s_waitcnt lgkmcnt(0)
	v_mfma_f32_16x16x32_bf16 v[120:123], v[138:141], v[188:191], v[120:123]
	v_mfma_f32_16x16x32_bf16 v[124:127], v[156:159], v[188:191], v[124:127]
	v_mfma_f32_16x16x32_bf16 v[108:111], v[138:141], v[196:199], v[108:111]
	v_mfma_f32_16x16x32_bf16 v[104:107], v[156:159], v[196:199], v[104:107]
	v_mfma_f32_16x16x32_bf16 v[92:95], v[138:141], v[204:207], v[92:95]
	v_mfma_f32_16x16x32_bf16 v[88:91], v[156:159], v[204:207], v[88:91]
	v_mfma_f32_16x16x32_bf16 v[76:79], v[138:141], v[212:215], v[76:79]
	v_mfma_f32_16x16x32_bf16 v[72:75], v[156:159], v[212:215], v[72:75]
	v_mfma_f32_16x16x32_bf16 v[120:123], v[152:155], v[192:195], v[120:123]
	v_mfma_f32_16x16x32_bf16 v[124:127], v[160:163], v[192:195], v[124:127]
	v_mfma_f32_16x16x32_bf16 v[108:111], v[152:155], v[200:203], v[108:111]
	v_mfma_f32_16x16x32_bf16 v[104:107], v[160:163], v[200:203], v[104:107]
	v_mfma_f32_16x16x32_bf16 v[92:95], v[152:155], v[208:211], v[92:95]
	v_mfma_f32_16x16x32_bf16 v[88:91], v[160:163], v[208:211], v[88:91]
	v_mfma_f32_16x16x32_bf16 v[76:79], v[152:155], v[216:219], v[76:79]
	v_mfma_f32_16x16x32_bf16 v[72:75], v[160:163], v[216:219], v[72:75]
	s_setprio 0
	s_setprio 1
	v_mfma_f32_16x16x32_bf16 v[116:119], v[164:167], v[188:191], v[116:119]
	v_mfma_f32_16x16x32_bf16 v[112:115], v[172:175], v[188:191], v[112:115]
	v_mfma_f32_16x16x32_bf16 v[100:103], v[164:167], v[196:199], v[100:103]
	v_mfma_f32_16x16x32_bf16 v[96:99], v[172:175], v[196:199], v[96:99]
	v_mfma_f32_16x16x32_bf16 v[84:87], v[164:167], v[204:207], v[84:87]
	v_mfma_f32_16x16x32_bf16 v[80:83], v[172:175], v[204:207], v[80:83]
	v_mfma_f32_16x16x32_bf16 v[68:71], v[164:167], v[212:215], v[68:71]
	v_mfma_f32_16x16x32_bf16 v[64:67], v[172:175], v[212:215], v[64:67]
	v_mfma_f32_16x16x32_bf16 v[116:119], v[168:171], v[192:195], v[116:119]
	v_mfma_f32_16x16x32_bf16 v[112:115], v[184:187], v[192:195], v[112:115]
	v_mfma_f32_16x16x32_bf16 v[100:103], v[168:171], v[200:203], v[100:103]
	v_mfma_f32_16x16x32_bf16 v[96:99], v[184:187], v[200:203], v[96:99]
	v_mfma_f32_16x16x32_bf16 v[84:87], v[168:171], v[208:211], v[84:87]
	v_mfma_f32_16x16x32_bf16 v[80:83], v[184:187], v[208:211], v[80:83]
	v_mfma_f32_16x16x32_bf16 v[68:71], v[168:171], v[216:219], v[68:71]
	v_mfma_f32_16x16x32_bf16 v[64:67], v[184:187], v[216:219], v[64:67]
	s_setprio 0
	s_barrier
	s_add_i32 s20, s20, s30
	v_lshl_add_u64 v[142:143], s[54:55], 0, v[176:177]
	s_mov_b32 m0, s20
	ds_read_b128 v[188:191], v151 offset:16384
	ds_read_b128 v[192:195], v151 offset:17408
	ds_read_b128 v[196:199], v151 offset:18432
	ds_read_b128 v[200:203], v151 offset:19456
	ds_read_b128 v[204:207], v151 offset:20480
	ds_read_b128 v[208:211], v151 offset:21504
	ds_read_b128 v[212:215], v151 offset:22528
	ds_read_b128 v[216:219], v151 offset:23552
	global_load_lds_dwordx4 v[142:143], off
	s_add_i32 m0, s20, 0x2000
	s_add_u32 s24, s54, s6
	v_lshl_add_u64 v[146:147], s[54:55], 0, v[128:129]
	s_addc_u32 s25, s55, s7
	s_add_i32 s20, s21, s30
	global_load_lds_dwordx4 v[146:147], off
	v_lshl_add_u64 v[220:221], s[24:25], 0, v[176:177]
	s_mov_b32 m0, s20
	v_lshl_add_u64 v[222:223], s[24:25], 0, v[128:129]
	global_load_lds_dwordx4 v[220:221], off
	s_add_i32 m0, s20, 0x2000
	v_lshl_add_u64 v[224:225], s[38:39], 0, v[132:133]
	global_load_lds_dwordx4 v[222:223], off
	s_mov_b32 m0, s31
	v_lshl_add_u64 v[226:227], s[38:39], 0, v[130:131]
	global_load_lds_dwordx4 v[224:225], off
	s_mov_b32 m0, s40
	s_nop 0
	global_load_lds_dwordx4 v[226:227], off
	s_nop 15
	s_nop 15
	s_waitcnt vmcnt(8)
	s_waitcnt lgkmcnt(0)
	s_barrier
; #define PG8_STAGE(bufoff, gbase, voff) do { _Pragma("unroll") for (int _i = 0; _i < 2; ++_i) \
;         __builtin_amdgcn_global_load_lds((const unsigned*)((const char*)(gbase) + (voff)[_i]), (LAS unsigned*)(lds + (bufoff) + ldsw + _i * 8192), 16, 0, 0); } while (0)
; #define PG8_LDA(dst, b, h) do { _Pragma("unroll") for (int m = 0; m < 4; ++m) _Pragma("unroll") for (int k = 0; k < 2; ++k) dst[m][k] = *(const LAS bf16x8*)(lds + PG8_SA(b, h) + aoff + m * 2048 + k * 1024); } while (0)
; #define PG8_LDB(dst, b, h) do { _Pragma("unroll") for (int n = 0; n < 2; ++n) _Pragma("unroll") for (int k = 0; k < 2; ++k) dst[n][k] = *(const LAS bf16x8*)(lds + PG8_SB(b, h) + boff + n * 2048 + k * 1024); } while (0)
; #define PG8_MMA(ai, bj, At, Bt) do { __builtin_amdgcn_s_setprio(1); _Pragma("unroll") for (int m = 0; m < 4; ++m) _Pragma("unroll") for (int n = 0; n < 2; ++n) _Pragma("unroll") for (int k = 0; k < 2; ++k) \
;         acc[ai][bj][m][n] = __builtin_amdgcn_mfma_f32_16x16x32_bf16(Bt[n][k], At[m][k], acc[ai][bj][m][n], 0, 0, 0); __builtin_amdgcn_s_setprio(0); } while (0)
; #define PG8_WAIT_V(n) asm volatile("s_waitcnt vmcnt(" #n ")" ::: "memory")
; #define PG8_WAIT_L(n) asm volatile("s_waitcnt lgkmcnt(" #n ")" ::: "memory")
; #define PG8_BAR __builtin_amdgcn_s_barrier()
; #define PG8_SCHED __builtin_amdgcn_sched_barrier(0)
; template <class Epi, bool ALIGN_EPI = PG8_ALIGN>
; __device__ __forceinline__ void gemm_phase(LAS unsigned char* lds, const Gemm g, const StaticOrder& S, const Epi& E) {
;     ...
;             PG8_WAIT_V(8); PG8_WAIT_L(0); PG8_BAR; PG8_MMA(1, 0, At, B0); PG8_MMA(1, 1, At, B1); PG8_BAR; PG8_SCHED;
;             PG8_LDB(B0, 1, 0); PG8_LDB(B1, 1, 1); PG8_SCHED; PG8_LDA(At, 1, 0); PG8_STAGE(PG8_SA(0, 1), a2 + hstepA, voffA);
;             PG8_WAIT_V(8); PG8_WAIT_L(0); PG8_BAR; PG8_MMA(0, 0, At, B0); PG8_MMA(0, 1, At, B1); PG8_BAR; PG8_SCHED;
	s_setprio 1
	s_waitcnt lgkmcnt(0)
	v_mfma_f32_16x16x32_bf16 v[60:63], v[138:141], v[188:191], v[60:63]
	v_mfma_f32_16x16x32_bf16 v[56:59], v[156:159], v[188:191], v[56:59]
	v_mfma_f32_16x16x32_bf16 v[44:47], v[138:141], v[196:199], v[44:47]
	v_mfma_f32_16x16x32_bf16 v[40:43], v[156:159], v[196:199], v[40:43]
	v_mfma_f32_16x16x32_bf16 v[28:31], v[138:141], v[204:207], v[28:31]
	v_mfma_f32_16x16x32_bf16 v[24:27], v[156:159], v[204:207], v[24:27]
	v_mfma_f32_16x16x32_bf16 v[12:15], v[138:141], v[212:215], v[12:15]
	v_mfma_f32_16x16x32_bf16 v[8:11], v[156:159], v[212:215], v[8:11]
	v_mfma_f32_16x16x32_bf16 v[60:63], v[152:155], v[192:195], v[60:63]
	v_mfma_f32_16x16x32_bf16 v[56:59], v[160:163], v[192:195], v[56:59]
	v_mfma_f32_16x16x32_bf16 v[44:47], v[152:155], v[200:203], v[44:47]
	v_mfma_f32_16x16x32_bf16 v[40:43], v[160:163], v[200:203], v[40:43]
	v_mfma_f32_16x16x32_bf16 v[28:31], v[152:155], v[208:211], v[28:31]
	v_mfma_f32_16x16x32_bf16 v[24:27], v[160:163], v[208:211], v[24:27]
	v_mfma_f32_16x16x32_bf16 v[12:15], v[152:155], v[216:219], v[12:15]
	v_mfma_f32_16x16x32_bf16 v[8:11], v[160:163], v[216:219], v[8:11]
	s_setprio 0
	s_setprio 1
	v_mfma_f32_16x16x32_bf16 v[52:55], v[164:167], v[188:191], v[52:55]
	v_mfma_f32_16x16x32_bf16 v[48:51], v[172:175], v[188:191], v[48:51]
	v_mfma_f32_16x16x32_bf16 v[36:39], v[164:167], v[196:199], v[36:39]
	v_mfma_f32_16x16x32_bf16 v[32:35], v[172:175], v[196:199], v[32:35]
	v_mfma_f32_16x16x32_bf16 v[20:23], v[164:167], v[204:207], v[20:23]
	v_mfma_f32_16x16x32_bf16 v[16:19], v[172:175], v[204:207], v[16:19]
	v_mfma_f32_16x16x32_bf16 v[4:7], v[164:167], v[212:215], v[4:7]
	v_mfma_f32_16x16x32_bf16 v[0:3], v[172:175], v[212:215], v[0:3]
	v_mfma_f32_16x16x32_bf16 v[52:55], v[168:171], v[192:195], v[52:55]
	v_mfma_f32_16x16x32_bf16 v[48:51], v[184:187], v[192:195], v[48:51]
	v_mfma_f32_16x16x32_bf16 v[36:39], v[168:171], v[200:203], v[36:39]
	v_mfma_f32_16x16x32_bf16 v[32:35], v[184:187], v[200:203], v[32:35]
	v_mfma_f32_16x16x32_bf16 v[20:23], v[168:171], v[208:211], v[20:23]
	v_mfma_f32_16x16x32_bf16 v[16:19], v[184:187], v[208:211], v[16:19]
	v_mfma_f32_16x16x32_bf16 v[4:7], v[168:171], v[216:219], v[4:7]
	v_mfma_f32_16x16x32_bf16 v[0:3], v[184:187], v[216:219], v[0:3]
	s_setprio 0
	s_barrier
	s_add_i32 s20, 16, 0x18000
	v_add_u32_e32 v144, s20, v149
	s_add_i32 s21, 16, 0x1c000
	ds_read_b128 v[138:141], v144
	ds_read_b128 v[152:155], v144 offset:1024
	ds_read_b128 v[156:159], v144 offset:2048
	ds_read_b128 v[160:163], v144 offset:3072
	v_add_u32_e32 v144, s21, v149
	ds_read_b128 v[164:167], v144
	ds_read_b128 v[168:171], v144 offset:1024
	ds_read_b128 v[172:175], v144 offset:2048
	ds_read_b128 v[184:187], v144 offset:3072
	s_add_u32 s24, s38, 0x110000
	s_addc_u32 s25, s39, 0
	s_mov_b32 m0, s41
	v_lshl_add_u64 v[228:229], s[24:25], 0, v[132:133]
	ds_read_b128 v[188:191], v151 offset:32768
	ds_read_b128 v[192:195], v151 offset:33792
	ds_read_b128 v[196:199], v151 offset:34816
	ds_read_b128 v[200:203], v151 offset:35840
	ds_read_b128 v[204:207], v151 offset:36864
	ds_read_b128 v[208:211], v151 offset:37888
	ds_read_b128 v[212:215], v151 offset:38912
	ds_read_b128 v[216:219], v151 offset:39936
	global_load_lds_dwordx4 v[228:229], off
	v_lshl_add_u64 v[228:229], s[24:25], 0, v[130:131]
	s_mov_b32 m0, s44
	s_nop 0
	global_load_lds_dwordx4 v[228:229], off
	s_waitcnt vmcnt(8)
	s_waitcnt lgkmcnt(0)
	s_barrier
	s_setprio 1
	s_waitcnt lgkmcnt(0)
	v_mfma_f32_16x16x32_bf16 v[120:123], v[138:141], v[188:191], v[120:123]
	v_mfma_f32_16x16x32_bf16 v[124:127], v[156:159], v[188:191], v[124:127]
	v_mfma_f32_16x16x32_bf16 v[108:111], v[138:141], v[196:199], v[108:111]
	v_mfma_f32_16x16x32_bf16 v[104:107], v[156:159], v[196:199], v[104:107]
	v_mfma_f32_16x16x32_bf16 v[92:95], v[138:141], v[204:207], v[92:95]
	v_mfma_f32_16x16x32_bf16 v[88:91], v[156:159], v[204:207], v[88:91]
	v_mfma_f32_16x16x32_bf16 v[76:79], v[138:141], v[212:215], v[76:79]
	v_mfma_f32_16x16x32_bf16 v[72:75], v[156:159], v[212:215], v[72:75]
	v_mfma_f32_16x16x32_bf16 v[120:123], v[152:155], v[192:195], v[120:123]
	v_mfma_f32_16x16x32_bf16 v[124:127], v[160:163], v[192:195], v[124:127]
	v_mfma_f32_16x16x32_bf16 v[108:111], v[152:155], v[200:203], v[108:111]
	v_mfma_f32_16x16x32_bf16 v[104:107], v[160:163], v[200:203], v[104:107]
	v_mfma_f32_16x16x32_bf16 v[92:95], v[152:155], v[208:211], v[92:95]
	v_mfma_f32_16x16x32_bf16 v[88:91], v[160:163], v[208:211], v[88:91]
	v_mfma_f32_16x16x32_bf16 v[76:79], v[152:155], v[216:219], v[76:79]
	v_mfma_f32_16x16x32_bf16 v[72:75], v[160:163], v[216:219], v[72:75]
	s_setprio 0
	s_setprio 1
	v_mfma_f32_16x16x32_bf16 v[116:119], v[164:167], v[188:191], v[116:119]
	v_mfma_f32_16x16x32_bf16 v[112:115], v[172:175], v[188:191], v[112:115]
	v_mfma_f32_16x16x32_bf16 v[100:103], v[164:167], v[196:199], v[100:103]
	v_mfma_f32_16x16x32_bf16 v[96:99], v[172:175], v[196:199], v[96:99]
	v_mfma_f32_16x16x32_bf16 v[84:87], v[164:167], v[204:207], v[84:87]
	v_mfma_f32_16x16x32_bf16 v[80:83], v[172:175], v[204:207], v[80:83]
	v_mfma_f32_16x16x32_bf16 v[68:71], v[164:167], v[212:215], v[68:71]
	v_mfma_f32_16x16x32_bf16 v[64:67], v[172:175], v[212:215], v[64:67]
	v_mfma_f32_16x16x32_bf16 v[116:119], v[168:171], v[192:195], v[116:119]
	v_mfma_f32_16x16x32_bf16 v[112:115], v[184:187], v[192:195], v[112:115]
	v_mfma_f32_16x16x32_bf16 v[100:103], v[168:171], v[200:203], v[100:103]
	v_mfma_f32_16x16x32_bf16 v[96:99], v[184:187], v[200:203], v[96:99]
	v_mfma_f32_16x16x32_bf16 v[84:87], v[168:171], v[208:211], v[84:87]
	v_mfma_f32_16x16x32_bf16 v[80:83], v[184:187], v[208:211], v[80:83]
	v_mfma_f32_16x16x32_bf16 v[68:71], v[168:171], v[216:219], v[68:71]
	v_mfma_f32_16x16x32_bf16 v[64:67], v[184:187], v[216:219], v[64:67]
	s_setprio 0
	s_barrier
; #define PG8_STAGE(bufoff, gbase, voff) do { _Pragma("unroll") for (int _i = 0; _i < 2; ++_i) \
;         __builtin_amdgcn_global_load_lds((const unsigned*)((const char*)(gbase) + (voff)[_i]), (LAS unsigned*)(lds + (bufoff) + ldsw + _i * 8192), 16, 0, 0); } while (0)
; #define PG8_LDA(dst, b, h) do { _Pragma("unroll") for (int m = 0; m < 4; ++m) _Pragma("unroll") for (int k = 0; k < 2; ++k) dst[m][k] = *(const LAS bf16x8*)(lds + PG8_SA(b, h) + aoff + m * 2048 + k * 1024); } while (0)
; #define PG8_MMA(ai, bj, At, Bt) do { __builtin_amdgcn_s_setprio(1); _Pragma("unroll") for (int m = 0; m < 4; ++m) _Pragma("unroll") for (int n = 0; n < 2; ++n) _Pragma("unroll") for (int k = 0; k < 2; ++k) \
;         acc[ai][bj][m][n] = __builtin_amdgcn_mfma_f32_16x16x32_bf16(Bt[n][k], At[m][k], acc[ai][bj][m][n], 0, 0, 0); __builtin_amdgcn_s_setprio(0); } while (0)
; #define PG8_WAIT_V(n) asm volatile("s_waitcnt vmcnt(" #n ")" ::: "memory")
; #define PG8_WAIT_L(n) asm volatile("s_waitcnt lgkmcnt(" #n ")" ::: "memory")
; #define PG8_BAR __builtin_amdgcn_s_barrier()
; #define PG8_SCHED __builtin_amdgcn_sched_barrier(0)
; template <class Epi, bool ALIGN_EPI = PG8_ALIGN>
; __device__ __forceinline__ void gemm_phase(LAS unsigned char* lds, const Gemm g, const StaticOrder& S, const Epi& E) {
;     ...
;             PG8_LDA(At, 1, 1); PG8_STAGE(PG8_SB(1, 0), b3, voffB); PG8_STAGE(PG8_SB(1, 1), b3 + hstepB, voffB); PG8_STAGE(PG8_SA(1, 0), a3, voffA);
;             PG8_WAIT_V(8); PG8_WAIT_L(0); PG8_BAR; PG8_MMA(1, 0, At, B0); PG8_MMA(1, 1, At, B1); PG8_BAR; PG8_SCHED;
;         }
	s_add_i32 s20, s20, s30
	v_lshl_add_u64 v[142:143], v[142:143], 0, s[0:1]
	s_mov_b32 m0, s20
	ds_read_b128 v[188:191], v151 offset:49152
	ds_read_b128 v[192:195], v151 offset:50176
	ds_read_b128 v[196:199], v151 offset:51200
	ds_read_b128 v[200:203], v151 offset:52224
	ds_read_b128 v[204:207], v151 offset:53248
	ds_read_b128 v[208:211], v151 offset:54272
	ds_read_b128 v[212:215], v151 offset:55296
	ds_read_b128 v[216:219], v151 offset:56320
	global_load_lds_dwordx4 v[142:143], off
	v_lshl_add_u64 v[142:143], v[146:147], 0, s[0:1]
	s_add_i32 m0, s20, 0x2000
	s_add_i32 s20, s21, s30
	global_load_lds_dwordx4 v[142:143], off
	v_lshl_add_u64 v[142:143], v[220:221], 0, s[0:1]
	s_mov_b32 m0, s20
	s_nop 0
	global_load_lds_dwordx4 v[142:143], off
	v_lshl_add_u64 v[142:143], v[222:223], 0, s[0:1]
	s_add_i32 m0, s20, 0x2000
	s_nop 0
	global_load_lds_dwordx4 v[142:143], off
	v_lshl_add_u64 v[142:143], v[224:225], 0, s[0:1]
	s_mov_b32 m0, s45
	s_nop 0
	global_load_lds_dwordx4 v[142:143], off
	v_lshl_add_u64 v[142:143], v[226:227], 0, s[0:1]
	s_mov_b32 m0, s46
	s_nop 0
	global_load_lds_dwordx4 v[142:143], off
	s_nop 15
	s_nop 15
	s_waitcnt vmcnt(8)
	s_waitcnt lgkmcnt(0)
	s_barrier
	s_setprio 1
	s_waitcnt lgkmcnt(0)
	v_mfma_f32_16x16x32_bf16 v[60:63], v[138:141], v[188:191], v[60:63]
	v_mfma_f32_16x16x32_bf16 v[56:59], v[156:159], v[188:191], v[56:59]
	v_mfma_f32_16x16x32_bf16 v[44:47], v[138:141], v[196:199], v[44:47]
	v_mfma_f32_16x16x32_bf16 v[40:43], v[156:159], v[196:199], v[40:43]
	v_mfma_f32_16x16x32_bf16 v[28:31], v[138:141], v[204:207], v[28:31]
	v_mfma_f32_16x16x32_bf16 v[24:27], v[156:159], v[204:207], v[24:27]
	v_mfma_f32_16x16x32_bf16 v[12:15], v[138:141], v[212:215], v[12:15]
	v_mfma_f32_16x16x32_bf16 v[8:11], v[156:159], v[212:215], v[8:11]
	v_mfma_f32_16x16x32_bf16 v[60:63], v[152:155], v[192:195], v[60:63]
	v_mfma_f32_16x16x32_bf16 v[56:59], v[160:163], v[192:195], v[56:59]
	v_mfma_f32_16x16x32_bf16 v[44:47], v[152:155], v[200:203], v[44:47]
	v_mfma_f32_16x16x32_bf16 v[40:43], v[160:163], v[200:203], v[40:43]
	v_mfma_f32_16x16x32_bf16 v[28:31], v[152:155], v[208:211], v[28:31]
	v_mfma_f32_16x16x32_bf16 v[24:27], v[160:163], v[208:211], v[24:27]
	v_mfma_f32_16x16x32_bf16 v[12:15], v[152:155], v[216:219], v[12:15]
	v_mfma_f32_16x16x32_bf16 v[8:11], v[160:163], v[216:219], v[8:11]
	s_setprio 0
	s_setprio 1
	v_mfma_f32_16x16x32_bf16 v[52:55], v[164:167], v[188:191], v[52:55]
	v_mfma_f32_16x16x32_bf16 v[48:51], v[172:175], v[188:191], v[48:51]
	v_mfma_f32_16x16x32_bf16 v[36:39], v[164:167], v[196:199], v[36:39]
	v_mfma_f32_16x16x32_bf16 v[32:35], v[172:175], v[196:199], v[32:35]
	v_mfma_f32_16x16x32_bf16 v[20:23], v[164:167], v[204:207], v[20:23]
	v_mfma_f32_16x16x32_bf16 v[16:19], v[172:175], v[204:207], v[16:19]
	v_mfma_f32_16x16x32_bf16 v[4:7], v[164:167], v[212:215], v[4:7]
	v_mfma_f32_16x16x32_bf16 v[0:3], v[172:175], v[212:215], v[0:3]
	v_mfma_f32_16x16x32_bf16 v[52:55], v[168:171], v[192:195], v[52:55]
	v_mfma_f32_16x16x32_bf16 v[48:51], v[184:187], v[192:195], v[48:51]
	v_mfma_f32_16x16x32_bf16 v[36:39], v[168:171], v[200:203], v[36:39]
	v_mfma_f32_16x16x32_bf16 v[32:35], v[184:187], v[200:203], v[32:35]
	v_mfma_f32_16x16x32_bf16 v[20:23], v[168:171], v[208:211], v[20:23]
	v_mfma_f32_16x16x32_bf16 v[16:19], v[184:187], v[208:211], v[16:19]
	v_mfma_f32_16x16x32_bf16 v[4:7], v[168:171], v[216:219], v[4:7]
	v_mfma_f32_16x16x32_bf16 v[0:3], v[184:187], v[216:219], v[0:3]
	s_setprio 0
	s_barrier
	s_add_u32 s51, s51, 0x100
	s_addc_u32 s52, s52, 0
	s_cmp_ge_i32 s53, s47
	s_mov_b64 s[24:25], s[36:37]
	s_mov_b32 s38, s53
	s_cbranch_scc0 .LBB0_642

; #define PG8_STAGE(bufoff, gbase, voff) do { _Pragma("unroll") for (int _i = 0; _i < 2; ++_i) \
;         __builtin_amdgcn_global_load_lds((const unsigned*)((const char*)(gbase) + (voff)[_i]), (LAS unsigned*)(lds + (bufoff) + ldsw + _i * 8192), 16, 0, 0); } while (0)
; #define PG8_LDA(dst, b, h) do { _Pragma("unroll") for (int m = 0; m < 4; ++m) _Pragma("unroll") for (int k = 0; k < 2; ++k) dst[m][k] = *(const LAS bf16x8*)(lds + PG8_SA(b, h) + aoff + m * 2048 + k * 1024); } while (0)
; #define PG8_LDB(dst, b, h) do { _Pragma("unroll") for (int n = 0; n < 2; ++n) _Pragma("unroll") for (int k = 0; k < 2; ++k) dst[n][k] = *(const LAS bf16x8*)(lds + PG8_SB(b, h) + boff + n * 2048 + k * 1024); } while (0)
; #define PG8_MMA(ai, bj, At, Bt) do { __builtin_amdgcn_s_setprio(1); _Pragma("unroll") for (int m = 0; m < 4; ++m) _Pragma("unroll") for (int n = 0; n < 2; ++n) _Pragma("unroll") for (int k = 0; k < 2; ++k) \
;         acc[ai][bj][m][n] = __builtin_amdgcn_mfma_f32_16x16x32_bf16(Bt[n][k], At[m][k], acc[ai][bj][m][n], 0, 0, 0); __builtin_amdgcn_s_setprio(0); } while (0)
; #define PG8_WAIT_V(n) asm volatile("s_waitcnt vmcnt(" #n ")" ::: "memory")
; #define PG8_WAIT_L(n) asm volatile("s_waitcnt lgkmcnt(" #n ")" ::: "memory")
; #define PG8_BAR __builtin_amdgcn_s_barrier()
; #define PG8_SCHED __builtin_amdgcn_sched_barrier(0)
; template <class Epi, bool ALIGN_EPI = PG8_ALIGN>
; __device__ __forceinline__ void gemm_phase(LAS unsigned char* lds, const Gemm g, const StaticOrder& S, const Epi& E) {
;     ...
;         for (int t = 0; t < nt; t += 2) {
;             const bool last = (t == nt - 2);
;             const char* a1 = cA + (size_t)(t + 1) * kstep;
;             const char* a2 = last ? nA : cA + (size_t)(t + 2) * kstep; const char* b2 = last ? nB : cB + (size_t)(t + 2) * kstep;
;             const char* a3 = a2 + kstep; const char* b3 = b2 + kstep;
;             PG8_LDB(B0, 0, 0); PG8_LDB(B1, 0, 1); PG8_SCHED; PG8_LDA(At, 0, 0); PG8_STAGE(PG8_SA(1, 1), a1 + hstepA, voffA);
;             PG8_WAIT_V(8); PG8_WAIT_L(0); PG8_BAR; PG8_MMA(0, 0, At, B0); PG8_MMA(0, 1, At, B1); PG8_BAR; PG8_SCHED;
;             PG8_LDA(At, 0, 1); PG8_STAGE(PG8_SB(0, 0), b2, voffB); PG8_STAGE(PG8_SB(0, 1), b2 + hstepB, voffB); PG8_STAGE(PG8_SA(0, 0), a2, voffA);
.LBB0_663:
	s_add_i32 s53, s38, 2
	s_add_u32 s36, s24, 0x100
	s_addc_u32 s37, s25, 0
	s_add_i32 s20, 16, 0x10000
	s_cmp_eq_u32 s48, s38
	s_cselect_b32 s39, s3, s37
	s_cselect_b32 s38, s2, s36
	v_add_u32_e32 v138, s20, v143
	s_cselect_b32 s55, s17, s52
	s_cselect_b32 s54, s16, s34
	s_add_i32 s21, 16, 0x14000
	ds_read_b128 v[152:155], v138
	ds_read_b128 v[156:159], v138 offset:1024
	ds_read_b128 v[160:163], v138 offset:2048
	ds_read_b128 v[164:167], v138 offset:3072
	v_add_u32_e32 v138, s21, v143
	ds_read_b128 v[168:171], v138
	ds_read_b128 v[172:175], v138 offset:1024
	ds_read_b128 v[184:187], v138 offset:2048
	ds_read_b128 v[188:191], v138 offset:3072
	v_lshl_add_u64 v[140:141], s[24:25], 0, v[134:135]
	s_add_i32 m0, s31, 0xc000
	ds_read_b128 v[192:195], v151
	ds_read_b128 v[196:199], v151 offset:1024
	ds_read_b128 v[200:203], v151 offset:2048
	ds_read_b128 v[204:207], v151 offset:3072
	ds_read_b128 v[208:211], v151 offset:4096
	ds_read_b128 v[212:215], v151 offset:5120
	ds_read_b128 v[216:219], v151 offset:6144
	ds_read_b128 v[220:223], v151 offset:7168
	global_load_lds_dwordx4 v[140:141], off
	v_lshl_add_u64 v[140:141], s[24:25], 0, v[136:137]
	s_add_i32 m0, s31, 0xe000
	s_nop 0
	global_load_lds_dwordx4 v[140:141], off
	s_waitcnt vmcnt(8)
	s_waitcnt lgkmcnt(0)
	s_barrier
	s_setprio 1
	s_waitcnt lgkmcnt(0)
	v_mfma_f32_16x16x32_bf16 v[120:123], v[152:155], v[192:195], v[120:123]
	v_mfma_f32_16x16x32_bf16 v[124:127], v[160:163], v[192:195], v[124:127]
	v_mfma_f32_16x16x32_bf16 v[108:111], v[152:155], v[200:203], v[108:111]
	v_mfma_f32_16x16x32_bf16 v[104:107], v[160:163], v[200:203], v[104:107]
	v_mfma_f32_16x16x32_bf16 v[92:95], v[152:155], v[208:211], v[92:95]
	v_mfma_f32_16x16x32_bf16 v[88:91], v[160:163], v[208:211], v[88:91]
	v_mfma_f32_16x16x32_bf16 v[76:79], v[152:155], v[216:219], v[76:79]
	v_mfma_f32_16x16x32_bf16 v[72:75], v[160:163], v[216:219], v[72:75]
	v_mfma_f32_16x16x32_bf16 v[120:123], v[156:159], v[196:199], v[120:123]
	v_mfma_f32_16x16x32_bf16 v[124:127], v[164:167], v[196:199], v[124:127]
	v_mfma_f32_16x16x32_bf16 v[108:111], v[156:159], v[204:207], v[108:111]
	v_mfma_f32_16x16x32_bf16 v[104:107], v[164:167], v[204:207], v[104:107]
	v_mfma_f32_16x16x32_bf16 v[92:95], v[156:159], v[212:215], v[92:95]
	v_mfma_f32_16x16x32_bf16 v[88:91], v[164:167], v[212:215], v[88:91]
	v_mfma_f32_16x16x32_bf16 v[76:79], v[156:159], v[220:223], v[76:79]
	v_mfma_f32_16x16x32_bf16 v[72:75], v[164:167], v[220:223], v[72:75]
	s_setprio 0
	s_setprio 1
	v_mfma_f32_16x16x32_bf16 v[116:119], v[168:171], v[192:195], v[116:119]
	v_mfma_f32_16x16x32_bf16 v[112:115], v[184:187], v[192:195], v[112:115]
	v_mfma_f32_16x16x32_bf16 v[100:103], v[168:171], v[200:203], v[100:103]
	v_mfma_f32_16x16x32_bf16 v[96:99], v[184:187], v[200:203], v[96:99]
	v_mfma_f32_16x16x32_bf16 v[84:87], v[168:171], v[208:211], v[84:87]
	v_mfma_f32_16x16x32_bf16 v[80:83], v[184:187], v[208:211], v[80:83]
	v_mfma_f32_16x16x32_bf16 v[68:71], v[168:171], v[216:219], v[68:71]
	v_mfma_f32_16x16x32_bf16 v[64:67], v[184:187], v[216:219], v[64:67]
	v_mfma_f32_16x16x32_bf16 v[116:119], v[172:175], v[196:199], v[116:119]
	v_mfma_f32_16x16x32_bf16 v[112:115], v[188:191], v[196:199], v[112:115]
	v_mfma_f32_16x16x32_bf16 v[100:103], v[172:175], v[204:207], v[100:103]
	v_mfma_f32_16x16x32_bf16 v[96:99], v[188:191], v[204:207], v[96:99]
	v_mfma_f32_16x16x32_bf16 v[84:87], v[172:175], v[212:215], v[84:87]
	v_mfma_f32_16x16x32_bf16 v[80:83], v[188:191], v[212:215], v[80:83]
	v_mfma_f32_16x16x32_bf16 v[68:71], v[172:175], v[220:223], v[68:71]
	v_mfma_f32_16x16x32_bf16 v[64:67], v[188:191], v[220:223], v[64:67]
	s_setprio 0
	s_barrier
	s_add_i32 s20, s20, s30
	v_lshl_add_u64 v[140:141], s[54:55], 0, v[176:177]
	s_mov_b32 m0, s20
	ds_read_b128 v[192:195], v151 offset:16384
	ds_read_b128 v[196:199], v151 offset:17408
	ds_read_b128 v[200:203], v151 offset:18432
	ds_read_b128 v[204:207], v151 offset:19456
	ds_read_b128 v[208:211], v151 offset:20480
	ds_read_b128 v[212:215], v151 offset:21504
	ds_read_b128 v[216:219], v151 offset:22528
	ds_read_b128 v[220:223], v151 offset:23552
	global_load_lds_dwordx4 v[140:141], off
	s_add_i32 m0, s20, 0x2000
	s_add_u32 s24, s54, s6
	v_lshl_add_u64 v[144:145], s[54:55], 0, v[128:129]
	s_addc_u32 s25, s55, s7
	s_add_i32 s20, s21, s30
	global_load_lds_dwordx4 v[144:145], off
	v_lshl_add_u64 v[148:149], s[24:25], 0, v[176:177]
	s_mov_b32 m0, s20
	v_lshl_add_u64 v[224:225], s[24:25], 0, v[128:129]
	global_load_lds_dwordx4 v[148:149], off
	s_add_i32 m0, s20, 0x2000
	v_lshl_add_u64 v[226:227], s[38:39], 0, v[132:133]
	global_load_lds_dwordx4 v[224:225], off
	s_mov_b32 m0, s31
	v_lshl_add_u64 v[228:229], s[38:39], 0, v[130:131]
	global_load_lds_dwordx4 v[226:227], off
	s_mov_b32 m0, s40
	s_nop 0
	global_load_lds_dwordx4 v[228:229], off
	s_nop 15
	s_nop 15
	s_waitcnt vmcnt(8)
	s_waitcnt lgkmcnt(0)
	s_barrier
; #define PG8_STAGE(bufoff, gbase, voff) do { _Pragma("unroll") for (int _i = 0; _i < 2; ++_i) \
;         __builtin_amdgcn_global_load_lds((const unsigned*)((const char*)(gbase) + (voff)[_i]), (LAS unsigned*)(lds + (bufoff) + ldsw + _i * 8192), 16, 0, 0); } while (0)
; #define PG8_LDA(dst, b, h) do { _Pragma("unroll") for (int m = 0; m < 4; ++m) _Pragma("unroll") for (int k = 0; k < 2; ++k) dst[m][k] = *(const LAS bf16x8*)(lds + PG8_SA(b, h) + aoff + m * 2048 + k * 1024); } while (0)
; #define PG8_LDB(dst, b, h) do { _Pragma("unroll") for (int n = 0; n < 2; ++n) _Pragma("unroll") for (int k = 0; k < 2; ++k) dst[n][k] = *(const LAS bf16x8*)(lds + PG8_SB(b, h) + boff + n * 2048 + k * 1024); } while (0)
; #define PG8_MMA(ai, bj, At, Bt) do { __builtin_amdgcn_s_setprio(1); _Pragma("unroll") for (int m = 0; m < 4; ++m) _Pragma("unroll") for (int n = 0; n < 2; ++n) _Pragma("unroll") for (int k = 0; k < 2; ++k) \
;         acc[ai][bj][m][n] = __builtin_amdgcn_mfma_f32_16x16x32_bf16(Bt[n][k], At[m][k], acc[ai][bj][m][n], 0, 0, 0); __builtin_amdgcn_s_setprio(0); } while (0)
; #define PG8_WAIT_V(n) asm volatile("s_waitcnt vmcnt(" #n ")" ::: "memory")
; #define PG8_WAIT_L(n) asm volatile("s_waitcnt lgkmcnt(" #n ")" ::: "memory")
; #define PG8_BAR __builtin_amdgcn_s_barrier()
; #define PG8_SCHED __builtin_amdgcn_sched_barrier(0)
; template <class Epi, bool ALIGN_EPI = PG8_ALIGN>
; __device__ __forceinline__ void gemm_phase(LAS unsigned char* lds, const Gemm g, const StaticOrder& S, const Epi& E) {
;     ...
;             PG8_WAIT_V(8); PG8_WAIT_L(0); PG8_BAR; PG8_MMA(1, 0, At, B0); PG8_MMA(1, 1, At, B1); PG8_BAR; PG8_SCHED;
;             PG8_LDB(B0, 1, 0); PG8_LDB(B1, 1, 1); PG8_SCHED; PG8_LDA(At, 1, 0); PG8_STAGE(PG8_SA(0, 1), a2 + hstepA, voffA);
;             PG8_WAIT_V(8); PG8_WAIT_L(0); PG8_BAR; PG8_MMA(0, 0, At, B0); PG8_MMA(0, 1, At, B1); PG8_BAR; PG8_SCHED;
	s_setprio 1
	s_waitcnt lgkmcnt(0)
	v_mfma_f32_16x16x32_bf16 v[60:63], v[152:155], v[192:195], v[60:63]
	v_mfma_f32_16x16x32_bf16 v[56:59], v[160:163], v[192:195], v[56:59]
	v_mfma_f32_16x16x32_bf16 v[44:47], v[152:155], v[200:203], v[44:47]
	v_mfma_f32_16x16x32_bf16 v[40:43], v[160:163], v[200:203], v[40:43]
	v_mfma_f32_16x16x32_bf16 v[28:31], v[152:155], v[208:211], v[28:31]
	v_mfma_f32_16x16x32_bf16 v[24:27], v[160:163], v[208:211], v[24:27]
	v_mfma_f32_16x16x32_bf16 v[12:15], v[152:155], v[216:219], v[12:15]
	v_mfma_f32_16x16x32_bf16 v[8:11], v[160:163], v[216:219], v[8:11]
	v_mfma_f32_16x16x32_bf16 v[60:63], v[156:159], v[196:199], v[60:63]
	v_mfma_f32_16x16x32_bf16 v[56:59], v[164:167], v[196:199], v[56:59]
	v_mfma_f32_16x16x32_bf16 v[44:47], v[156:159], v[204:207], v[44:47]
	v_mfma_f32_16x16x32_bf16 v[40:43], v[164:167], v[204:207], v[40:43]
	v_mfma_f32_16x16x32_bf16 v[28:31], v[156:159], v[212:215], v[28:31]
	v_mfma_f32_16x16x32_bf16 v[24:27], v[164:167], v[212:215], v[24:27]
	v_mfma_f32_16x16x32_bf16 v[12:15], v[156:159], v[220:223], v[12:15]
	v_mfma_f32_16x16x32_bf16 v[8:11], v[164:167], v[220:223], v[8:11]
	s_setprio 0
	s_setprio 1
	v_mfma_f32_16x16x32_bf16 v[52:55], v[168:171], v[192:195], v[52:55]
	v_mfma_f32_16x16x32_bf16 v[48:51], v[184:187], v[192:195], v[48:51]
	v_mfma_f32_16x16x32_bf16 v[36:39], v[168:171], v[200:203], v[36:39]
	v_mfma_f32_16x16x32_bf16 v[32:35], v[184:187], v[200:203], v[32:35]
	v_mfma_f32_16x16x32_bf16 v[20:23], v[168:171], v[208:211], v[20:23]
	v_mfma_f32_16x16x32_bf16 v[16:19], v[184:187], v[208:211], v[16:19]
	v_mfma_f32_16x16x32_bf16 v[4:7], v[168:171], v[216:219], v[4:7]
	v_mfma_f32_16x16x32_bf16 v[0:3], v[184:187], v[216:219], v[0:3]
	v_mfma_f32_16x16x32_bf16 v[52:55], v[172:175], v[196:199], v[52:55]
	v_mfma_f32_16x16x32_bf16 v[48:51], v[188:191], v[196:199], v[48:51]
	v_mfma_f32_16x16x32_bf16 v[36:39], v[172:175], v[204:207], v[36:39]
	v_mfma_f32_16x16x32_bf16 v[32:35], v[188:191], v[204:207], v[32:35]
	v_mfma_f32_16x16x32_bf16 v[20:23], v[172:175], v[212:215], v[20:23]
	v_mfma_f32_16x16x32_bf16 v[16:19], v[188:191], v[212:215], v[16:19]
	v_mfma_f32_16x16x32_bf16 v[4:7], v[172:175], v[220:223], v[4:7]
	v_mfma_f32_16x16x32_bf16 v[0:3], v[188:191], v[220:223], v[0:3]
	s_setprio 0
	s_barrier
	s_add_i32 s20, 16, 0x18000
	v_add_u32_e32 v138, s20, v143
	s_add_i32 s21, 16, 0x1c000
	ds_read_b128 v[152:155], v138
	ds_read_b128 v[156:159], v138 offset:1024
	ds_read_b128 v[160:163], v138 offset:2048
	ds_read_b128 v[164:167], v138 offset:3072
	v_add_u32_e32 v138, s21, v143
	ds_read_b128 v[168:171], v138
	ds_read_b128 v[172:175], v138 offset:1024
	ds_read_b128 v[184:187], v138 offset:2048
	ds_read_b128 v[188:191], v138 offset:3072
	s_add_u32 s24, s38, 0x110000
	s_addc_u32 s25, s39, 0
	s_mov_b32 m0, s41
	v_lshl_add_u64 v[230:231], s[24:25], 0, v[132:133]
	ds_read_b128 v[192:195], v151 offset:32768
	ds_read_b128 v[196:199], v151 offset:33792
	ds_read_b128 v[200:203], v151 offset:34816
	ds_read_b128 v[204:207], v151 offset:35840
	ds_read_b128 v[208:211], v151 offset:36864
	ds_read_b128 v[212:215], v151 offset:37888
	ds_read_b128 v[216:219], v151 offset:38912
	ds_read_b128 v[220:223], v151 offset:39936
	global_load_lds_dwordx4 v[230:231], off
	v_lshl_add_u64 v[230:231], s[24:25], 0, v[130:131]
	s_mov_b32 m0, s44
	s_nop 0
	global_load_lds_dwordx4 v[230:231], off
	s_waitcnt vmcnt(8)
	s_waitcnt lgkmcnt(0)
	s_barrier
	s_setprio 1
	s_waitcnt lgkmcnt(0)
	v_mfma_f32_16x16x32_bf16 v[120:123], v[152:155], v[192:195], v[120:123]
	v_mfma_f32_16x16x32_bf16 v[124:127], v[160:163], v[192:195], v[124:127]
	v_mfma_f32_16x16x32_bf16 v[108:111], v[152:155], v[200:203], v[108:111]
	v_mfma_f32_16x16x32_bf16 v[104:107], v[160:163], v[200:203], v[104:107]
	v_mfma_f32_16x16x32_bf16 v[92:95], v[152:155], v[208:211], v[92:95]
	v_mfma_f32_16x16x32_bf16 v[88:91], v[160:163], v[208:211], v[88:91]
	v_mfma_f32_16x16x32_bf16 v[76:79], v[152:155], v[216:219], v[76:79]
	v_mfma_f32_16x16x32_bf16 v[72:75], v[160:163], v[216:219], v[72:75]
	v_mfma_f32_16x16x32_bf16 v[120:123], v[156:159], v[196:199], v[120:123]
	v_mfma_f32_16x16x32_bf16 v[124:127], v[164:167], v[196:199], v[124:127]
	v_mfma_f32_16x16x32_bf16 v[108:111], v[156:159], v[204:207], v[108:111]
	v_mfma_f32_16x16x32_bf16 v[104:107], v[164:167], v[204:207], v[104:107]
	v_mfma_f32_16x16x32_bf16 v[92:95], v[156:159], v[212:215], v[92:95]
	v_mfma_f32_16x16x32_bf16 v[88:91], v[164:167], v[212:215], v[88:91]
	v_mfma_f32_16x16x32_bf16 v[76:79], v[156:159], v[220:223], v[76:79]
	v_mfma_f32_16x16x32_bf16 v[72:75], v[164:167], v[220:223], v[72:75]
	s_setprio 0
	s_setprio 1
	v_mfma_f32_16x16x32_bf16 v[116:119], v[168:171], v[192:195], v[116:119]
	v_mfma_f32_16x16x32_bf16 v[112:115], v[184:187], v[192:195], v[112:115]
	v_mfma_f32_16x16x32_bf16 v[100:103], v[168:171], v[200:203], v[100:103]
	v_mfma_f32_16x16x32_bf16 v[96:99], v[184:187], v[200:203], v[96:99]
	v_mfma_f32_16x16x32_bf16 v[84:87], v[168:171], v[208:211], v[84:87]
	v_mfma_f32_16x16x32_bf16 v[80:83], v[184:187], v[208:211], v[80:83]
	v_mfma_f32_16x16x32_bf16 v[68:71], v[168:171], v[216:219], v[68:71]
	v_mfma_f32_16x16x32_bf16 v[64:67], v[184:187], v[216:219], v[64:67]
	v_mfma_f32_16x16x32_bf16 v[116:119], v[172:175], v[196:199], v[116:119]
	v_mfma_f32_16x16x32_bf16 v[112:115], v[188:191], v[196:199], v[112:115]
	v_mfma_f32_16x16x32_bf16 v[100:103], v[172:175], v[204:207], v[100:103]
	v_mfma_f32_16x16x32_bf16 v[96:99], v[188:191], v[204:207], v[96:99]
	v_mfma_f32_16x16x32_bf16 v[84:87], v[172:175], v[212:215], v[84:87]
	v_mfma_f32_16x16x32_bf16 v[80:83], v[188:191], v[212:215], v[80:83]
	v_mfma_f32_16x16x32_bf16 v[68:71], v[172:175], v[220:223], v[68:71]
	v_mfma_f32_16x16x32_bf16 v[64:67], v[188:191], v[220:223], v[64:67]
	s_setprio 0
	s_barrier
; #define PG8_STAGE(bufoff, gbase, voff) do { _Pragma("unroll") for (int _i = 0; _i < 2; ++_i) \
;         __builtin_amdgcn_global_load_lds((const unsigned*)((const char*)(gbase) + (voff)[_i]), (LAS unsigned*)(lds + (bufoff) + ldsw + _i * 8192), 16, 0, 0); } while (0)
; #define PG8_LDA(dst, b, h) do { _Pragma("unroll") for (int m = 0; m < 4; ++m) _Pragma("unroll") for (int k = 0; k < 2; ++k) dst[m][k] = *(const LAS bf16x8*)(lds + PG8_SA(b, h) + aoff + m * 2048 + k * 1024); } while (0)
; #define PG8_MMA(ai, bj, At, Bt) do { __builtin_amdgcn_s_setprio(1); _Pragma("unroll") for (int m = 0; m < 4; ++m) _Pragma("unroll") for (int n = 0; n < 2; ++n) _Pragma("unroll") for (int k = 0; k < 2; ++k) \
;         acc[ai][bj][m][n] = __builtin_amdgcn_mfma_f32_16x16x32_bf16(Bt[n][k], At[m][k], acc[ai][bj][m][n], 0, 0, 0); __builtin_amdgcn_s_setprio(0); } while (0)
; #define PG8_WAIT_V(n) asm volatile("s_waitcnt vmcnt(" #n ")" ::: "memory")
; #define PG8_WAIT_L(n) asm volatile("s_waitcnt lgkmcnt(" #n ")" ::: "memory")
; #define PG8_BAR __builtin_amdgcn_s_barrier()
; #define PG8_SCHED __builtin_amdgcn_sched_barrier(0)
; template <class Epi, bool ALIGN_EPI = PG8_ALIGN>
; __device__ __forceinline__ void gemm_phase(LAS unsigned char* lds, const Gemm g, const StaticOrder& S, const Epi& E) {
;     ...
;             PG8_LDA(At, 1, 1); PG8_STAGE(PG8_SB(1, 0), b3, voffB); PG8_STAGE(PG8_SB(1, 1), b3 + hstepB, voffB); PG8_STAGE(PG8_SA(1, 0), a3, voffA);
;             PG8_WAIT_V(8); PG8_WAIT_L(0); PG8_BAR; PG8_MMA(1, 0, At, B0); PG8_MMA(1, 1, At, B1); PG8_BAR; PG8_SCHED;
;         }
	s_add_i32 s20, s20, s30
	v_lshl_add_u64 v[140:141], v[140:141], 0, s[0:1]
	s_mov_b32 m0, s20
	ds_read_b128 v[192:195], v151 offset:49152
	ds_read_b128 v[196:199], v151 offset:50176
	ds_read_b128 v[200:203], v151 offset:51200
	ds_read_b128 v[204:207], v151 offset:52224
	ds_read_b128 v[208:211], v151 offset:53248
	ds_read_b128 v[212:215], v151 offset:54272
	ds_read_b128 v[216:219], v151 offset:55296
	ds_read_b128 v[220:223], v151 offset:56320
	global_load_lds_dwordx4 v[140:141], off
	v_lshl_add_u64 v[140:141], v[144:145], 0, s[0:1]
	s_add_i32 m0, s20, 0x2000
	s_add_i32 s20, s21, s30
	global_load_lds_dwordx4 v[140:141], off
	v_lshl_add_u64 v[140:141], v[148:149], 0, s[0:1]
	s_mov_b32 m0, s20
	s_nop 0
	global_load_lds_dwordx4 v[140:141], off
	v_lshl_add_u64 v[140:141], v[224:225], 0, s[0:1]
	s_add_i32 m0, s20, 0x2000
	s_nop 0
	global_load_lds_dwordx4 v[140:141], off
	v_lshl_add_u64 v[140:141], v[226:227], 0, s[0:1]
	s_mov_b32 m0, s45
	s_nop 0
	global_load_lds_dwordx4 v[140:141], off
	v_lshl_add_u64 v[140:141], v[228:229], 0, s[0:1]
	s_mov_b32 m0, s46
	s_nop 0
	global_load_lds_dwordx4 v[140:141], off
	s_nop 15
	s_nop 15
	s_waitcnt vmcnt(8)
	s_waitcnt lgkmcnt(0)
	s_barrier
	s_setprio 1
	s_waitcnt lgkmcnt(0)
	v_mfma_f32_16x16x32_bf16 v[60:63], v[152:155], v[192:195], v[60:63]
	v_mfma_f32_16x16x32_bf16 v[56:59], v[160:163], v[192:195], v[56:59]
	v_mfma_f32_16x16x32_bf16 v[44:47], v[152:155], v[200:203], v[44:47]
	v_mfma_f32_16x16x32_bf16 v[40:43], v[160:163], v[200:203], v[40:43]
	v_mfma_f32_16x16x32_bf16 v[28:31], v[152:155], v[208:211], v[28:31]
	v_mfma_f32_16x16x32_bf16 v[24:27], v[160:163], v[208:211], v[24:27]
	v_mfma_f32_16x16x32_bf16 v[12:15], v[152:155], v[216:219], v[12:15]
	v_mfma_f32_16x16x32_bf16 v[8:11], v[160:163], v[216:219], v[8:11]
	v_mfma_f32_16x16x32_bf16 v[60:63], v[156:159], v[196:199], v[60:63]
	v_mfma_f32_16x16x32_bf16 v[56:59], v[164:167], v[196:199], v[56:59]
	v_mfma_f32_16x16x32_bf16 v[44:47], v[156:159], v[204:207], v[44:47]
	v_mfma_f32_16x16x32_bf16 v[40:43], v[164:167], v[204:207], v[40:43]
	v_mfma_f32_16x16x32_bf16 v[28:31], v[156:159], v[212:215], v[28:31]
	v_mfma_f32_16x16x32_bf16 v[24:27], v[164:167], v[212:215], v[24:27]
	v_mfma_f32_16x16x32_bf16 v[12:15], v[156:159], v[220:223], v[12:15]
	v_mfma_f32_16x16x32_bf16 v[8:11], v[164:167], v[220:223], v[8:11]
	s_setprio 0
	s_setprio 1
	v_mfma_f32_16x16x32_bf16 v[52:55], v[168:171], v[192:195], v[52:55]
	v_mfma_f32_16x16x32_bf16 v[48:51], v[184:187], v[192:195], v[48:51]
	v_mfma_f32_16x16x32_bf16 v[36:39], v[168:171], v[200:203], v[36:39]
	v_mfma_f32_16x16x32_bf16 v[32:35], v[184:187], v[200:203], v[32:35]
	v_mfma_f32_16x16x32_bf16 v[20:23], v[168:171], v[208:211], v[20:23]
	v_mfma_f32_16x16x32_bf16 v[16:19], v[184:187], v[208:211], v[16:19]
	v_mfma_f32_16x16x32_bf16 v[4:7], v[168:171], v[216:219], v[4:7]
	v_mfma_f32_16x16x32_bf16 v[0:3], v[184:187], v[216:219], v[0:3]
	v_mfma_f32_16x16x32_bf16 v[52:55], v[172:175], v[196:199], v[52:55]
	v_mfma_f32_16x16x32_bf16 v[48:51], v[188:191], v[196:199], v[48:51]
	v_mfma_f32_16x16x32_bf16 v[36:39], v[172:175], v[204:207], v[36:39]
	v_mfma_f32_16x16x32_bf16 v[32:35], v[188:191], v[204:207], v[32:35]
	v_mfma_f32_16x16x32_bf16 v[20:23], v[172:175], v[212:215], v[20:23]
	v_mfma_f32_16x16x32_bf16 v[16:19], v[188:191], v[212:215], v[16:19]
	v_mfma_f32_16x16x32_bf16 v[4:7], v[172:175], v[220:223], v[4:7]
	v_mfma_f32_16x16x32_bf16 v[0:3], v[188:191], v[220:223], v[0:3]
	s_setprio 0
	s_barrier
	s_add_u32 s34, s34, 0x100
	s_addc_u32 s52, s52, 0
	s_cmp_ge_i32 s53, s47
	s_mov_b64 s[24:25], s[36:37]
	s_mov_b32 s38, s53
	s_cbranch_scc0 .LBB0_663

; #define S5_LDS_FENCE() do { __builtin_amdgcn_wave_barrier(); asm volatile("s_waitcnt lgkmcnt(0)" ::: "memory"); } while (0)
; template <bool WRITEH>
; __device__ __forceinline__ void s5_block(const S5Coef& C, const bf16x8 (&bm)[8], u32x4 uw, float* Hs, int lane, float& hr, float& hi) {
;     ...
;     for (int nb = 0; nb < 8; ++nb) { const f32x4 d = __builtin_amdgcn_mfma_f32_16x16x32_bf16(ua, bm[nb], (f32x4){0.f, 0.f, 0.f, 0.f}, 0, 0, 0);
; #pragma unroll
;         for (int i = 0; i < 4; ++i) Hs[(4 * (lane >> 4) + i) * 132 + 16 * nb + (lane & 15)] = d[i]; }
;     S5_LDS_FENCE();
;     float bur[16], bui[16];
; #pragma unroll
;     for (int tl = 0; tl < 16; ++tl) { bur[tl] = Hs[tl * 132 + lane]; bui[tl] = Hs[tl * 132 + 64 + lane]; }
; #pragma unroll
;     for (int tl = 0; tl < 16; ++tl) { const float nr = C.ar * hr - C.ai * hi + bur[tl], ni = C.ar * hi + C.ai * hr + bui[tl]; hr = nr; hi = ni; bur[tl] = hr; bui[tl] = hi; }
; __device__ __forceinline__ void s5_unit(ArgsP A, int l, int unit, unsigned char* lds, int wave_, int lane_) {
;     ...
;     for (int gi = 0; gi < 4; ++gi) {
;         const int g = 4 * wave + gi;
;         S5Coef C; bf16x8 bm[8]; s5_fetch(A, l, g, lane, C, bm);
;         bf16x8 chl[8];
;         { const bf16x8* ct = (const bf16x8*)(A->ws + WS_S5T + (size_t)(l * 32 + g) * S5T_BYTES + 9216);
; #pragma unroll
;           for (int q = 0; q < 8; ++q) chl[q] = ct[q * 64 + lane]; }
;         const f32x2_t hin = ((const f32x2_t*)(A->ws + WS_S5H))[(size_t)((b * 64 + c) * 32 + g) * 64 + lane]; float hr = hin.x, hi = hin.y;
;         u32x4 uw[4];
; #pragma unroll
;         for (int blk = 0; blk < 4; ++blk) uw[blk] = s5_load_ua(PROJ, rowbase + 16 * blk, g, lane);
;         const float dv = A->in[20][l * 512 + 16 * g + (lane & 15)];
; #pragma unroll
;         for (int blk = 0; blk < 4; ++blk) {
;             unsigned short uraw[4];
; #pragma unroll
;             for (int i = 0; i < 4; ++i) uraw[i] = PROJ[(size_t)(rowbase + 16 * blk + 4 * (lane >> 4) + i) * INWP + C_S5 + 16 * g + (lane & 15)];
;             s5_block<true>(C, bm, uw[blk], Hs, lane, hr, hi);
.LBB0_792:
	s_waitcnt lgkmcnt(0)
	v_lshl_add_u64 v[4:5], s[2:3], 0, v[98:99]
	v_add_co_u32_e32 v0, vcc, 0x2e7b0000, v4
	v_lshl_add_u64 v[66:67], s[2:3], 0, v[96:97]
	s_nop 0
	v_addc_co_u32_e32 v1, vcc, 0, v5, vcc
	global_load_dwordx4 v[32:35], v[0:1], off
	global_load_dwordx4 v[62:65], v[0:1], off offset:1024
	global_load_dwordx4 v[58:61], v[0:1], off offset:2048
	global_load_dwordx4 v[54:57], v[0:1], off offset:3072
	v_add_co_u32_e32 v0, vcc, 0x2e7b1000, v4
	v_ashrrev_i32_e32 v79, 31, v78
	s_nop 0
	v_addc_co_u32_e32 v1, vcc, 0, v5, vcc
	global_load_dwordx4 v[50:53], v[0:1], off
	global_load_dwordx4 v[46:49], v[0:1], off offset:1024
	global_load_dwordx4 v[42:45], v[0:1], off offset:2048
	global_load_dwordx4 v[38:41], v[0:1], off offset:3072
	v_add_co_u32_e32 v0, vcc, 0x2e7b2000, v4
	v_add_u32_e32 v115, 32, v112
	s_nop 0
	v_addc_co_u32_e32 v1, vcc, 0, v5, vcc
	global_load_dwordx4 v[34:37], v[0:1], off
	global_load_dwordx4 v[24:27], v[0:1], off offset:1024
	global_load_dwordx4 v[28:31], v[0:1], off offset:2048
	global_load_dwordx4 v[16:19], v[0:1], off offset:3072
	v_add_co_u32_e32 v0, vcc, 0x2e7b3000, v4
	v_add_u32_e32 v126, 0xd0, v112
	s_nop 0
	v_addc_co_u32_e32 v1, vcc, 0, v5, vcc
	v_add_co_u32_e32 v4, vcc, 0x2e7b4000, v4
	global_load_dwordx4 v[20:23], v[0:1], off
	global_load_dwordx4 v[8:11], v[0:1], off offset:1024
	global_load_dwordx4 v[12:15], v[0:1], off offset:2048
	s_nop 0
	global_load_dwordx4 v[0:3], v[0:1], off offset:3072
	v_addc_co_u32_e32 v5, vcc, 0, v5, vcc
	global_load_dwordx4 v[4:7], v[4:5], off
	s_load_dwordx2 s[6:7], s[26:27], 0xa0
	global_load_dwordx2 v[100:101], v[66:67], off
	v_lshl_add_u64 v[66:67], s[2:3], 0, v[94:95]
	global_load_dwordx4 v[116:119], v[66:67], off
	v_lshl_add_u64 v[66:67], s[2:3], 0, v[92:93]
	s_waitcnt lgkmcnt(0)
	v_lshl_add_u64 v[102:103], v[78:79], 2, s[6:7]
	global_load_dword v79, v[102:103], off
	v_lshl_add_u64 v[102:103], s[2:3], 0, v[86:87]
	v_add_co_u32_e32 v124, vcc, s12, v102
	global_load_dwordx4 v[74:77], v[66:67], off
	s_nop 0
	v_addc_co_u32_e32 v125, vcc, 0, v103, vcc
	global_load_ushort v162, v[124:125], off
	v_add_co_u32_e32 v124, vcc, s13, v102
	v_lshl_add_u64 v[66:67], s[2:3], 0, v[90:91]
	s_nop 0
	v_addc_co_u32_e32 v125, vcc, 0, v103, vcc
	global_load_ushort v131, v[124:125], off offset:512
	v_add_co_u32_e32 v124, vcc, s33, v102
	global_load_dwordx4 v[70:73], v[66:67], off
	s_nop 0
	v_addc_co_u32_e32 v125, vcc, 0, v103, vcc
	v_add_co_u32_e32 v102, vcc, s28, v102
	v_lshl_add_u64 v[66:67], s[2:3], 0, v[88:89]
	s_nop 0
	v_addc_co_u32_e32 v103, vcc, 0, v103, vcc
	global_load_dwordx4 v[66:69], v[66:67], off
	v_add_u32_e32 v127, 0xe0, v112
	global_load_ushort v130, v[124:125], off offset:1024
	global_load_ushort v129, v[102:103], off offset:1536
	v_add_u32_e32 v124, 0xb0, v112
	v_add_u32_e32 v125, 0xc0, v112
	v_add_u32_e32 v128, 0xf0, v112
	s_mov_b64 s[6:7], 0x4400
	v_add_u32_e32 v78, 16, v78
	v_lshl_add_u64 v[86:87], v[86:87], 0, 32
	v_lshl_add_u64 v[88:89], v[88:89], 0, 32
	v_lshl_add_u64 v[90:91], v[90:91], 0, 32
	v_lshl_add_u64 v[92:93], v[92:93], 0, 32
	v_lshl_add_u64 v[94:95], v[94:95], 0, 32
	v_lshl_add_u64 v[96:97], v[96:97], 0, s[14:15]
	v_lshl_add_u64 v[98:99], v[98:99], 0, s[6:7]
	s_waitcnt vmcnt(8)
	v_mfma_f32_16x16x32_bf16 v[120:123], v[116:119], v[62:65], 0
	s_nop 7
	ds_write_b32 v106, v120
	ds_write_b32 v106, v121 offset:528
	ds_write_b32 v106, v122 offset:1056
	ds_write_b32 v107, v123
	v_mfma_f32_16x16x32_bf16 v[120:123], v[116:119], v[58:61], 0
	s_nop 7
	ds_write_b32 v106, v120 offset:64
	ds_write_b32 v106, v121 offset:592
	ds_write_b32 v106, v122 offset:1120
	ds_write_b32 v107, v123 offset:64
	v_mfma_f32_16x16x32_bf16 v[120:123], v[116:119], v[54:57], 0
	s_nop 7
	ds_write_b32 v106, v120 offset:128
	ds_write_b32 v106, v121 offset:656
	ds_write_b32 v106, v122 offset:1184
	ds_write_b32 v107, v123 offset:128
	v_mfma_f32_16x16x32_bf16 v[120:123], v[116:119], v[50:53], 0
	s_nop 7
	ds_write2_b32 v108, v120, v121 offset1:132
	ds_write_b32 v108, v122 offset:1056
	ds_write_b32 v109, v123
	v_mfma_f32_16x16x32_bf16 v[120:123], v[116:119], v[46:49], 0
	s_nop 7
	ds_write_b32 v106, v120 offset:256
	ds_write_b32 v106, v121 offset:784
	ds_write_b32 v106, v122 offset:1312
	ds_write_b32 v107, v123 offset:256
	v_mfma_f32_16x16x32_bf16 v[120:123], v[116:119], v[42:45], 0
	s_nop 7
	ds_write_b32 v106, v120 offset:320
	ds_write_b32 v106, v121 offset:848
	ds_write_b32 v106, v122 offset:1376
	ds_write_b32 v107, v123 offset:320
	v_mfma_f32_16x16x32_bf16 v[120:123], v[116:119], v[38:41], 0
	s_nop 7
	ds_write_b32 v106, v120 offset:384
	ds_write_b32 v106, v121 offset:912
	ds_write_b32 v106, v122 offset:1440
	ds_write_b32 v107, v123 offset:384
	v_mfma_f32_16x16x32_bf16 v[116:119], v[116:119], v[34:37], 0
	s_nop 7
	ds_write2_b32 v110, v116, v117 offset1:132
	ds_write_b32 v110, v118 offset:1056
	ds_write_b32 v111, v119
	s_waitcnt lgkmcnt(0)
	ds_read2st64_b32 v[102:103], v112 offset1:1
	ds_read2_b32 v[132:133], v112 offset0:132 offset1:196
	v_mul_f32_e32 v163, v33, v101
	v_mul_f32_e32 v101, v32, v101
	v_fmac_f32_e32 v101, v33, v100
	v_fma_f32 v163, v32, v100, -v163
	s_waitcnt lgkmcnt(1)
	v_add_f32_e32 v100, v101, v103
	ds_read2st64_b32 v[134:135], v115 offset0:4 offset1:5
	v_add_f32_e32 v102, v163, v102
	v_mul_f32_e32 v103, v32, v100
	v_mul_f32_e32 v101, v33, v100
	v_fmac_f32_e32 v103, v33, v102
	v_fma_f32 v101, v32, v102, -v101
	s_waitcnt lgkmcnt(1)
	v_add_f32_e32 v103, v133, v103
	v_add_f32_e32 v101, v132, v101
	v_mul_f32_e32 v132, v33, v103
	v_add_u32_e32 v116, 48, v112
	v_fma_f32 v132, v32, v101, -v132
	ds_read2st64_b32 v[136:137], v116 offset0:6 offset1:7
	s_waitcnt lgkmcnt(1)
; __device__ __forceinline__ unsigned cvt_pk(float lo, float hi) { f32x2_t v = {lo, hi}; bf16x2_t b = __builtin_convertvector(v, bf16x2_t); return __builtin_bit_cast(unsigned, b); }
; __device__ __forceinline__ float bflo(unsigned w) { return __uint_as_float(w << 16); }
; __device__ __forceinline__ float bfhi(unsigned w) { return __uint_as_float(w & 0xffff0000u); }
; template <bool WRITEH>
; __device__ __forceinline__ void s5_block(const S5Coef& C, const bf16x8 (&bm)[8], u32x4 uw, float* Hs, int lane, float& hr, float& hi) {
;     ...
;     for (int tl = 0; tl < 16; ++tl) { bur[tl] = Hs[tl * 132 + lane]; bui[tl] = Hs[tl * 132 + 64 + lane]; }
; #pragma unroll
;     for (int tl = 0; tl < 16; ++tl) { const float nr = C.ar * hr - C.ai * hi + bur[tl], ni = C.ar * hi + C.ai * hr + bui[tl]; hr = nr; hi = ni; bur[tl] = hr; bui[tl] = hi; }
;     if (WRITEH) {
; #pragma unroll
;         for (int tl = 0; tl < 16; ++tl) { Hs[tl * 132 + lane] = bur[tl]; Hs[tl * 132 + 64 + lane] = bui[tl]; }
; __device__ __forceinline__ void s5_unit(ArgsP A, int l, int unit, unsigned char* lds, int wave_, int lane_) {
;     ...
;             for (int ks = 0; ks < 4; ++ks) { const float* hp = Hs + (lane & 15) * 132 + 32 * ks + 8 * (lane >> 4); const f32x4 h0 = *(const f32x4*)hp, h1 = *(const f32x4*)(hp + 4);
;                 u32x4 wh; wh.x = cvt_pk(h0[0], h0[1]); wh.y = cvt_pk(h0[2], h0[3]); wh.z = cvt_pk(h1[0], h1[1]); wh.w = cvt_pk(h1[2], h1[3]);
;                 u32x4 wl; wl.x = cvt_pk(h0[0] - bflo(wh.x), h0[1] - bfhi(wh.x)); wl.y = cvt_pk(h0[2] - bflo(wh.y), h0[3] - bfhi(wh.y)); wl.z = cvt_pk(h1[0] - bflo(wh.z), h1[1] - bfhi(wh.z)); wl.w = cvt_pk(h1[2] - bflo(wh.w), h1[3] - bfhi(wh.w));
	v_add_f32_e32 v134, v134, v132
	v_mul_f32_e32 v132, v32, v103
	v_fmac_f32_e32 v132, v33, v101
	v_add_f32_e32 v135, v135, v132
	v_mul_f32_e32 v132, v33, v135
	v_add_u32_e32 v117, 64, v112
	v_fma_f32 v132, v32, v134, -v132
	ds_read2st64_b32 v[138:139], v117 offset0:8 offset1:9
	s_waitcnt lgkmcnt(1)
	v_add_f32_e32 v136, v136, v132
	v_mul_f32_e32 v132, v32, v135
	v_fmac_f32_e32 v132, v33, v134
	v_add_f32_e32 v137, v137, v132
	v_mul_f32_e32 v132, v33, v137
	v_add_u32_e32 v118, 0x50, v112
	v_fma_f32 v132, v32, v136, -v132
	ds_read2st64_b32 v[140:141], v118 offset0:10 offset1:11
	s_waitcnt lgkmcnt(1)
	v_add_f32_e32 v138, v138, v132
	v_mul_f32_e32 v132, v32, v137
	v_fmac_f32_e32 v132, v33, v136
	v_add_f32_e32 v139, v139, v132
	v_mul_f32_e32 v132, v33, v139
	v_add_u32_e32 v119, 0x60, v112
	v_fma_f32 v132, v32, v138, -v132
	ds_read2st64_b32 v[142:143], v119 offset0:12 offset1:13
	s_waitcnt lgkmcnt(1)
	v_add_f32_e32 v140, v140, v132
	v_mul_f32_e32 v132, v32, v139
	v_fmac_f32_e32 v132, v33, v138
	v_add_f32_e32 v141, v141, v132
	v_mul_f32_e32 v132, v33, v141
	v_add_u32_e32 v120, 0x70, v112
	v_fma_f32 v132, v32, v140, -v132
	ds_read2st64_b32 v[144:145], v120 offset0:14 offset1:15
	s_waitcnt lgkmcnt(1)
	v_add_f32_e32 v142, v142, v132
	v_mul_f32_e32 v132, v32, v141
	v_fmac_f32_e32 v132, v33, v140
	v_add_f32_e32 v143, v143, v132
	v_mul_f32_e32 v132, v33, v143
	v_add_u32_e32 v121, 0x80, v112
	v_fma_f32 v132, v32, v142, -v132
	ds_read2st64_b32 v[146:147], v121 offset0:16 offset1:17
	s_waitcnt lgkmcnt(1)
	v_add_f32_e32 v144, v144, v132
	v_mul_f32_e32 v132, v32, v143
	v_fmac_f32_e32 v132, v33, v142
	v_add_f32_e32 v145, v145, v132
	v_mul_f32_e32 v132, v33, v145
	v_add_u32_e32 v122, 0x90, v112
	v_fma_f32 v132, v32, v144, -v132
	ds_read2st64_b32 v[148:149], v122 offset0:18 offset1:19
	s_waitcnt lgkmcnt(1)
	v_add_f32_e32 v146, v146, v132
	v_mul_f32_e32 v132, v32, v145
	v_fmac_f32_e32 v132, v33, v144
	v_add_f32_e32 v147, v147, v132
	v_mul_f32_e32 v132, v33, v147
	v_add_u32_e32 v123, 0xa0, v112
	v_fma_f32 v132, v32, v146, -v132
	ds_read2st64_b32 v[150:151], v123 offset0:20 offset1:21
	s_waitcnt lgkmcnt(1)
	v_add_f32_e32 v148, v148, v132
	v_mul_f32_e32 v132, v32, v147
	v_fmac_f32_e32 v132, v33, v146
	v_add_f32_e32 v149, v149, v132
	v_mul_f32_e32 v132, v33, v149
	v_fma_f32 v132, v32, v148, -v132
	ds_read2st64_b32 v[152:153], v124 offset0:22 offset1:23
	s_waitcnt lgkmcnt(1)
	v_add_f32_e32 v150, v150, v132
	v_mul_f32_e32 v132, v32, v149
	v_fmac_f32_e32 v132, v33, v148
	v_add_f32_e32 v151, v151, v132
	v_mul_f32_e32 v132, v33, v151
	v_fma_f32 v132, v32, v150, -v132
	ds_read2st64_b32 v[154:155], v125 offset0:24 offset1:25
	s_waitcnt lgkmcnt(1)
	v_add_f32_e32 v152, v152, v132
	v_mul_f32_e32 v132, v32, v151
	v_fmac_f32_e32 v132, v33, v150
	v_add_f32_e32 v153, v153, v132
	v_mul_f32_e32 v132, v33, v153
	v_fma_f32 v132, v32, v152, -v132
	ds_read2st64_b32 v[156:157], v126 offset0:26 offset1:27
	s_waitcnt lgkmcnt(1)
	v_add_f32_e32 v154, v154, v132
	v_mul_f32_e32 v132, v32, v153
	v_fmac_f32_e32 v132, v33, v152
	v_add_f32_e32 v155, v155, v132
	v_mul_f32_e32 v132, v33, v155
	v_fma_f32 v132, v32, v154, -v132
	ds_read2st64_b32 v[158:159], v127 offset0:28 offset1:29
	s_waitcnt lgkmcnt(1)
	v_add_f32_e32 v156, v156, v132
	v_mul_f32_e32 v132, v32, v155
	v_fmac_f32_e32 v132, v33, v154
	v_add_f32_e32 v157, v157, v132
	v_mul_f32_e32 v132, v33, v157
	v_fma_f32 v132, v32, v156, -v132
	ds_read2st64_b32 v[160:161], v128 offset0:30 offset1:31
	s_waitcnt lgkmcnt(1)
	v_add_f32_e32 v158, v158, v132
	v_mul_f32_e32 v132, v32, v157
	v_fmac_f32_e32 v132, v33, v156
	v_add_f32_e32 v159, v159, v132
	v_mul_f32_e32 v132, v33, v159
	v_mul_f32_e32 v133, v32, v159
	v_fma_f32 v132, v32, v158, -v132
	v_fmac_f32_e32 v133, v33, v158
	s_waitcnt lgkmcnt(0)
	v_add_f32_e32 v132, v160, v132
	v_add_f32_e32 v133, v161, v133
	ds_write2st64_b32 v112, v102, v100 offset1:1
	ds_write2_b32 v112, v101, v103 offset0:132 offset1:196
	ds_write2st64_b32 v115, v134, v135 offset0:4 offset1:5
	ds_write2st64_b32 v116, v136, v137 offset0:6 offset1:7
	ds_write2st64_b32 v117, v138, v139 offset0:8 offset1:9
	ds_write2st64_b32 v118, v140, v141 offset0:10 offset1:11
	ds_write2st64_b32 v119, v142, v143 offset0:12 offset1:13
	ds_write2st64_b32 v120, v144, v145 offset0:14 offset1:15
	ds_write2st64_b32 v121, v146, v147 offset0:16 offset1:17
	ds_write2st64_b32 v122, v148, v149 offset0:18 offset1:19
	ds_write2st64_b32 v123, v150, v151 offset0:20 offset1:21
	ds_write2st64_b32 v124, v152, v153 offset0:22 offset1:23
	ds_write2st64_b32 v125, v154, v155 offset0:24 offset1:25
	ds_write2st64_b32 v126, v156, v157 offset0:26 offset1:27
	ds_write2st64_b32 v127, v158, v159 offset0:28 offset1:29
	ds_write2st64_b32 v128, v132, v133 offset0:30 offset1:31
	s_waitcnt lgkmcnt(0)
	ds_read_b128 v[100:103], v113
	ds_read_b128 v[134:137], v113 offset:16
	s_waitcnt vmcnt(4)
	v_lshlrev_b32_e32 v131, 16, v131
	v_mul_f32_e32 v160, v33, v133
	v_fma_f32 v160, v32, v132, -v160
	s_waitcnt lgkmcnt(1)
	v_cvt_pk_bf16_f32 v138, v100, v101
	v_cvt_pk_bf16_f32 v139, v102, v103
	v_lshlrev_b32_e32 v142, 16, v138
	v_and_b32_e32 v143, 0xffff0000, v138
	v_pk_add_f32 v[100:101], v[100:101], v[142:143] neg_lo:[0,1] neg_hi:[0,1]
	v_lshlrev_b32_e32 v142, 16, v139
	v_and_b32_e32 v143, 0xffff0000, v139
	s_waitcnt lgkmcnt(0)
; __device__ __forceinline__ unsigned cvt_pk(float lo, float hi) { f32x2_t v = {lo, hi}; bf16x2_t b = __builtin_convertvector(v, bf16x2_t); return __builtin_bit_cast(unsigned, b); }
; __device__ __forceinline__ float bf2f(unsigned short h) { return __uint_as_float(((unsigned)h) << 16); }
; __device__ __forceinline__ float bflo(unsigned w) { return __uint_as_float(w << 16); }
; __device__ __forceinline__ float bfhi(unsigned w) { return __uint_as_float(w & 0xffff0000u); }
; __device__ __forceinline__ unsigned short f2bf(float f) { return (unsigned short)(cvt_pk(f, 0.f) & 0xffffu); }
; __device__ __forceinline__ void s5_unit(ArgsP A, int l, int unit, unsigned char* lds, int wave_, int lane_) {
;     ...
;             for (int ks = 0; ks < 4; ++ks) { const float* hp = Hs + (lane & 15) * 132 + 32 * ks + 8 * (lane >> 4); const f32x4 h0 = *(const f32x4*)hp, h1 = *(const f32x4*)(hp + 4);
;                 u32x4 wh; wh.x = cvt_pk(h0[0], h0[1]); wh.y = cvt_pk(h0[2], h0[3]); wh.z = cvt_pk(h1[0], h1[1]); wh.w = cvt_pk(h1[2], h1[3]);
;                 u32x4 wl; wl.x = cvt_pk(h0[0] - bflo(wh.x), h0[1] - bfhi(wh.x)); wl.y = cvt_pk(h0[2] - bflo(wh.y), h0[3] - bfhi(wh.y)); wl.z = cvt_pk(h1[0] - bflo(wh.z), h1[1] - bfhi(wh.z)); wl.w = cvt_pk(h1[2] - bflo(wh.w), h1[3] - bfhi(wh.w));
;                 const bf16x8 hh_ = __builtin_bit_cast(bf16x8, wh), hl_ = __builtin_bit_cast(bf16x8, wl);
;                 y = __builtin_amdgcn_mfma_f32_16x16x32_bf16(hh_, chl[2 * ks], y, 0, 0, 0); y2 = __builtin_amdgcn_mfma_f32_16x16x32_bf16(hh_, chl[2 * ks + 1], y2, 0, 0, 0);
;                 y2 = __builtin_amdgcn_mfma_f32_16x16x32_bf16(hl_, chl[2 * ks], y2, 0, 0, 0); }
;             y = y + y2;
; #pragma unroll
;             for (int i = 0; i < 4; ++i) { const int t = 16 * blk + 4 * (lane >> 4) + i; const int col = 16 * g + (lane & 15);
;                 const float uval = bf2f(uraw[i]); const float v = gelu_tanh(y[i] + dv * uval); ys[t * YS_STRIDE + col] = f2bf(v); }
	v_cvt_pk_bf16_f32 v140, v134, v135
	v_cvt_pk_bf16_f32 v141, v136, v137
	v_pk_add_f32 v[102:103], v[102:103], v[142:143] neg_lo:[0,1] neg_hi:[0,1]
	v_cvt_pk_bf16_f32 v100, v100, v101
	v_cvt_pk_bf16_f32 v101, v102, v103
	v_lshlrev_b32_e32 v102, 16, v140
	v_and_b32_e32 v103, 0xffff0000, v140
	v_pk_add_f32 v[102:103], v[134:135], v[102:103] neg_lo:[0,1] neg_hi:[0,1]
	v_lshlrev_b32_e32 v134, 16, v141
	v_and_b32_e32 v135, 0xffff0000, v141
	v_pk_add_f32 v[134:135], v[136:137], v[134:135] neg_lo:[0,1] neg_hi:[0,1]
	v_cvt_pk_bf16_f32 v102, v102, v103
	v_cvt_pk_bf16_f32 v103, v134, v135
	v_mfma_f32_16x16x32_bf16 v[134:137], v[138:141], v[24:27], 0
	v_mfma_f32_16x16x32_bf16 v[138:141], v[138:141], v[28:31], 0
	v_mfma_f32_16x16x32_bf16 v[100:103], v[100:103], v[24:27], v[138:141]
	s_nop 6
	ds_read_b128 v[138:141], v113 offset:128
	ds_read_b128 v[142:145], v113 offset:144
	s_waitcnt lgkmcnt(1)
	v_cvt_pk_bf16_f32 v146, v138, v139
	v_cvt_pk_bf16_f32 v147, v140, v141
	v_lshlrev_b32_e32 v150, 16, v146
	v_and_b32_e32 v151, 0xffff0000, v146
	v_pk_add_f32 v[138:139], v[138:139], v[150:151] neg_lo:[0,1] neg_hi:[0,1]
	v_lshlrev_b32_e32 v150, 16, v147
	v_and_b32_e32 v151, 0xffff0000, v147
	s_waitcnt lgkmcnt(0)
	v_cvt_pk_bf16_f32 v148, v142, v143
	v_cvt_pk_bf16_f32 v149, v144, v145
	v_pk_add_f32 v[140:141], v[140:141], v[150:151] neg_lo:[0,1] neg_hi:[0,1]
	v_cvt_pk_bf16_f32 v138, v138, v139
	v_cvt_pk_bf16_f32 v139, v140, v141
	v_lshlrev_b32_e32 v140, 16, v148
	v_and_b32_e32 v141, 0xffff0000, v148
	v_pk_add_f32 v[140:141], v[142:143], v[140:141] neg_lo:[0,1] neg_hi:[0,1]
	v_lshlrev_b32_e32 v142, 16, v149
	v_and_b32_e32 v143, 0xffff0000, v149
	v_pk_add_f32 v[142:143], v[144:145], v[142:143] neg_lo:[0,1] neg_hi:[0,1]
	v_cvt_pk_bf16_f32 v140, v140, v141
	v_cvt_pk_bf16_f32 v141, v142, v143
	v_mfma_f32_16x16x32_bf16 v[100:103], v[146:149], v[20:23], v[100:103]
	s_nop 0
	v_mfma_f32_16x16x32_bf16 v[100:103], v[138:141], v[16:19], v[100:103]
	ds_read_b128 v[138:141], v113 offset:256
	ds_read_b128 v[142:145], v113 offset:272
	v_mfma_f32_16x16x32_bf16 v[134:137], v[146:149], v[16:19], v[134:137]
	s_waitcnt lgkmcnt(1)
	v_cvt_pk_bf16_f32 v146, v138, v139
	v_cvt_pk_bf16_f32 v147, v140, v141
	v_lshlrev_b32_e32 v150, 16, v146
	v_and_b32_e32 v151, 0xffff0000, v146
	v_pk_add_f32 v[138:139], v[138:139], v[150:151] neg_lo:[0,1] neg_hi:[0,1]
	v_lshlrev_b32_e32 v150, 16, v147
	v_and_b32_e32 v151, 0xffff0000, v147
	s_waitcnt lgkmcnt(0)
	v_cvt_pk_bf16_f32 v148, v142, v143
	v_cvt_pk_bf16_f32 v149, v144, v145
	v_pk_add_f32 v[140:141], v[140:141], v[150:151] neg_lo:[0,1] neg_hi:[0,1]
	v_cvt_pk_bf16_f32 v138, v138, v139
	v_cvt_pk_bf16_f32 v139, v140, v141
	v_lshlrev_b32_e32 v140, 16, v148
	v_and_b32_e32 v141, 0xffff0000, v148
	v_pk_add_f32 v[140:141], v[142:143], v[140:141] neg_lo:[0,1] neg_hi:[0,1]
	v_lshlrev_b32_e32 v142, 16, v149
	v_and_b32_e32 v143, 0xffff0000, v149
	v_pk_add_f32 v[142:143], v[144:145], v[142:143] neg_lo:[0,1] neg_hi:[0,1]
	v_cvt_pk_bf16_f32 v140, v140, v141
	v_cvt_pk_bf16_f32 v141, v142, v143
	v_mfma_f32_16x16x32_bf16 v[100:103], v[146:149], v[12:15], v[100:103]
	s_nop 0
	v_mfma_f32_16x16x32_bf16 v[100:103], v[138:141], v[8:11], v[100:103]
	ds_read_b128 v[138:141], v113 offset:384
	ds_read_b128 v[142:145], v113 offset:400
	v_mfma_f32_16x16x32_bf16 v[134:137], v[146:149], v[8:11], v[134:137]
	s_waitcnt lgkmcnt(1)
	v_cvt_pk_bf16_f32 v146, v138, v139
	v_cvt_pk_bf16_f32 v147, v140, v141
	v_lshlrev_b32_e32 v150, 16, v146
	v_and_b32_e32 v151, 0xffff0000, v146
	v_pk_add_f32 v[138:139], v[138:139], v[150:151] neg_lo:[0,1] neg_hi:[0,1]
	v_lshlrev_b32_e32 v150, 16, v147
	v_and_b32_e32 v151, 0xffff0000, v147
	s_waitcnt lgkmcnt(0)
	v_cvt_pk_bf16_f32 v148, v142, v143
	v_cvt_pk_bf16_f32 v149, v144, v145
	v_pk_add_f32 v[140:141], v[140:141], v[150:151] neg_lo:[0,1] neg_hi:[0,1]
	v_cvt_pk_bf16_f32 v138, v138, v139
	v_cvt_pk_bf16_f32 v139, v140, v141
	v_lshlrev_b32_e32 v140, 16, v148
	v_and_b32_e32 v141, 0xffff0000, v148
	v_pk_add_f32 v[140:141], v[142:143], v[140:141] neg_lo:[0,1] neg_hi:[0,1]
	v_lshlrev_b32_e32 v142, 16, v149
	v_and_b32_e32 v143, 0xffff0000, v149
	v_pk_add_f32 v[142:143], v[144:145], v[142:143] neg_lo:[0,1] neg_hi:[0,1]
	v_cvt_pk_bf16_f32 v140, v140, v141
	v_cvt_pk_bf16_f32 v141, v142, v143
	v_mfma_f32_16x16x32_bf16 v[100:103], v[146:149], v[4:7], v[100:103]
	v_mfma_f32_16x16x32_bf16 v[134:137], v[146:149], v[0:3], v[134:137]
	v_mfma_f32_16x16x32_bf16 v[138:141], v[138:141], v[0:3], v[100:103]
	s_nop 7
	v_pk_add_f32 v[102:103], v[134:135], v[138:139]
	v_lshlrev_b32_e32 v134, 16, v162
	v_fma_f32 v102, v79, v134, v102
	v_fmac_f32_e32 v103, v79, v131
	v_mul_f32_e32 v134, 0x3d372713, v102
	v_mul_f32_e32 v131, 0x3d372713, v103
	v_mul_f32_e32 v134, v102, v134
	v_mul_f32_e32 v131, v103, v131
	v_fma_f32 v134, v102, v134, v102
	v_fma_f32 v131, v103, v131, v103
	v_mul_f32_e32 v134, 0x3f4c422a, v134
	v_mul_f32_e32 v131, 0x3f4c422a, v131
	v_add_f32_e32 v134, v134, v134
	v_add_f32_e32 v131, v131, v131
	v_mul_f32_e32 v134, 0x3fb8aa3b, v134
	v_mul_f32_e32 v131, 0x3fb8aa3b, v131
	v_exp_f32_e32 v134, v134
	v_exp_f32_e32 v131, v131
	v_mul_f32_e32 v102, 0.5, v102
	v_mul_f32_e32 v103, 0.5, v103
	v_add_f32_e32 v134, 1.0, v134
	v_add_f32_e32 v131, 1.0, v131
	v_rcp_f32_e32 v134, v134
	v_rcp_f32_e32 v131, v131
	v_pk_add_f32 v[100:101], v[136:137], v[140:141]
	v_fma_f32 v134, v134, -2.0, 1.0
	v_fma_f32 v131, v131, -2.0, 1.0
	v_add_f32_e32 v134, 1.0, v134
	v_add_f32_e32 v131, 1.0, v131
	v_mul_f32_e32 v102, v102, v134
	v_mul_f32_e32 v103, v103, v131
	v_cvt_pk_bf16_f32 v134, v102, s0
	v_add_u32_e32 v102, s5, v114
	v_cvt_pk_bf16_f32 v103, v103, s0
	ds_write_b16 v102, v103 offset:1040
	s_waitcnt vmcnt(1)
; __device__ __forceinline__ float bf2f(unsigned short h) { return __uint_as_float(((unsigned)h) << 16); }
; __device__ __forceinline__ unsigned short f2bf(float f) { return (unsigned short)(cvt_pk(f, 0.f) & 0xffffu); }
; #define S5_LDS_FENCE() do { __builtin_amdgcn_wave_barrier(); asm volatile("s_waitcnt lgkmcnt(0)" ::: "memory"); } while (0)
; template <bool WRITEH>
; __device__ __forceinline__ void s5_block(const S5Coef& C, const bf16x8 (&bm)[8], u32x4 uw, float* Hs, int lane, float& hr, float& hi) {
;     ...
;     for (int nb = 0; nb < 8; ++nb) { const f32x4 d = __builtin_amdgcn_mfma_f32_16x16x32_bf16(ua, bm[nb], (f32x4){0.f, 0.f, 0.f, 0.f}, 0, 0, 0);
; #pragma unroll
;         for (int i = 0; i < 4; ++i) Hs[(4 * (lane >> 4) + i) * 132 + 16 * nb + (lane & 15)] = d[i]; }
;     S5_LDS_FENCE();
;     float bur[16], bui[16];
; #pragma unroll
;     for (int tl = 0; tl < 16; ++tl) { bur[tl] = Hs[tl * 132 + lane]; bui[tl] = Hs[tl * 132 + 64 + lane]; }
; #pragma unroll
;     for (int tl = 0; tl < 16; ++tl) { const float nr = C.ar * hr - C.ai * hi + bur[tl], ni = C.ar * hi + C.ai * hr + bui[tl]; hr = nr; hi = ni; bur[tl] = hr; bui[tl] = hi; }
; __device__ __forceinline__ void s5_unit(ArgsP A, int l, int unit, unsigned char* lds, int wave_, int lane_) {
;     ...
;             for (int i = 0; i < 4; ++i) { const int t = 16 * blk + 4 * (lane >> 4) + i; const int col = 16 * g + (lane & 15);
;                 const float uval = bf2f(uraw[i]); const float v = gelu_tanh(y[i] + dv * uval); ys[t * YS_STRIDE + col] = f2bf(v); }
	v_lshlrev_b32_e32 v103, 16, v130
	v_fma_f32 v100, v79, v103, v100
	v_mul_f32_e32 v103, 0x3d372713, v100
	v_mul_f32_e32 v103, v100, v103
	v_fma_f32 v103, v100, v103, v100
	v_mul_f32_e32 v103, 0x3f4c422a, v103
	v_add_f32_e32 v103, v103, v103
	v_mul_f32_e32 v103, 0x3fb8aa3b, v103
	v_exp_f32_e32 v103, v103
	v_mul_f32_e32 v100, 0.5, v100
	ds_write_b16 v102, v134
	v_mfma_f32_16x16x32_bf16 v[134:137], v[74:77], v[62:65], 0
	v_add_f32_e32 v103, 1.0, v103
	v_rcp_f32_e32 v103, v103
	s_add_i32 s5, s5, 32
	s_cmpk_lg_i32 s5, 0x80
	v_fma_f32 v103, v103, -2.0, 1.0
	v_add_f32_e32 v103, 1.0, v103
	v_mul_f32_e32 v100, v100, v103
	v_cvt_pk_bf16_f32 v100, v100, s0
	ds_write_b16 v102, v100 offset:2080
	s_waitcnt vmcnt(0)
	v_lshlrev_b32_e32 v100, 16, v129
	v_fmac_f32_e32 v101, v79, v100
	v_mul_f32_e32 v100, 0x3d372713, v101
	v_mul_f32_e32 v100, v101, v100
	v_fma_f32 v100, v101, v100, v101
	v_mul_f32_e32 v100, 0x3f4c422a, v100
	v_add_f32_e32 v100, v100, v100
	v_mul_f32_e32 v100, 0x3fb8aa3b, v100
	v_exp_f32_e32 v100, v100
	v_mul_f32_e32 v101, 0.5, v101
	v_add_f32_e32 v100, 1.0, v100
	v_rcp_f32_e32 v100, v100
	s_nop 0
	v_fma_f32 v100, v100, -2.0, 1.0
	v_add_f32_e32 v100, 1.0, v100
	v_mul_f32_e32 v100, v101, v100
	v_cvt_pk_bf16_f32 v100, v100, s0
	ds_write_b16 v102, v100 offset:3120
	s_waitcnt lgkmcnt(0)
	ds_write_b32 v106, v134
	ds_write_b32 v106, v135 offset:528
	ds_write_b32 v106, v136 offset:1056
	ds_write_b32 v107, v137
	v_mfma_f32_16x16x32_bf16 v[134:137], v[74:77], v[58:61], 0
	s_nop 7
	ds_write_b32 v106, v134 offset:64
	ds_write_b32 v106, v135 offset:592
	ds_write_b32 v106, v136 offset:1120
	ds_write_b32 v107, v137 offset:64
	v_mfma_f32_16x16x32_bf16 v[134:137], v[74:77], v[54:57], 0
	s_nop 7
	ds_write_b32 v106, v134 offset:128
	ds_write_b32 v106, v135 offset:656
	ds_write_b32 v106, v136 offset:1184
	ds_write_b32 v107, v137 offset:128
	v_mfma_f32_16x16x32_bf16 v[134:137], v[74:77], v[50:53], 0
	s_nop 7
	ds_write2_b32 v108, v134, v135 offset1:132
	ds_write_b32 v108, v136 offset:1056
	ds_write_b32 v109, v137
	v_mfma_f32_16x16x32_bf16 v[134:137], v[74:77], v[46:49], 0
	s_nop 7
	ds_write_b32 v106, v134 offset:256
	ds_write_b32 v106, v135 offset:784
	ds_write_b32 v106, v136 offset:1312
	ds_write_b32 v107, v137 offset:256
	v_mfma_f32_16x16x32_bf16 v[134:137], v[74:77], v[42:45], 0
	s_nop 7
	ds_write_b32 v106, v134 offset:320
	ds_write_b32 v106, v135 offset:848
	ds_write_b32 v106, v136 offset:1376
	ds_write_b32 v107, v137 offset:320
	v_mfma_f32_16x16x32_bf16 v[134:137], v[74:77], v[38:41], 0
	v_lshl_add_u64 v[100:101], s[2:3], 0, v[84:85]
	s_nop 6
	ds_write_b32 v106, v134 offset:384
	ds_write_b32 v106, v135 offset:912
	ds_write_b32 v106, v136 offset:1440
	ds_write_b32 v107, v137 offset:384
	v_mfma_f32_16x16x32_bf16 v[74:77], v[74:77], v[34:37], 0
	s_nop 7
	ds_write2_b32 v110, v74, v75 offset1:132
	ds_write_b32 v110, v76 offset:1056
	ds_write_b32 v111, v77
	v_add_co_u32_e32 v74, vcc, s12, v100
	v_lshl_add_u64 v[84:85], v[84:85], 0, 32
	s_nop 0
	v_addc_co_u32_e32 v75, vcc, 0, v101, vcc
	global_load_ushort v103, v[74:75], off
	v_add_co_u32_e32 v74, vcc, s13, v100
	s_waitcnt vmcnt(0)
	v_lshlrev_b32_e32 v103, 16, v103
	v_addc_co_u32_e32 v75, vcc, 0, v101, vcc
	global_load_ushort v129, v[74:75], off offset:512
	v_add_co_u32_e32 v74, vcc, s33, v100
	s_nop 1
	v_addc_co_u32_e32 v75, vcc, 0, v101, vcc
	global_load_ushort v158, v[74:75], off offset:1024
	v_add_co_u32_e32 v74, vcc, s28, v100
	s_nop 1
	v_addc_co_u32_e32 v75, vcc, 0, v101, vcc
	global_load_ushort v159, v[74:75], off offset:1536
	s_waitcnt lgkmcnt(0)
	ds_read2st64_b32 v[74:75], v112 offset1:1
	ds_read2_b32 v[76:77], v112 offset0:132 offset1:196
	ds_read2st64_b32 v[100:101], v115 offset0:4 offset1:5
	ds_read2st64_b32 v[130:131], v116 offset0:6 offset1:7
	ds_read2st64_b32 v[134:135], v117 offset0:8 offset1:9
	ds_read2st64_b32 v[136:137], v118 offset0:10 offset1:11
	ds_read2st64_b32 v[138:139], v119 offset0:12 offset1:13
	ds_read2st64_b32 v[140:141], v120 offset0:14 offset1:15
	ds_read2st64_b32 v[142:143], v121 offset0:16 offset1:17
	ds_read2st64_b32 v[144:145], v122 offset0:18 offset1:19
	ds_read2st64_b32 v[146:147], v123 offset0:20 offset1:21
	ds_read2st64_b32 v[148:149], v124 offset0:22 offset1:23
	ds_read2st64_b32 v[150:151], v125 offset0:24 offset1:25
	ds_read2st64_b32 v[152:153], v126 offset0:26 offset1:27
	ds_read2st64_b32 v[154:155], v127 offset0:28 offset1:29
	ds_read2st64_b32 v[156:157], v128 offset0:30 offset1:31
	s_waitcnt lgkmcnt(14)
	v_add_f32_e32 v160, v160, v74
	v_mul_f32_e32 v74, v32, v133
	v_fmac_f32_e32 v74, v33, v132
	v_add_f32_e32 v132, v74, v75
	v_mul_f32_e32 v74, v33, v132
	v_fma_f32 v74, v32, v160, -v74
	v_add_f32_e32 v76, v76, v74
	v_mul_f32_e32 v74, v32, v132
	v_fmac_f32_e32 v74, v33, v160
	v_add_f32_e32 v77, v77, v74
	v_mul_f32_e32 v74, v33, v77
	v_fma_f32 v74, v32, v76, -v74
	s_waitcnt lgkmcnt(13)
	v_add_f32_e32 v100, v100, v74
	v_mul_f32_e32 v74, v32, v77
	v_fmac_f32_e32 v74, v33, v76
	v_add_f32_e32 v101, v101, v74
	v_mul_f32_e32 v74, v33, v101
	v_fma_f32 v74, v32, v100, -v74
	s_waitcnt lgkmcnt(12)
	v_add_f32_e32 v130, v130, v74
	v_mul_f32_e32 v74, v32, v101
	v_fmac_f32_e32 v74, v33, v100
	v_add_f32_e32 v131, v131, v74
	v_mul_f32_e32 v74, v33, v131
	v_fma_f32 v74, v32, v130, -v74
	s_waitcnt lgkmcnt(11)
	v_add_f32_e32 v133, v134, v74
	v_mul_f32_e32 v74, v32, v131
	v_fmac_f32_e32 v74, v33, v130
	v_add_f32_e32 v134, v135, v74
	v_mul_f32_e32 v74, v33, v134
	v_fma_f32 v74, v32, v133, -v74
	s_waitcnt lgkmcnt(10)
	v_add_f32_e32 v135, v136, v74
	v_mul_f32_e32 v74, v32, v134
	v_fmac_f32_e32 v74, v33, v133
	v_add_f32_e32 v136, v137, v74
	v_mul_f32_e32 v74, v33, v136
	v_fma_f32 v74, v32, v135, -v74
	s_waitcnt lgkmcnt(9)
; __device__ __forceinline__ unsigned cvt_pk(float lo, float hi) { f32x2_t v = {lo, hi}; bf16x2_t b = __builtin_convertvector(v, bf16x2_t); return __builtin_bit_cast(unsigned, b); }
; __device__ __forceinline__ float bflo(unsigned w) { return __uint_as_float(w << 16); }
; __device__ __forceinline__ float bfhi(unsigned w) { return __uint_as_float(w & 0xffff0000u); }
; template <bool WRITEH>
; __device__ __forceinline__ void s5_block(const S5Coef& C, const bf16x8 (&bm)[8], u32x4 uw, float* Hs, int lane, float& hr, float& hi) {
;     ...
;     for (int tl = 0; tl < 16; ++tl) { const float nr = C.ar * hr - C.ai * hi + bur[tl], ni = C.ar * hi + C.ai * hr + bui[tl]; hr = nr; hi = ni; bur[tl] = hr; bui[tl] = hi; }
;     if (WRITEH) {
; #pragma unroll
;         for (int tl = 0; tl < 16; ++tl) { Hs[tl * 132 + lane] = bur[tl]; Hs[tl * 132 + 64 + lane] = bui[tl]; }
; __device__ __forceinline__ void s5_unit(ArgsP A, int l, int unit, unsigned char* lds, int wave_, int lane_) {
;     ...
;             for (int ks = 0; ks < 4; ++ks) { const float* hp = Hs + (lane & 15) * 132 + 32 * ks + 8 * (lane >> 4); const f32x4 h0 = *(const f32x4*)hp, h1 = *(const f32x4*)(hp + 4);
;                 u32x4 wh; wh.x = cvt_pk(h0[0], h0[1]); wh.y = cvt_pk(h0[2], h0[3]); wh.z = cvt_pk(h1[0], h1[1]); wh.w = cvt_pk(h1[2], h1[3]);
;                 u32x4 wl; wl.x = cvt_pk(h0[0] - bflo(wh.x), h0[1] - bfhi(wh.x)); wl.y = cvt_pk(h0[2] - bflo(wh.y), h0[3] - bfhi(wh.y)); wl.z = cvt_pk(h1[0] - bflo(wh.z), h1[1] - bfhi(wh.z)); wl.w = cvt_pk(h1[2] - bflo(wh.w), h1[3] - bfhi(wh.w));
;                 const bf16x8 hh_ = __builtin_bit_cast(bf16x8, wh), hl_ = __builtin_bit_cast(bf16x8, wl);
;                 y = __builtin_amdgcn_mfma_f32_16x16x32_bf16(hh_, chl[2 * ks], y, 0, 0, 0); y2 = __builtin_amdgcn_mfma_f32_16x16x32_bf16(hh_, chl[2 * ks + 1], y2, 0, 0, 0);
;                 y2 = __builtin_amdgcn_mfma_f32_16x16x32_bf16(hl_, chl[2 * ks], y2, 0, 0, 0); }
	v_add_f32_e32 v137, v138, v74
	v_mul_f32_e32 v74, v32, v136
	v_fmac_f32_e32 v74, v33, v135
	v_add_f32_e32 v138, v139, v74
	v_mul_f32_e32 v74, v33, v138
	v_fma_f32 v74, v32, v137, -v74
	s_waitcnt lgkmcnt(8)
	v_add_f32_e32 v139, v140, v74
	v_mul_f32_e32 v74, v32, v138
	v_fmac_f32_e32 v74, v33, v137
	v_add_f32_e32 v140, v141, v74
	v_mul_f32_e32 v74, v33, v140
	v_fma_f32 v74, v32, v139, -v74
	s_waitcnt lgkmcnt(7)
	v_add_f32_e32 v141, v142, v74
	v_mul_f32_e32 v74, v32, v140
	v_fmac_f32_e32 v74, v33, v139
	v_add_f32_e32 v142, v143, v74
	v_mul_f32_e32 v74, v33, v142
	v_fma_f32 v74, v32, v141, -v74
	s_waitcnt lgkmcnt(6)
	v_add_f32_e32 v143, v144, v74
	v_mul_f32_e32 v74, v32, v142
	v_fmac_f32_e32 v74, v33, v141
	v_add_f32_e32 v144, v145, v74
	v_mul_f32_e32 v74, v33, v144
	v_fma_f32 v74, v32, v143, -v74
	s_waitcnt lgkmcnt(5)
	v_add_f32_e32 v145, v146, v74
	v_mul_f32_e32 v74, v32, v144
	v_fmac_f32_e32 v74, v33, v143
	v_add_f32_e32 v146, v147, v74
	v_mul_f32_e32 v74, v33, v146
	v_fma_f32 v74, v32, v145, -v74
	s_waitcnt lgkmcnt(4)
	v_add_f32_e32 v147, v148, v74
	v_mul_f32_e32 v74, v32, v146
	v_fmac_f32_e32 v74, v33, v145
	v_add_f32_e32 v148, v149, v74
	v_mul_f32_e32 v74, v33, v148
	v_fma_f32 v74, v32, v147, -v74
	s_waitcnt lgkmcnt(3)
	v_add_f32_e32 v149, v150, v74
	v_mul_f32_e32 v74, v32, v148
	v_fmac_f32_e32 v74, v33, v147
	v_add_f32_e32 v150, v151, v74
	v_mul_f32_e32 v74, v33, v150
	v_fma_f32 v74, v32, v149, -v74
	s_waitcnt lgkmcnt(2)
	v_add_f32_e32 v151, v152, v74
	v_mul_f32_e32 v74, v32, v150
	v_fmac_f32_e32 v74, v33, v149
	v_add_f32_e32 v152, v153, v74
	v_mul_f32_e32 v74, v33, v152
	v_fma_f32 v74, v32, v151, -v74
	s_waitcnt lgkmcnt(1)
	v_add_f32_e32 v153, v154, v74
	v_mul_f32_e32 v74, v32, v152
	v_fmac_f32_e32 v74, v33, v151
	v_add_f32_e32 v154, v155, v74
	v_mul_f32_e32 v74, v33, v154
	v_mul_f32_e32 v75, v32, v154
	v_fma_f32 v74, v32, v153, -v74
	v_fmac_f32_e32 v75, v33, v153
	s_waitcnt lgkmcnt(0)
	v_add_f32_e32 v74, v156, v74
	v_add_f32_e32 v75, v157, v75
	ds_write2st64_b32 v112, v160, v132 offset1:1
	ds_write2_b32 v112, v76, v77 offset0:132 offset1:196
	ds_write2st64_b32 v115, v100, v101 offset0:4 offset1:5
	ds_write2st64_b32 v116, v130, v131 offset0:6 offset1:7
	ds_write2st64_b32 v117, v133, v134 offset0:8 offset1:9
	ds_write2st64_b32 v118, v135, v136 offset0:10 offset1:11
	ds_write2st64_b32 v119, v137, v138 offset0:12 offset1:13
	ds_write2st64_b32 v120, v139, v140 offset0:14 offset1:15
	ds_write2st64_b32 v121, v141, v142 offset0:16 offset1:17
	ds_write2st64_b32 v122, v143, v144 offset0:18 offset1:19
	ds_write2st64_b32 v123, v145, v146 offset0:20 offset1:21
	ds_write2st64_b32 v124, v147, v148 offset0:22 offset1:23
	ds_write2st64_b32 v125, v149, v150 offset0:24 offset1:25
	ds_write2st64_b32 v126, v151, v152 offset0:26 offset1:27
	ds_write2st64_b32 v127, v153, v154 offset0:28 offset1:29
	ds_write2st64_b32 v128, v74, v75 offset0:30 offset1:31
	s_waitcnt lgkmcnt(0)
	ds_read_b128 v[130:133], v113
	ds_read_b128 v[134:137], v113 offset:16
	v_mul_f32_e32 v156, v33, v75
	v_fma_f32 v156, v32, v74, -v156
	s_waitcnt lgkmcnt(1)
	v_cvt_pk_bf16_f32 v138, v130, v131
	v_lshlrev_b32_e32 v76, 16, v138
	v_and_b32_e32 v77, 0xffff0000, v138
	v_cvt_pk_bf16_f32 v139, v132, v133
	v_pk_add_f32 v[76:77], v[130:131], v[76:77] neg_lo:[0,1] neg_hi:[0,1]
	s_waitcnt lgkmcnt(0)
	v_cvt_pk_bf16_f32 v140, v134, v135
	v_cvt_pk_bf16_f32 v130, v76, v77
	v_lshlrev_b32_e32 v76, 16, v139
	v_and_b32_e32 v77, 0xffff0000, v139
	v_pk_add_f32 v[76:77], v[132:133], v[76:77] neg_lo:[0,1] neg_hi:[0,1]
	v_cvt_pk_bf16_f32 v141, v136, v137
	v_cvt_pk_bf16_f32 v131, v76, v77
	v_lshlrev_b32_e32 v76, 16, v140
	v_and_b32_e32 v77, 0xffff0000, v140
	v_pk_add_f32 v[76:77], v[134:135], v[76:77] neg_lo:[0,1] neg_hi:[0,1]
	s_nop 0
	v_cvt_pk_bf16_f32 v132, v76, v77
	v_lshlrev_b32_e32 v76, 16, v141
	v_and_b32_e32 v77, 0xffff0000, v141
	v_pk_add_f32 v[76:77], v[136:137], v[76:77] neg_lo:[0,1] neg_hi:[0,1]
	v_mfma_f32_16x16x32_bf16 v[134:137], v[138:141], v[24:27], 0
	v_cvt_pk_bf16_f32 v133, v76, v77
	v_mfma_f32_16x16x32_bf16 v[138:141], v[138:141], v[28:31], 0
	s_nop 0
	v_mfma_f32_16x16x32_bf16 v[130:133], v[130:133], v[24:27], v[138:141]
	s_nop 5
	ds_read_b128 v[138:141], v113 offset:128
	ds_read_b128 v[142:145], v113 offset:144
	s_waitcnt lgkmcnt(1)
	v_cvt_pk_bf16_f32 v146, v138, v139
	v_lshlrev_b32_e32 v76, 16, v146
	v_and_b32_e32 v77, 0xffff0000, v146
	v_cvt_pk_bf16_f32 v147, v140, v141
	v_pk_add_f32 v[76:77], v[138:139], v[76:77] neg_lo:[0,1] neg_hi:[0,1]
	s_waitcnt lgkmcnt(0)
	v_cvt_pk_bf16_f32 v148, v142, v143
	v_cvt_pk_bf16_f32 v138, v76, v77
	v_lshlrev_b32_e32 v76, 16, v147
	v_and_b32_e32 v77, 0xffff0000, v147
	v_pk_add_f32 v[76:77], v[140:141], v[76:77] neg_lo:[0,1] neg_hi:[0,1]
	v_cvt_pk_bf16_f32 v149, v144, v145
	v_cvt_pk_bf16_f32 v139, v76, v77
	v_lshlrev_b32_e32 v76, 16, v148
	v_and_b32_e32 v77, 0xffff0000, v148
	v_pk_add_f32 v[76:77], v[142:143], v[76:77] neg_lo:[0,1] neg_hi:[0,1]
	v_mfma_f32_16x16x32_bf16 v[130:133], v[146:149], v[20:23], v[130:133]
	v_cvt_pk_bf16_f32 v140, v76, v77
	v_lshlrev_b32_e32 v76, 16, v149
	v_and_b32_e32 v77, 0xffff0000, v149
	v_pk_add_f32 v[76:77], v[144:145], v[76:77] neg_lo:[0,1] neg_hi:[0,1]
	v_mfma_f32_16x16x32_bf16 v[134:137], v[146:149], v[16:19], v[134:137]
	v_cvt_pk_bf16_f32 v141, v76, v77
	s_nop 1
	v_mfma_f32_16x16x32_bf16 v[130:133], v[138:141], v[16:19], v[130:133]
	ds_read_b128 v[138:141], v113 offset:256
	ds_read_b128 v[142:145], v113 offset:272
	s_waitcnt lgkmcnt(1)
	v_cvt_pk_bf16_f32 v146, v138, v139
	v_lshlrev_b32_e32 v76, 16, v146
	v_and_b32_e32 v77, 0xffff0000, v146
	v_cvt_pk_bf16_f32 v147, v140, v141
	v_pk_add_f32 v[76:77], v[138:139], v[76:77] neg_lo:[0,1] neg_hi:[0,1]
	s_waitcnt lgkmcnt(0)
; __device__ __forceinline__ float bf2f(unsigned short h) { return __uint_as_float(((unsigned)h) << 16); }
; __device__ __forceinline__ unsigned short f2bf(float f) { return (unsigned short)(cvt_pk(f, 0.f) & 0xffffu); }
; template <bool WRITEH>
; __device__ __forceinline__ void s5_block(const S5Coef& C, const bf16x8 (&bm)[8], u32x4 uw, float* Hs, int lane, float& hr, float& hi) {
;     ...
;     for (int nb = 0; nb < 8; ++nb) { const f32x4 d = __builtin_amdgcn_mfma_f32_16x16x32_bf16(ua, bm[nb], (f32x4){0.f, 0.f, 0.f, 0.f}, 0, 0, 0);
; #pragma unroll
;         for (int i = 0; i < 4; ++i) Hs[(4 * (lane >> 4) + i) * 132 + 16 * nb + (lane & 15)] = d[i]; }
; __device__ __forceinline__ void s5_unit(ArgsP A, int l, int unit, unsigned char* lds, int wave_, int lane_) {
;     ...
;                 y = __builtin_amdgcn_mfma_f32_16x16x32_bf16(hh_, chl[2 * ks], y, 0, 0, 0); y2 = __builtin_amdgcn_mfma_f32_16x16x32_bf16(hh_, chl[2 * ks + 1], y2, 0, 0, 0);
;                 y2 = __builtin_amdgcn_mfma_f32_16x16x32_bf16(hl_, chl[2 * ks], y2, 0, 0, 0); }
;             y = y + y2;
; #pragma unroll
;             for (int i = 0; i < 4; ++i) { const int t = 16 * blk + 4 * (lane >> 4) + i; const int col = 16 * g + (lane & 15);
;                 const float uval = bf2f(uraw[i]); const float v = gelu_tanh(y[i] + dv * uval); ys[t * YS_STRIDE + col] = f2bf(v); }
	v_cvt_pk_bf16_f32 v148, v142, v143
	v_cvt_pk_bf16_f32 v138, v76, v77
	v_lshlrev_b32_e32 v76, 16, v147
	v_and_b32_e32 v77, 0xffff0000, v147
	v_pk_add_f32 v[76:77], v[140:141], v[76:77] neg_lo:[0,1] neg_hi:[0,1]
	v_cvt_pk_bf16_f32 v149, v144, v145
	v_cvt_pk_bf16_f32 v139, v76, v77
	v_lshlrev_b32_e32 v76, 16, v148
	v_and_b32_e32 v77, 0xffff0000, v148
	v_pk_add_f32 v[76:77], v[142:143], v[76:77] neg_lo:[0,1] neg_hi:[0,1]
	v_mfma_f32_16x16x32_bf16 v[130:133], v[146:149], v[12:15], v[130:133]
	v_cvt_pk_bf16_f32 v140, v76, v77
	v_lshlrev_b32_e32 v76, 16, v149
	v_and_b32_e32 v77, 0xffff0000, v149
	v_pk_add_f32 v[76:77], v[144:145], v[76:77] neg_lo:[0,1] neg_hi:[0,1]
	v_mfma_f32_16x16x32_bf16 v[134:137], v[146:149], v[8:11], v[134:137]
	v_cvt_pk_bf16_f32 v141, v76, v77
	s_nop 1
	v_mfma_f32_16x16x32_bf16 v[130:133], v[138:141], v[8:11], v[130:133]
	ds_read_b128 v[138:141], v113 offset:384
	ds_read_b128 v[142:145], v113 offset:400
	s_waitcnt lgkmcnt(1)
	v_cvt_pk_bf16_f32 v146, v138, v139
	v_lshlrev_b32_e32 v76, 16, v146
	v_and_b32_e32 v77, 0xffff0000, v146
	v_cvt_pk_bf16_f32 v147, v140, v141
	v_pk_add_f32 v[76:77], v[138:139], v[76:77] neg_lo:[0,1] neg_hi:[0,1]
	s_waitcnt lgkmcnt(0)
	v_cvt_pk_bf16_f32 v148, v142, v143
	v_cvt_pk_bf16_f32 v138, v76, v77
	v_lshlrev_b32_e32 v76, 16, v147
	v_and_b32_e32 v77, 0xffff0000, v147
	v_pk_add_f32 v[76:77], v[140:141], v[76:77] neg_lo:[0,1] neg_hi:[0,1]
	v_cvt_pk_bf16_f32 v149, v144, v145
	v_cvt_pk_bf16_f32 v139, v76, v77
	v_lshlrev_b32_e32 v76, 16, v148
	v_and_b32_e32 v77, 0xffff0000, v148
	v_pk_add_f32 v[76:77], v[142:143], v[76:77] neg_lo:[0,1] neg_hi:[0,1]
	v_mfma_f32_16x16x32_bf16 v[130:133], v[146:149], v[4:7], v[130:133]
	v_cvt_pk_bf16_f32 v140, v76, v77
	v_lshlrev_b32_e32 v76, 16, v149
	v_and_b32_e32 v77, 0xffff0000, v149
	v_pk_add_f32 v[76:77], v[144:145], v[76:77] neg_lo:[0,1] neg_hi:[0,1]
	v_mfma_f32_16x16x32_bf16 v[134:137], v[146:149], v[0:3], v[134:137]
	v_cvt_pk_bf16_f32 v141, v76, v77
	s_nop 1
	v_mfma_f32_16x16x32_bf16 v[130:133], v[138:141], v[0:3], v[130:133]
	s_nop 7
	v_pk_add_f32 v[100:101], v[134:135], v[130:131]
	v_pk_add_f32 v[76:77], v[136:137], v[132:133]
	v_fma_f32 v100, v79, v103, v100
	v_mul_f32_e32 v103, 0x3d372713, v100
	v_mul_f32_e32 v103, v100, v103
	v_fma_f32 v103, v100, v103, v100
	v_mul_f32_e32 v103, 0x3f4c422a, v103
	v_add_f32_e32 v103, v103, v103
	v_mul_f32_e32 v103, 0x3fb8aa3b, v103
	v_exp_f32_e32 v103, v103
	v_mul_f32_e32 v100, 0.5, v100
	v_mfma_f32_16x16x32_bf16 v[130:133], v[70:73], v[62:65], 0
	v_add_f32_e32 v103, 1.0, v103
	v_rcp_f32_e32 v103, v103
	v_mfma_f32_16x16x32_bf16 v[62:65], v[66:69], v[62:65], 0
	v_fma_f32 v103, v103, -2.0, 1.0
	v_add_f32_e32 v103, 1.0, v103
	v_mul_f32_e32 v100, v100, v103
	v_cvt_pk_bf16_f32 v100, v100, s0
	ds_write_b16 v102, v100 offset:16640
	s_waitcnt vmcnt(2)
	v_lshlrev_b32_e32 v100, 16, v129
	v_fmac_f32_e32 v101, v79, v100
	v_mul_f32_e32 v100, 0x3d372713, v101
	v_mul_f32_e32 v100, v101, v100
	v_fma_f32 v100, v101, v100, v101
	v_mul_f32_e32 v100, 0x3f4c422a, v100
	v_add_f32_e32 v100, v100, v100
	v_mul_f32_e32 v100, 0x3fb8aa3b, v100
	v_exp_f32_e32 v100, v100
	v_mul_f32_e32 v101, 0.5, v101
	v_add_f32_e32 v100, 1.0, v100
	v_rcp_f32_e32 v100, v100
	s_nop 0
	v_fma_f32 v100, v100, -2.0, 1.0
	v_add_f32_e32 v100, 1.0, v100
	v_mul_f32_e32 v100, v101, v100
	v_cvt_pk_bf16_f32 v100, v100, s0
	ds_write_b16 v102, v100 offset:17680
	s_waitcnt vmcnt(1)
	v_lshlrev_b32_e32 v100, 16, v158
	v_fma_f32 v76, v79, v100, v76
	v_mul_f32_e32 v100, 0x3d372713, v76
	v_mul_f32_e32 v100, v76, v100
	v_fma_f32 v100, v76, v100, v76
	v_mul_f32_e32 v100, 0x3f4c422a, v100
	v_add_f32_e32 v100, v100, v100
	v_mul_f32_e32 v100, 0x3fb8aa3b, v100
	v_exp_f32_e32 v100, v100
	v_mul_f32_e32 v76, 0.5, v76
	v_add_f32_e32 v100, 1.0, v100
	v_rcp_f32_e32 v100, v100
	s_nop 0
	v_fma_f32 v100, v100, -2.0, 1.0
	v_add_f32_e32 v100, 1.0, v100
	v_mul_f32_e32 v76, v76, v100
	v_cvt_pk_bf16_f32 v76, v76, s0
	ds_write_b16 v102, v76 offset:18720
	s_waitcnt vmcnt(0)
	v_lshlrev_b32_e32 v76, 16, v159
	v_fmac_f32_e32 v77, v79, v76
	v_mul_f32_e32 v76, 0x3d372713, v77
	v_mul_f32_e32 v76, v77, v76
	v_fma_f32 v76, v77, v76, v77
	v_mul_f32_e32 v76, 0x3f4c422a, v76
	v_add_f32_e32 v76, v76, v76
	v_mul_f32_e32 v76, 0x3fb8aa3b, v76
	v_exp_f32_e32 v76, v76
	v_mul_f32_e32 v77, 0.5, v77
	v_add_f32_e32 v76, 1.0, v76
	v_rcp_f32_e32 v76, v76
	s_nop 0
	v_fma_f32 v76, v76, -2.0, 1.0
	v_add_f32_e32 v76, 1.0, v76
	v_mul_f32_e32 v76, v77, v76
	v_cvt_pk_bf16_f32 v76, v76, s0
	ds_write_b16 v102, v76 offset:19760
	s_waitcnt lgkmcnt(0)
; #define S5_LDS_FENCE() do { __builtin_amdgcn_wave_barrier(); asm volatile("s_waitcnt lgkmcnt(0)" ::: "memory"); } while (0)
; template <bool WRITEH>
; __device__ __forceinline__ void s5_block(const S5Coef& C, const bf16x8 (&bm)[8], u32x4 uw, float* Hs, int lane, float& hr, float& hi) {
;     ...
;     for (int nb = 0; nb < 8; ++nb) { const f32x4 d = __builtin_amdgcn_mfma_f32_16x16x32_bf16(ua, bm[nb], (f32x4){0.f, 0.f, 0.f, 0.f}, 0, 0, 0);
; #pragma unroll
;         for (int i = 0; i < 4; ++i) Hs[(4 * (lane >> 4) + i) * 132 + 16 * nb + (lane & 15)] = d[i]; }
;     S5_LDS_FENCE();
;     float bur[16], bui[16];
; #pragma unroll
;     for (int tl = 0; tl < 16; ++tl) { bur[tl] = Hs[tl * 132 + lane]; bui[tl] = Hs[tl * 132 + 64 + lane]; }
; #pragma unroll
;     for (int tl = 0; tl < 16; ++tl) { const float nr = C.ar * hr - C.ai * hi + bur[tl], ni = C.ar * hi + C.ai * hr + bui[tl]; hr = nr; hi = ni; bur[tl] = hr; bui[tl] = hi; }
; __device__ __forceinline__ void s5_unit(ArgsP A, int l, int unit, unsigned char* lds, int wave_, int lane_) {
;     ...
;             unsigned short uraw[4];
; #pragma unroll
;             for (int i = 0; i < 4; ++i) uraw[i] = PROJ[(size_t)(rowbase + 16 * blk + 4 * (lane >> 4) + i) * INWP + C_S5 + 16 * g + (lane & 15)];
;             s5_block<true>(C, bm, uw[blk], Hs, lane, hr, hi);
	ds_write_b32 v106, v130
	ds_write_b32 v106, v131 offset:528
	ds_write_b32 v106, v132 offset:1056
	ds_write_b32 v107, v133
	v_mfma_f32_16x16x32_bf16 v[130:133], v[70:73], v[58:61], 0
	s_nop 7
	ds_write_b32 v106, v130 offset:64
	ds_write_b32 v106, v131 offset:592
	ds_write_b32 v106, v132 offset:1120
	ds_write_b32 v107, v133 offset:64
	v_mfma_f32_16x16x32_bf16 v[130:133], v[70:73], v[54:57], 0
	s_nop 7
	ds_write_b32 v106, v130 offset:128
	ds_write_b32 v106, v131 offset:656
	ds_write_b32 v106, v132 offset:1184
	ds_write_b32 v107, v133 offset:128
	v_mfma_f32_16x16x32_bf16 v[130:133], v[70:73], v[50:53], 0
	s_nop 7
	ds_write2_b32 v108, v130, v131 offset1:132
	ds_write_b32 v108, v132 offset:1056
	ds_write_b32 v109, v133
	v_mfma_f32_16x16x32_bf16 v[130:133], v[70:73], v[46:49], 0
	s_nop 7
	ds_write_b32 v106, v130 offset:256
	ds_write_b32 v106, v131 offset:784
	ds_write_b32 v106, v132 offset:1312
	ds_write_b32 v107, v133 offset:256
	v_mfma_f32_16x16x32_bf16 v[130:133], v[70:73], v[42:45], 0
	s_nop 7
	ds_write_b32 v106, v130 offset:320
	ds_write_b32 v106, v131 offset:848
	ds_write_b32 v106, v132 offset:1376
	ds_write_b32 v107, v133 offset:320
	v_mfma_f32_16x16x32_bf16 v[130:133], v[70:73], v[38:41], 0
	v_lshl_add_u64 v[76:77], s[2:3], 0, v[82:83]
	s_nop 6
	ds_write_b32 v106, v130 offset:384
	ds_write_b32 v106, v131 offset:912
	ds_write_b32 v106, v132 offset:1440
	ds_write_b32 v107, v133 offset:384
	v_mfma_f32_16x16x32_bf16 v[70:73], v[70:73], v[34:37], 0
	s_nop 7
	ds_write2_b32 v110, v70, v71 offset1:132
	ds_write_b32 v110, v72 offset:1056
	ds_write_b32 v111, v73
	v_add_co_u32_e32 v70, vcc, s12, v76
	v_mfma_f32_16x16x32_bf16 v[58:61], v[66:69], v[58:61], 0
	s_nop 0
	v_addc_co_u32_e32 v71, vcc, 0, v77, vcc
	global_load_ushort v103, v[70:71], off
	v_add_co_u32_e32 v70, vcc, s13, v76
	v_mfma_f32_16x16x32_bf16 v[54:57], v[66:69], v[54:57], 0
	s_nop 0
	v_addc_co_u32_e32 v71, vcc, 0, v77, vcc
	global_load_ushort v129, v[70:71], off offset:512
	v_add_co_u32_e32 v70, vcc, s33, v76
	v_mfma_f32_16x16x32_bf16 v[50:53], v[66:69], v[50:53], 0
	s_nop 0
	v_addc_co_u32_e32 v71, vcc, 0, v77, vcc
	global_load_ushort v154, v[70:71], off offset:1024
	v_add_co_u32_e32 v70, vcc, s28, v76
	v_mfma_f32_16x16x32_bf16 v[46:49], v[66:69], v[46:49], 0
	s_nop 0
	v_addc_co_u32_e32 v71, vcc, 0, v77, vcc
	global_load_ushort v155, v[70:71], off offset:1536
	s_waitcnt lgkmcnt(0)
	ds_read2st64_b32 v[70:71], v112 offset1:1
	ds_read2_b32 v[72:73], v112 offset0:132 offset1:196
	ds_read2st64_b32 v[76:77], v115 offset0:4 offset1:5
	ds_read2st64_b32 v[100:101], v116 offset0:6 offset1:7
	ds_read2st64_b32 v[130:131], v117 offset0:8 offset1:9
	ds_read2st64_b32 v[132:133], v118 offset0:10 offset1:11
	ds_read2st64_b32 v[134:135], v119 offset0:12 offset1:13
	ds_read2st64_b32 v[136:137], v120 offset0:14 offset1:15
	ds_read2st64_b32 v[138:139], v121 offset0:16 offset1:17
	ds_read2st64_b32 v[140:141], v122 offset0:18 offset1:19
	ds_read2st64_b32 v[142:143], v123 offset0:20 offset1:21
	ds_read2st64_b32 v[144:145], v124 offset0:22 offset1:23
	ds_read2st64_b32 v[146:147], v125 offset0:24 offset1:25
	ds_read2st64_b32 v[148:149], v126 offset0:26 offset1:27
	ds_read2st64_b32 v[150:151], v127 offset0:28 offset1:29
	ds_read2st64_b32 v[152:153], v128 offset0:30 offset1:31
	s_waitcnt lgkmcnt(14)
	v_add_f32_e32 v156, v156, v70
	v_mul_f32_e32 v70, v32, v75
	v_fmac_f32_e32 v70, v33, v74
	v_add_f32_e32 v74, v70, v71
	v_mul_f32_e32 v70, v33, v74
	v_fma_f32 v70, v32, v156, -v70
	v_add_f32_e32 v72, v72, v70
	v_mul_f32_e32 v70, v32, v74
	v_fmac_f32_e32 v70, v33, v156
	v_add_f32_e32 v73, v73, v70
	v_mul_f32_e32 v70, v33, v73
	v_fma_f32 v70, v32, v72, -v70
	s_waitcnt lgkmcnt(13)
	v_add_f32_e32 v75, v76, v70
	v_mul_f32_e32 v70, v32, v73
	v_fmac_f32_e32 v70, v33, v72
	v_add_f32_e32 v76, v77, v70
	v_mul_f32_e32 v70, v33, v76
	v_fma_f32 v70, v32, v75, -v70
	s_waitcnt lgkmcnt(12)
	v_add_f32_e32 v77, v100, v70
	v_mul_f32_e32 v70, v32, v76
	v_fmac_f32_e32 v70, v33, v75
	v_add_f32_e32 v100, v101, v70
	v_mul_f32_e32 v70, v33, v100
	v_fma_f32 v70, v32, v77, -v70
	s_waitcnt lgkmcnt(11)
	v_add_f32_e32 v101, v130, v70
	v_mul_f32_e32 v70, v32, v100
	v_fmac_f32_e32 v70, v33, v77
	v_add_f32_e32 v130, v131, v70
	v_mul_f32_e32 v70, v33, v130
	v_fma_f32 v70, v32, v101, -v70
	s_waitcnt lgkmcnt(10)
	v_add_f32_e32 v131, v132, v70
	v_mul_f32_e32 v70, v32, v130
	v_fmac_f32_e32 v70, v33, v101
	v_add_f32_e32 v132, v133, v70
	v_mul_f32_e32 v70, v33, v132
	v_fma_f32 v70, v32, v131, -v70
	s_waitcnt lgkmcnt(9)
	v_add_f32_e32 v133, v134, v70
	v_mul_f32_e32 v70, v32, v132
	v_fmac_f32_e32 v70, v33, v131
	v_add_f32_e32 v134, v135, v70
	v_mul_f32_e32 v70, v33, v134
	v_fma_f32 v70, v32, v133, -v70
	s_waitcnt lgkmcnt(8)
	v_add_f32_e32 v135, v136, v70
	v_mul_f32_e32 v70, v32, v134
	v_fmac_f32_e32 v70, v33, v133
	v_add_f32_e32 v136, v137, v70
	v_mul_f32_e32 v70, v33, v136
	v_fma_f32 v70, v32, v135, -v70
	s_waitcnt lgkmcnt(7)
	v_add_f32_e32 v137, v138, v70
	v_mul_f32_e32 v70, v32, v136
	v_fmac_f32_e32 v70, v33, v135
	v_add_f32_e32 v138, v139, v70
	v_mul_f32_e32 v70, v33, v138
	v_fma_f32 v70, v32, v137, -v70
	s_waitcnt lgkmcnt(6)
	v_add_f32_e32 v139, v140, v70
	v_mul_f32_e32 v70, v32, v138
	v_fmac_f32_e32 v70, v33, v137
	v_add_f32_e32 v140, v141, v70
	v_mul_f32_e32 v70, v33, v140
	v_fma_f32 v70, v32, v139, -v70
	s_waitcnt lgkmcnt(5)
	v_add_f32_e32 v141, v142, v70
	v_mul_f32_e32 v70, v32, v140
	v_fmac_f32_e32 v70, v33, v139
	v_add_f32_e32 v142, v143, v70
	v_mul_f32_e32 v70, v33, v142
	v_fma_f32 v70, v32, v141, -v70
	s_waitcnt lgkmcnt(4)
	v_add_f32_e32 v143, v144, v70
	v_mul_f32_e32 v70, v32, v142
	v_fmac_f32_e32 v70, v33, v141
	v_add_f32_e32 v144, v145, v70
	v_mul_f32_e32 v70, v33, v144
	v_fma_f32 v70, v32, v143, -v70
	s_waitcnt lgkmcnt(3)
; __device__ __forceinline__ unsigned cvt_pk(float lo, float hi) { f32x2_t v = {lo, hi}; bf16x2_t b = __builtin_convertvector(v, bf16x2_t); return __builtin_bit_cast(unsigned, b); }
; __device__ __forceinline__ float bflo(unsigned w) { return __uint_as_float(w << 16); }
; __device__ __forceinline__ float bfhi(unsigned w) { return __uint_as_float(w & 0xffff0000u); }
; template <bool WRITEH>
; __device__ __forceinline__ void s5_block(const S5Coef& C, const bf16x8 (&bm)[8], u32x4 uw, float* Hs, int lane, float& hr, float& hi) {
;     ...
;     for (int tl = 0; tl < 16; ++tl) { const float nr = C.ar * hr - C.ai * hi + bur[tl], ni = C.ar * hi + C.ai * hr + bui[tl]; hr = nr; hi = ni; bur[tl] = hr; bui[tl] = hi; }
;     if (WRITEH) {
; #pragma unroll
;         for (int tl = 0; tl < 16; ++tl) { Hs[tl * 132 + lane] = bur[tl]; Hs[tl * 132 + 64 + lane] = bui[tl]; }
; __device__ __forceinline__ void s5_unit(ArgsP A, int l, int unit, unsigned char* lds, int wave_, int lane_) {
;     ...
;             for (int ks = 0; ks < 4; ++ks) { const float* hp = Hs + (lane & 15) * 132 + 32 * ks + 8 * (lane >> 4); const f32x4 h0 = *(const f32x4*)hp, h1 = *(const f32x4*)(hp + 4);
;                 u32x4 wh; wh.x = cvt_pk(h0[0], h0[1]); wh.y = cvt_pk(h0[2], h0[3]); wh.z = cvt_pk(h1[0], h1[1]); wh.w = cvt_pk(h1[2], h1[3]);
;                 u32x4 wl; wl.x = cvt_pk(h0[0] - bflo(wh.x), h0[1] - bfhi(wh.x)); wl.y = cvt_pk(h0[2] - bflo(wh.y), h0[3] - bfhi(wh.y)); wl.z = cvt_pk(h1[0] - bflo(wh.z), h1[1] - bfhi(wh.z)); wl.w = cvt_pk(h1[2] - bflo(wh.w), h1[3] - bfhi(wh.w));
;                 const bf16x8 hh_ = __builtin_bit_cast(bf16x8, wh), hl_ = __builtin_bit_cast(bf16x8, wl);
;                 y = __builtin_amdgcn_mfma_f32_16x16x32_bf16(hh_, chl[2 * ks], y, 0, 0, 0); y2 = __builtin_amdgcn_mfma_f32_16x16x32_bf16(hh_, chl[2 * ks + 1], y2, 0, 0, 0);
;                 y2 = __builtin_amdgcn_mfma_f32_16x16x32_bf16(hl_, chl[2 * ks], y2, 0, 0, 0); }
	v_add_f32_e32 v145, v146, v70
	v_mul_f32_e32 v70, v32, v144
	v_fmac_f32_e32 v70, v33, v143
	v_add_f32_e32 v146, v147, v70
	v_mul_f32_e32 v70, v33, v146
	v_fma_f32 v70, v32, v145, -v70
	s_waitcnt lgkmcnt(2)
	v_add_f32_e32 v147, v148, v70
	v_mul_f32_e32 v70, v32, v146
	v_fmac_f32_e32 v70, v33, v145
	v_add_f32_e32 v148, v149, v70
	v_mul_f32_e32 v70, v33, v148
	v_fma_f32 v70, v32, v147, -v70
	s_waitcnt lgkmcnt(1)
	v_add_f32_e32 v149, v150, v70
	v_mul_f32_e32 v70, v32, v148
	v_fmac_f32_e32 v70, v33, v147
	v_add_f32_e32 v150, v151, v70
	v_mul_f32_e32 v70, v33, v150
	v_mul_f32_e32 v71, v32, v150
	v_fma_f32 v70, v32, v149, -v70
	v_fmac_f32_e32 v71, v33, v149
	s_waitcnt lgkmcnt(0)
	v_add_f32_e32 v70, v152, v70
	v_add_f32_e32 v71, v153, v71
	ds_write2st64_b32 v112, v156, v74 offset1:1
	ds_write2_b32 v112, v72, v73 offset0:132 offset1:196
	ds_write2st64_b32 v115, v75, v76 offset0:4 offset1:5
	ds_write2st64_b32 v116, v77, v100 offset0:6 offset1:7
	ds_write2st64_b32 v117, v101, v130 offset0:8 offset1:9
	ds_write2st64_b32 v118, v131, v132 offset0:10 offset1:11
	ds_write2st64_b32 v119, v133, v134 offset0:12 offset1:13
	ds_write2st64_b32 v120, v135, v136 offset0:14 offset1:15
	ds_write2st64_b32 v121, v137, v138 offset0:16 offset1:17
	ds_write2st64_b32 v122, v139, v140 offset0:18 offset1:19
	ds_write2st64_b32 v123, v141, v142 offset0:20 offset1:21
	ds_write2st64_b32 v124, v143, v144 offset0:22 offset1:23
	ds_write2st64_b32 v125, v145, v146 offset0:24 offset1:25
	ds_write2st64_b32 v126, v147, v148 offset0:26 offset1:27
	ds_write2st64_b32 v127, v149, v150 offset0:28 offset1:29
	ds_write2st64_b32 v128, v70, v71 offset0:30 offset1:31
	s_waitcnt lgkmcnt(0)
	ds_read_b128 v[72:75], v113
	ds_read_b128 v[130:133], v113 offset:16
	v_mfma_f32_16x16x32_bf16 v[42:45], v[66:69], v[42:45], 0
	v_lshl_add_u64 v[82:83], v[82:83], 0, 32
	s_waitcnt lgkmcnt(1)
	v_cvt_pk_bf16_f32 v134, v72, v73
	v_cvt_pk_bf16_f32 v135, v74, v75
	v_lshlrev_b32_e32 v76, 16, v134
	v_and_b32_e32 v77, 0xffff0000, v134
	s_waitcnt lgkmcnt(0)
	v_cvt_pk_bf16_f32 v136, v130, v131
	v_cvt_pk_bf16_f32 v137, v132, v133
	v_pk_add_f32 v[72:73], v[72:73], v[76:77] neg_lo:[0,1] neg_hi:[0,1]
	v_lshlrev_b32_e32 v76, 16, v135
	v_and_b32_e32 v77, 0xffff0000, v135
	v_pk_add_f32 v[74:75], v[74:75], v[76:77] neg_lo:[0,1] neg_hi:[0,1]
	v_cvt_pk_bf16_f32 v72, v72, v73
	v_cvt_pk_bf16_f32 v73, v74, v75
	v_lshlrev_b32_e32 v74, 16, v136
	v_and_b32_e32 v75, 0xffff0000, v136
	v_lshlrev_b32_e32 v76, 16, v137
	v_and_b32_e32 v77, 0xffff0000, v137
	v_pk_add_f32 v[74:75], v[130:131], v[74:75] neg_lo:[0,1] neg_hi:[0,1]
	v_pk_add_f32 v[76:77], v[132:133], v[76:77] neg_lo:[0,1] neg_hi:[0,1]
	v_cvt_pk_bf16_f32 v74, v74, v75
	v_cvt_pk_bf16_f32 v75, v76, v77
	v_mfma_f32_16x16x32_bf16 v[130:133], v[134:137], v[24:27], 0
	v_mfma_f32_16x16x32_bf16 v[134:137], v[134:137], v[28:31], 0
	v_mfma_f32_16x16x32_bf16 v[72:75], v[72:75], v[24:27], v[134:137]
	s_nop 6
	ds_read_b128 v[134:137], v113 offset:128
	ds_read_b128 v[138:141], v113 offset:144
	s_waitcnt lgkmcnt(1)
	v_cvt_pk_bf16_f32 v142, v134, v135
	v_lshlrev_b32_e32 v76, 16, v142
	v_and_b32_e32 v77, 0xffff0000, v142
	v_cvt_pk_bf16_f32 v143, v136, v137
	v_pk_add_f32 v[76:77], v[134:135], v[76:77] neg_lo:[0,1] neg_hi:[0,1]
	s_waitcnt lgkmcnt(0)
	v_cvt_pk_bf16_f32 v144, v138, v139
	v_cvt_pk_bf16_f32 v134, v76, v77
	v_lshlrev_b32_e32 v76, 16, v143
	v_and_b32_e32 v77, 0xffff0000, v143
	v_pk_add_f32 v[76:77], v[136:137], v[76:77] neg_lo:[0,1] neg_hi:[0,1]
	v_cvt_pk_bf16_f32 v145, v140, v141
	v_cvt_pk_bf16_f32 v135, v76, v77
	v_lshlrev_b32_e32 v76, 16, v144
	v_and_b32_e32 v77, 0xffff0000, v144
	v_pk_add_f32 v[76:77], v[138:139], v[76:77] neg_lo:[0,1] neg_hi:[0,1]
	v_mfma_f32_16x16x32_bf16 v[72:75], v[142:145], v[20:23], v[72:75]
	v_cvt_pk_bf16_f32 v136, v76, v77
	v_lshlrev_b32_e32 v76, 16, v145
	v_and_b32_e32 v77, 0xffff0000, v145
	v_pk_add_f32 v[76:77], v[140:141], v[76:77] neg_lo:[0,1] neg_hi:[0,1]
	v_mfma_f32_16x16x32_bf16 v[130:133], v[142:145], v[16:19], v[130:133]
	v_cvt_pk_bf16_f32 v137, v76, v77
	s_nop 1
	v_mfma_f32_16x16x32_bf16 v[72:75], v[134:137], v[16:19], v[72:75]
	ds_read_b128 v[134:137], v113 offset:256
	ds_read_b128 v[138:141], v113 offset:272
	s_waitcnt lgkmcnt(1)
	v_cvt_pk_bf16_f32 v142, v134, v135
	v_lshlrev_b32_e32 v76, 16, v142
	v_and_b32_e32 v77, 0xffff0000, v142
	v_cvt_pk_bf16_f32 v143, v136, v137
	v_pk_add_f32 v[76:77], v[134:135], v[76:77] neg_lo:[0,1] neg_hi:[0,1]
	s_waitcnt lgkmcnt(0)
	v_cvt_pk_bf16_f32 v144, v138, v139
	v_cvt_pk_bf16_f32 v134, v76, v77
	v_lshlrev_b32_e32 v76, 16, v143
	v_and_b32_e32 v77, 0xffff0000, v143
	v_pk_add_f32 v[76:77], v[136:137], v[76:77] neg_lo:[0,1] neg_hi:[0,1]
	v_cvt_pk_bf16_f32 v145, v140, v141
	v_cvt_pk_bf16_f32 v135, v76, v77
	v_lshlrev_b32_e32 v76, 16, v144
	v_and_b32_e32 v77, 0xffff0000, v144
	v_pk_add_f32 v[76:77], v[138:139], v[76:77] neg_lo:[0,1] neg_hi:[0,1]
	v_mfma_f32_16x16x32_bf16 v[72:75], v[142:145], v[12:15], v[72:75]
	v_cvt_pk_bf16_f32 v136, v76, v77
	v_lshlrev_b32_e32 v76, 16, v145
	v_and_b32_e32 v77, 0xffff0000, v145
	v_pk_add_f32 v[76:77], v[140:141], v[76:77] neg_lo:[0,1] neg_hi:[0,1]
	v_mfma_f32_16x16x32_bf16 v[130:133], v[142:145], v[8:11], v[130:133]
	v_cvt_pk_bf16_f32 v137, v76, v77
	s_nop 1
	v_mfma_f32_16x16x32_bf16 v[72:75], v[134:137], v[8:11], v[72:75]
	ds_read_b128 v[134:137], v113 offset:384
	ds_read_b128 v[138:141], v113 offset:400
	s_waitcnt lgkmcnt(1)
	v_cvt_pk_bf16_f32 v142, v134, v135
	v_lshlrev_b32_e32 v76, 16, v142
	v_and_b32_e32 v77, 0xffff0000, v142
	v_cvt_pk_bf16_f32 v143, v136, v137
	v_pk_add_f32 v[76:77], v[134:135], v[76:77] neg_lo:[0,1] neg_hi:[0,1]
	s_waitcnt lgkmcnt(0)
; __device__ __forceinline__ float bf2f(unsigned short h) { return __uint_as_float(((unsigned)h) << 16); }
; __device__ __forceinline__ unsigned short f2bf(float f) { return (unsigned short)(cvt_pk(f, 0.f) & 0xffffu); }
; #define S5_LDS_FENCE() do { __builtin_amdgcn_wave_barrier(); asm volatile("s_waitcnt lgkmcnt(0)" ::: "memory"); } while (0)
; template <bool WRITEH>
; __device__ __forceinline__ void s5_block(const S5Coef& C, const bf16x8 (&bm)[8], u32x4 uw, float* Hs, int lane, float& hr, float& hi) {
;     ...
;     for (int nb = 0; nb < 8; ++nb) { const f32x4 d = __builtin_amdgcn_mfma_f32_16x16x32_bf16(ua, bm[nb], (f32x4){0.f, 0.f, 0.f, 0.f}, 0, 0, 0);
; #pragma unroll
;         for (int i = 0; i < 4; ++i) Hs[(4 * (lane >> 4) + i) * 132 + 16 * nb + (lane & 15)] = d[i]; }
;     S5_LDS_FENCE();
;     float bur[16], bui[16];
; #pragma unroll
;     for (int tl = 0; tl < 16; ++tl) { bur[tl] = Hs[tl * 132 + lane]; bui[tl] = Hs[tl * 132 + 64 + lane]; }
; __device__ __forceinline__ void s5_unit(ArgsP A, int l, int unit, unsigned char* lds, int wave_, int lane_) {
;     ...
;                 y = __builtin_amdgcn_mfma_f32_16x16x32_bf16(hh_, chl[2 * ks], y, 0, 0, 0); y2 = __builtin_amdgcn_mfma_f32_16x16x32_bf16(hh_, chl[2 * ks + 1], y2, 0, 0, 0);
;                 y2 = __builtin_amdgcn_mfma_f32_16x16x32_bf16(hl_, chl[2 * ks], y2, 0, 0, 0); }
;             y = y + y2;
; #pragma unroll
;             for (int i = 0; i < 4; ++i) { const int t = 16 * blk + 4 * (lane >> 4) + i; const int col = 16 * g + (lane & 15);
;                 const float uval = bf2f(uraw[i]); const float v = gelu_tanh(y[i] + dv * uval); ys[t * YS_STRIDE + col] = f2bf(v); }
	v_cvt_pk_bf16_f32 v144, v138, v139
	v_cvt_pk_bf16_f32 v134, v76, v77
	v_lshlrev_b32_e32 v76, 16, v143
	v_and_b32_e32 v77, 0xffff0000, v143
	v_pk_add_f32 v[76:77], v[136:137], v[76:77] neg_lo:[0,1] neg_hi:[0,1]
	v_cvt_pk_bf16_f32 v145, v140, v141
	v_cvt_pk_bf16_f32 v135, v76, v77
	v_lshlrev_b32_e32 v76, 16, v144
	v_and_b32_e32 v77, 0xffff0000, v144
	v_pk_add_f32 v[76:77], v[138:139], v[76:77] neg_lo:[0,1] neg_hi:[0,1]
	v_mfma_f32_16x16x32_bf16 v[72:75], v[142:145], v[4:7], v[72:75]
	v_cvt_pk_bf16_f32 v136, v76, v77
	v_lshlrev_b32_e32 v76, 16, v145
	v_and_b32_e32 v77, 0xffff0000, v145
	v_pk_add_f32 v[76:77], v[140:141], v[76:77] neg_lo:[0,1] neg_hi:[0,1]
	v_mfma_f32_16x16x32_bf16 v[130:133], v[142:145], v[0:3], v[130:133]
	v_cvt_pk_bf16_f32 v137, v76, v77
	s_waitcnt vmcnt(3)
	v_lshlrev_b32_e32 v76, 16, v103
	v_mfma_f32_16x16x32_bf16 v[72:75], v[134:137], v[0:3], v[72:75]
	v_mfma_f32_16x16x32_bf16 v[38:41], v[66:69], v[38:41], 0
	s_nop 6
	v_add_f32_e64 v72, v130, v72
	v_add_f32_e64 v73, v131, v73
	v_pk_add_f32 v[74:75], v[132:133], v[74:75]
	v_fma_f32 v72, v79, v76, v72
	v_mul_f32_e32 v76, 0x3d372713, v72
	v_mul_f32_e32 v76, v72, v76
	v_fma_f32 v76, v72, v76, v72
	v_mul_f32_e32 v76, 0x3f4c422a, v76
	v_add_f32_e32 v76, v76, v76
	v_mul_f32_e32 v76, 0x3fb8aa3b, v76
	v_exp_f32_e32 v76, v76
	v_mul_f32_e32 v72, 0.5, v72
	v_mfma_f32_16x16x32_bf16 v[34:37], v[66:69], v[34:37], 0
	v_add_f32_e32 v76, 1.0, v76
	v_rcp_f32_e32 v76, v76
	s_nop 0
	v_fma_f32 v76, v76, -2.0, 1.0
	v_add_f32_e32 v76, 1.0, v76
	v_mul_f32_e32 v72, v72, v76
	v_cvt_pk_bf16_f32 v72, v72, s0
	ds_write_b16 v102, v72 offset:33280
	s_waitcnt vmcnt(2)
	v_lshlrev_b32_e32 v72, 16, v129
	v_fmac_f32_e32 v73, v79, v72
	v_mul_f32_e32 v72, 0x3d372713, v73
	v_mul_f32_e32 v72, v73, v72
	v_fma_f32 v72, v73, v72, v73
	v_mul_f32_e32 v72, 0x3f4c422a, v72
	v_add_f32_e32 v72, v72, v72
	v_mul_f32_e32 v72, 0x3fb8aa3b, v72
	v_exp_f32_e32 v72, v72
	v_mul_f32_e32 v73, 0.5, v73
	v_add_f32_e32 v72, 1.0, v72
	v_rcp_f32_e32 v72, v72
	s_nop 0
	v_fma_f32 v72, v72, -2.0, 1.0
	v_add_f32_e32 v72, 1.0, v72
	v_mul_f32_e32 v72, v73, v72
	v_cvt_pk_bf16_f32 v72, v72, s0
	ds_write_b16 v102, v72 offset:34320
	s_waitcnt vmcnt(1)
	v_lshlrev_b32_e32 v72, 16, v154
	v_fma_f32 v72, v79, v72, v74
	v_mul_f32_e32 v73, 0x3d372713, v72
	v_mul_f32_e32 v73, v72, v73
	v_fma_f32 v73, v72, v73, v72
	v_mul_f32_e32 v73, 0x3f4c422a, v73
	v_add_f32_e32 v73, v73, v73
	v_mul_f32_e32 v73, 0x3fb8aa3b, v73
	v_exp_f32_e32 v73, v73
	v_mul_f32_e32 v72, 0.5, v72
	v_add_f32_e32 v73, 1.0, v73
	v_rcp_f32_e32 v73, v73
	s_nop 0
	v_fma_f32 v73, v73, -2.0, 1.0
	v_add_f32_e32 v73, 1.0, v73
	v_mul_f32_e32 v72, v72, v73
	v_cvt_pk_bf16_f32 v72, v72, s0
	ds_write_b16 v102, v72 offset:35360
	s_waitcnt vmcnt(0)
	v_lshlrev_b32_e32 v72, 16, v155
	v_fmac_f32_e32 v75, v79, v72
	v_mul_f32_e32 v72, 0x3d372713, v75
	v_mul_f32_e32 v72, v75, v72
	v_fma_f32 v72, v75, v72, v75
	v_mul_f32_e32 v72, 0x3f4c422a, v72
	v_add_f32_e32 v72, v72, v72
	v_mul_f32_e32 v72, 0x3fb8aa3b, v72
	v_exp_f32_e32 v72, v72
	v_mul_f32_e32 v73, 0.5, v75
	v_add_f32_e32 v72, 1.0, v72
	v_rcp_f32_e32 v72, v72
	s_nop 0
	v_fma_f32 v72, v72, -2.0, 1.0
	v_add_f32_e32 v72, 1.0, v72
	v_mul_f32_e32 v72, v73, v72
	v_cvt_pk_bf16_f32 v72, v72, s0
	ds_write_b16 v102, v72 offset:36400
	v_lshl_add_u64 v[72:73], s[2:3], 0, v[80:81]
	s_waitcnt lgkmcnt(0)
	ds_write_b32 v106, v62
	ds_write_b32 v106, v63 offset:528
	ds_write_b32 v106, v64 offset:1056
	ds_write_b32 v107, v65
	ds_write_b32 v106, v58 offset:64
	ds_write_b32 v106, v59 offset:592
	ds_write_b32 v106, v60 offset:1120
	ds_write_b32 v107, v61 offset:64
	ds_write_b32 v106, v54 offset:128
	ds_write_b32 v106, v55 offset:656
	ds_write_b32 v106, v56 offset:1184
	ds_write_b32 v107, v57 offset:128
	ds_write2_b32 v108, v50, v51 offset1:132
	ds_write_b32 v108, v52 offset:1056
	ds_write_b32 v109, v53
	ds_write_b32 v106, v46 offset:256
	ds_write_b32 v106, v47 offset:784
	ds_write_b32 v106, v48 offset:1312
	ds_write_b32 v107, v49 offset:256
	ds_write_b32 v106, v42 offset:320
	ds_write_b32 v106, v43 offset:848
	ds_write_b32 v106, v44 offset:1376
	ds_write_b32 v107, v45 offset:320
	ds_write_b32 v106, v38 offset:384
	ds_write_b32 v106, v39 offset:912
	ds_write_b32 v106, v40 offset:1440
	ds_write_b32 v107, v41 offset:384
	ds_write2_b32 v110, v34, v35 offset1:132
	ds_write_b32 v110, v36 offset:1056
	ds_write_b32 v111, v37
	v_add_co_u32_e32 v34, vcc, s12, v72
	v_lshl_add_u64 v[80:81], v[80:81], 0, 32
	s_nop 0
	v_addc_co_u32_e32 v35, vcc, 0, v73, vcc
	global_load_ushort v66, v[34:35], off
	v_add_co_u32_e32 v34, vcc, s13, v72
	s_nop 1
	v_addc_co_u32_e32 v35, vcc, 0, v73, vcc
	global_load_ushort v67, v[34:35], off offset:512
	v_add_co_u32_e32 v34, vcc, s33, v72
	s_nop 1
	v_addc_co_u32_e32 v35, vcc, 0, v73, vcc
	global_load_ushort v68, v[34:35], off offset:1024
	v_add_co_u32_e32 v34, vcc, s28, v72
	v_mul_f32_e32 v72, v33, v71
	s_nop 0
	v_addc_co_u32_e32 v35, vcc, 0, v73, vcc
	global_load_ushort v69, v[34:35], off offset:1536
	s_waitcnt lgkmcnt(0)
	v_mul_f32_e32 v71, v32, v71
	ds_read2st64_b32 v[34:35], v112 offset1:1
	ds_read2_b32 v[36:37], v112 offset0:132 offset1:196
	ds_read2st64_b32 v[38:39], v115 offset0:4 offset1:5
	ds_read2st64_b32 v[40:41], v116 offset0:6 offset1:7
	ds_read2st64_b32 v[42:43], v117 offset0:8 offset1:9
	ds_read2st64_b32 v[44:45], v118 offset0:10 offset1:11
	ds_read2st64_b32 v[46:47], v119 offset0:12 offset1:13
	ds_read2st64_b32 v[48:49], v120 offset0:14 offset1:15
	ds_read2st64_b32 v[50:51], v121 offset0:16 offset1:17
	ds_read2st64_b32 v[52:53], v122 offset0:18 offset1:19
	ds_read2st64_b32 v[54:55], v123 offset0:20 offset1:21
	ds_read2st64_b32 v[56:57], v124 offset0:22 offset1:23
	ds_read2st64_b32 v[58:59], v125 offset0:24 offset1:25
	ds_read2st64_b32 v[60:61], v126 offset0:26 offset1:27
	ds_read2st64_b32 v[62:63], v127 offset0:28 offset1:29
	ds_read2st64_b32 v[64:65], v128 offset0:30 offset1:31
	v_fmac_f32_e32 v71, v33, v70
	v_fma_f32 v72, v32, v70, -v72
	s_waitcnt lgkmcnt(14)
; __device__ __forceinline__ unsigned cvt_pk(float lo, float hi) { f32x2_t v = {lo, hi}; bf16x2_t b = __builtin_convertvector(v, bf16x2_t); return __builtin_bit_cast(unsigned, b); }
; __device__ __forceinline__ float bflo(unsigned w) { return __uint_as_float(w << 16); }
; __device__ __forceinline__ float bfhi(unsigned w) { return __uint_as_float(w & 0xffff0000u); }
; template <bool WRITEH>
; __device__ __forceinline__ void s5_block(const S5Coef& C, const bf16x8 (&bm)[8], u32x4 uw, float* Hs, int lane, float& hr, float& hi) {
;     ...
;     for (int tl = 0; tl < 16; ++tl) { bur[tl] = Hs[tl * 132 + lane]; bui[tl] = Hs[tl * 132 + 64 + lane]; }
; #pragma unroll
;     for (int tl = 0; tl < 16; ++tl) { const float nr = C.ar * hr - C.ai * hi + bur[tl], ni = C.ar * hi + C.ai * hr + bui[tl]; hr = nr; hi = ni; bur[tl] = hr; bui[tl] = hi; }
;     if (WRITEH) {
; #pragma unroll
;         for (int tl = 0; tl < 16; ++tl) { Hs[tl * 132 + lane] = bur[tl]; Hs[tl * 132 + 64 + lane] = bui[tl]; }
; __device__ __forceinline__ void s5_unit(ArgsP A, int l, int unit, unsigned char* lds, int wave_, int lane_) {
;     ...
;             for (int ks = 0; ks < 4; ++ks) { const float* hp = Hs + (lane & 15) * 132 + 32 * ks + 8 * (lane >> 4); const f32x4 h0 = *(const f32x4*)hp, h1 = *(const f32x4*)(hp + 4);
;                 u32x4 wh; wh.x = cvt_pk(h0[0], h0[1]); wh.y = cvt_pk(h0[2], h0[3]); wh.z = cvt_pk(h1[0], h1[1]); wh.w = cvt_pk(h1[2], h1[3]);
;                 u32x4 wl; wl.x = cvt_pk(h0[0] - bflo(wh.x), h0[1] - bfhi(wh.x)); wl.y = cvt_pk(h0[2] - bflo(wh.y), h0[3] - bfhi(wh.y)); wl.z = cvt_pk(h1[0] - bflo(wh.z), h1[1] - bfhi(wh.z)); wl.w = cvt_pk(h1[2] - bflo(wh.w), h1[3] - bfhi(wh.w));
;                 const bf16x8 hh_ = __builtin_bit_cast(bf16x8, wh), hl_ = __builtin_bit_cast(bf16x8, wl);
;                 y = __builtin_amdgcn_mfma_f32_16x16x32_bf16(hh_, chl[2 * ks], y, 0, 0, 0); y2 = __builtin_amdgcn_mfma_f32_16x16x32_bf16(hh_, chl[2 * ks + 1], y2, 0, 0, 0);
;                 y2 = __builtin_amdgcn_mfma_f32_16x16x32_bf16(hl_, chl[2 * ks], y2, 0, 0, 0); }
	v_add_f32_e32 v35, v71, v35
	v_add_f32_e32 v34, v72, v34
	v_mul_f32_e32 v70, v33, v35
	v_fma_f32 v70, v32, v34, -v70
	v_add_f32_e32 v36, v36, v70
	v_mul_f32_e32 v70, v32, v35
	v_fmac_f32_e32 v70, v33, v34
	v_add_f32_e32 v37, v37, v70
	v_mul_f32_e32 v70, v33, v37
	v_fma_f32 v70, v32, v36, -v70
	s_waitcnt lgkmcnt(13)
	v_add_f32_e32 v38, v38, v70
	v_mul_f32_e32 v70, v32, v37
	v_fmac_f32_e32 v70, v33, v36
	v_add_f32_e32 v39, v39, v70
	v_mul_f32_e32 v70, v33, v39
	v_fma_f32 v70, v32, v38, -v70
	s_waitcnt lgkmcnt(12)
	v_add_f32_e32 v40, v40, v70
	v_mul_f32_e32 v70, v32, v39
	v_fmac_f32_e32 v70, v33, v38
	v_add_f32_e32 v41, v41, v70
	v_mul_f32_e32 v70, v33, v41
	v_fma_f32 v70, v32, v40, -v70
	s_waitcnt lgkmcnt(11)
	v_add_f32_e32 v42, v42, v70
	v_mul_f32_e32 v70, v32, v41
	v_fmac_f32_e32 v70, v33, v40
	v_add_f32_e32 v43, v43, v70
	v_mul_f32_e32 v70, v33, v43
	v_fma_f32 v70, v32, v42, -v70
	s_waitcnt lgkmcnt(10)
	v_add_f32_e32 v44, v44, v70
	v_mul_f32_e32 v70, v32, v43
	v_fmac_f32_e32 v70, v33, v42
	v_add_f32_e32 v45, v45, v70
	v_mul_f32_e32 v70, v33, v45
	v_fma_f32 v70, v32, v44, -v70
	s_waitcnt lgkmcnt(9)
	v_add_f32_e32 v46, v46, v70
	v_mul_f32_e32 v70, v32, v45
	v_fmac_f32_e32 v70, v33, v44
	v_add_f32_e32 v47, v47, v70
	v_mul_f32_e32 v70, v33, v47
	v_fma_f32 v70, v32, v46, -v70
	s_waitcnt lgkmcnt(8)
	v_add_f32_e32 v48, v48, v70
	v_mul_f32_e32 v70, v32, v47
	v_fmac_f32_e32 v70, v33, v46
	v_add_f32_e32 v49, v49, v70
	v_mul_f32_e32 v70, v33, v49
	v_fma_f32 v70, v32, v48, -v70
	s_waitcnt lgkmcnt(7)
	v_add_f32_e32 v50, v50, v70
	v_mul_f32_e32 v70, v32, v49
	v_fmac_f32_e32 v70, v33, v48
	v_add_f32_e32 v51, v51, v70
	v_mul_f32_e32 v70, v33, v51
	v_fma_f32 v70, v32, v50, -v70
	s_waitcnt lgkmcnt(6)
	v_add_f32_e32 v52, v52, v70
	v_mul_f32_e32 v70, v32, v51
	v_fmac_f32_e32 v70, v33, v50
	v_add_f32_e32 v53, v53, v70
	v_mul_f32_e32 v70, v33, v53
	v_fma_f32 v70, v32, v52, -v70
	s_waitcnt lgkmcnt(5)
	v_add_f32_e32 v54, v54, v70
	v_mul_f32_e32 v70, v32, v53
	v_fmac_f32_e32 v70, v33, v52
	v_add_f32_e32 v55, v55, v70
	v_mul_f32_e32 v70, v33, v55
	v_fma_f32 v70, v32, v54, -v70
	s_waitcnt lgkmcnt(4)
	v_add_f32_e32 v56, v56, v70
	v_mul_f32_e32 v70, v32, v55
	v_fmac_f32_e32 v70, v33, v54
	v_add_f32_e32 v57, v57, v70
	v_mul_f32_e32 v70, v33, v57
	v_fma_f32 v70, v32, v56, -v70
	s_waitcnt lgkmcnt(3)
	v_add_f32_e32 v58, v58, v70
	v_mul_f32_e32 v70, v32, v57
	v_fmac_f32_e32 v70, v33, v56
	v_add_f32_e32 v59, v59, v70
	v_mul_f32_e32 v70, v33, v59
	v_fma_f32 v70, v32, v58, -v70
	s_waitcnt lgkmcnt(2)
	v_add_f32_e32 v60, v60, v70
	v_mul_f32_e32 v70, v32, v59
	v_fmac_f32_e32 v70, v33, v58
	v_add_f32_e32 v61, v61, v70
	v_mul_f32_e32 v70, v33, v61
	v_fma_f32 v70, v32, v60, -v70
	s_waitcnt lgkmcnt(1)
	v_add_f32_e32 v62, v62, v70
	v_mul_f32_e32 v70, v32, v61
	v_fmac_f32_e32 v70, v33, v60
	v_add_f32_e32 v63, v63, v70
	v_mul_f32_e32 v70, v33, v63
	v_fma_f32 v70, v32, v62, -v70
	v_mul_f32_e32 v32, v32, v63
	v_fmac_f32_e32 v32, v33, v62
	s_waitcnt lgkmcnt(0)
	v_add_f32_e32 v64, v64, v70
	v_add_f32_e32 v32, v65, v32
	ds_write2st64_b32 v112, v34, v35 offset1:1
	ds_write2_b32 v112, v36, v37 offset0:132 offset1:196
	ds_write2st64_b32 v115, v38, v39 offset0:4 offset1:5
	ds_write2st64_b32 v116, v40, v41 offset0:6 offset1:7
	ds_write2st64_b32 v117, v42, v43 offset0:8 offset1:9
	ds_write2st64_b32 v118, v44, v45 offset0:10 offset1:11
	ds_write2st64_b32 v119, v46, v47 offset0:12 offset1:13
	ds_write2st64_b32 v120, v48, v49 offset0:14 offset1:15
	ds_write2st64_b32 v121, v50, v51 offset0:16 offset1:17
	ds_write2st64_b32 v122, v52, v53 offset0:18 offset1:19
	ds_write2st64_b32 v123, v54, v55 offset0:20 offset1:21
	ds_write2st64_b32 v124, v56, v57 offset0:22 offset1:23
	ds_write2st64_b32 v125, v58, v59 offset0:24 offset1:25
	ds_write2st64_b32 v126, v60, v61 offset0:26 offset1:27
	ds_write2st64_b32 v127, v62, v63 offset0:28 offset1:29
	ds_write2st64_b32 v128, v64, v32 offset0:30 offset1:31
	s_waitcnt lgkmcnt(0)
	ds_read_b128 v[32:35], v113
	ds_read_b128 v[36:39], v113 offset:16
	s_waitcnt lgkmcnt(1)
	v_cvt_pk_bf16_f32 v40, v32, v33
	v_cvt_pk_bf16_f32 v41, v34, v35
	v_lshlrev_b32_e32 v44, 16, v40
	v_and_b32_e32 v45, 0xffff0000, v40
	v_pk_add_f32 v[32:33], v[32:33], v[44:45] neg_lo:[0,1] neg_hi:[0,1]
	v_lshlrev_b32_e32 v44, 16, v41
	v_and_b32_e32 v45, 0xffff0000, v41
	s_waitcnt lgkmcnt(0)
	v_cvt_pk_bf16_f32 v42, v36, v37
	v_cvt_pk_bf16_f32 v43, v38, v39
	v_pk_add_f32 v[34:35], v[34:35], v[44:45] neg_lo:[0,1] neg_hi:[0,1]
	v_cvt_pk_bf16_f32 v32, v32, v33
	v_cvt_pk_bf16_f32 v33, v34, v35
	v_lshlrev_b32_e32 v34, 16, v42
	v_and_b32_e32 v35, 0xffff0000, v42
	v_pk_add_f32 v[34:35], v[36:37], v[34:35] neg_lo:[0,1] neg_hi:[0,1]
	v_lshlrev_b32_e32 v36, 16, v43
	v_and_b32_e32 v37, 0xffff0000, v43
	v_pk_add_f32 v[36:37], v[38:39], v[36:37] neg_lo:[0,1] neg_hi:[0,1]
	v_cvt_pk_bf16_f32 v34, v34, v35
	v_cvt_pk_bf16_f32 v35, v36, v37
	v_mfma_f32_16x16x32_bf16 v[28:31], v[40:43], v[28:31], 0
	v_mfma_f32_16x16x32_bf16 v[36:39], v[40:43], v[24:27], 0
	v_mfma_f32_16x16x32_bf16 v[24:27], v[32:35], v[24:27], v[28:31]
	s_nop 5
	ds_read_b128 v[28:31], v113 offset:128
	ds_read_b128 v[32:35], v113 offset:144
	s_waitcnt lgkmcnt(1)
	v_cvt_pk_bf16_f32 v40, v28, v29
	v_cvt_pk_bf16_f32 v41, v30, v31
	v_lshlrev_b32_e32 v44, 16, v40
	v_and_b32_e32 v45, 0xffff0000, v40
	v_pk_add_f32 v[28:29], v[28:29], v[44:45] neg_lo:[0,1] neg_hi:[0,1]
	v_lshlrev_b32_e32 v44, 16, v41
	v_and_b32_e32 v45, 0xffff0000, v41
	s_waitcnt lgkmcnt(0)
; __device__ __forceinline__ unsigned cvt_pk(float lo, float hi) { f32x2_t v = {lo, hi}; bf16x2_t b = __builtin_convertvector(v, bf16x2_t); return __builtin_bit_cast(unsigned, b); }
; __device__ __forceinline__ float bf2f(unsigned short h) { return __uint_as_float(((unsigned)h) << 16); }
; __device__ __forceinline__ float bflo(unsigned w) { return __uint_as_float(w << 16); }
; __device__ __forceinline__ float bfhi(unsigned w) { return __uint_as_float(w & 0xffff0000u); }
; __device__ __forceinline__ unsigned short f2bf(float f) { return (unsigned short)(cvt_pk(f, 0.f) & 0xffffu); }
; __device__ __forceinline__ void s5_unit(ArgsP A, int l, int unit, unsigned char* lds, int wave_, int lane_) {
;     ...
;             for (int ks = 0; ks < 4; ++ks) { const float* hp = Hs + (lane & 15) * 132 + 32 * ks + 8 * (lane >> 4); const f32x4 h0 = *(const f32x4*)hp, h1 = *(const f32x4*)(hp + 4);
;                 u32x4 wh; wh.x = cvt_pk(h0[0], h0[1]); wh.y = cvt_pk(h0[2], h0[3]); wh.z = cvt_pk(h1[0], h1[1]); wh.w = cvt_pk(h1[2], h1[3]);
;                 u32x4 wl; wl.x = cvt_pk(h0[0] - bflo(wh.x), h0[1] - bfhi(wh.x)); wl.y = cvt_pk(h0[2] - bflo(wh.y), h0[3] - bfhi(wh.y)); wl.z = cvt_pk(h1[0] - bflo(wh.z), h1[1] - bfhi(wh.z)); wl.w = cvt_pk(h1[2] - bflo(wh.w), h1[3] - bfhi(wh.w));
;                 const bf16x8 hh_ = __builtin_bit_cast(bf16x8, wh), hl_ = __builtin_bit_cast(bf16x8, wl);
;                 y = __builtin_amdgcn_mfma_f32_16x16x32_bf16(hh_, chl[2 * ks], y, 0, 0, 0); y2 = __builtin_amdgcn_mfma_f32_16x16x32_bf16(hh_, chl[2 * ks + 1], y2, 0, 0, 0);
;                 y2 = __builtin_amdgcn_mfma_f32_16x16x32_bf16(hl_, chl[2 * ks], y2, 0, 0, 0); }
;             y = y + y2;
; #pragma unroll
;             for (int i = 0; i < 4; ++i) { const int t = 16 * blk + 4 * (lane >> 4) + i; const int col = 16 * g + (lane & 15);
;                 const float uval = bf2f(uraw[i]); const float v = gelu_tanh(y[i] + dv * uval); ys[t * YS_STRIDE + col] = f2bf(v); }
;             __builtin_amdgcn_wave_barrier(); asm volatile("s_waitcnt lgkmcnt(0)" ::: "memory");
;         }
;     }
	v_cvt_pk_bf16_f32 v42, v32, v33
	v_cvt_pk_bf16_f32 v43, v34, v35
	v_pk_add_f32 v[30:31], v[30:31], v[44:45] neg_lo:[0,1] neg_hi:[0,1]
	v_cvt_pk_bf16_f32 v28, v28, v29
	v_cvt_pk_bf16_f32 v29, v30, v31
	v_lshlrev_b32_e32 v30, 16, v42
	v_and_b32_e32 v31, 0xffff0000, v42
	v_pk_add_f32 v[30:31], v[32:33], v[30:31] neg_lo:[0,1] neg_hi:[0,1]
	v_lshlrev_b32_e32 v32, 16, v43
	v_and_b32_e32 v33, 0xffff0000, v43
	v_pk_add_f32 v[32:33], v[34:35], v[32:33] neg_lo:[0,1] neg_hi:[0,1]
	v_cvt_pk_bf16_f32 v30, v30, v31
	v_cvt_pk_bf16_f32 v31, v32, v33
	v_mfma_f32_16x16x32_bf16 v[20:23], v[40:43], v[20:23], v[24:27]
	v_mfma_f32_16x16x32_bf16 v[32:35], v[40:43], v[16:19], v[36:39]
	v_mfma_f32_16x16x32_bf16 v[16:19], v[28:31], v[16:19], v[20:23]
	s_nop 5
	ds_read_b128 v[20:23], v113 offset:256
	ds_read_b128 v[24:27], v113 offset:272
	s_waitcnt lgkmcnt(1)
	v_cvt_pk_bf16_f32 v28, v20, v21
	v_cvt_pk_bf16_f32 v29, v22, v23
	v_lshlrev_b32_e32 v36, 16, v28
	v_and_b32_e32 v37, 0xffff0000, v28
	v_pk_add_f32 v[20:21], v[20:21], v[36:37] neg_lo:[0,1] neg_hi:[0,1]
	v_lshlrev_b32_e32 v36, 16, v29
	v_and_b32_e32 v37, 0xffff0000, v29
	s_waitcnt lgkmcnt(0)
	v_cvt_pk_bf16_f32 v30, v24, v25
	v_cvt_pk_bf16_f32 v31, v26, v27
	v_pk_add_f32 v[22:23], v[22:23], v[36:37] neg_lo:[0,1] neg_hi:[0,1]
	v_cvt_pk_bf16_f32 v20, v20, v21
	v_cvt_pk_bf16_f32 v21, v22, v23
	v_lshlrev_b32_e32 v22, 16, v30
	v_and_b32_e32 v23, 0xffff0000, v30
	v_pk_add_f32 v[22:23], v[24:25], v[22:23] neg_lo:[0,1] neg_hi:[0,1]
	v_lshlrev_b32_e32 v24, 16, v31
	v_and_b32_e32 v25, 0xffff0000, v31
	v_pk_add_f32 v[24:25], v[26:27], v[24:25] neg_lo:[0,1] neg_hi:[0,1]
	v_cvt_pk_bf16_f32 v22, v22, v23
	v_cvt_pk_bf16_f32 v23, v24, v25
	v_mfma_f32_16x16x32_bf16 v[12:15], v[28:31], v[12:15], v[16:19]
	v_mfma_f32_16x16x32_bf16 v[24:27], v[28:31], v[8:11], v[32:35]
	v_mfma_f32_16x16x32_bf16 v[8:11], v[20:23], v[8:11], v[12:15]
	s_nop 5
	ds_read_b128 v[12:15], v113 offset:384
	ds_read_b128 v[16:19], v113 offset:400
	s_waitcnt lgkmcnt(1)
	v_cvt_pk_bf16_f32 v20, v12, v13
	v_cvt_pk_bf16_f32 v21, v14, v15
	v_lshlrev_b32_e32 v28, 16, v20
	v_and_b32_e32 v29, 0xffff0000, v20
	v_pk_add_f32 v[12:13], v[12:13], v[28:29] neg_lo:[0,1] neg_hi:[0,1]
	v_lshlrev_b32_e32 v28, 16, v21
	v_and_b32_e32 v29, 0xffff0000, v21
	s_waitcnt lgkmcnt(0)
	v_cvt_pk_bf16_f32 v22, v16, v17
	v_cvt_pk_bf16_f32 v23, v18, v19
	v_pk_add_f32 v[14:15], v[14:15], v[28:29] neg_lo:[0,1] neg_hi:[0,1]
	v_cvt_pk_bf16_f32 v12, v12, v13
	v_cvt_pk_bf16_f32 v13, v14, v15
	v_lshlrev_b32_e32 v14, 16, v22
	v_and_b32_e32 v15, 0xffff0000, v22
	v_pk_add_f32 v[14:15], v[16:17], v[14:15] neg_lo:[0,1] neg_hi:[0,1]
	v_lshlrev_b32_e32 v16, 16, v23
	v_and_b32_e32 v17, 0xffff0000, v23
	v_pk_add_f32 v[16:17], v[18:19], v[16:17] neg_lo:[0,1] neg_hi:[0,1]
	v_cvt_pk_bf16_f32 v14, v14, v15
	v_cvt_pk_bf16_f32 v15, v16, v17
	v_mfma_f32_16x16x32_bf16 v[4:7], v[20:23], v[4:7], v[8:11]
	v_mfma_f32_16x16x32_bf16 v[16:19], v[20:23], v[0:3], v[24:27]
	v_mfma_f32_16x16x32_bf16 v[0:3], v[12:15], v[0:3], v[4:7]
	s_waitcnt vmcnt(3)
	s_nop 4
	v_lshlrev_b32_e32 v4, 16, v66
	s_nop 0
	v_pk_add_f32 v[0:1], v[16:17], v[0:1]
	v_pk_add_f32 v[2:3], v[18:19], v[2:3]
	v_fma_f32 v0, v79, v4, v0
	v_mul_f32_e32 v4, 0x3d372713, v0
	v_mul_f32_e32 v4, v0, v4
	v_fma_f32 v4, v0, v4, v0
	v_mul_f32_e32 v4, 0x3f4c422a, v4
	v_add_f32_e32 v4, v4, v4
	v_mul_f32_e32 v4, 0x3fb8aa3b, v4
	v_exp_f32_e32 v4, v4
	v_mul_f32_e32 v0, 0.5, v0
	v_add_f32_e32 v4, 1.0, v4
	v_rcp_f32_e32 v4, v4
	s_nop 0
	v_fma_f32 v4, v4, -2.0, 1.0
	v_add_f32_e32 v4, 1.0, v4
	v_mul_f32_e32 v0, v0, v4
	v_cvt_pk_bf16_f32 v0, v0, s0
	ds_write_b16 v102, v0 offset:49920
	s_waitcnt vmcnt(2)
	v_lshlrev_b32_e32 v0, 16, v67
	v_fmac_f32_e32 v1, v79, v0
	v_mul_f32_e32 v0, 0x3d372713, v1
	v_mul_f32_e32 v0, v1, v0
	v_fma_f32 v0, v1, v0, v1
	v_mul_f32_e32 v0, 0x3f4c422a, v0
	v_add_f32_e32 v0, v0, v0
	v_mul_f32_e32 v0, 0x3fb8aa3b, v0
	v_exp_f32_e32 v0, v0
	v_mul_f32_e32 v1, 0.5, v1
	v_add_f32_e32 v0, 1.0, v0
	v_rcp_f32_e32 v0, v0
	s_nop 0
	v_fma_f32 v0, v0, -2.0, 1.0
	v_add_f32_e32 v0, 1.0, v0
	v_mul_f32_e32 v0, v1, v0
	v_cvt_pk_bf16_f32 v0, v0, s0
	ds_write_b16 v102, v0 offset:50960
	s_waitcnt vmcnt(1)
	v_lshlrev_b32_e32 v0, 16, v68
	v_fma_f32 v0, v79, v0, v2
	v_mul_f32_e32 v1, 0x3d372713, v0
	v_mul_f32_e32 v1, v0, v1
	v_fma_f32 v1, v0, v1, v0
	v_mul_f32_e32 v1, 0x3f4c422a, v1
	v_add_f32_e32 v1, v1, v1
	v_mul_f32_e32 v1, 0x3fb8aa3b, v1
	v_exp_f32_e32 v1, v1
	v_mul_f32_e32 v0, 0.5, v0
	v_add_f32_e32 v1, 1.0, v1
	v_rcp_f32_e32 v1, v1
	s_nop 0
	v_fma_f32 v1, v1, -2.0, 1.0
	v_add_f32_e32 v1, 1.0, v1
	v_mul_f32_e32 v0, v0, v1
	v_cvt_pk_bf16_f32 v0, v0, s0
	ds_write_b16 v102, v0 offset:52000
	s_waitcnt vmcnt(0)
	v_lshlrev_b32_e32 v0, 16, v69
	v_fmac_f32_e32 v3, v79, v0
	v_mul_f32_e32 v0, 0x3d372713, v3
	v_mul_f32_e32 v0, v3, v0
	v_fma_f32 v0, v3, v0, v3
	v_mul_f32_e32 v0, 0x3f4c422a, v0
	v_add_f32_e32 v0, v0, v0
	v_mul_f32_e32 v0, 0x3fb8aa3b, v0
	v_exp_f32_e32 v0, v0
	v_mul_f32_e32 v1, 0.5, v3
	v_add_f32_e32 v0, 1.0, v0
	v_rcp_f32_e32 v0, v0
	s_nop 0
	v_fma_f32 v0, v0, -2.0, 1.0
	v_add_f32_e32 v0, 1.0, v0
	v_mul_f32_e32 v0, v1, v0
	v_cvt_pk_bf16_f32 v0, v0, s0
	ds_write_b16 v102, v0 offset:53040
	s_waitcnt lgkmcnt(0)
	s_cbranch_scc1 .LBB0_792
; __device__ __forceinline__ void s5_unit(ArgsP A, int l, int unit, unsigned char* lds, int wave_, int lane_) {
;     ...
;     __syncthreads();
;     const bf16_t* WG = (const bf16_t*)(A->ws + WS_W + (size_t)l * WL_SIZE + WL_WGLU);
;     f32x4 acc[4][4];
; #pragma unroll
;     for (int mb = 0; mb < 4; ++mb)
; #pragma unroll
;         for (int nb = 0; nb < 4; ++nb) acc[mb][nb] = (f32x4){0.f, 0.f, 0.f, 0.f};
;     {
;         const bf16_t* wb = WG + (size_t)(64 * wave + (lane & 15)) * 512 + 8 * (lane >> 4);
;         bf16x8 bq[4][4];
; #pragma unroll
;         for (int p = 0; p < 4; ++p)
; #pragma unroll
;             for (int nb = 0; nb < 4; ++nb) bq[p][nb] = *(const bf16x8*)(wb + (size_t)(16 * nb) * 512 + 32 * p);
; #pragma unroll
;         for (int ks = 0; ks < 16; ++ks) {
;             bf16x8 af[4];
; #pragma unroll
;             for (int mb = 0; mb < 4; ++mb) af[mb] = *(const bf16x8*)(ys + (16 * mb + (lane & 15)) * YS_STRIDE + 32 * ks + 8 * (lane >> 4));
;             asm volatile("" : "+v"(bq[ks & 3][0]), "+v"(bq[ks & 3][1]), "+v"(bq[ks & 3][2]), "+v"(bq[ks & 3][3]) :: "memory");
; #pragma unroll
;             for (int mb = 0; mb < 4; ++mb)
; #pragma unroll
;                 for (int nb = 0; nb < 4; ++nb) acc[mb][nb] = __builtin_amdgcn_mfma_f32_16x16x32_bf16(af[mb], bq[ks & 3][nb], acc[mb][nb], 0, 0, 0);
;             if (ks + 4 < 16) {
; #pragma unroll
;                 for (int nb = 0; nb < 4; ++nb) bq[ks & 3][nb] = *(const bf16x8*)(wb + (size_t)(16 * nb) * 512 + 32 * (ks + 4));
;             }
;         }
	v_readlane_b32 s5, v255, 15
	v_or_b32_e32 v64, s4, v104
	s_add_u32 s6, s2, s5
	v_ashrrev_i32_e32 v65, 31, v64
	s_addc_u32 s7, s3, 0
	v_lshlrev_b64 v[0:1], 10, v[64:65]
	v_lshl_add_u64 v[0:1], s[6:7], 0, v[0:1]
	v_and_b32_e32 v176, 48, v105
	v_lshl_add_u64 v[34:35], v[0:1], 0, v[176:177]
	s_mov_b64 s[4:5], 0xa650000
	v_lshl_add_u64 v[48:49], v[34:35], 0, s[4:5]
	s_mov_b32 s4, 0xa65c000
	v_add_co_u32_e32 v16, vcc, s4, v34
	s_mov_b32 s4, 0xa658000
	s_nop 0
	v_addc_co_u32_e32 v17, vcc, 0, v35, vcc
	v_add_co_u32_e32 v18, vcc, s4, v34
	s_mov_b32 s4, 0xa654000
	s_nop 0
	v_addc_co_u32_e32 v19, vcc, 0, v35, vcc
	v_add_co_u32_e32 v32, vcc, s4, v34
	s_mov_b32 s4, 0xa650000
	s_nop 0
	v_addc_co_u32_e32 v33, vcc, 0, v35, vcc
	v_mul_u32_u24_e32 v0, 0x410, v104
	v_add_co_u32_e32 v34, vcc, s4, v34
	v_add3_u32 v67, 16, v176, v0
	s_nop 0
	v_addc_co_u32_e32 v35, vcc, 0, v35, vcc
	s_waitcnt lgkmcnt(0)
	s_barrier
	ds_read_b128 v[0:3], v67
	ds_read_b128 v[4:7], v67 offset:16640
	ds_read_b128 v[8:11], v67 offset:33280
	ds_read_b128 v[12:15], v67 offset:49920
	global_load_dwordx4 v[20:23], v[16:17], off
	global_load_dwordx4 v[24:27], v[18:19], off
	global_load_dwordx4 v[28:31], v[32:33], off
	s_nop 0
	global_load_dwordx4 v[34:37], v[34:35], off
	s_nop 0
	global_load_dwordx4 v[38:41], v[16:17], off offset:64
	global_load_dwordx4 v[42:45], v[18:19], off offset:64
	global_load_dwordx4 v[50:53], v[32:33], off offset:64
	global_load_dwordx4 v[54:57], v[48:49], off offset:64
	global_load_dwordx4 v[58:61], v[16:17], off offset:128
	global_load_dwordx4 v[68:71], v[18:19], off offset:128
	global_load_dwordx4 v[72:75], v[32:33], off offset:128
	global_load_dwordx4 v[76:79], v[48:49], off offset:128
	global_load_dwordx4 v[80:83], v[16:17], off offset:192
	global_load_dwordx4 v[84:87], v[18:19], off offset:192
	global_load_dwordx4 v[88:91], v[32:33], off offset:192
	global_load_dwordx4 v[92:95], v[48:49], off offset:192
	v_lshrrev_b32_e32 v66, 4, v105
	s_add_u32 s2, s2, 0x24f90000
	s_addc_u32 s3, s3, 0
	s_waitcnt vmcnt(12)
	s_waitcnt lgkmcnt(3)
	v_mfma_f32_16x16x32_bf16 v[96:99], v[0:3], v[34:37], 0
	v_mfma_f32_16x16x32_bf16 v[100:103], v[0:3], v[28:31], 0
	v_mfma_f32_16x16x32_bf16 v[106:109], v[0:3], v[24:27], 0
	v_mfma_f32_16x16x32_bf16 v[0:3], v[0:3], v[20:23], 0
	s_waitcnt lgkmcnt(2)
	v_mfma_f32_16x16x32_bf16 v[110:113], v[4:7], v[34:37], 0
	v_mfma_f32_16x16x32_bf16 v[114:117], v[4:7], v[28:31], 0
	v_mfma_f32_16x16x32_bf16 v[118:121], v[4:7], v[24:27], 0
	v_mfma_f32_16x16x32_bf16 v[4:7], v[4:7], v[20:23], 0
	s_waitcnt lgkmcnt(1)
	v_mfma_f32_16x16x32_bf16 v[122:125], v[8:11], v[34:37], 0
	v_mfma_f32_16x16x32_bf16 v[126:129], v[8:11], v[28:31], 0
	v_mfma_f32_16x16x32_bf16 v[130:133], v[8:11], v[24:27], 0
	v_mfma_f32_16x16x32_bf16 v[8:11], v[8:11], v[20:23], 0
	s_waitcnt lgkmcnt(0)
	v_mfma_f32_16x16x32_bf16 v[34:37], v[12:15], v[34:37], 0
	v_mfma_f32_16x16x32_bf16 v[28:31], v[12:15], v[28:31], 0
	v_mfma_f32_16x16x32_bf16 v[24:27], v[12:15], v[24:27], 0
	v_mfma_f32_16x16x32_bf16 v[12:15], v[12:15], v[20:23], 0
	ds_read_b128 v[20:23], v67 offset:64
	ds_read_b128 v[134:137], v67 offset:16704
	ds_read_b128 v[138:141], v67 offset:33344
	ds_read_b128 v[142:145], v67 offset:49984
	global_load_dwordx4 v[146:149], v[16:17], off offset:256
	global_load_dwordx4 v[150:153], v[18:19], off offset:256
	global_load_dwordx4 v[154:157], v[32:33], off offset:256
	global_load_dwordx4 v[158:161], v[48:49], off offset:256
	s_waitcnt vmcnt(12)
	s_waitcnt lgkmcnt(3)
	v_mfma_f32_16x16x32_bf16 v[96:99], v[20:23], v[54:57], v[96:99]
	v_mfma_f32_16x16x32_bf16 v[100:103], v[20:23], v[50:53], v[100:103]
	v_mfma_f32_16x16x32_bf16 v[106:109], v[20:23], v[42:45], v[106:109]
	v_mfma_f32_16x16x32_bf16 v[0:3], v[20:23], v[38:41], v[0:3]
	s_waitcnt lgkmcnt(2)
	v_mfma_f32_16x16x32_bf16 v[20:23], v[134:137], v[54:57], v[110:113]
	v_mfma_f32_16x16x32_bf16 v[110:113], v[134:137], v[50:53], v[114:117]
	v_mfma_f32_16x16x32_bf16 v[114:117], v[134:137], v[42:45], v[118:121]
	v_mfma_f32_16x16x32_bf16 v[4:7], v[134:137], v[38:41], v[4:7]
	s_waitcnt lgkmcnt(1)
	v_mfma_f32_16x16x32_bf16 v[118:121], v[138:141], v[54:57], v[122:125]
	v_mfma_f32_16x16x32_bf16 v[122:125], v[138:141], v[50:53], v[126:129]
	v_mfma_f32_16x16x32_bf16 v[126:129], v[138:141], v[42:45], v[130:133]
	v_mfma_f32_16x16x32_bf16 v[8:11], v[138:141], v[38:41], v[8:11]
	s_waitcnt lgkmcnt(0)
	v_mfma_f32_16x16x32_bf16 v[34:37], v[142:145], v[54:57], v[34:37]
	v_mfma_f32_16x16x32_bf16 v[28:31], v[142:145], v[50:53], v[28:31]
	v_mfma_f32_16x16x32_bf16 v[24:27], v[142:145], v[42:45], v[24:27]
	v_mfma_f32_16x16x32_bf16 v[12:15], v[142:145], v[38:41], v[12:15]
	ds_read_b128 v[38:41], v67 offset:128
	ds_read_b128 v[42:45], v67 offset:16768
	ds_read_b128 v[50:53], v67 offset:33408
	ds_read_b128 v[54:57], v67 offset:50048
	global_load_dwordx4 v[130:133], v[16:17], off offset:320
	global_load_dwordx4 v[134:137], v[18:19], off offset:320
	global_load_dwordx4 v[138:141], v[32:33], off offset:320
	global_load_dwordx4 v[142:145], v[48:49], off offset:320
	s_waitcnt vmcnt(12)
	s_waitcnt lgkmcnt(3)
	v_mfma_f32_16x16x32_bf16 v[96:99], v[38:41], v[76:79], v[96:99]
	v_mfma_f32_16x16x32_bf16 v[100:103], v[38:41], v[72:75], v[100:103]
	v_mfma_f32_16x16x32_bf16 v[106:109], v[38:41], v[68:71], v[106:109]
	v_mfma_f32_16x16x32_bf16 v[0:3], v[38:41], v[58:61], v[0:3]
	s_waitcnt lgkmcnt(2)
	v_mfma_f32_16x16x32_bf16 v[20:23], v[42:45], v[76:79], v[20:23]
	v_mfma_f32_16x16x32_bf16 v[38:41], v[42:45], v[72:75], v[110:113]
	v_mfma_f32_16x16x32_bf16 v[110:113], v[42:45], v[68:71], v[114:117]
	v_mfma_f32_16x16x32_bf16 v[4:7], v[42:45], v[58:61], v[4:7]
	s_waitcnt lgkmcnt(1)
; __device__ __forceinline__ void s5_unit(ArgsP A, int l, int unit, unsigned char* lds, int wave_, int lane_) {
;     ...
;         for (int ks = 0; ks < 16; ++ks) {
;             bf16x8 af[4];
; #pragma unroll
;             for (int mb = 0; mb < 4; ++mb) af[mb] = *(const bf16x8*)(ys + (16 * mb + (lane & 15)) * YS_STRIDE + 32 * ks + 8 * (lane >> 4));
;             asm volatile("" : "+v"(bq[ks & 3][0]), "+v"(bq[ks & 3][1]), "+v"(bq[ks & 3][2]), "+v"(bq[ks & 3][3]) :: "memory");
; #pragma unroll
;             for (int mb = 0; mb < 4; ++mb)
; #pragma unroll
;                 for (int nb = 0; nb < 4; ++nb) acc[mb][nb] = __builtin_amdgcn_mfma_f32_16x16x32_bf16(af[mb], bq[ks & 3][nb], acc[mb][nb], 0, 0, 0);
;             if (ks + 4 < 16) {
; #pragma unroll
;                 for (int nb = 0; nb < 4; ++nb) bq[ks & 3][nb] = *(const bf16x8*)(wb + (size_t)(16 * nb) * 512 + 32 * (ks + 4));
;             }
;         }
	v_mfma_f32_16x16x32_bf16 v[42:45], v[50:53], v[76:79], v[118:121]
	v_mfma_f32_16x16x32_bf16 v[114:117], v[50:53], v[72:75], v[122:125]
	v_mfma_f32_16x16x32_bf16 v[118:121], v[50:53], v[68:71], v[126:129]
	v_mfma_f32_16x16x32_bf16 v[8:11], v[50:53], v[58:61], v[8:11]
	s_waitcnt lgkmcnt(0)
	v_mfma_f32_16x16x32_bf16 v[34:37], v[54:57], v[76:79], v[34:37]
	v_mfma_f32_16x16x32_bf16 v[28:31], v[54:57], v[72:75], v[28:31]
	v_mfma_f32_16x16x32_bf16 v[24:27], v[54:57], v[68:71], v[24:27]
	v_mfma_f32_16x16x32_bf16 v[12:15], v[54:57], v[58:61], v[12:15]
	ds_read_b128 v[50:53], v67 offset:192
	ds_read_b128 v[54:57], v67 offset:16832
	ds_read_b128 v[58:61], v67 offset:33472
	ds_read_b128 v[68:71], v67 offset:50112
	global_load_dwordx4 v[72:75], v[16:17], off offset:384
	global_load_dwordx4 v[76:79], v[18:19], off offset:384
	global_load_dwordx4 v[122:125], v[32:33], off offset:384
	global_load_dwordx4 v[126:129], v[48:49], off offset:384
	s_waitcnt vmcnt(12)
	s_waitcnt lgkmcnt(3)
	v_mfma_f32_16x16x32_bf16 v[96:99], v[50:53], v[92:95], v[96:99]
	v_mfma_f32_16x16x32_bf16 v[100:103], v[50:53], v[88:91], v[100:103]
	v_mfma_f32_16x16x32_bf16 v[106:109], v[50:53], v[84:87], v[106:109]
	v_mfma_f32_16x16x32_bf16 v[0:3], v[50:53], v[80:83], v[0:3]
	s_waitcnt lgkmcnt(2)
	v_mfma_f32_16x16x32_bf16 v[20:23], v[54:57], v[92:95], v[20:23]
	v_mfma_f32_16x16x32_bf16 v[38:41], v[54:57], v[88:91], v[38:41]
	v_mfma_f32_16x16x32_bf16 v[50:53], v[54:57], v[84:87], v[110:113]
	v_mfma_f32_16x16x32_bf16 v[4:7], v[54:57], v[80:83], v[4:7]
	s_waitcnt lgkmcnt(1)
	v_mfma_f32_16x16x32_bf16 v[42:45], v[58:61], v[92:95], v[42:45]
	v_mfma_f32_16x16x32_bf16 v[54:57], v[58:61], v[88:91], v[114:117]
	v_mfma_f32_16x16x32_bf16 v[110:113], v[58:61], v[84:87], v[118:121]
	v_mfma_f32_16x16x32_bf16 v[8:11], v[58:61], v[80:83], v[8:11]
	s_waitcnt lgkmcnt(0)
	v_mfma_f32_16x16x32_bf16 v[34:37], v[68:71], v[92:95], v[34:37]
	v_mfma_f32_16x16x32_bf16 v[28:31], v[68:71], v[88:91], v[28:31]
	v_mfma_f32_16x16x32_bf16 v[24:27], v[68:71], v[84:87], v[24:27]
	v_mfma_f32_16x16x32_bf16 v[12:15], v[68:71], v[80:83], v[12:15]
	ds_read_b128 v[58:61], v67 offset:256
	ds_read_b128 v[68:71], v67 offset:16896
	ds_read_b128 v[80:83], v67 offset:33536
	ds_read_b128 v[84:87], v67 offset:50176
	global_load_dwordx4 v[88:91], v[16:17], off offset:448
	global_load_dwordx4 v[92:95], v[18:19], off offset:448
	global_load_dwordx4 v[114:117], v[32:33], off offset:448
	global_load_dwordx4 v[118:121], v[48:49], off offset:448
	s_waitcnt vmcnt(12)
	s_waitcnt lgkmcnt(3)
	v_mfma_f32_16x16x32_bf16 v[96:99], v[58:61], v[158:161], v[96:99]
	v_mfma_f32_16x16x32_bf16 v[100:103], v[58:61], v[154:157], v[100:103]
	v_mfma_f32_16x16x32_bf16 v[106:109], v[58:61], v[150:153], v[106:109]
	v_mfma_f32_16x16x32_bf16 v[0:3], v[58:61], v[146:149], v[0:3]
	s_waitcnt lgkmcnt(2)
	v_mfma_f32_16x16x32_bf16 v[20:23], v[68:71], v[158:161], v[20:23]
	v_mfma_f32_16x16x32_bf16 v[38:41], v[68:71], v[154:157], v[38:41]
	v_mfma_f32_16x16x32_bf16 v[50:53], v[68:71], v[150:153], v[50:53]
	v_mfma_f32_16x16x32_bf16 v[4:7], v[68:71], v[146:149], v[4:7]
	s_waitcnt lgkmcnt(1)
	v_mfma_f32_16x16x32_bf16 v[42:45], v[80:83], v[158:161], v[42:45]
	v_mfma_f32_16x16x32_bf16 v[54:57], v[80:83], v[154:157], v[54:57]
	v_mfma_f32_16x16x32_bf16 v[58:61], v[80:83], v[150:153], v[110:113]
	v_mfma_f32_16x16x32_bf16 v[8:11], v[80:83], v[146:149], v[8:11]
	s_waitcnt lgkmcnt(0)
	v_mfma_f32_16x16x32_bf16 v[34:37], v[84:87], v[158:161], v[34:37]
	v_mfma_f32_16x16x32_bf16 v[28:31], v[84:87], v[154:157], v[28:31]
	v_mfma_f32_16x16x32_bf16 v[24:27], v[84:87], v[150:153], v[24:27]
	v_mfma_f32_16x16x32_bf16 v[12:15], v[84:87], v[146:149], v[12:15]
	ds_read_b128 v[68:71], v67 offset:320
	ds_read_b128 v[80:83], v67 offset:16960
	ds_read_b128 v[84:87], v67 offset:33600
	ds_read_b128 v[110:113], v67 offset:50240
	global_load_dwordx4 v[146:149], v[16:17], off offset:512
	global_load_dwordx4 v[150:153], v[18:19], off offset:512
	global_load_dwordx4 v[154:157], v[32:33], off offset:512
	global_load_dwordx4 v[158:161], v[48:49], off offset:512
	s_waitcnt vmcnt(12)
	s_waitcnt lgkmcnt(3)
	v_mfma_f32_16x16x32_bf16 v[96:99], v[68:71], v[142:145], v[96:99]
	v_mfma_f32_16x16x32_bf16 v[100:103], v[68:71], v[138:141], v[100:103]
	v_mfma_f32_16x16x32_bf16 v[106:109], v[68:71], v[134:137], v[106:109]
	v_mfma_f32_16x16x32_bf16 v[0:3], v[68:71], v[130:133], v[0:3]
	s_waitcnt lgkmcnt(2)
	v_mfma_f32_16x16x32_bf16 v[20:23], v[80:83], v[142:145], v[20:23]
	v_mfma_f32_16x16x32_bf16 v[38:41], v[80:83], v[138:141], v[38:41]
	v_mfma_f32_16x16x32_bf16 v[50:53], v[80:83], v[134:137], v[50:53]
	v_mfma_f32_16x16x32_bf16 v[4:7], v[80:83], v[130:133], v[4:7]
	s_waitcnt lgkmcnt(1)
	v_mfma_f32_16x16x32_bf16 v[42:45], v[84:87], v[142:145], v[42:45]
	v_mfma_f32_16x16x32_bf16 v[54:57], v[84:87], v[138:141], v[54:57]
	v_mfma_f32_16x16x32_bf16 v[58:61], v[84:87], v[134:137], v[58:61]
	v_mfma_f32_16x16x32_bf16 v[8:11], v[84:87], v[130:133], v[8:11]
	s_waitcnt lgkmcnt(0)
	v_mfma_f32_16x16x32_bf16 v[34:37], v[110:113], v[142:145], v[34:37]
	v_mfma_f32_16x16x32_bf16 v[28:31], v[110:113], v[138:141], v[28:31]
	v_mfma_f32_16x16x32_bf16 v[24:27], v[110:113], v[134:137], v[24:27]
	v_mfma_f32_16x16x32_bf16 v[12:15], v[110:113], v[130:133], v[12:15]
	ds_read_b128 v[68:71], v67 offset:384
	ds_read_b128 v[80:83], v67 offset:17024
	ds_read_b128 v[84:87], v67 offset:33664
	ds_read_b128 v[110:113], v67 offset:50304
	global_load_dwordx4 v[130:133], v[16:17], off offset:576
	global_load_dwordx4 v[134:137], v[18:19], off offset:576
	global_load_dwordx4 v[138:141], v[32:33], off offset:576
	global_load_dwordx4 v[142:145], v[48:49], off offset:576
	s_waitcnt vmcnt(12)
; __device__ __forceinline__ void s5_unit(ArgsP A, int l, int unit, unsigned char* lds, int wave_, int lane_) {
;     ...
;         for (int ks = 0; ks < 16; ++ks) {
;             bf16x8 af[4];
; #pragma unroll
;             for (int mb = 0; mb < 4; ++mb) af[mb] = *(const bf16x8*)(ys + (16 * mb + (lane & 15)) * YS_STRIDE + 32 * ks + 8 * (lane >> 4));
;             asm volatile("" : "+v"(bq[ks & 3][0]), "+v"(bq[ks & 3][1]), "+v"(bq[ks & 3][2]), "+v"(bq[ks & 3][3]) :: "memory");
; #pragma unroll
;             for (int mb = 0; mb < 4; ++mb)
; #pragma unroll
;                 for (int nb = 0; nb < 4; ++nb) acc[mb][nb] = __builtin_amdgcn_mfma_f32_16x16x32_bf16(af[mb], bq[ks & 3][nb], acc[mb][nb], 0, 0, 0);
;             if (ks + 4 < 16) {
; #pragma unroll
;                 for (int nb = 0; nb < 4; ++nb) bq[ks & 3][nb] = *(const bf16x8*)(wb + (size_t)(16 * nb) * 512 + 32 * (ks + 4));
;             }
;         }
	s_waitcnt lgkmcnt(3)
	v_mfma_f32_16x16x32_bf16 v[96:99], v[68:71], v[126:129], v[96:99]
	v_mfma_f32_16x16x32_bf16 v[100:103], v[68:71], v[122:125], v[100:103]
	v_mfma_f32_16x16x32_bf16 v[106:109], v[68:71], v[76:79], v[106:109]
	v_mfma_f32_16x16x32_bf16 v[0:3], v[68:71], v[72:75], v[0:3]
	s_waitcnt lgkmcnt(2)
	v_mfma_f32_16x16x32_bf16 v[20:23], v[80:83], v[126:129], v[20:23]
	v_mfma_f32_16x16x32_bf16 v[38:41], v[80:83], v[122:125], v[38:41]
	v_mfma_f32_16x16x32_bf16 v[50:53], v[80:83], v[76:79], v[50:53]
	v_mfma_f32_16x16x32_bf16 v[4:7], v[80:83], v[72:75], v[4:7]
	s_waitcnt lgkmcnt(1)
	v_mfma_f32_16x16x32_bf16 v[42:45], v[84:87], v[126:129], v[42:45]
	v_mfma_f32_16x16x32_bf16 v[54:57], v[84:87], v[122:125], v[54:57]
	v_mfma_f32_16x16x32_bf16 v[58:61], v[84:87], v[76:79], v[58:61]
	v_mfma_f32_16x16x32_bf16 v[8:11], v[84:87], v[72:75], v[8:11]
	s_waitcnt lgkmcnt(0)
	v_mfma_f32_16x16x32_bf16 v[34:37], v[110:113], v[126:129], v[34:37]
	v_mfma_f32_16x16x32_bf16 v[28:31], v[110:113], v[122:125], v[28:31]
	v_mfma_f32_16x16x32_bf16 v[24:27], v[110:113], v[76:79], v[24:27]
	v_mfma_f32_16x16x32_bf16 v[12:15], v[110:113], v[72:75], v[12:15]
	ds_read_b128 v[68:71], v67 offset:448
	ds_read_b128 v[72:75], v67 offset:17088
	ds_read_b128 v[76:79], v67 offset:33728
	ds_read_b128 v[80:83], v67 offset:50368
	global_load_dwordx4 v[84:87], v[16:17], off offset:640
	global_load_dwordx4 v[110:113], v[18:19], off offset:640
	global_load_dwordx4 v[122:125], v[32:33], off offset:640
	global_load_dwordx4 v[126:129], v[48:49], off offset:640
	s_waitcnt vmcnt(12)
	s_waitcnt lgkmcnt(3)
	v_mfma_f32_16x16x32_bf16 v[96:99], v[68:71], v[118:121], v[96:99]
	v_mfma_f32_16x16x32_bf16 v[100:103], v[68:71], v[114:117], v[100:103]
	v_mfma_f32_16x16x32_bf16 v[106:109], v[68:71], v[92:95], v[106:109]
	v_mfma_f32_16x16x32_bf16 v[0:3], v[68:71], v[88:91], v[0:3]
	s_waitcnt lgkmcnt(2)
	v_mfma_f32_16x16x32_bf16 v[20:23], v[72:75], v[118:121], v[20:23]
	v_mfma_f32_16x16x32_bf16 v[38:41], v[72:75], v[114:117], v[38:41]
	v_mfma_f32_16x16x32_bf16 v[50:53], v[72:75], v[92:95], v[50:53]
	v_mfma_f32_16x16x32_bf16 v[4:7], v[72:75], v[88:91], v[4:7]
	s_waitcnt lgkmcnt(1)
	v_mfma_f32_16x16x32_bf16 v[42:45], v[76:79], v[118:121], v[42:45]
	v_mfma_f32_16x16x32_bf16 v[54:57], v[76:79], v[114:117], v[54:57]
	v_mfma_f32_16x16x32_bf16 v[58:61], v[76:79], v[92:95], v[58:61]
	v_mfma_f32_16x16x32_bf16 v[8:11], v[76:79], v[88:91], v[8:11]
	s_waitcnt lgkmcnt(0)
	v_mfma_f32_16x16x32_bf16 v[34:37], v[80:83], v[118:121], v[34:37]
	v_mfma_f32_16x16x32_bf16 v[28:31], v[80:83], v[114:117], v[28:31]
	v_mfma_f32_16x16x32_bf16 v[24:27], v[80:83], v[92:95], v[24:27]
	v_mfma_f32_16x16x32_bf16 v[12:15], v[80:83], v[88:91], v[12:15]
	ds_read_b128 v[68:71], v67 offset:512
	ds_read_b128 v[72:75], v67 offset:17152
	ds_read_b128 v[76:79], v67 offset:33792
	ds_read_b128 v[80:83], v67 offset:50432
	global_load_dwordx4 v[88:91], v[16:17], off offset:704
	global_load_dwordx4 v[92:95], v[18:19], off offset:704
	global_load_dwordx4 v[114:117], v[32:33], off offset:704
	global_load_dwordx4 v[118:121], v[48:49], off offset:704
	s_waitcnt vmcnt(12)
	s_waitcnt lgkmcnt(3)
	v_mfma_f32_16x16x32_bf16 v[96:99], v[68:71], v[158:161], v[96:99]
	v_mfma_f32_16x16x32_bf16 v[100:103], v[68:71], v[154:157], v[100:103]
	v_mfma_f32_16x16x32_bf16 v[106:109], v[68:71], v[150:153], v[106:109]
	v_mfma_f32_16x16x32_bf16 v[0:3], v[68:71], v[146:149], v[0:3]
	s_waitcnt lgkmcnt(2)
	v_mfma_f32_16x16x32_bf16 v[20:23], v[72:75], v[158:161], v[20:23]
	v_mfma_f32_16x16x32_bf16 v[68:71], v[72:75], v[154:157], v[38:41]
	v_mfma_f32_16x16x32_bf16 v[162:165], v[72:75], v[150:153], v[50:53]
	v_mfma_f32_16x16x32_bf16 v[4:7], v[72:75], v[146:149], v[4:7]
	s_waitcnt lgkmcnt(1)
	v_mfma_f32_16x16x32_bf16 v[72:75], v[76:79], v[158:161], v[42:45]
	v_mfma_f32_16x16x32_bf16 v[166:169], v[76:79], v[154:157], v[54:57]
	v_mfma_f32_16x16x32_bf16 v[56:59], v[76:79], v[150:153], v[58:61]
	v_mfma_f32_16x16x32_bf16 v[8:11], v[76:79], v[146:149], v[8:11]
	s_waitcnt lgkmcnt(0)
	v_mfma_f32_16x16x32_bf16 v[34:37], v[80:83], v[158:161], v[34:37]
	v_mfma_f32_16x16x32_bf16 v[28:31], v[80:83], v[154:157], v[28:31]
	v_mfma_f32_16x16x32_bf16 v[24:27], v[80:83], v[150:153], v[24:27]
	v_mfma_f32_16x16x32_bf16 v[12:15], v[80:83], v[146:149], v[12:15]
	ds_read_b128 v[76:79], v67 offset:576
	ds_read_b128 v[80:83], v67 offset:17216
	ds_read_b128 v[146:149], v67 offset:33856
	ds_read_b128 v[150:153], v67 offset:50496
	global_load_dwordx4 v[40:43], v[16:17], off offset:768
	global_load_dwordx4 v[44:47], v[18:19], off offset:768
	global_load_dwordx4 v[52:55], v[32:33], off offset:768
	global_load_dwordx4 v[60:63], v[48:49], off offset:768
	s_waitcnt vmcnt(12)
	s_waitcnt lgkmcnt(3)
	v_mfma_f32_16x16x32_bf16 v[96:99], v[76:79], v[142:145], v[96:99]
	v_mfma_f32_16x16x32_bf16 v[100:103], v[76:79], v[138:141], v[100:103]
	v_mfma_f32_16x16x32_bf16 v[106:109], v[76:79], v[134:137], v[106:109]
	v_mfma_f32_16x16x32_bf16 v[0:3], v[76:79], v[130:133], v[0:3]
	s_waitcnt lgkmcnt(2)
	v_mfma_f32_16x16x32_bf16 v[20:23], v[80:83], v[142:145], v[20:23]
	v_mfma_f32_16x16x32_bf16 v[68:71], v[80:83], v[138:141], v[68:71]
	v_mfma_f32_16x16x32_bf16 v[76:79], v[80:83], v[134:137], v[162:165]
	v_mfma_f32_16x16x32_bf16 v[4:7], v[80:83], v[130:133], v[4:7]
	s_waitcnt lgkmcnt(1)
	v_mfma_f32_16x16x32_bf16 v[72:75], v[146:149], v[142:145], v[72:75]
	v_mfma_f32_16x16x32_bf16 v[80:83], v[146:149], v[138:141], v[166:169]
	v_mfma_f32_16x16x32_bf16 v[56:59], v[146:149], v[134:137], v[56:59]
	v_mfma_f32_16x16x32_bf16 v[146:149], v[146:149], v[130:133], v[8:11]
	s_waitcnt lgkmcnt(0)
; __device__ __forceinline__ void s5_unit(ArgsP A, int l, int unit, unsigned char* lds, int wave_, int lane_) {
;     ...
;         for (int ks = 0; ks < 16; ++ks) {
;             bf16x8 af[4];
; #pragma unroll
;             for (int mb = 0; mb < 4; ++mb) af[mb] = *(const bf16x8*)(ys + (16 * mb + (lane & 15)) * YS_STRIDE + 32 * ks + 8 * (lane >> 4));
;             asm volatile("" : "+v"(bq[ks & 3][0]), "+v"(bq[ks & 3][1]), "+v"(bq[ks & 3][2]), "+v"(bq[ks & 3][3]) :: "memory");
; #pragma unroll
;             for (int mb = 0; mb < 4; ++mb)
; #pragma unroll
;                 for (int nb = 0; nb < 4; ++nb) acc[mb][nb] = __builtin_amdgcn_mfma_f32_16x16x32_bf16(af[mb], bq[ks & 3][nb], acc[mb][nb], 0, 0, 0);
;             if (ks + 4 < 16) {
; #pragma unroll
;                 for (int nb = 0; nb < 4; ++nb) bq[ks & 3][nb] = *(const bf16x8*)(wb + (size_t)(16 * nb) * 512 + 32 * (ks + 4));
;             }
;         }
	v_mfma_f32_16x16x32_bf16 v[142:145], v[150:153], v[142:145], v[34:37]
	v_mfma_f32_16x16x32_bf16 v[138:141], v[150:153], v[138:141], v[28:31]
	v_mfma_f32_16x16x32_bf16 v[134:137], v[150:153], v[134:137], v[24:27]
	v_mfma_f32_16x16x32_bf16 v[12:15], v[150:153], v[130:133], v[12:15]
	ds_read_b128 v[130:133], v67 offset:640
	ds_read_b128 v[150:153], v67 offset:17280
	ds_read_b128 v[154:157], v67 offset:33920
	ds_read_b128 v[158:161], v67 offset:50560
	global_load_dwordx4 v[8:11], v[16:17], off offset:832
	global_load_dwordx4 v[24:27], v[18:19], off offset:832
	global_load_dwordx4 v[28:31], v[32:33], off offset:832
	global_load_dwordx4 v[36:39], v[48:49], off offset:832
	s_waitcnt vmcnt(12)
	s_waitcnt lgkmcnt(3)
	v_mfma_f32_16x16x32_bf16 v[96:99], v[130:133], v[126:129], v[96:99]
	v_mfma_f32_16x16x32_bf16 v[100:103], v[130:133], v[122:125], v[100:103]
	v_mfma_f32_16x16x32_bf16 v[106:109], v[130:133], v[110:113], v[106:109]
	s_waitcnt lgkmcnt(2)
	v_mfma_f32_16x16x32_bf16 v[162:165], v[150:153], v[126:129], v[20:23]
	v_mfma_f32_16x16x32_bf16 v[68:71], v[150:153], v[122:125], v[68:71]
	v_mfma_f32_16x16x32_bf16 v[76:79], v[150:153], v[110:113], v[76:79]
	s_waitcnt lgkmcnt(1)
	v_mfma_f32_16x16x32_bf16 v[72:75], v[154:157], v[126:129], v[72:75]
	v_mfma_f32_16x16x32_bf16 v[80:83], v[154:157], v[122:125], v[80:83]
	v_mfma_f32_16x16x32_bf16 v[56:59], v[154:157], v[110:113], v[56:59]
	v_mfma_f32_16x16x32_bf16 v[146:149], v[154:157], v[84:87], v[146:149]
	s_waitcnt lgkmcnt(0)
	v_mfma_f32_16x16x32_bf16 v[126:129], v[158:161], v[126:129], v[142:145]
	v_mfma_f32_16x16x32_bf16 v[122:125], v[158:161], v[122:125], v[138:141]
	v_mfma_f32_16x16x32_bf16 v[110:113], v[158:161], v[110:113], v[134:137]
	s_nop 2
	ds_read_b128 v[134:137], v67 offset:704
	ds_read_b128 v[138:141], v67 offset:17344
	ds_read_b128 v[142:145], v67 offset:33984
	ds_read_b128 v[154:157], v67 offset:50624
	v_mfma_f32_16x16x32_bf16 v[130:133], v[130:133], v[84:87], v[0:3]
	v_mfma_f32_16x16x32_bf16 v[150:153], v[150:153], v[84:87], v[4:7]
	v_mfma_f32_16x16x32_bf16 v[84:87], v[158:161], v[84:87], v[12:15]
	s_nop 0
	global_load_dwordx4 v[0:3], v[16:17], off offset:896
	global_load_dwordx4 v[4:7], v[18:19], off offset:896
	global_load_dwordx4 v[12:15], v[32:33], off offset:896
	global_load_dwordx4 v[20:23], v[48:49], off offset:896
	s_waitcnt vmcnt(12)
	s_waitcnt lgkmcnt(3)
	v_mfma_f32_16x16x32_bf16 v[96:99], v[134:137], v[118:121], v[96:99]
	v_mfma_f32_16x16x32_bf16 v[100:103], v[134:137], v[114:117], v[100:103]
	v_mfma_f32_16x16x32_bf16 v[106:109], v[134:137], v[92:95], v[106:109]
	v_mfma_f32_16x16x32_bf16 v[130:133], v[134:137], v[88:91], v[130:133]
	s_waitcnt lgkmcnt(2)
	v_mfma_f32_16x16x32_bf16 v[134:137], v[138:141], v[118:121], v[162:165]
	v_mfma_f32_16x16x32_bf16 v[68:71], v[138:141], v[114:117], v[68:71]
	v_mfma_f32_16x16x32_bf16 v[76:79], v[138:141], v[92:95], v[76:79]
	v_mfma_f32_16x16x32_bf16 v[138:141], v[138:141], v[88:91], v[150:153]
	s_waitcnt lgkmcnt(1)
	v_mfma_f32_16x16x32_bf16 v[72:75], v[142:145], v[118:121], v[72:75]
	v_mfma_f32_16x16x32_bf16 v[80:83], v[142:145], v[114:117], v[80:83]
	v_mfma_f32_16x16x32_bf16 v[150:153], v[142:145], v[92:95], v[56:59]
	v_mfma_f32_16x16x32_bf16 v[142:145], v[142:145], v[88:91], v[146:149]
	s_waitcnt lgkmcnt(0)
	v_mfma_f32_16x16x32_bf16 v[118:121], v[154:157], v[118:121], v[126:129]
	v_mfma_f32_16x16x32_bf16 v[114:117], v[154:157], v[114:117], v[122:125]
	v_mfma_f32_16x16x32_bf16 v[92:95], v[154:157], v[92:95], v[110:113]
	v_mfma_f32_16x16x32_bf16 v[84:87], v[154:157], v[88:91], v[84:87]
	ds_read_b128 v[88:91], v67 offset:768
	s_nop 0
	ds_read_b128 v[110:113], v67 offset:17408
	ds_read_b128 v[122:125], v67 offset:34048
	ds_read_b128 v[126:129], v67 offset:50688
	global_load_dwordx4 v[56:59], v[16:17], off offset:960
	s_nop 0
	global_load_dwordx4 v[16:19], v[18:19], off offset:960
	s_nop 0
	global_load_dwordx4 v[32:35], v[32:33], off offset:960
	s_nop 0
	global_load_dwordx4 v[48:51], v[48:49], off offset:960
	s_waitcnt vmcnt(12)
	s_waitcnt lgkmcnt(3)
	v_mfma_f32_16x16x32_bf16 v[96:99], v[88:91], v[60:63], v[96:99]
	v_mfma_f32_16x16x32_bf16 v[100:103], v[88:91], v[52:55], v[100:103]
	v_mfma_f32_16x16x32_bf16 v[106:109], v[88:91], v[44:47], v[106:109]
	v_mfma_f32_16x16x32_bf16 v[88:91], v[88:91], v[40:43], v[130:133]
	s_waitcnt lgkmcnt(2)
	v_mfma_f32_16x16x32_bf16 v[130:133], v[110:113], v[60:63], v[134:137]
	v_mfma_f32_16x16x32_bf16 v[68:71], v[110:113], v[52:55], v[68:71]
	v_mfma_f32_16x16x32_bf16 v[76:79], v[110:113], v[44:47], v[76:79]
	v_mfma_f32_16x16x32_bf16 v[110:113], v[110:113], v[40:43], v[138:141]
	s_waitcnt lgkmcnt(1)
	v_mfma_f32_16x16x32_bf16 v[72:75], v[122:125], v[60:63], v[72:75]
	v_mfma_f32_16x16x32_bf16 v[80:83], v[122:125], v[52:55], v[80:83]
	v_mfma_f32_16x16x32_bf16 v[134:137], v[122:125], v[44:47], v[150:153]
	v_mfma_f32_16x16x32_bf16 v[122:125], v[122:125], v[40:43], v[142:145]
	s_waitcnt lgkmcnt(0)
	v_mfma_f32_16x16x32_bf16 v[60:63], v[126:129], v[60:63], v[118:121]
	v_mfma_f32_16x16x32_bf16 v[52:55], v[126:129], v[52:55], v[114:117]
	v_mfma_f32_16x16x32_bf16 v[44:47], v[126:129], v[44:47], v[92:95]
	v_mfma_f32_16x16x32_bf16 v[40:43], v[126:129], v[40:43], v[84:87]
	s_nop 2
	ds_read_b128 v[84:87], v67 offset:832
	ds_read_b128 v[92:95], v67 offset:17472
	ds_read_b128 v[114:117], v67 offset:34112
	ds_read_b128 v[118:121], v67 offset:50752
	s_waitcnt vmcnt(8)
	s_waitcnt lgkmcnt(3)
	v_mfma_f32_16x16x32_bf16 v[96:99], v[84:87], v[36:39], v[96:99]
	v_mfma_f32_16x16x32_bf16 v[100:103], v[84:87], v[28:31], v[100:103]
	v_mfma_f32_16x16x32_bf16 v[106:109], v[84:87], v[24:27], v[106:109]
	v_mfma_f32_16x16x32_bf16 v[84:87], v[84:87], v[8:11], v[88:91]
	s_waitcnt lgkmcnt(2)
; __device__ __forceinline__ float bf2f(unsigned short h) { return __uint_as_float(((unsigned)h) << 16); }
; __device__ __forceinline__ unsigned short f2bf(float f) { return (unsigned short)(cvt_pk(f, 0.f) & 0xffffu); }
; __device__ __forceinline__ float sigmoidf_(float x) { return fast_rcp(1.f + fast_exp2(-x * LOG2E)); }
; __device__ __forceinline__ void s5_unit(ArgsP A, int l, int unit, unsigned char* lds, int wave_, int lane_) {
;     ...
;         for (int ks = 0; ks < 16; ++ks) {
;             bf16x8 af[4];
; #pragma unroll
;             for (int mb = 0; mb < 4; ++mb) af[mb] = *(const bf16x8*)(ys + (16 * mb + (lane & 15)) * YS_STRIDE + 32 * ks + 8 * (lane >> 4));
;             asm volatile("" : "+v"(bq[ks & 3][0]), "+v"(bq[ks & 3][1]), "+v"(bq[ks & 3][2]), "+v"(bq[ks & 3][3]) :: "memory");
; #pragma unroll
;             for (int mb = 0; mb < 4; ++mb)
; #pragma unroll
;                 for (int nb = 0; nb < 4; ++nb) acc[mb][nb] = __builtin_amdgcn_mfma_f32_16x16x32_bf16(af[mb], bq[ks & 3][nb], acc[mb][nb], 0, 0, 0);
;             if (ks + 4 < 16) {
; #pragma unroll
;                 for (int nb = 0; nb < 4; ++nb) bq[ks & 3][nb] = *(const bf16x8*)(wb + (size_t)(16 * nb) * 512 + 32 * (ks + 4));
;             }
;         }
;     }
;     bf16_t* MIX = (bf16_t*)(A->ws + WS_MIX);
;     float bglv[4];
; #pragma unroll
;     for (int nb = 0; nb < 4; ++nb) bglv[nb] = A->in[22][l * 512 + 64 * wave + 16 * nb + (lane & 15)];
; #pragma unroll
;     for (int nb = 0; nb < 4; ++nb) { const int n = 64 * wave + 16 * nb + (lane & 15); const float bgl = bglv[nb];
; #pragma unroll
;         for (int mb = 0; mb < 4; ++mb)
; #pragma unroll
;             for (int i = 0; i < 4; ++i) { const int t = 16 * mb + 4 * (lane >> 4) + i; const float yv = bf2f(ys[t * YS_STRIDE + n]);
;                 MIX[(size_t)(rowbase + t) * DM + n] = f2bf(yv * sigmoidf_(acc[mb][nb][i] + bgl)); } }
	v_mfma_f32_16x16x32_bf16 v[88:91], v[92:95], v[36:39], v[130:133]
	v_mfma_f32_16x16x32_bf16 v[68:71], v[92:95], v[28:31], v[68:71]
	v_mfma_f32_16x16x32_bf16 v[76:79], v[92:95], v[24:27], v[76:79]
	v_mfma_f32_16x16x32_bf16 v[92:95], v[92:95], v[8:11], v[110:113]
	s_waitcnt lgkmcnt(1)
	v_mfma_f32_16x16x32_bf16 v[72:75], v[114:117], v[36:39], v[72:75]
	v_mfma_f32_16x16x32_bf16 v[80:83], v[114:117], v[28:31], v[80:83]
	v_mfma_f32_16x16x32_bf16 v[110:113], v[114:117], v[24:27], v[134:137]
	v_mfma_f32_16x16x32_bf16 v[114:117], v[114:117], v[8:11], v[122:125]
	s_waitcnt lgkmcnt(0)
	v_mfma_f32_16x16x32_bf16 v[36:39], v[118:121], v[36:39], v[60:63]
	v_mfma_f32_16x16x32_bf16 v[28:31], v[118:121], v[28:31], v[52:55]
	v_mfma_f32_16x16x32_bf16 v[24:27], v[118:121], v[24:27], v[44:47]
	v_mfma_f32_16x16x32_bf16 v[8:11], v[118:121], v[8:11], v[40:43]
	s_nop 2
	ds_read_b128 v[40:43], v67 offset:896
	ds_read_b128 v[44:47], v67 offset:17536
	ds_read_b128 v[52:55], v67 offset:34176
	ds_read_b128 v[60:63], v67 offset:50816
	s_waitcnt vmcnt(4)
	s_waitcnt lgkmcnt(3)
	v_mfma_f32_16x16x32_bf16 v[96:99], v[40:43], v[20:23], v[96:99]
	v_mfma_f32_16x16x32_bf16 v[100:103], v[40:43], v[12:15], v[100:103]
	v_mfma_f32_16x16x32_bf16 v[106:109], v[40:43], v[4:7], v[106:109]
	v_mfma_f32_16x16x32_bf16 v[40:43], v[40:43], v[0:3], v[84:87]
	s_waitcnt lgkmcnt(2)
	v_mfma_f32_16x16x32_bf16 v[84:87], v[44:47], v[20:23], v[88:91]
	v_mfma_f32_16x16x32_bf16 v[76:79], v[44:47], v[4:7], v[76:79]
	v_mfma_f32_16x16x32_bf16 v[88:91], v[44:47], v[0:3], v[92:95]
	s_waitcnt lgkmcnt(1)
	v_mfma_f32_16x16x32_bf16 v[92:95], v[52:55], v[4:7], v[110:113]
	v_mfma_f32_16x16x32_bf16 v[110:113], v[52:55], v[0:3], v[114:117]
	s_waitcnt lgkmcnt(0)
	v_mfma_f32_16x16x32_bf16 v[122:125], v[60:63], v[4:7], v[24:27]
	v_mfma_f32_16x16x32_bf16 v[0:3], v[60:63], v[0:3], v[8:11]
	ds_read_b128 v[4:7], v67 offset:960
	s_nop 1
	ds_read_b128 v[8:11], v67 offset:17600
	ds_read_b128 v[126:129], v67 offset:34240
	ds_read_b128 v[130:133], v67 offset:50880
	s_waitcnt vmcnt(0)
	s_load_dwordx2 s[4:5], s[26:27], 0xb0
	v_mfma_f32_16x16x32_bf16 v[68:71], v[44:47], v[12:15], v[68:71]
	v_lshl_add_u32 v67, v64, 1, 16
	v_mfma_f32_16x16x32_bf16 v[80:83], v[52:55], v[12:15], v[80:83]
	v_mfma_f32_16x16x32_bf16 v[114:117], v[60:63], v[20:23], v[36:39]
	v_mfma_f32_16x16x32_bf16 v[118:121], v[60:63], v[12:15], v[28:31]
	s_waitcnt lgkmcnt(0)
	v_mfma_f32_16x16x32_bf16 v[134:137], v[4:7], v[48:51], v[96:99]
	v_mfma_f32_16x16x32_bf16 v[44:47], v[4:7], v[32:35], v[100:103]
	v_mfma_f32_16x16x32_bf16 v[28:31], v[4:7], v[16:19], v[106:109]
	v_mfma_f32_16x16x32_bf16 v[12:15], v[4:7], v[56:59], v[40:43]
	v_mfma_f32_16x16x32_bf16 v[60:63], v[8:11], v[48:51], v[84:87]
	v_mfma_f32_16x16x32_bf16 v[40:43], v[8:11], v[32:35], v[68:71]
	v_mfma_f32_16x16x32_bf16 v[24:27], v[8:11], v[16:19], v[76:79]
	v_mfma_f32_16x16x32_bf16 v[8:11], v[8:11], v[56:59], v[88:91]
	s_nop 1
	v_lshl_add_u64 v[76:77], v[64:65], 1, s[2:3]
	v_mfma_f32_16x16x32_bf16 v[4:7], v[126:129], v[56:59], v[110:113]
	v_mfma_f32_16x16x32_bf16 v[0:3], v[130:133], v[56:59], v[0:3]
	v_or_b32_e32 v56, s11, v104
	v_ashrrev_i32_e32 v57, 31, v56
	v_lshl_add_u64 v[56:57], v[56:57], 2, s[4:5]
	v_mfma_f32_16x16x32_bf16 v[72:75], v[52:55], v[20:23], v[72:75]
	s_movk_i32 s4, 0x1040
	v_mfma_f32_16x16x32_bf16 v[20:23], v[126:129], v[16:19], v[92:95]
	global_load_dword v97, v[56:57], off
	global_load_dword v96, v[56:57], off offset:64
	s_nop 0
	global_load_dword v94, v[56:57], off offset:128
	global_load_dword v92, v[56:57], off offset:192
	v_mad_u32_u24 v95, v66, s4, v67
	ds_read_u16 v57, v95
	v_lshlrev_b32_e32 v56, 2, v66
	v_mfma_f32_16x16x32_bf16 v[52:55], v[126:129], v[48:51], v[72:75]
	v_or_b32_e32 v70, 48, v56
	s_movk_i32 s4, 0x410
	s_waitcnt lgkmcnt(0)
	v_lshlrev_b32_e32 v57, 16, v57
	v_or_b32_e32 v74, s10, v56
	v_ashrrev_i32_e32 v75, 31, v74
	v_mfma_f32_16x16x32_bf16 v[36:39], v[126:129], v[32:35], v[80:83]
	s_waitcnt vmcnt(3)
	v_add_f32_e32 v58, v134, v97
	v_mul_f32_e32 v58, 0xbfb8aa3b, v58
	v_exp_f32_e32 v58, v58
	v_add_f32_e32 v60, v60, v97
	v_mul_f32_e32 v60, 0xbfb8aa3b, v60
	v_exp_f32_e32 v60, v60
	v_add_f32_e32 v58, 1.0, v58
	v_rcp_f32_e32 v58, v58
	v_add_f32_e32 v61, v61, v97
	v_add_f32_e32 v60, 1.0, v60
	v_rcp_f32_e32 v60, v60
	v_mul_f32_e32 v57, v58, v57
	v_cvt_pk_bf16_f32 v65, v57, s0
	v_lshlrev_b64 v[56:57], 12, v[74:75]
	v_lshl_add_u64 v[58:59], v[76:77], 0, v[56:57]
	global_store_short v[58:59], v65, off
	v_add_f32_e32 v59, v135, v97
	v_mul_f32_e32 v59, 0xbfb8aa3b, v59
	v_exp_f32_e32 v59, v59
	v_mad_u32_u24 v65, v70, s4, v67
	v_add_u32_e32 v93, 0xffff4110, v65
	ds_read_u16 v58, v93
	v_add_f32_e32 v59, 1.0, v59
	v_rcp_f32_e32 v59, v59
	v_mul_f32_e32 v61, 0xbfb8aa3b, v61
	v_exp_f32_e32 v61, v61
	s_waitcnt lgkmcnt(0)
	v_lshlrev_b32_e32 v58, 16, v58
	v_mul_f32_e32 v58, v59, v58
	v_cvt_pk_bf16_f32 v68, v58, s0
	v_or_b32_e32 v58, 1, v74
	v_ashrrev_i32_e32 v59, 31, v58
	v_lshlrev_b64 v[58:59], 12, v[58:59]
	v_lshl_add_u64 v[66:67], v[76:77], 0, v[58:59]
	global_store_short v[66:67], v68, off
	v_add_f32_e32 v67, v136, v97
	v_mul_f32_e32 v67, 0xbfb8aa3b, v67
	v_exp_f32_e32 v67, v67
	ds_read_u16 v66, v93 offset:1040
	v_add_f32_e32 v61, 1.0, v61
	v_rcp_f32_e32 v61, v61
	v_add_f32_e32 v67, 1.0, v67
	v_rcp_f32_e32 v67, v67
	s_waitcnt lgkmcnt(0)
	v_lshlrev_b32_e32 v66, 16, v66
	v_add_f32_e32 v62, v62, v97
	v_mul_f32_e32 v62, 0xbfb8aa3b, v62
	v_mul_f32_e32 v66, v67, v66
	v_cvt_pk_bf16_f32 v71, v66, s0
	v_or_b32_e32 v66, 2, v74
	v_ashrrev_i32_e32 v67, 31, v66
	v_lshlrev_b64 v[66:67], 12, v[66:67]
	v_lshl_add_u64 v[68:69], v[76:77], 0, v[66:67]
	global_store_short v[68:69], v71, off
	v_add_f32_e32 v69, v137, v97
	v_mul_f32_e32 v69, 0xbfb8aa3b, v69
	v_exp_f32_e32 v69, v69
	ds_read_u16 v68, v93 offset:2080
	v_exp_f32_e32 v62, v62
	v_add_f32_e32 v63, v63, v97
	v_add_f32_e32 v69, 1.0, v69
	v_rcp_f32_e32 v69, v69
	s_waitcnt lgkmcnt(0)
; __device__ __forceinline__ float bf2f(unsigned short h) { return __uint_as_float(((unsigned)h) << 16); }
; __device__ __forceinline__ unsigned short f2bf(float f) { return (unsigned short)(cvt_pk(f, 0.f) & 0xffffu); }
; __device__ __forceinline__ float sigmoidf_(float x) { return fast_rcp(1.f + fast_exp2(-x * LOG2E)); }
; __device__ __forceinline__ void s5_unit(ArgsP A, int l, int unit, unsigned char* lds, int wave_, int lane_) {
;     ...
;     float bglv[4];
; #pragma unroll
;     for (int nb = 0; nb < 4; ++nb) bglv[nb] = A->in[22][l * 512 + 64 * wave + 16 * nb + (lane & 15)];
; #pragma unroll
;     for (int nb = 0; nb < 4; ++nb) { const int n = 64 * wave + 16 * nb + (lane & 15); const float bgl = bglv[nb];
; #pragma unroll
;         for (int mb = 0; mb < 4; ++mb)
; #pragma unroll
;             for (int i = 0; i < 4; ++i) { const int t = 16 * mb + 4 * (lane >> 4) + i; const float yv = bf2f(ys[t * YS_STRIDE + n]);
;                 MIX[(size_t)(rowbase + t) * DM + n] = f2bf(yv * sigmoidf_(acc[mb][nb][i] + bgl)); } }
	v_lshlrev_b32_e32 v68, 16, v68
	v_add_f32_e32 v62, 1.0, v62
	v_rcp_f32_e32 v62, v62
	v_mul_f32_e32 v68, v69, v68
	v_cvt_pk_bf16_f32 v71, v68, s0
	v_or_b32_e32 v68, 3, v74
	v_ashrrev_i32_e32 v69, 31, v68
	v_lshlrev_b64 v[78:79], 12, v[68:69]
	v_lshl_add_u64 v[68:69], v[76:77], 0, v[78:79]
	global_store_short v[68:69], v71, off
	ds_read_u16 v68, v93 offset:15600
	v_mul_f32_e32 v63, 0xbfb8aa3b, v63
	v_exp_f32_e32 v63, v63
	v_add_f32_e32 v52, v52, v97
	v_mul_f32_e32 v52, 0xbfb8aa3b, v52
	s_waitcnt lgkmcnt(0)
	v_lshlrev_b32_e32 v68, 16, v68
	v_mul_f32_e32 v60, v60, v68
	v_or_b32_e32 v68, 16, v74
	v_ashrrev_i32_e32 v69, 31, v68
	v_lshlrev_b64 v[80:81], 12, v[68:69]
	v_cvt_pk_bf16_f32 v60, v60, s0
	v_lshl_add_u64 v[68:69], v[76:77], 0, v[80:81]
	global_store_short v[68:69], v60, off
	ds_read_u16 v60, v93 offset:16640
	v_add_f32_e32 v63, 1.0, v63
	v_rcp_f32_e32 v63, v63
	v_exp_f32_e32 v52, v52
	v_add_f32_e32 v53, v53, v97
	s_waitcnt lgkmcnt(0)
	v_lshlrev_b32_e32 v60, 16, v60
	v_mul_f32_e32 v60, v61, v60
	v_cvt_pk_bf16_f32 v71, v60, s0
	v_or_b32_e32 v60, 17, v74
	v_ashrrev_i32_e32 v61, 31, v60
	v_lshlrev_b64 v[60:61], 12, v[60:61]
	v_lshl_add_u64 v[68:69], v[76:77], 0, v[60:61]
	global_store_short v[68:69], v71, off
	ds_read_u16 v68, v93 offset:17680
	v_add_f32_e32 v52, 1.0, v52
	v_rcp_f32_e32 v52, v52
	v_mul_f32_e32 v53, 0xbfb8aa3b, v53
	v_exp_f32_e32 v53, v53
	s_waitcnt lgkmcnt(0)
	v_lshlrev_b32_e32 v68, 16, v68
	v_mul_f32_e32 v62, v62, v68
	v_or_b32_e32 v68, 18, v74
	v_ashrrev_i32_e32 v69, 31, v68
	v_lshlrev_b64 v[82:83], 12, v[68:69]
	v_cvt_pk_bf16_f32 v62, v62, s0
	v_lshl_add_u64 v[68:69], v[76:77], 0, v[82:83]
	global_store_short v[68:69], v62, off
	ds_read_u16 v62, v93 offset:18720
	v_add_f32_e32 v53, 1.0, v53
	v_rcp_f32_e32 v53, v53
	v_mfma_f32_16x16x32_bf16 v[48:51], v[130:133], v[48:51], v[114:117]
	s_waitcnt vmcnt(9)
	v_add_f32_e32 v44, v44, v96
	s_waitcnt lgkmcnt(0)
	v_lshlrev_b32_e32 v62, 16, v62
	v_mul_f32_e32 v62, v63, v62
	v_cvt_pk_bf16_f32 v71, v62, s0
	v_or_b32_e32 v62, 19, v74
	v_ashrrev_i32_e32 v63, 31, v62
	v_lshlrev_b64 v[62:63], 12, v[62:63]
	v_lshl_add_u64 v[68:69], v[76:77], 0, v[62:63]
	global_store_short v[68:69], v71, off
	ds_read_u16 v68, v93 offset:32240
	v_add_f32_e32 v48, v48, v97
	v_mul_f32_e32 v48, 0xbfb8aa3b, v48
	v_exp_f32_e32 v48, v48
	v_add_f32_e32 v49, v49, v97
	s_waitcnt lgkmcnt(0)
	v_lshlrev_b32_e32 v68, 16, v68
	v_mul_f32_e32 v52, v52, v68
	v_or_b32_e32 v68, 32, v74
	v_ashrrev_i32_e32 v69, 31, v68
	v_lshlrev_b64 v[84:85], 12, v[68:69]
	v_cvt_pk_bf16_f32 v52, v52, s0
	v_lshl_add_u64 v[68:69], v[76:77], 0, v[84:85]
	global_store_short v[68:69], v52, off
	ds_read_u16 v52, v93 offset:33280
	v_add_f32_e32 v48, 1.0, v48
	v_rcp_f32_e32 v48, v48
	v_mul_f32_e32 v49, 0xbfb8aa3b, v49
	v_exp_f32_e32 v49, v49
	s_waitcnt lgkmcnt(0)
	v_lshlrev_b32_e32 v52, 16, v52
	v_mul_f32_e32 v52, v53, v52
	v_cvt_pk_bf16_f32 v68, v52, s0
	v_or_b32_e32 v52, 33, v74
	v_ashrrev_i32_e32 v53, 31, v52
	v_lshlrev_b64 v[86:87], 12, v[52:53]
	v_lshl_add_u64 v[52:53], v[76:77], 0, v[86:87]
	global_store_short v[52:53], v68, off
	v_add_f32_e32 v53, v54, v97
	v_mul_f32_e32 v53, 0xbfb8aa3b, v53
	v_exp_f32_e32 v53, v53
	ds_read_u16 v52, v93 offset:34320
	v_add_f32_e32 v49, 1.0, v49
	v_rcp_f32_e32 v49, v49
	v_add_f32_e32 v53, 1.0, v53
	v_rcp_f32_e32 v53, v53
	s_waitcnt lgkmcnt(0)
	v_lshlrev_b32_e32 v52, 16, v52
	v_mul_f32_e32 v44, 0xbfb8aa3b, v44
	v_exp_f32_e32 v44, v44
	v_mul_f32_e32 v52, v53, v52
	v_cvt_pk_bf16_f32 v54, v52, s0
	v_or_b32_e32 v52, 34, v74
	v_ashrrev_i32_e32 v53, 31, v52
	v_lshlrev_b64 v[88:89], 12, v[52:53]
	v_lshl_add_u64 v[52:53], v[76:77], 0, v[88:89]
	global_store_short v[52:53], v54, off
	v_add_f32_e32 v53, v55, v97
	v_mul_f32_e32 v53, 0xbfb8aa3b, v53
	v_exp_f32_e32 v53, v53
	ds_read_u16 v52, v93 offset:35360
	v_add_f32_e32 v44, 1.0, v44
	v_rcp_f32_e32 v44, v44
	v_add_f32_e32 v53, 1.0, v53
	v_rcp_f32_e32 v53, v53
	s_waitcnt lgkmcnt(0)
	v_lshlrev_b32_e32 v52, 16, v52
	v_add_f32_e32 v45, v45, v96
	v_mul_f32_e32 v45, 0xbfb8aa3b, v45
	v_mul_f32_e32 v52, v53, v52
	v_cvt_pk_bf16_f32 v54, v52, s0
	v_or_b32_e32 v52, 35, v74
	v_ashrrev_i32_e32 v53, 31, v52
	v_lshlrev_b64 v[90:91], 12, v[52:53]
	v_lshl_add_u64 v[52:53], v[76:77], 0, v[90:91]
	global_store_short v[52:53], v54, off
	ds_read_u16 v52, v65
	v_exp_f32_e32 v45, v45
	v_add_f32_e32 v46, v46, v96
	v_mul_f32_e32 v46, 0xbfb8aa3b, v46
	v_exp_f32_e32 v46, v46
	s_waitcnt lgkmcnt(0)
	v_lshlrev_b32_e32 v52, 16, v52
	v_mul_f32_e32 v48, v48, v52
	v_or_b32_e32 v52, s10, v70
	v_ashrrev_i32_e32 v53, 31, v52
	v_lshlrev_b64 v[68:69], 12, v[52:53]
	v_cvt_pk_bf16_f32 v48, v48, s0
	v_lshl_add_u64 v[52:53], v[76:77], 0, v[68:69]
	global_store_short v[52:53], v48, off
	ds_read_u16 v48, v65 offset:1040
	v_add_f32_e32 v45, 1.0, v45
	v_rcp_f32_e32 v45, v45
	v_add_f32_e32 v46, 1.0, v46
	v_rcp_f32_e32 v46, v46
	s_waitcnt lgkmcnt(0)
	v_lshlrev_b32_e32 v48, 16, v48
	v_mul_f32_e32 v48, v49, v48
	v_cvt_pk_bf16_f32 v52, v48, s0
	v_or_b32_e32 v48, 49, v74
	v_ashrrev_i32_e32 v49, 31, v48
	v_lshlrev_b64 v[70:71], 12, v[48:49]
	v_lshl_add_u64 v[48:49], v[76:77], 0, v[70:71]
	global_store_short v[48:49], v52, off
	v_add_f32_e32 v49, v50, v97
	v_mul_f32_e32 v49, 0xbfb8aa3b, v49
	v_exp_f32_e32 v49, v49
	ds_read_u16 v48, v65 offset:2080
	v_add_f32_e32 v47, v47, v96
	v_mul_f32_e32 v47, 0xbfb8aa3b, v47
	v_add_f32_e32 v49, 1.0, v49
	v_rcp_f32_e32 v49, v49
	s_waitcnt lgkmcnt(0)
; __device__ __forceinline__ float bf2f(unsigned short h) { return __uint_as_float(((unsigned)h) << 16); }
; __device__ __forceinline__ unsigned short f2bf(float f) { return (unsigned short)(cvt_pk(f, 0.f) & 0xffffu); }
; __device__ __forceinline__ float sigmoidf_(float x) { return fast_rcp(1.f + fast_exp2(-x * LOG2E)); }
; __device__ __forceinline__ void s5_unit(ArgsP A, int l, int unit, unsigned char* lds, int wave_, int lane_) {
;     ...
;     for (int nb = 0; nb < 4; ++nb) { const int n = 64 * wave + 16 * nb + (lane & 15); const float bgl = bglv[nb];
; #pragma unroll
;         for (int mb = 0; mb < 4; ++mb)
; #pragma unroll
;             for (int i = 0; i < 4; ++i) { const int t = 16 * mb + 4 * (lane >> 4) + i; const float yv = bf2f(ys[t * YS_STRIDE + n]);
;                 MIX[(size_t)(rowbase + t) * DM + n] = f2bf(yv * sigmoidf_(acc[mb][nb][i] + bgl)); } }
;     __syncthreads();
	v_lshlrev_b32_e32 v48, 16, v48
	v_exp_f32_e32 v47, v47
	v_add_f32_e32 v40, v40, v96
	v_mul_f32_e32 v48, v49, v48
	v_cvt_pk_bf16_f32 v50, v48, s0
	v_or_b32_e32 v48, 50, v74
	v_ashrrev_i32_e32 v49, 31, v48
	v_lshlrev_b64 v[72:73], 12, v[48:49]
	v_lshl_add_u64 v[48:49], v[76:77], 0, v[72:73]
	global_store_short v[48:49], v50, off
	v_add_f32_e32 v49, v51, v97
	v_mul_f32_e32 v49, 0xbfb8aa3b, v49
	v_exp_f32_e32 v49, v49
	ds_read_u16 v48, v65 offset:3120
	v_add_f32_e32 v47, 1.0, v47
	v_rcp_f32_e32 v47, v47
	v_add_f32_e32 v49, 1.0, v49
	v_rcp_f32_e32 v49, v49
	s_waitcnt lgkmcnt(0)
	v_lshlrev_b32_e32 v48, 16, v48
	v_mul_f32_e32 v40, 0xbfb8aa3b, v40
	v_exp_f32_e32 v40, v40
	v_mul_f32_e32 v48, v49, v48
	v_cvt_pk_bf16_f32 v50, v48, s0
	v_or_b32_e32 v48, 51, v74
	v_ashrrev_i32_e32 v49, 31, v48
	v_lshlrev_b64 v[74:75], 12, v[48:49]
	v_lshl_add_u64 v[48:49], v[76:77], 0, v[74:75]
	global_store_short v[48:49], v50, off
	ds_read_u16 v48, v95 offset:32
	v_or_b32_e32 v50, 16, v64
	v_ashrrev_i32_e32 v51, 31, v50
	v_lshlrev_b64 v[76:77], 1, v[50:51]
	v_add_f32_e32 v40, 1.0, v40
	s_waitcnt lgkmcnt(0)
	v_lshlrev_b32_e32 v48, 16, v48
	v_mul_f32_e32 v44, v44, v48
	v_lshl_add_u64 v[48:49], s[2:3], 0, v[56:57]
	v_cvt_pk_bf16_f32 v44, v44, s0
	v_lshl_add_u64 v[50:51], v[48:49], 0, v[76:77]
	global_store_short v[50:51], v44, off
	ds_read_u16 v44, v93 offset:32
	v_rcp_f32_e32 v40, v40
	v_add_f32_e32 v41, v41, v96
	v_mul_f32_e32 v41, 0xbfb8aa3b, v41
	v_exp_f32_e32 v41, v41
	s_waitcnt lgkmcnt(0)
	v_lshlrev_b32_e32 v44, 16, v44
	v_mul_f32_e32 v44, v45, v44
	v_cvt_pk_bf16_f32 v52, v44, s0
	v_lshl_add_u64 v[44:45], s[2:3], 0, v[58:59]
	v_lshl_add_u64 v[50:51], v[44:45], 0, v[76:77]
	global_store_short v[50:51], v52, off
	ds_read_u16 v50, v93 offset:1072
	v_add_f32_e32 v41, 1.0, v41
	v_rcp_f32_e32 v41, v41
	v_add_f32_e32 v36, v36, v96
	v_mul_f32_e32 v36, 0xbfb8aa3b, v36
	s_waitcnt lgkmcnt(0)
	v_lshlrev_b32_e32 v50, 16, v50
	v_mul_f32_e32 v46, v46, v50
	v_lshl_add_u64 v[50:51], s[2:3], 0, v[66:67]
	v_cvt_pk_bf16_f32 v46, v46, s0
	v_lshl_add_u64 v[52:53], v[50:51], 0, v[76:77]
	global_store_short v[52:53], v46, off
	ds_read_u16 v46, v93 offset:2112
	v_exp_f32_e32 v36, v36
	v_add_f32_e32 v37, v37, v96
	v_mul_f32_e32 v37, 0xbfb8aa3b, v37
	v_exp_f32_e32 v37, v37
	s_waitcnt lgkmcnt(0)
	v_lshlrev_b32_e32 v46, 16, v46
	v_mul_f32_e32 v46, v47, v46
	v_cvt_pk_bf16_f32 v54, v46, s0
	v_lshl_add_u64 v[46:47], s[2:3], 0, v[78:79]
	v_lshl_add_u64 v[52:53], v[46:47], 0, v[76:77]
	global_store_short v[52:53], v54, off
	ds_read_u16 v52, v93 offset:15632
	v_add_f32_e32 v36, 1.0, v36
	v_rcp_f32_e32 v36, v36
	v_add_f32_e32 v37, 1.0, v37
	v_rcp_f32_e32 v37, v37
	s_waitcnt lgkmcnt(0)
	v_lshlrev_b32_e32 v52, 16, v52
	v_mul_f32_e32 v40, v40, v52
	v_lshl_add_u64 v[52:53], s[2:3], 0, v[80:81]
	v_cvt_pk_bf16_f32 v40, v40, s0
	v_lshl_add_u64 v[54:55], v[52:53], 0, v[76:77]
	global_store_short v[54:55], v40, off
	ds_read_u16 v40, v93 offset:16672
	v_lshl_add_u64 v[54:55], s[2:3], 0, v[60:61]
	v_lshl_add_u64 v[60:61], s[2:3], 0, v[86:87]
	v_mfma_f32_16x16x32_bf16 v[32:35], v[130:133], v[32:35], v[118:121]
	v_lshl_add_u64 v[66:67], s[2:3], 0, v[90:91]
	s_waitcnt lgkmcnt(0)
	v_lshlrev_b32_e32 v40, 16, v40
	v_mul_f32_e32 v40, v41, v40
	v_cvt_pk_bf16_f32 v56, v40, s0
	v_lshl_add_u64 v[40:41], v[54:55], 0, v[76:77]
	global_store_short v[40:41], v56, off
	v_add_f32_e32 v41, v42, v96
	v_mul_f32_e32 v41, 0xbfb8aa3b, v41
	v_exp_f32_e32 v41, v41
	ds_read_u16 v40, v93 offset:17712
	v_lshl_add_u64 v[56:57], s[2:3], 0, v[82:83]
	v_add_f32_e32 v32, v32, v96
	v_add_f32_e32 v41, 1.0, v41
	v_rcp_f32_e32 v41, v41
	s_waitcnt lgkmcnt(0)
	v_lshlrev_b32_e32 v40, 16, v40
	v_mul_f32_e32 v32, 0xbfb8aa3b, v32
	v_exp_f32_e32 v32, v32
	v_mul_f32_e32 v40, v41, v40
	v_cvt_pk_bf16_f32 v42, v40, s0
	v_lshl_add_u64 v[40:41], v[56:57], 0, v[76:77]
	global_store_short v[40:41], v42, off
	v_add_f32_e32 v41, v43, v96
	v_mul_f32_e32 v41, 0xbfb8aa3b, v41
	v_exp_f32_e32 v41, v41
	ds_read_u16 v40, v93 offset:18752
	v_lshl_add_u64 v[42:43], s[2:3], 0, v[62:63]
	v_lshl_add_u64 v[62:63], s[2:3], 0, v[88:89]
	v_add_f32_e32 v41, 1.0, v41
	v_rcp_f32_e32 v41, v41
	s_waitcnt lgkmcnt(0)
	v_lshlrev_b32_e32 v40, 16, v40
	v_add_f32_e32 v32, 1.0, v32
	v_rcp_f32_e32 v32, v32
	v_mul_f32_e32 v40, v41, v40
	v_cvt_pk_bf16_f32 v58, v40, s0
	v_lshl_add_u64 v[40:41], v[42:43], 0, v[76:77]
	global_store_short v[40:41], v58, off
	ds_read_u16 v40, v93 offset:32272
	v_lshl_add_u64 v[58:59], s[2:3], 0, v[84:85]
	v_add_f32_e32 v33, v33, v96
	v_mul_f32_e32 v33, 0xbfb8aa3b, v33
	v_exp_f32_e32 v33, v33
	s_waitcnt lgkmcnt(0)
	v_lshlrev_b32_e32 v40, 16, v40
	v_mul_f32_e32 v36, v36, v40
	v_cvt_pk_bf16_f32 v36, v36, s0
	v_lshl_add_u64 v[40:41], v[58:59], 0, v[76:77]
	global_store_short v[40:41], v36, off
	ds_read_u16 v36, v93 offset:33312
	v_add_f32_e32 v33, 1.0, v33
	v_rcp_f32_e32 v33, v33
	s_waitcnt vmcnt(26)
	v_add_f32_e32 v28, v28, v94
	v_mul_f32_e32 v28, 0xbfb8aa3b, v28
	s_waitcnt lgkmcnt(0)
	v_lshlrev_b32_e32 v36, 16, v36
	v_mul_f32_e32 v36, v37, v36
	v_cvt_pk_bf16_f32 v40, v36, s0
	v_lshl_add_u64 v[36:37], v[60:61], 0, v[76:77]
	global_store_short v[36:37], v40, off
	v_add_f32_e32 v37, v38, v96
	v_mul_f32_e32 v37, 0xbfb8aa3b, v37
	v_exp_f32_e32 v37, v37
	ds_read_u16 v36, v93 offset:34352
	v_exp_f32_e32 v28, v28
	v_add_f32_e32 v29, v29, v94
	v_add_f32_e32 v37, 1.0, v37
	v_rcp_f32_e32 v37, v37
	s_waitcnt lgkmcnt(0)
	v_lshlrev_b32_e32 v36, 16, v36
	v_add_f32_e32 v28, 1.0, v28
	v_rcp_f32_e32 v28, v28
	v_mul_f32_e32 v36, v37, v36
	v_cvt_pk_bf16_f32 v38, v36, s0
	v_lshl_add_u64 v[36:37], v[62:63], 0, v[76:77]
	global_store_short v[36:37], v38, off
	v_add_f32_e32 v37, v39, v96
	v_mul_f32_e32 v37, 0xbfb8aa3b, v37
	v_exp_f32_e32 v37, v37
	ds_read_u16 v36, v93 offset:35392
	v_mul_f32_e32 v29, 0xbfb8aa3b, v29
	v_exp_f32_e32 v29, v29
	v_add_f32_e32 v37, 1.0, v37
	v_rcp_f32_e32 v37, v37
	s_waitcnt lgkmcnt(0)
; __device__ __forceinline__ float bf2f(unsigned short h) { return __uint_as_float(((unsigned)h) << 16); }
; __device__ __forceinline__ unsigned short f2bf(float f) { return (unsigned short)(cvt_pk(f, 0.f) & 0xffffu); }
; __device__ __forceinline__ float sigmoidf_(float x) { return fast_rcp(1.f + fast_exp2(-x * LOG2E)); }
; __device__ __forceinline__ void s5_unit(ArgsP A, int l, int unit, unsigned char* lds, int wave_, int lane_) {
;     ...
;     for (int nb = 0; nb < 4; ++nb) { const int n = 64 * wave + 16 * nb + (lane & 15); const float bgl = bglv[nb];
; #pragma unroll
;         for (int mb = 0; mb < 4; ++mb)
; #pragma unroll
;             for (int i = 0; i < 4; ++i) { const int t = 16 * mb + 4 * (lane >> 4) + i; const float yv = bf2f(ys[t * YS_STRIDE + n]);
;                 MIX[(size_t)(rowbase + t) * DM + n] = f2bf(yv * sigmoidf_(acc[mb][nb][i] + bgl)); } }
;     __syncthreads();
	v_lshlrev_b32_e32 v36, 16, v36
	v_add_f32_e32 v29, 1.0, v29
	v_rcp_f32_e32 v29, v29
	v_mul_f32_e32 v36, v37, v36
	v_cvt_pk_bf16_f32 v38, v36, s0
	v_lshl_add_u64 v[36:37], v[66:67], 0, v[76:77]
	global_store_short v[36:37], v38, off
	ds_read_u16 v36, v65 offset:32
	v_add_f32_e32 v24, v24, v94
	v_mul_f32_e32 v24, 0xbfb8aa3b, v24
	v_exp_f32_e32 v24, v24
	v_add_f32_e32 v25, v25, v94
	s_waitcnt lgkmcnt(0)
	v_lshlrev_b32_e32 v36, 16, v36
	v_mul_f32_e32 v32, v32, v36
	v_lshl_add_u64 v[36:37], s[2:3], 0, v[68:69]
	v_cvt_pk_bf16_f32 v32, v32, s0
	v_lshl_add_u64 v[38:39], v[36:37], 0, v[76:77]
	global_store_short v[38:39], v32, off
	ds_read_u16 v32, v65 offset:1072
	v_lshl_add_u64 v[38:39], s[2:3], 0, v[70:71]
	v_add_f32_e32 v24, 1.0, v24
	v_rcp_f32_e32 v24, v24
	v_mul_f32_e32 v25, 0xbfb8aa3b, v25
	s_waitcnt lgkmcnt(0)
	v_lshlrev_b32_e32 v32, 16, v32
	v_mul_f32_e32 v32, v33, v32
	v_cvt_pk_bf16_f32 v40, v32, s0
	v_lshl_add_u64 v[32:33], v[38:39], 0, v[76:77]
	global_store_short v[32:33], v40, off
	v_add_f32_e32 v33, v34, v96
	v_mul_f32_e32 v33, 0xbfb8aa3b, v33
	v_exp_f32_e32 v33, v33
	ds_read_u16 v32, v65 offset:2112
	v_lshl_add_u64 v[40:41], s[2:3], 0, v[72:73]
	v_exp_f32_e32 v25, v25
	v_add_f32_e32 v33, 1.0, v33
	v_rcp_f32_e32 v33, v33
	s_waitcnt lgkmcnt(0)
	v_lshlrev_b32_e32 v32, 16, v32
	v_add_f32_e32 v25, 1.0, v25
	v_rcp_f32_e32 v25, v25
	v_mul_f32_e32 v32, v33, v32
	v_cvt_pk_bf16_f32 v34, v32, s0
	v_lshl_add_u64 v[32:33], v[40:41], 0, v[76:77]
	global_store_short v[32:33], v34, off
	v_add_f32_e32 v33, v35, v96
	v_mul_f32_e32 v33, 0xbfb8aa3b, v33
	v_exp_f32_e32 v33, v33
	ds_read_u16 v32, v65 offset:3152
	v_add_f32_e32 v20, v20, v94
	v_mul_f32_e32 v20, 0xbfb8aa3b, v20
	v_add_f32_e32 v33, 1.0, v33
	v_rcp_f32_e32 v33, v33
	s_waitcnt lgkmcnt(0)
	v_lshlrev_b32_e32 v32, 16, v32
	v_exp_f32_e32 v20, v20
	v_add_f32_e32 v21, v21, v94
	v_mul_f32_e32 v32, v33, v32
	v_cvt_pk_bf16_f32 v68, v32, s0
	v_lshl_add_u64 v[32:33], s[2:3], 0, v[74:75]
	v_lshl_add_u64 v[34:35], v[32:33], 0, v[76:77]
	global_store_short v[34:35], v68, off
	ds_read_u16 v68, v95 offset:64
	v_or_b32_e32 v34, 32, v64
	v_ashrrev_i32_e32 v35, 31, v34
	v_lshlrev_b64 v[34:35], 1, v[34:35]
	v_add_f32_e32 v20, 1.0, v20
	s_waitcnt lgkmcnt(0)
	v_lshlrev_b32_e32 v68, 16, v68
	v_mul_f32_e32 v28, v28, v68
	v_cvt_pk_bf16_f32 v28, v28, s0
	v_lshl_add_u64 v[68:69], v[48:49], 0, v[34:35]
	global_store_short v[68:69], v28, off
	ds_read_u16 v28, v93 offset:64
	v_rcp_f32_e32 v20, v20
	v_mul_f32_e32 v21, 0xbfb8aa3b, v21
	v_exp_f32_e32 v21, v21
	v_mfma_f32_16x16x32_bf16 v[16:19], v[130:133], v[16:19], v[122:125]
	s_waitcnt lgkmcnt(0)
	v_lshlrev_b32_e32 v28, 16, v28
	v_mul_f32_e32 v28, v29, v28
	v_cvt_pk_bf16_f32 v68, v28, s0
	v_lshl_add_u64 v[28:29], v[44:45], 0, v[34:35]
	global_store_short v[28:29], v68, off
	v_add_f32_e32 v29, v30, v94
	v_mul_f32_e32 v29, 0xbfb8aa3b, v29
	v_exp_f32_e32 v29, v29
	ds_read_u16 v28, v93 offset:1104
	v_add_f32_e32 v21, 1.0, v21
	v_rcp_f32_e32 v21, v21
	v_add_f32_e32 v29, 1.0, v29
	v_rcp_f32_e32 v29, v29
	s_waitcnt lgkmcnt(0)
	v_lshlrev_b32_e32 v28, 16, v28
	v_add_f32_e32 v16, v16, v94
	v_mul_f32_e32 v16, 0xbfb8aa3b, v16
	v_mul_f32_e32 v28, v29, v28
	v_cvt_pk_bf16_f32 v30, v28, s0
	v_lshl_add_u64 v[28:29], v[50:51], 0, v[34:35]
	global_store_short v[28:29], v30, off
	v_add_f32_e32 v29, v31, v94
	v_mul_f32_e32 v29, 0xbfb8aa3b, v29
	v_exp_f32_e32 v29, v29
	ds_read_u16 v28, v93 offset:2144
	v_exp_f32_e32 v16, v16
	v_add_f32_e32 v17, v17, v94
	v_add_f32_e32 v29, 1.0, v29
	v_rcp_f32_e32 v29, v29
	s_waitcnt lgkmcnt(0)
	v_lshlrev_b32_e32 v28, 16, v28
	v_add_f32_e32 v16, 1.0, v16
	v_rcp_f32_e32 v16, v16
	v_mul_f32_e32 v28, v29, v28
	v_cvt_pk_bf16_f32 v30, v28, s0
	v_lshl_add_u64 v[28:29], v[46:47], 0, v[34:35]
	global_store_short v[28:29], v30, off
	ds_read_u16 v28, v93 offset:15664
	v_mul_f32_e32 v17, 0xbfb8aa3b, v17
	v_exp_f32_e32 v17, v17
	s_waitcnt vmcnt(36)
	v_add_f32_e32 v12, v12, v92
	v_mul_f32_e32 v12, 0xbfb8aa3b, v12
	s_waitcnt lgkmcnt(0)
	v_lshlrev_b32_e32 v28, 16, v28
	v_mul_f32_e32 v24, v24, v28
	v_cvt_pk_bf16_f32 v24, v24, s0
	v_lshl_add_u64 v[28:29], v[52:53], 0, v[34:35]
	global_store_short v[28:29], v24, off
	ds_read_u16 v24, v93 offset:16704
	v_add_f32_e32 v17, 1.0, v17
	v_rcp_f32_e32 v17, v17
	v_exp_f32_e32 v12, v12
	v_add_f32_e32 v13, v13, v92
	s_waitcnt lgkmcnt(0)
	v_lshlrev_b32_e32 v24, 16, v24
	v_mul_f32_e32 v24, v25, v24
	v_cvt_pk_bf16_f32 v28, v24, s0
	v_lshl_add_u64 v[24:25], v[54:55], 0, v[34:35]
	global_store_short v[24:25], v28, off
	v_add_f32_e32 v25, v26, v94
	v_mul_f32_e32 v25, 0xbfb8aa3b, v25
	v_exp_f32_e32 v25, v25
	ds_read_u16 v24, v93 offset:17744
	v_add_f32_e32 v12, 1.0, v12
	v_rcp_f32_e32 v12, v12
	v_add_f32_e32 v25, 1.0, v25
	v_rcp_f32_e32 v25, v25
	s_waitcnt lgkmcnt(0)
	v_lshlrev_b32_e32 v24, 16, v24
	v_mul_f32_e32 v13, 0xbfb8aa3b, v13
	v_exp_f32_e32 v13, v13
	v_mul_f32_e32 v24, v25, v24
	v_cvt_pk_bf16_f32 v26, v24, s0
	v_lshl_add_u64 v[24:25], v[56:57], 0, v[34:35]
	global_store_short v[24:25], v26, off
	v_add_f32_e32 v25, v27, v94
	v_mul_f32_e32 v25, 0xbfb8aa3b, v25
	v_exp_f32_e32 v25, v25
	ds_read_u16 v24, v93 offset:18784
	v_add_f32_e32 v13, 1.0, v13
	v_rcp_f32_e32 v13, v13
	v_add_f32_e32 v25, 1.0, v25
	v_rcp_f32_e32 v25, v25
	s_waitcnt lgkmcnt(0)
	v_lshlrev_b32_e32 v24, 16, v24
	v_add_f32_e32 v8, v8, v92
	v_mul_f32_e32 v8, 0xbfb8aa3b, v8
	v_mul_f32_e32 v24, v25, v24
	v_cvt_pk_bf16_f32 v26, v24, s0
	v_lshl_add_u64 v[24:25], v[42:43], 0, v[34:35]
	global_store_short v[24:25], v26, off
	ds_read_u16 v24, v93 offset:32304
	v_exp_f32_e32 v8, v8
	v_add_f32_e32 v9, v9, v92
	v_mul_f32_e32 v9, 0xbfb8aa3b, v9
	v_exp_f32_e32 v9, v9
	s_waitcnt lgkmcnt(0)
; __device__ __forceinline__ float bf2f(unsigned short h) { return __uint_as_float(((unsigned)h) << 16); }
; __device__ __forceinline__ unsigned short f2bf(float f) { return (unsigned short)(cvt_pk(f, 0.f) & 0xffffu); }
; __device__ __forceinline__ float sigmoidf_(float x) { return fast_rcp(1.f + fast_exp2(-x * LOG2E)); }
; __device__ __forceinline__ void s5_unit(ArgsP A, int l, int unit, unsigned char* lds, int wave_, int lane_) {
;     ...
;     for (int nb = 0; nb < 4; ++nb) { const int n = 64 * wave + 16 * nb + (lane & 15); const float bgl = bglv[nb];
; #pragma unroll
;         for (int mb = 0; mb < 4; ++mb)
; #pragma unroll
;             for (int i = 0; i < 4; ++i) { const int t = 16 * mb + 4 * (lane >> 4) + i; const float yv = bf2f(ys[t * YS_STRIDE + n]);
;                 MIX[(size_t)(rowbase + t) * DM + n] = f2bf(yv * sigmoidf_(acc[mb][nb][i] + bgl)); } }
;     __syncthreads();
	v_lshlrev_b32_e32 v24, 16, v24
	v_mul_f32_e32 v20, v20, v24
	v_cvt_pk_bf16_f32 v20, v20, s0
	v_lshl_add_u64 v[24:25], v[58:59], 0, v[34:35]
	global_store_short v[24:25], v20, off
	ds_read_u16 v20, v93 offset:33344
	v_add_f32_e32 v8, 1.0, v8
	v_rcp_f32_e32 v8, v8
	v_add_f32_e32 v9, 1.0, v9
	v_rcp_f32_e32 v9, v9
	s_waitcnt lgkmcnt(0)
	v_lshlrev_b32_e32 v20, 16, v20
	v_mul_f32_e32 v20, v21, v20
	v_cvt_pk_bf16_f32 v24, v20, s0
	v_lshl_add_u64 v[20:21], v[60:61], 0, v[34:35]
	global_store_short v[20:21], v24, off
	v_add_f32_e32 v21, v22, v94
	v_mul_f32_e32 v21, 0xbfb8aa3b, v21
	v_exp_f32_e32 v21, v21
	ds_read_u16 v20, v93 offset:34384
	v_add_f32_e32 v4, v4, v92
	v_mul_f32_e32 v4, 0xbfb8aa3b, v4
	v_add_f32_e32 v21, 1.0, v21
	v_rcp_f32_e32 v21, v21
	s_waitcnt lgkmcnt(0)
	v_lshlrev_b32_e32 v20, 16, v20
	v_exp_f32_e32 v4, v4
	v_add_f32_e32 v5, v5, v92
	v_mul_f32_e32 v20, v21, v20
	v_cvt_pk_bf16_f32 v22, v20, s0
	v_lshl_add_u64 v[20:21], v[62:63], 0, v[34:35]
	global_store_short v[20:21], v22, off
	v_add_f32_e32 v21, v23, v94
	v_mul_f32_e32 v21, 0xbfb8aa3b, v21
	v_exp_f32_e32 v21, v21
	ds_read_u16 v20, v93 offset:35424
	v_add_f32_e32 v4, 1.0, v4
	v_rcp_f32_e32 v4, v4
	v_add_f32_e32 v21, 1.0, v21
	v_rcp_f32_e32 v21, v21
	s_waitcnt lgkmcnt(0)
	v_lshlrev_b32_e32 v20, 16, v20
	v_mul_f32_e32 v5, 0xbfb8aa3b, v5
	v_exp_f32_e32 v5, v5
	v_mul_f32_e32 v20, v21, v20
	v_cvt_pk_bf16_f32 v22, v20, s0
	v_lshl_add_u64 v[20:21], v[66:67], 0, v[34:35]
	global_store_short v[20:21], v22, off
	ds_read_u16 v20, v65 offset:64
	v_add_f32_e32 v5, 1.0, v5
	v_rcp_f32_e32 v5, v5
	v_add_f32_e32 v0, v0, v92
	v_mul_f32_e32 v0, 0xbfb8aa3b, v0
	s_waitcnt lgkmcnt(0)
	v_lshlrev_b32_e32 v20, 16, v20
	v_mul_f32_e32 v16, v16, v20
	v_cvt_pk_bf16_f32 v16, v16, s0
	v_lshl_add_u64 v[20:21], v[36:37], 0, v[34:35]
	global_store_short v[20:21], v16, off
	ds_read_u16 v16, v65 offset:1104
	v_exp_f32_e32 v0, v0
	v_add_f32_e32 v1, v1, v92
	v_mul_f32_e32 v1, 0xbfb8aa3b, v1
	v_exp_f32_e32 v1, v1
	s_waitcnt lgkmcnt(0)
	v_lshlrev_b32_e32 v16, 16, v16
	v_mul_f32_e32 v16, v17, v16
	v_cvt_pk_bf16_f32 v20, v16, s0
	v_lshl_add_u64 v[16:17], v[38:39], 0, v[34:35]
	global_store_short v[16:17], v20, off
	v_add_f32_e32 v17, v18, v94
	v_mul_f32_e32 v17, 0xbfb8aa3b, v17
	v_exp_f32_e32 v17, v17
	ds_read_u16 v16, v65 offset:2144
	v_add_f32_e32 v0, 1.0, v0
	v_rcp_f32_e32 v0, v0
	v_add_f32_e32 v17, 1.0, v17
	v_rcp_f32_e32 v17, v17
	s_waitcnt lgkmcnt(0)
	v_lshlrev_b32_e32 v16, 16, v16
	v_add_f32_e32 v1, 1.0, v1
	v_rcp_f32_e32 v1, v1
	v_mul_f32_e32 v16, v17, v16
	v_cvt_pk_bf16_f32 v18, v16, s0
	v_lshl_add_u64 v[16:17], v[40:41], 0, v[34:35]
	global_store_short v[16:17], v18, off
	v_add_f32_e32 v17, v19, v94
	v_mul_f32_e32 v17, 0xbfb8aa3b, v17
	v_exp_f32_e32 v17, v17
	ds_read_u16 v16, v65 offset:3184
	s_mov_b64 s[2:3], 0
	v_add_f32_e32 v17, 1.0, v17
	v_rcp_f32_e32 v17, v17
	s_waitcnt lgkmcnt(0)
	v_lshlrev_b32_e32 v16, 16, v16
	v_mul_f32_e32 v16, v17, v16
	v_cvt_pk_bf16_f32 v18, v16, s0
	v_lshl_add_u64 v[16:17], v[32:33], 0, v[34:35]
	global_store_short v[16:17], v18, off
	ds_read_u16 v18, v95 offset:96
	v_or_b32_e32 v16, 48, v64
	v_ashrrev_i32_e32 v17, 31, v16
	v_lshlrev_b64 v[16:17], 1, v[16:17]
	s_waitcnt lgkmcnt(0)
	v_lshlrev_b32_e32 v18, 16, v18
	v_mul_f32_e32 v12, v12, v18
	v_cvt_pk_bf16_f32 v12, v12, s0
	v_lshl_add_u64 v[18:19], v[48:49], 0, v[16:17]
	global_store_short v[18:19], v12, off
	ds_read_u16 v12, v93 offset:96
	s_waitcnt lgkmcnt(0)
	v_lshlrev_b32_e32 v12, 16, v12
	v_mul_f32_e32 v12, v13, v12
	v_cvt_pk_bf16_f32 v18, v12, s0
	v_lshl_add_u64 v[12:13], v[44:45], 0, v[16:17]
	global_store_short v[12:13], v18, off
	v_add_f32_e32 v13, v14, v92
	v_mul_f32_e32 v13, 0xbfb8aa3b, v13
	v_exp_f32_e32 v13, v13
	ds_read_u16 v12, v93 offset:1136
	v_add_f32_e32 v13, 1.0, v13
	v_rcp_f32_e32 v13, v13
	s_waitcnt lgkmcnt(0)
; __device__ __forceinline__ float bf2f(unsigned short h) { return __uint_as_float(((unsigned)h) << 16); }
; __device__ __forceinline__ unsigned short f2bf(float f) { return (unsigned short)(cvt_pk(f, 0.f) & 0xffffu); }
; __device__ __forceinline__ float sigmoidf_(float x) { return fast_rcp(1.f + fast_exp2(-x * LOG2E)); }
; __device__ __forceinline__ void s5_unit(ArgsP A, int l, int unit, unsigned char* lds, int wave_, int lane_) {
;     ...
;     for (int nb = 0; nb < 4; ++nb) { const int n = 64 * wave + 16 * nb + (lane & 15); const float bgl = bglv[nb];
; #pragma unroll
;         for (int mb = 0; mb < 4; ++mb)
; #pragma unroll
;             for (int i = 0; i < 4; ++i) { const int t = 16 * mb + 4 * (lane >> 4) + i; const float yv = bf2f(ys[t * YS_STRIDE + n]);
;                 MIX[(size_t)(rowbase + t) * DM + n] = f2bf(yv * sigmoidf_(acc[mb][nb][i] + bgl)); } }
;     __syncthreads();
; }
	v_lshlrev_b32_e32 v12, 16, v12
	v_mul_f32_e32 v12, v13, v12
	v_cvt_pk_bf16_f32 v14, v12, s0
	v_lshl_add_u64 v[12:13], v[50:51], 0, v[16:17]
	global_store_short v[12:13], v14, off
	v_add_f32_e32 v13, v15, v92
	v_mul_f32_e32 v13, 0xbfb8aa3b, v13
	v_exp_f32_e32 v13, v13
	ds_read_u16 v12, v93 offset:2176
	v_add_f32_e32 v13, 1.0, v13
	v_rcp_f32_e32 v13, v13
	s_waitcnt lgkmcnt(0)
	v_lshlrev_b32_e32 v12, 16, v12
	v_mul_f32_e32 v12, v13, v12
	v_cvt_pk_bf16_f32 v14, v12, s0
	v_lshl_add_u64 v[12:13], v[46:47], 0, v[16:17]
	global_store_short v[12:13], v14, off
	ds_read_u16 v12, v93 offset:15696
	s_waitcnt lgkmcnt(0)
	v_lshlrev_b32_e32 v12, 16, v12
	v_mul_f32_e32 v8, v8, v12
	v_cvt_pk_bf16_f32 v8, v8, s0
	v_lshl_add_u64 v[12:13], v[52:53], 0, v[16:17]
	global_store_short v[12:13], v8, off
	ds_read_u16 v8, v93 offset:16736
	s_waitcnt lgkmcnt(0)
	v_lshlrev_b32_e32 v8, 16, v8
	v_mul_f32_e32 v8, v9, v8
	v_cvt_pk_bf16_f32 v12, v8, s0
	v_lshl_add_u64 v[8:9], v[54:55], 0, v[16:17]
	global_store_short v[8:9], v12, off
	v_add_f32_e32 v9, v10, v92
	v_mul_f32_e32 v9, 0xbfb8aa3b, v9
	v_exp_f32_e32 v9, v9
	ds_read_u16 v8, v93 offset:17776
	v_add_f32_e32 v9, 1.0, v9
	v_rcp_f32_e32 v9, v9
	s_waitcnt lgkmcnt(0)
	v_lshlrev_b32_e32 v8, 16, v8
	v_mul_f32_e32 v8, v9, v8
	v_cvt_pk_bf16_f32 v10, v8, s0
	v_lshl_add_u64 v[8:9], v[56:57], 0, v[16:17]
	global_store_short v[8:9], v10, off
	v_add_f32_e32 v9, v11, v92
	v_mul_f32_e32 v9, 0xbfb8aa3b, v9
	v_exp_f32_e32 v9, v9
	ds_read_u16 v8, v93 offset:18816
	v_add_f32_e32 v9, 1.0, v9
	v_rcp_f32_e32 v9, v9
	s_waitcnt lgkmcnt(0)
	v_lshlrev_b32_e32 v8, 16, v8
	v_mul_f32_e32 v8, v9, v8
	v_cvt_pk_bf16_f32 v10, v8, s0
	v_lshl_add_u64 v[8:9], v[42:43], 0, v[16:17]
	global_store_short v[8:9], v10, off
	ds_read_u16 v8, v93 offset:32336
	s_waitcnt lgkmcnt(0)
	v_lshlrev_b32_e32 v8, 16, v8
	v_mul_f32_e32 v4, v4, v8
	v_cvt_pk_bf16_f32 v4, v4, s0
	v_lshl_add_u64 v[8:9], v[58:59], 0, v[16:17]
	global_store_short v[8:9], v4, off
	ds_read_u16 v4, v93 offset:33376
	s_waitcnt lgkmcnt(0)
	v_lshlrev_b32_e32 v4, 16, v4
	v_mul_f32_e32 v4, v5, v4
	v_cvt_pk_bf16_f32 v8, v4, s0
	v_lshl_add_u64 v[4:5], v[60:61], 0, v[16:17]
	global_store_short v[4:5], v8, off
	v_add_f32_e32 v5, v6, v92
	v_mul_f32_e32 v5, 0xbfb8aa3b, v5
	v_exp_f32_e32 v5, v5
	ds_read_u16 v4, v93 offset:34416
	v_add_f32_e32 v5, 1.0, v5
	v_rcp_f32_e32 v5, v5
	s_waitcnt lgkmcnt(0)
	v_lshlrev_b32_e32 v4, 16, v4
	v_mul_f32_e32 v4, v5, v4
	v_cvt_pk_bf16_f32 v6, v4, s0
	v_lshl_add_u64 v[4:5], v[62:63], 0, v[16:17]
	global_store_short v[4:5], v6, off
	v_add_f32_e32 v5, v7, v92
	v_mul_f32_e32 v5, 0xbfb8aa3b, v5
	v_exp_f32_e32 v5, v5
	ds_read_u16 v4, v93 offset:35456
	v_add_f32_e32 v5, 1.0, v5
	v_rcp_f32_e32 v5, v5
	s_waitcnt lgkmcnt(0)
	v_lshlrev_b32_e32 v4, 16, v4
	v_mul_f32_e32 v4, v5, v4
	v_cvt_pk_bf16_f32 v6, v4, s0
	v_lshl_add_u64 v[4:5], v[66:67], 0, v[16:17]
	global_store_short v[4:5], v6, off
	ds_read_u16 v4, v65 offset:96
	s_waitcnt lgkmcnt(0)
	v_lshlrev_b32_e32 v4, 16, v4
	v_mul_f32_e32 v0, v0, v4
	v_cvt_pk_bf16_f32 v0, v0, s0
	v_lshl_add_u64 v[4:5], v[36:37], 0, v[16:17]
	global_store_short v[4:5], v0, off
	ds_read_u16 v0, v65 offset:1136
	s_waitcnt lgkmcnt(0)
	v_lshlrev_b32_e32 v0, 16, v0
	v_mul_f32_e32 v0, v1, v0
	v_cvt_pk_bf16_f32 v4, v0, s0
	v_lshl_add_u64 v[0:1], v[38:39], 0, v[16:17]
	global_store_short v[0:1], v4, off
	v_add_f32_e32 v1, v2, v92
	v_mul_f32_e32 v1, 0xbfb8aa3b, v1
	v_exp_f32_e32 v1, v1
	ds_read_u16 v0, v65 offset:2176
	v_add_f32_e32 v1, 1.0, v1
	v_rcp_f32_e32 v1, v1
	s_waitcnt lgkmcnt(0)
	v_lshlrev_b32_e32 v0, 16, v0
	v_mul_f32_e32 v0, v1, v0
	v_cvt_pk_bf16_f32 v2, v0, s0
	v_lshl_add_u64 v[0:1], v[40:41], 0, v[16:17]
	global_store_short v[0:1], v2, off
	v_add_f32_e32 v1, v3, v92
	v_mul_f32_e32 v1, 0xbfb8aa3b, v1
	v_exp_f32_e32 v1, v1
	ds_read_u16 v0, v65 offset:3216
	v_add_f32_e32 v1, 1.0, v1
	v_rcp_f32_e32 v1, v1
	s_waitcnt lgkmcnt(0)
	v_lshlrev_b32_e32 v0, 16, v0
	v_mul_f32_e32 v0, v1, v0
	v_cvt_pk_bf16_f32 v2, v0, s0
	v_lshl_add_u64 v[0:1], v[32:33], 0, v[16:17]
	global_store_short v[0:1], v2, off
	s_waitcnt vmcnt(63) expcnt(7) lgkmcnt(15)
	s_barrier
	s_branch .LBB0_785

; #define PG8_STAGE(bufoff, gbase, voff) do { _Pragma("unroll") for (int _i = 0; _i < 2; ++_i) \
;         __builtin_amdgcn_global_load_lds((const unsigned*)((const char*)(gbase) + (voff)[_i]), (LAS unsigned*)(lds + (bufoff) + ldsw + _i * 8192), 16, 0, 0); } while (0)
; #define PG8_LDA(dst, b, h) do { _Pragma("unroll") for (int m = 0; m < 4; ++m) _Pragma("unroll") for (int k = 0; k < 2; ++k) dst[m][k] = *(const LAS bf16x8*)(lds + PG8_SA(b, h) + aoff + m * 2048 + k * 1024); } while (0)
; #define PG8_LDB(dst, b, h) do { _Pragma("unroll") for (int n = 0; n < 2; ++n) _Pragma("unroll") for (int k = 0; k < 2; ++k) dst[n][k] = *(const LAS bf16x8*)(lds + PG8_SB(b, h) + boff + n * 2048 + k * 1024); } while (0)
; #define PG8_MMA(ai, bj, At, Bt) do { __builtin_amdgcn_s_setprio(1); _Pragma("unroll") for (int m = 0; m < 4; ++m) _Pragma("unroll") for (int n = 0; n < 2; ++n) _Pragma("unroll") for (int k = 0; k < 2; ++k) \
;         acc[ai][bj][m][n] = __builtin_amdgcn_mfma_f32_16x16x32_bf16(Bt[n][k], At[m][k], acc[ai][bj][m][n], 0, 0, 0); __builtin_amdgcn_s_setprio(0); } while (0)
; #define PG8_BAR __builtin_amdgcn_s_barrier()
; template <class Epi, bool ALIGN_EPI = PG8_ALIGN>
; __device__ __forceinline__ void gemm_phase(LAS unsigned char* lds, const Gemm g, const StaticOrder& S, const Epi& E) {
;     ...
;         const bool has_next = S.next(ui + 1, nxt);
;         const char* nA = has_next ? (const char*)g.A + (size_t)nxt.pm * tstepA : cA; const char* nB = has_next ? (const char*)g.Bt + (size_t)nxt.pn * tstepB : cB;
;         for (int t = 0; t < nt; t += 2) {
;             const bool last = (t == nt - 2);
;             const char* a1 = cA + (size_t)(t + 1) * kstep;
;             const char* a2 = last ? nA : cA + (size_t)(t + 2) * kstep; const char* b2 = last ? nB : cB + (size_t)(t + 2) * kstep;
;             const char* a3 = a2 + kstep; const char* b3 = b2 + kstep;
;             PG8_LDB(B0, 0, 0); PG8_LDB(B1, 0, 1); PG8_SCHED; PG8_LDA(At, 0, 0); PG8_STAGE(PG8_SA(1, 1), a1 + hstepA, voffA);
;             PG8_WAIT_V(8); PG8_WAIT_L(0); PG8_BAR; PG8_MMA(0, 0, At, B0); PG8_MMA(0, 1, At, B1); PG8_BAR; PG8_SCHED;
;             PG8_LDA(At, 0, 1); PG8_STAGE(PG8_SB(0, 0), b2, voffB); PG8_STAGE(PG8_SB(0, 1), b2 + hstepB, voffB); PG8_STAGE(PG8_SA(0, 0), a2, voffA);
;             PG8_WAIT_V(8); PG8_WAIT_L(0); PG8_BAR; PG8_MMA(1, 0, At, B0); PG8_MMA(1, 1, At, B1); PG8_BAR; PG8_SCHED;
.LBB0_901:
	s_add_i32 s53, s40, 2
	s_add_u32 s20, s4, 0xfff80080
	s_addc_u32 s21, s5, -1
	s_add_i32 s22, 16, 0x10000
	s_cmp_eq_u32 s47, s40
	s_cselect_b32 s41, s25, s21
	s_cselect_b32 s40, s52, s20
	s_cselect_b32 s21, s37, s43
	s_cselect_b32 s20, s36, s42
	s_add_i32 s23, 16, 0x14000
	v_add_u32_e32 v154, s22, v139
	v_add_u32_e32 v170, s23, v139
	ds_read_b128 v[142:145], v154
	ds_read_b128 v[146:149], v154 offset:1024
	ds_read_b128 v[150:153], v154 offset:2048
	ds_read_b128 v[154:157], v154 offset:3072
	ds_read_b128 v[158:161], v170
	ds_read_b128 v[162:165], v170 offset:1024
	ds_read_b128 v[166:169], v170 offset:2048
	ds_read_b128 v[170:173], v170 offset:3072
	v_lshl_add_u64 v[174:175], s[4:5], 0, v[134:135]
	s_add_i32 m0, s29, 0xc000
	ds_read_b128 v[184:187], v141
	ds_read_b128 v[188:191], v141 offset:1024
	ds_read_b128 v[192:195], v141 offset:2048
	ds_read_b128 v[196:199], v141 offset:3072
	ds_read_b128 v[200:203], v141 offset:4096
	ds_read_b128 v[204:207], v141 offset:5120
	ds_read_b128 v[208:211], v141 offset:6144
	ds_read_b128 v[212:215], v141 offset:7168
	global_load_lds_dwordx4 v[174:175], off
	v_lshl_add_u64 v[174:175], s[4:5], 0, v[136:137]
	s_add_i32 m0, s29, 0xe000
	s_nop 0
	global_load_lds_dwordx4 v[174:175], off
	s_waitcnt vmcnt(8)
	s_waitcnt lgkmcnt(0)
	s_barrier
	s_setprio 1
	s_waitcnt lgkmcnt(0)
	v_mfma_f32_16x16x32_bf16 v[120:123], v[142:145], v[184:187], v[120:123]
	v_mfma_f32_16x16x32_bf16 v[124:127], v[150:153], v[184:187], v[124:127]
	v_mfma_f32_16x16x32_bf16 v[108:111], v[142:145], v[192:195], v[108:111]
	v_mfma_f32_16x16x32_bf16 v[104:107], v[150:153], v[192:195], v[104:107]
	v_mfma_f32_16x16x32_bf16 v[92:95], v[142:145], v[200:203], v[92:95]
	v_mfma_f32_16x16x32_bf16 v[88:91], v[150:153], v[200:203], v[88:91]
	v_mfma_f32_16x16x32_bf16 v[76:79], v[142:145], v[208:211], v[76:79]
	v_mfma_f32_16x16x32_bf16 v[72:75], v[150:153], v[208:211], v[72:75]
	v_mfma_f32_16x16x32_bf16 v[120:123], v[146:149], v[188:191], v[120:123]
	v_mfma_f32_16x16x32_bf16 v[124:127], v[154:157], v[188:191], v[124:127]
	v_mfma_f32_16x16x32_bf16 v[108:111], v[146:149], v[196:199], v[108:111]
	v_mfma_f32_16x16x32_bf16 v[104:107], v[154:157], v[196:199], v[104:107]
	v_mfma_f32_16x16x32_bf16 v[92:95], v[146:149], v[204:207], v[92:95]
	v_mfma_f32_16x16x32_bf16 v[88:91], v[154:157], v[204:207], v[88:91]
	v_mfma_f32_16x16x32_bf16 v[76:79], v[146:149], v[212:215], v[76:79]
	v_mfma_f32_16x16x32_bf16 v[72:75], v[154:157], v[212:215], v[72:75]
	s_setprio 0
	s_setprio 1
	v_mfma_f32_16x16x32_bf16 v[116:119], v[158:161], v[184:187], v[116:119]
	v_mfma_f32_16x16x32_bf16 v[112:115], v[166:169], v[184:187], v[112:115]
	v_mfma_f32_16x16x32_bf16 v[100:103], v[158:161], v[192:195], v[100:103]
	v_mfma_f32_16x16x32_bf16 v[96:99], v[166:169], v[192:195], v[96:99]
	v_mfma_f32_16x16x32_bf16 v[84:87], v[158:161], v[200:203], v[84:87]
	v_mfma_f32_16x16x32_bf16 v[80:83], v[166:169], v[200:203], v[80:83]
	v_mfma_f32_16x16x32_bf16 v[68:71], v[158:161], v[208:211], v[68:71]
	v_mfma_f32_16x16x32_bf16 v[64:67], v[166:169], v[208:211], v[64:67]
	v_mfma_f32_16x16x32_bf16 v[116:119], v[162:165], v[188:191], v[116:119]
	v_mfma_f32_16x16x32_bf16 v[112:115], v[170:173], v[188:191], v[112:115]
	v_mfma_f32_16x16x32_bf16 v[100:103], v[162:165], v[196:199], v[100:103]
	v_mfma_f32_16x16x32_bf16 v[96:99], v[170:173], v[196:199], v[96:99]
	v_mfma_f32_16x16x32_bf16 v[84:87], v[162:165], v[204:207], v[84:87]
	v_mfma_f32_16x16x32_bf16 v[80:83], v[170:173], v[204:207], v[80:83]
	v_mfma_f32_16x16x32_bf16 v[68:71], v[162:165], v[212:215], v[68:71]
	v_mfma_f32_16x16x32_bf16 v[64:67], v[170:173], v[212:215], v[64:67]
	s_setprio 0
	s_barrier
	s_add_i32 s22, s22, s18
	v_lshl_add_u64 v[174:175], s[20:21], 0, v[176:177]
	s_mov_b32 m0, s22
	ds_read_b128 v[184:187], v141 offset:16384
	ds_read_b128 v[188:191], v141 offset:17408
	ds_read_b128 v[192:195], v141 offset:18432
	ds_read_b128 v[196:199], v141 offset:19456
	ds_read_b128 v[200:203], v141 offset:20480
	ds_read_b128 v[204:207], v141 offset:21504
	ds_read_b128 v[208:211], v141 offset:22528
	ds_read_b128 v[212:215], v141 offset:23552
	global_load_lds_dwordx4 v[174:175], off
	s_add_i32 m0, s22, 0x2000
	v_lshl_add_u64 v[180:181], s[20:21], 0, v[128:129]
	s_add_u32 s20, s20, s8
	s_addc_u32 s21, s21, s9
	s_add_i32 s22, s23, s18
	global_load_lds_dwordx4 v[180:181], off
	v_lshl_add_u64 v[182:183], s[20:21], 0, v[176:177]
	s_mov_b32 m0, s22
	v_lshl_add_u64 v[216:217], s[20:21], 0, v[128:129]
	global_load_lds_dwordx4 v[182:183], off
	s_add_i32 m0, s22, 0x2000
	v_lshl_add_u64 v[218:219], s[40:41], 0, v[132:133]
	global_load_lds_dwordx4 v[216:217], off
	s_mov_b32 m0, s29
	v_lshl_add_u64 v[220:221], s[40:41], 0, v[130:131]
	global_load_lds_dwordx4 v[218:219], off
	s_mov_b32 m0, s30
	s_nop 0
	global_load_lds_dwordx4 v[220:221], off
	s_nop 15
	s_nop 15
	s_waitcnt vmcnt(8)
	s_waitcnt lgkmcnt(0)
	s_barrier
; #define PG8_STAGE(bufoff, gbase, voff) do { _Pragma("unroll") for (int _i = 0; _i < 2; ++_i) \
;         __builtin_amdgcn_global_load_lds((const unsigned*)((const char*)(gbase) + (voff)[_i]), (LAS unsigned*)(lds + (bufoff) + ldsw + _i * 8192), 16, 0, 0); } while (0)
; #define PG8_LDA(dst, b, h) do { _Pragma("unroll") for (int m = 0; m < 4; ++m) _Pragma("unroll") for (int k = 0; k < 2; ++k) dst[m][k] = *(const LAS bf16x8*)(lds + PG8_SA(b, h) + aoff + m * 2048 + k * 1024); } while (0)
; #define PG8_LDB(dst, b, h) do { _Pragma("unroll") for (int n = 0; n < 2; ++n) _Pragma("unroll") for (int k = 0; k < 2; ++k) dst[n][k] = *(const LAS bf16x8*)(lds + PG8_SB(b, h) + boff + n * 2048 + k * 1024); } while (0)
; #define PG8_MMA(ai, bj, At, Bt) do { __builtin_amdgcn_s_setprio(1); _Pragma("unroll") for (int m = 0; m < 4; ++m) _Pragma("unroll") for (int n = 0; n < 2; ++n) _Pragma("unroll") for (int k = 0; k < 2; ++k) \
;         acc[ai][bj][m][n] = __builtin_amdgcn_mfma_f32_16x16x32_bf16(Bt[n][k], At[m][k], acc[ai][bj][m][n], 0, 0, 0); __builtin_amdgcn_s_setprio(0); } while (0)
; #define PG8_WAIT_V(n) asm volatile("s_waitcnt vmcnt(" #n ")" ::: "memory")
; #define PG8_WAIT_L(n) asm volatile("s_waitcnt lgkmcnt(" #n ")" ::: "memory")
; #define PG8_BAR __builtin_amdgcn_s_barrier()
; #define PG8_SCHED __builtin_amdgcn_sched_barrier(0)
; template <class Epi, bool ALIGN_EPI = PG8_ALIGN>
; __device__ __forceinline__ void gemm_phase(LAS unsigned char* lds, const Gemm g, const StaticOrder& S, const Epi& E) {
;     ...
;             PG8_WAIT_V(8); PG8_WAIT_L(0); PG8_BAR; PG8_MMA(1, 0, At, B0); PG8_MMA(1, 1, At, B1); PG8_BAR; PG8_SCHED;
;             PG8_LDB(B0, 1, 0); PG8_LDB(B1, 1, 1); PG8_SCHED; PG8_LDA(At, 1, 0); PG8_STAGE(PG8_SA(0, 1), a2 + hstepA, voffA);
;             PG8_WAIT_V(8); PG8_WAIT_L(0); PG8_BAR; PG8_MMA(0, 0, At, B0); PG8_MMA(0, 1, At, B1); PG8_BAR; PG8_SCHED;
	s_setprio 1
	s_waitcnt lgkmcnt(0)
	v_mfma_f32_16x16x32_bf16 v[60:63], v[142:145], v[184:187], v[60:63]
	v_mfma_f32_16x16x32_bf16 v[56:59], v[150:153], v[184:187], v[56:59]
	v_mfma_f32_16x16x32_bf16 v[44:47], v[142:145], v[192:195], v[44:47]
	v_mfma_f32_16x16x32_bf16 v[40:43], v[150:153], v[192:195], v[40:43]
	v_mfma_f32_16x16x32_bf16 v[28:31], v[142:145], v[200:203], v[28:31]
	v_mfma_f32_16x16x32_bf16 v[24:27], v[150:153], v[200:203], v[24:27]
	v_mfma_f32_16x16x32_bf16 v[12:15], v[142:145], v[208:211], v[12:15]
	v_mfma_f32_16x16x32_bf16 v[8:11], v[150:153], v[208:211], v[8:11]
	v_mfma_f32_16x16x32_bf16 v[60:63], v[146:149], v[188:191], v[60:63]
	v_mfma_f32_16x16x32_bf16 v[56:59], v[154:157], v[188:191], v[56:59]
	v_mfma_f32_16x16x32_bf16 v[44:47], v[146:149], v[196:199], v[44:47]
	v_mfma_f32_16x16x32_bf16 v[40:43], v[154:157], v[196:199], v[40:43]
	v_mfma_f32_16x16x32_bf16 v[28:31], v[146:149], v[204:207], v[28:31]
	v_mfma_f32_16x16x32_bf16 v[24:27], v[154:157], v[204:207], v[24:27]
	v_mfma_f32_16x16x32_bf16 v[12:15], v[146:149], v[212:215], v[12:15]
	v_mfma_f32_16x16x32_bf16 v[8:11], v[154:157], v[212:215], v[8:11]
	s_setprio 0
	s_setprio 1
	v_mfma_f32_16x16x32_bf16 v[52:55], v[158:161], v[184:187], v[52:55]
	v_mfma_f32_16x16x32_bf16 v[48:51], v[166:169], v[184:187], v[48:51]
	v_mfma_f32_16x16x32_bf16 v[36:39], v[158:161], v[192:195], v[36:39]
	v_mfma_f32_16x16x32_bf16 v[32:35], v[166:169], v[192:195], v[32:35]
	v_mfma_f32_16x16x32_bf16 v[20:23], v[158:161], v[200:203], v[20:23]
	v_mfma_f32_16x16x32_bf16 v[16:19], v[166:169], v[200:203], v[16:19]
	v_mfma_f32_16x16x32_bf16 v[4:7], v[158:161], v[208:211], v[4:7]
	v_mfma_f32_16x16x32_bf16 v[0:3], v[166:169], v[208:211], v[0:3]
	v_mfma_f32_16x16x32_bf16 v[52:55], v[162:165], v[188:191], v[52:55]
	v_mfma_f32_16x16x32_bf16 v[48:51], v[170:173], v[188:191], v[48:51]
	v_mfma_f32_16x16x32_bf16 v[36:39], v[162:165], v[196:199], v[36:39]
	v_mfma_f32_16x16x32_bf16 v[32:35], v[170:173], v[196:199], v[32:35]
	v_mfma_f32_16x16x32_bf16 v[20:23], v[162:165], v[204:207], v[20:23]
	v_mfma_f32_16x16x32_bf16 v[16:19], v[170:173], v[204:207], v[16:19]
	v_mfma_f32_16x16x32_bf16 v[4:7], v[162:165], v[212:215], v[4:7]
	v_mfma_f32_16x16x32_bf16 v[0:3], v[170:173], v[212:215], v[0:3]
	s_setprio 0
	s_barrier
	s_add_i32 s22, 16, 0x18000
	s_add_i32 s23, 16, 0x1c000
	v_add_u32_e32 v154, s22, v139
	v_add_u32_e32 v170, s23, v139
	ds_read_b128 v[142:145], v154
	ds_read_b128 v[146:149], v154 offset:1024
	ds_read_b128 v[150:153], v154 offset:2048
	ds_read_b128 v[154:157], v154 offset:3072
	ds_read_b128 v[158:161], v170
	ds_read_b128 v[162:165], v170 offset:1024
	ds_read_b128 v[166:169], v170 offset:2048
	ds_read_b128 v[170:173], v170 offset:3072
	s_add_u32 s20, s40, 0x80000
	s_addc_u32 s21, s41, 0
	s_mov_b32 m0, s31
	v_lshl_add_u64 v[222:223], s[20:21], 0, v[132:133]
	ds_read_b128 v[184:187], v141 offset:32768
	ds_read_b128 v[188:191], v141 offset:33792
	ds_read_b128 v[192:195], v141 offset:34816
	ds_read_b128 v[196:199], v141 offset:35840
	ds_read_b128 v[200:203], v141 offset:36864
	ds_read_b128 v[204:207], v141 offset:37888
	ds_read_b128 v[208:211], v141 offset:38912
	ds_read_b128 v[212:215], v141 offset:39936
	global_load_lds_dwordx4 v[222:223], off
	v_lshl_add_u64 v[222:223], s[20:21], 0, v[130:131]
	s_mov_b32 m0, s44
	s_nop 0
	global_load_lds_dwordx4 v[222:223], off
	s_waitcnt vmcnt(8)
	s_waitcnt lgkmcnt(0)
	s_barrier
	s_setprio 1
	s_waitcnt lgkmcnt(0)
	v_mfma_f32_16x16x32_bf16 v[120:123], v[142:145], v[184:187], v[120:123]
	v_mfma_f32_16x16x32_bf16 v[124:127], v[150:153], v[184:187], v[124:127]
	v_mfma_f32_16x16x32_bf16 v[108:111], v[142:145], v[192:195], v[108:111]
	v_mfma_f32_16x16x32_bf16 v[104:107], v[150:153], v[192:195], v[104:107]
	v_mfma_f32_16x16x32_bf16 v[92:95], v[142:145], v[200:203], v[92:95]
	v_mfma_f32_16x16x32_bf16 v[88:91], v[150:153], v[200:203], v[88:91]
	v_mfma_f32_16x16x32_bf16 v[76:79], v[142:145], v[208:211], v[76:79]
	v_mfma_f32_16x16x32_bf16 v[72:75], v[150:153], v[208:211], v[72:75]
	v_mfma_f32_16x16x32_bf16 v[120:123], v[146:149], v[188:191], v[120:123]
	v_mfma_f32_16x16x32_bf16 v[124:127], v[154:157], v[188:191], v[124:127]
	v_mfma_f32_16x16x32_bf16 v[108:111], v[146:149], v[196:199], v[108:111]
	v_mfma_f32_16x16x32_bf16 v[104:107], v[154:157], v[196:199], v[104:107]
	v_mfma_f32_16x16x32_bf16 v[92:95], v[146:149], v[204:207], v[92:95]
	v_mfma_f32_16x16x32_bf16 v[88:91], v[154:157], v[204:207], v[88:91]
	v_mfma_f32_16x16x32_bf16 v[76:79], v[146:149], v[212:215], v[76:79]
	v_mfma_f32_16x16x32_bf16 v[72:75], v[154:157], v[212:215], v[72:75]
	s_setprio 0
	s_setprio 1
	v_mfma_f32_16x16x32_bf16 v[116:119], v[158:161], v[184:187], v[116:119]
	v_mfma_f32_16x16x32_bf16 v[112:115], v[166:169], v[184:187], v[112:115]
	v_mfma_f32_16x16x32_bf16 v[100:103], v[158:161], v[192:195], v[100:103]
	v_mfma_f32_16x16x32_bf16 v[96:99], v[166:169], v[192:195], v[96:99]
	v_mfma_f32_16x16x32_bf16 v[84:87], v[158:161], v[200:203], v[84:87]
	v_mfma_f32_16x16x32_bf16 v[80:83], v[166:169], v[200:203], v[80:83]
	v_mfma_f32_16x16x32_bf16 v[68:71], v[158:161], v[208:211], v[68:71]
	v_mfma_f32_16x16x32_bf16 v[64:67], v[166:169], v[208:211], v[64:67]
	v_mfma_f32_16x16x32_bf16 v[116:119], v[162:165], v[188:191], v[116:119]
	v_mfma_f32_16x16x32_bf16 v[112:115], v[170:173], v[188:191], v[112:115]
	v_mfma_f32_16x16x32_bf16 v[100:103], v[162:165], v[196:199], v[100:103]
	v_mfma_f32_16x16x32_bf16 v[96:99], v[170:173], v[196:199], v[96:99]
	v_mfma_f32_16x16x32_bf16 v[84:87], v[162:165], v[204:207], v[84:87]
	v_mfma_f32_16x16x32_bf16 v[80:83], v[170:173], v[204:207], v[80:83]
	v_mfma_f32_16x16x32_bf16 v[68:71], v[162:165], v[212:215], v[68:71]
	v_mfma_f32_16x16x32_bf16 v[64:67], v[170:173], v[212:215], v[64:67]
	s_setprio 0
	s_barrier
; #define PG8_STAGE(bufoff, gbase, voff) do { _Pragma("unroll") for (int _i = 0; _i < 2; ++_i) \
;         __builtin_amdgcn_global_load_lds((const unsigned*)((const char*)(gbase) + (voff)[_i]), (LAS unsigned*)(lds + (bufoff) + ldsw + _i * 8192), 16, 0, 0); } while (0)
; #define PG8_LDA(dst, b, h) do { _Pragma("unroll") for (int m = 0; m < 4; ++m) _Pragma("unroll") for (int k = 0; k < 2; ++k) dst[m][k] = *(const LAS bf16x8*)(lds + PG8_SA(b, h) + aoff + m * 2048 + k * 1024); } while (0)
; #define PG8_MMA(ai, bj, At, Bt) do { __builtin_amdgcn_s_setprio(1); _Pragma("unroll") for (int m = 0; m < 4; ++m) _Pragma("unroll") for (int n = 0; n < 2; ++n) _Pragma("unroll") for (int k = 0; k < 2; ++k) \
;         acc[ai][bj][m][n] = __builtin_amdgcn_mfma_f32_16x16x32_bf16(Bt[n][k], At[m][k], acc[ai][bj][m][n], 0, 0, 0); __builtin_amdgcn_s_setprio(0); } while (0)
; #define PG8_WAIT_V(n) asm volatile("s_waitcnt vmcnt(" #n ")" ::: "memory")
; #define PG8_WAIT_L(n) asm volatile("s_waitcnt lgkmcnt(" #n ")" ::: "memory")
; #define PG8_BAR __builtin_amdgcn_s_barrier()
; #define PG8_SCHED __builtin_amdgcn_sched_barrier(0)
; template <class Epi, bool ALIGN_EPI = PG8_ALIGN>
; __device__ __forceinline__ void gemm_phase(LAS unsigned char* lds, const Gemm g, const StaticOrder& S, const Epi& E) {
;     ...
;             PG8_LDA(At, 1, 1); PG8_STAGE(PG8_SB(1, 0), b3, voffB); PG8_STAGE(PG8_SB(1, 1), b3 + hstepB, voffB); PG8_STAGE(PG8_SA(1, 0), a3, voffA);
;             PG8_WAIT_V(8); PG8_WAIT_L(0); PG8_BAR; PG8_MMA(1, 0, At, B0); PG8_MMA(1, 1, At, B1); PG8_BAR; PG8_SCHED;
;         }
	s_add_i32 s20, s22, s18
	v_lshl_add_u64 v[174:175], v[174:175], 0, s[0:1]
	s_mov_b32 m0, s20
	ds_read_b128 v[184:187], v141 offset:49152
	ds_read_b128 v[188:191], v141 offset:50176
	ds_read_b128 v[192:195], v141 offset:51200
	ds_read_b128 v[196:199], v141 offset:52224
	ds_read_b128 v[200:203], v141 offset:53248
	ds_read_b128 v[204:207], v141 offset:54272
	ds_read_b128 v[208:211], v141 offset:55296
	ds_read_b128 v[212:215], v141 offset:56320
	global_load_lds_dwordx4 v[174:175], off
	v_lshl_add_u64 v[174:175], v[180:181], 0, s[0:1]
	s_add_i32 m0, s20, 0x2000
	s_add_i32 s20, s23, s18
	global_load_lds_dwordx4 v[174:175], off
	v_lshl_add_u64 v[174:175], v[182:183], 0, s[0:1]
	s_mov_b32 m0, s20
	s_nop 0
	global_load_lds_dwordx4 v[174:175], off
	v_lshl_add_u64 v[174:175], v[216:217], 0, s[0:1]
	s_add_i32 m0, s20, 0x2000
	s_nop 0
	global_load_lds_dwordx4 v[174:175], off
	v_lshl_add_u64 v[174:175], v[218:219], 0, s[0:1]
	s_mov_b32 m0, s45
	s_nop 0
	global_load_lds_dwordx4 v[174:175], off
	v_lshl_add_u64 v[174:175], v[220:221], 0, s[0:1]
	s_mov_b32 m0, s46
	s_nop 0
	global_load_lds_dwordx4 v[174:175], off
	s_nop 15
	s_nop 15
	s_waitcnt vmcnt(8)
	s_waitcnt lgkmcnt(0)
	s_barrier
	s_setprio 1
	s_waitcnt lgkmcnt(0)
	v_mfma_f32_16x16x32_bf16 v[60:63], v[142:145], v[184:187], v[60:63]
	v_mfma_f32_16x16x32_bf16 v[56:59], v[150:153], v[184:187], v[56:59]
	v_mfma_f32_16x16x32_bf16 v[44:47], v[142:145], v[192:195], v[44:47]
	v_mfma_f32_16x16x32_bf16 v[40:43], v[150:153], v[192:195], v[40:43]
	v_mfma_f32_16x16x32_bf16 v[28:31], v[142:145], v[200:203], v[28:31]
	v_mfma_f32_16x16x32_bf16 v[24:27], v[150:153], v[200:203], v[24:27]
	v_mfma_f32_16x16x32_bf16 v[12:15], v[142:145], v[208:211], v[12:15]
	v_mfma_f32_16x16x32_bf16 v[8:11], v[150:153], v[208:211], v[8:11]
	v_mfma_f32_16x16x32_bf16 v[60:63], v[146:149], v[188:191], v[60:63]
	v_mfma_f32_16x16x32_bf16 v[56:59], v[154:157], v[188:191], v[56:59]
	v_mfma_f32_16x16x32_bf16 v[44:47], v[146:149], v[196:199], v[44:47]
	v_mfma_f32_16x16x32_bf16 v[40:43], v[154:157], v[196:199], v[40:43]
	v_mfma_f32_16x16x32_bf16 v[28:31], v[146:149], v[204:207], v[28:31]
	v_mfma_f32_16x16x32_bf16 v[24:27], v[154:157], v[204:207], v[24:27]
	v_mfma_f32_16x16x32_bf16 v[12:15], v[146:149], v[212:215], v[12:15]
	v_mfma_f32_16x16x32_bf16 v[8:11], v[154:157], v[212:215], v[8:11]
	s_setprio 0
	s_setprio 1
	v_mfma_f32_16x16x32_bf16 v[52:55], v[158:161], v[184:187], v[52:55]
	v_mfma_f32_16x16x32_bf16 v[48:51], v[166:169], v[184:187], v[48:51]
	v_mfma_f32_16x16x32_bf16 v[36:39], v[158:161], v[192:195], v[36:39]
	v_mfma_f32_16x16x32_bf16 v[32:35], v[166:169], v[192:195], v[32:35]
	v_mfma_f32_16x16x32_bf16 v[20:23], v[158:161], v[200:203], v[20:23]
	v_mfma_f32_16x16x32_bf16 v[16:19], v[166:169], v[200:203], v[16:19]
	v_mfma_f32_16x16x32_bf16 v[4:7], v[158:161], v[208:211], v[4:7]
	v_mfma_f32_16x16x32_bf16 v[0:3], v[166:169], v[208:211], v[0:3]
	v_mfma_f32_16x16x32_bf16 v[52:55], v[162:165], v[188:191], v[52:55]
	v_mfma_f32_16x16x32_bf16 v[48:51], v[170:173], v[188:191], v[48:51]
	v_mfma_f32_16x16x32_bf16 v[36:39], v[162:165], v[196:199], v[36:39]
	v_mfma_f32_16x16x32_bf16 v[32:35], v[170:173], v[196:199], v[32:35]
	v_mfma_f32_16x16x32_bf16 v[20:23], v[162:165], v[204:207], v[20:23]
	v_mfma_f32_16x16x32_bf16 v[16:19], v[170:173], v[204:207], v[16:19]
	v_mfma_f32_16x16x32_bf16 v[4:7], v[162:165], v[212:215], v[4:7]
	v_mfma_f32_16x16x32_bf16 v[0:3], v[170:173], v[212:215], v[0:3]
	s_setprio 0
	s_barrier
	s_add_u32 s4, s4, 0x100
	s_addc_u32 s5, s5, 0
	s_add_u32 s42, s42, 0x100
	s_addc_u32 s43, s43, 0
	s_cmp_ge_i32 s53, s34
	s_mov_b32 s40, s53
	s_cbranch_scc0 .LBB0_901

; #define PG8_STAGE(bufoff, gbase, voff) do { _Pragma("unroll") for (int _i = 0; _i < 2; ++_i) \
;         __builtin_amdgcn_global_load_lds((const unsigned*)((const char*)(gbase) + (voff)[_i]), (LAS unsigned*)(lds + (bufoff) + ldsw + _i * 8192), 16, 0, 0); } while (0)
; #define PG8_LDA(dst, b, h) do { _Pragma("unroll") for (int m = 0; m < 4; ++m) _Pragma("unroll") for (int k = 0; k < 2; ++k) dst[m][k] = *(const LAS bf16x8*)(lds + PG8_SA(b, h) + aoff + m * 2048 + k * 1024); } while (0)
; #define PG8_LDB(dst, b, h) do { _Pragma("unroll") for (int n = 0; n < 2; ++n) _Pragma("unroll") for (int k = 0; k < 2; ++k) dst[n][k] = *(const LAS bf16x8*)(lds + PG8_SB(b, h) + boff + n * 2048 + k * 1024); } while (0)
; #define PG8_MMA(ai, bj, At, Bt) do { __builtin_amdgcn_s_setprio(1); _Pragma("unroll") for (int m = 0; m < 4; ++m) _Pragma("unroll") for (int n = 0; n < 2; ++n) _Pragma("unroll") for (int k = 0; k < 2; ++k) \
;         acc[ai][bj][m][n] = __builtin_amdgcn_mfma_f32_16x16x32_bf16(Bt[n][k], At[m][k], acc[ai][bj][m][n], 0, 0, 0); __builtin_amdgcn_s_setprio(0); } while (0)
; #define PG8_WAIT_V(n) asm volatile("s_waitcnt vmcnt(" #n ")" ::: "memory")
; #define PG8_WAIT_L(n) asm volatile("s_waitcnt lgkmcnt(" #n ")" ::: "memory")
; #define PG8_BAR __builtin_amdgcn_s_barrier()
; #define PG8_SCHED __builtin_amdgcn_sched_barrier(0)
; template <class Epi, bool ALIGN_EPI = PG8_ALIGN>
; __device__ __forceinline__ void gemm_phase(LAS unsigned char* lds, const Gemm g, const StaticOrder& S, const Epi& E) {
;     ...
;         for (int t = 0; t < nt; t += 2) {
;             const bool last = (t == nt - 2);
;             const char* a1 = cA + (size_t)(t + 1) * kstep;
;             const char* a2 = last ? nA : cA + (size_t)(t + 2) * kstep; const char* b2 = last ? nB : cB + (size_t)(t + 2) * kstep;
;             const char* a3 = a2 + kstep; const char* b3 = b2 + kstep;
;             PG8_LDB(B0, 0, 0); PG8_LDB(B1, 0, 1); PG8_SCHED; PG8_LDA(At, 0, 0); PG8_STAGE(PG8_SA(1, 1), a1 + hstepA, voffA);
;             PG8_WAIT_V(8); PG8_WAIT_L(0); PG8_BAR; PG8_MMA(0, 0, At, B0); PG8_MMA(0, 1, At, B1); PG8_BAR; PG8_SCHED;
;             PG8_LDA(At, 0, 1); PG8_STAGE(PG8_SB(0, 0), b2, voffB); PG8_STAGE(PG8_SB(0, 1), b2 + hstepB, voffB); PG8_STAGE(PG8_SA(0, 0), a2, voffA);
;             PG8_WAIT_V(8); PG8_WAIT_L(0); PG8_BAR; PG8_MMA(1, 0, At, B0); PG8_MMA(1, 1, At, B1); PG8_BAR; PG8_SCHED;
.LBB0_1028:
	s_add_i32 s31, s24, 2
	s_add_u32 s20, s2, 0xfff80080
	s_addc_u32 s21, s3, -1
	s_add_i32 s22, 16, 0x10000
	s_cmp_eq_u32 s53, s24
	s_cselect_b32 s25, s17, s21
	s_cselect_b32 s24, s27, s20
	s_cselect_b32 s21, s39, s30
	s_cselect_b32 s20, s38, s29
	s_add_i32 s23, 16, 0x14000
	v_add_u32_e32 v140, s22, v220
	v_add_u32_e32 v156, s23, v220
	ds_read_b128 v[128:131], v140
	ds_read_b128 v[132:135], v140 offset:1024
	ds_read_b128 v[136:139], v140 offset:2048
	ds_read_b128 v[140:143], v140 offset:3072
	ds_read_b128 v[144:147], v156
	ds_read_b128 v[148:151], v156 offset:1024
	ds_read_b128 v[152:155], v156 offset:2048
	ds_read_b128 v[156:159], v156 offset:3072
	v_lshl_add_u64 v[180:181], s[2:3], 0, v[192:193]
	s_add_i32 m0, s47, 0xc000
	ds_read_b128 v[160:163], v223
	ds_read_b128 v[164:167], v223 offset:1024
	ds_read_b128 v[168:171], v223 offset:2048
	ds_read_b128 v[172:175], v223 offset:3072
	ds_read_b128 v[196:199], v223 offset:4096
	ds_read_b128 v[200:203], v223 offset:5120
	ds_read_b128 v[204:207], v223 offset:6144
	ds_read_b128 v[208:211], v223 offset:7168
	global_load_lds_dwordx4 v[180:181], off
	v_lshl_add_u64 v[180:181], s[2:3], 0, v[194:195]
	s_add_i32 m0, s47, 0xe000
	s_nop 0
	global_load_lds_dwordx4 v[180:181], off
	s_waitcnt vmcnt(8)
	s_waitcnt lgkmcnt(0)
	s_barrier
	s_setprio 1
	s_waitcnt lgkmcnt(0)
	v_mfma_f32_16x16x32_bf16 v[124:127], v[128:131], v[160:163], v[124:127]
	v_mfma_f32_16x16x32_bf16 v[116:119], v[136:139], v[160:163], v[116:119]
	v_mfma_f32_16x16x32_bf16 v[108:111], v[128:131], v[168:171], v[108:111]
	v_mfma_f32_16x16x32_bf16 v[100:103], v[136:139], v[168:171], v[100:103]
	v_mfma_f32_16x16x32_bf16 v[92:95], v[128:131], v[196:199], v[92:95]
	v_mfma_f32_16x16x32_bf16 v[84:87], v[136:139], v[196:199], v[84:87]
	v_mfma_f32_16x16x32_bf16 v[76:79], v[128:131], v[204:207], v[76:79]
	v_mfma_f32_16x16x32_bf16 v[68:71], v[136:139], v[204:207], v[68:71]
	v_mfma_f32_16x16x32_bf16 v[124:127], v[132:135], v[164:167], v[124:127]
	v_mfma_f32_16x16x32_bf16 v[116:119], v[140:143], v[164:167], v[116:119]
	v_mfma_f32_16x16x32_bf16 v[108:111], v[132:135], v[172:175], v[108:111]
	v_mfma_f32_16x16x32_bf16 v[100:103], v[140:143], v[172:175], v[100:103]
	v_mfma_f32_16x16x32_bf16 v[92:95], v[132:135], v[200:203], v[92:95]
	v_mfma_f32_16x16x32_bf16 v[84:87], v[140:143], v[200:203], v[84:87]
	v_mfma_f32_16x16x32_bf16 v[76:79], v[132:135], v[208:211], v[76:79]
	v_mfma_f32_16x16x32_bf16 v[68:71], v[140:143], v[208:211], v[68:71]
	s_setprio 0
	s_setprio 1
	v_mfma_f32_16x16x32_bf16 v[120:123], v[144:147], v[160:163], v[120:123]
	v_mfma_f32_16x16x32_bf16 v[112:115], v[152:155], v[160:163], v[112:115]
	v_mfma_f32_16x16x32_bf16 v[104:107], v[144:147], v[168:171], v[104:107]
	v_mfma_f32_16x16x32_bf16 v[96:99], v[152:155], v[168:171], v[96:99]
	v_mfma_f32_16x16x32_bf16 v[88:91], v[144:147], v[196:199], v[88:91]
	v_mfma_f32_16x16x32_bf16 v[80:83], v[152:155], v[196:199], v[80:83]
	v_mfma_f32_16x16x32_bf16 v[72:75], v[144:147], v[204:207], v[72:75]
	v_mfma_f32_16x16x32_bf16 v[64:67], v[152:155], v[204:207], v[64:67]
	v_mfma_f32_16x16x32_bf16 v[120:123], v[148:151], v[164:167], v[120:123]
	v_mfma_f32_16x16x32_bf16 v[112:115], v[156:159], v[164:167], v[112:115]
	v_mfma_f32_16x16x32_bf16 v[104:107], v[148:151], v[172:175], v[104:107]
	v_mfma_f32_16x16x32_bf16 v[96:99], v[156:159], v[172:175], v[96:99]
	v_mfma_f32_16x16x32_bf16 v[88:91], v[148:151], v[200:203], v[88:91]
	v_mfma_f32_16x16x32_bf16 v[80:83], v[156:159], v[200:203], v[80:83]
	v_mfma_f32_16x16x32_bf16 v[72:75], v[148:151], v[208:211], v[72:75]
	v_mfma_f32_16x16x32_bf16 v[64:67], v[156:159], v[208:211], v[64:67]
	s_setprio 0
	s_barrier
	s_add_i32 s22, s22, s46
	v_lshl_add_u64 v[180:181], s[20:21], 0, v[188:189]
	s_mov_b32 m0, s22
	ds_read_b128 v[160:163], v223 offset:16384
	ds_read_b128 v[164:167], v223 offset:17408
	ds_read_b128 v[168:171], v223 offset:18432
	ds_read_b128 v[172:175], v223 offset:19456
	ds_read_b128 v[196:199], v223 offset:20480
	ds_read_b128 v[200:203], v223 offset:21504
	ds_read_b128 v[204:207], v223 offset:22528
	ds_read_b128 v[208:211], v223 offset:23552
	global_load_lds_dwordx4 v[180:181], off
	s_add_i32 m0, s22, 0x2000
	v_lshl_add_u64 v[182:183], s[20:21], 0, v[184:185]
	s_add_u32 s20, s20, s4
	s_addc_u32 s21, s21, s5
	s_add_i32 s22, s23, s46
	global_load_lds_dwordx4 v[182:183], off
	v_lshl_add_u64 v[212:213], s[20:21], 0, v[188:189]
	s_mov_b32 m0, s22
	v_lshl_add_u64 v[214:215], s[20:21], 0, v[184:185]
	global_load_lds_dwordx4 v[212:213], off
	s_add_i32 m0, s22, 0x2000
	v_lshl_add_u64 v[216:217], s[24:25], 0, v[190:191]
	global_load_lds_dwordx4 v[214:215], off
	s_mov_b32 m0, s47
	v_lshl_add_u64 v[218:219], s[24:25], 0, v[186:187]
	global_load_lds_dwordx4 v[216:217], off
	s_mov_b32 m0, s48
	s_nop 0
	global_load_lds_dwordx4 v[218:219], off
	s_nop 15
	s_nop 15
	s_waitcnt vmcnt(8)
	s_waitcnt lgkmcnt(0)
	s_barrier
; #define PG8_STAGE(bufoff, gbase, voff) do { _Pragma("unroll") for (int _i = 0; _i < 2; ++_i) \
;         __builtin_amdgcn_global_load_lds((const unsigned*)((const char*)(gbase) + (voff)[_i]), (LAS unsigned*)(lds + (bufoff) + ldsw + _i * 8192), 16, 0, 0); } while (0)
; #define PG8_LDA(dst, b, h) do { _Pragma("unroll") for (int m = 0; m < 4; ++m) _Pragma("unroll") for (int k = 0; k < 2; ++k) dst[m][k] = *(const LAS bf16x8*)(lds + PG8_SA(b, h) + aoff + m * 2048 + k * 1024); } while (0)
; #define PG8_LDB(dst, b, h) do { _Pragma("unroll") for (int n = 0; n < 2; ++n) _Pragma("unroll") for (int k = 0; k < 2; ++k) dst[n][k] = *(const LAS bf16x8*)(lds + PG8_SB(b, h) + boff + n * 2048 + k * 1024); } while (0)
; #define PG8_MMA(ai, bj, At, Bt) do { __builtin_amdgcn_s_setprio(1); _Pragma("unroll") for (int m = 0; m < 4; ++m) _Pragma("unroll") for (int n = 0; n < 2; ++n) _Pragma("unroll") for (int k = 0; k < 2; ++k) \
;         acc[ai][bj][m][n] = __builtin_amdgcn_mfma_f32_16x16x32_bf16(Bt[n][k], At[m][k], acc[ai][bj][m][n], 0, 0, 0); __builtin_amdgcn_s_setprio(0); } while (0)
; #define PG8_WAIT_V(n) asm volatile("s_waitcnt vmcnt(" #n ")" ::: "memory")
; #define PG8_WAIT_L(n) asm volatile("s_waitcnt lgkmcnt(" #n ")" ::: "memory")
; #define PG8_BAR __builtin_amdgcn_s_barrier()
; #define PG8_SCHED __builtin_amdgcn_sched_barrier(0)
; template <class Epi, bool ALIGN_EPI = PG8_ALIGN>
; __device__ __forceinline__ void gemm_phase(LAS unsigned char* lds, const Gemm g, const StaticOrder& S, const Epi& E) {
;     ...
;             PG8_WAIT_V(8); PG8_WAIT_L(0); PG8_BAR; PG8_MMA(1, 0, At, B0); PG8_MMA(1, 1, At, B1); PG8_BAR; PG8_SCHED;
;             PG8_LDB(B0, 1, 0); PG8_LDB(B1, 1, 1); PG8_SCHED; PG8_LDA(At, 1, 0); PG8_STAGE(PG8_SA(0, 1), a2 + hstepA, voffA);
;             PG8_WAIT_V(8); PG8_WAIT_L(0); PG8_BAR; PG8_MMA(0, 0, At, B0); PG8_MMA(0, 1, At, B1); PG8_BAR; PG8_SCHED;
	s_setprio 1
	s_waitcnt lgkmcnt(0)
	v_mfma_f32_16x16x32_bf16 v[60:63], v[128:131], v[160:163], v[60:63]
	v_mfma_f32_16x16x32_bf16 v[52:55], v[136:139], v[160:163], v[52:55]
	v_mfma_f32_16x16x32_bf16 v[44:47], v[128:131], v[168:171], v[44:47]
	v_mfma_f32_16x16x32_bf16 v[36:39], v[136:139], v[168:171], v[36:39]
	v_mfma_f32_16x16x32_bf16 v[28:31], v[128:131], v[196:199], v[28:31]
	v_mfma_f32_16x16x32_bf16 v[20:23], v[136:139], v[196:199], v[20:23]
	v_mfma_f32_16x16x32_bf16 v[12:15], v[128:131], v[204:207], v[12:15]
	v_mfma_f32_16x16x32_bf16 v[4:7], v[136:139], v[204:207], v[4:7]
	v_mfma_f32_16x16x32_bf16 v[60:63], v[132:135], v[164:167], v[60:63]
	v_mfma_f32_16x16x32_bf16 v[52:55], v[140:143], v[164:167], v[52:55]
	v_mfma_f32_16x16x32_bf16 v[44:47], v[132:135], v[172:175], v[44:47]
	v_mfma_f32_16x16x32_bf16 v[36:39], v[140:143], v[172:175], v[36:39]
	v_mfma_f32_16x16x32_bf16 v[28:31], v[132:135], v[200:203], v[28:31]
	v_mfma_f32_16x16x32_bf16 v[20:23], v[140:143], v[200:203], v[20:23]
	v_mfma_f32_16x16x32_bf16 v[12:15], v[132:135], v[208:211], v[12:15]
	v_mfma_f32_16x16x32_bf16 v[4:7], v[140:143], v[208:211], v[4:7]
	s_setprio 0
	s_setprio 1
	v_mfma_f32_16x16x32_bf16 v[56:59], v[144:147], v[160:163], v[56:59]
	v_mfma_f32_16x16x32_bf16 v[48:51], v[152:155], v[160:163], v[48:51]
	v_mfma_f32_16x16x32_bf16 v[40:43], v[144:147], v[168:171], v[40:43]
	v_mfma_f32_16x16x32_bf16 v[32:35], v[152:155], v[168:171], v[32:35]
	v_mfma_f32_16x16x32_bf16 v[24:27], v[144:147], v[196:199], v[24:27]
	v_mfma_f32_16x16x32_bf16 v[16:19], v[152:155], v[196:199], v[16:19]
	v_mfma_f32_16x16x32_bf16 v[8:11], v[144:147], v[204:207], v[8:11]
	v_mfma_f32_16x16x32_bf16 v[0:3], v[152:155], v[204:207], v[0:3]
	v_mfma_f32_16x16x32_bf16 v[56:59], v[148:151], v[164:167], v[56:59]
	v_mfma_f32_16x16x32_bf16 v[48:51], v[156:159], v[164:167], v[48:51]
	v_mfma_f32_16x16x32_bf16 v[40:43], v[148:151], v[172:175], v[40:43]
	v_mfma_f32_16x16x32_bf16 v[32:35], v[156:159], v[172:175], v[32:35]
	v_mfma_f32_16x16x32_bf16 v[24:27], v[148:151], v[200:203], v[24:27]
	v_mfma_f32_16x16x32_bf16 v[16:19], v[156:159], v[200:203], v[16:19]
	v_mfma_f32_16x16x32_bf16 v[8:11], v[148:151], v[208:211], v[8:11]
	v_mfma_f32_16x16x32_bf16 v[0:3], v[156:159], v[208:211], v[0:3]
	s_setprio 0
	s_barrier
	s_add_i32 s22, 16, 0x18000
	s_add_i32 s23, 16, 0x1c000
	v_add_u32_e32 v140, s22, v220
	v_add_u32_e32 v156, s23, v220
	ds_read_b128 v[128:131], v140
	ds_read_b128 v[132:135], v140 offset:1024
	ds_read_b128 v[136:139], v140 offset:2048
	ds_read_b128 v[140:143], v140 offset:3072
	ds_read_b128 v[144:147], v156
	ds_read_b128 v[148:151], v156 offset:1024
	ds_read_b128 v[152:155], v156 offset:2048
	ds_read_b128 v[156:159], v156 offset:3072
	s_add_u32 s20, s24, 0x80000
	s_addc_u32 s21, s25, 0
	s_mov_b32 m0, s49
	v_lshl_add_u64 v[224:225], s[20:21], 0, v[190:191]
	ds_read_b128 v[160:163], v223 offset:32768
	ds_read_b128 v[164:167], v223 offset:33792
	ds_read_b128 v[168:171], v223 offset:34816
	ds_read_b128 v[172:175], v223 offset:35840
	ds_read_b128 v[196:199], v223 offset:36864
	ds_read_b128 v[200:203], v223 offset:37888
	ds_read_b128 v[204:207], v223 offset:38912
	ds_read_b128 v[208:211], v223 offset:39936
	global_load_lds_dwordx4 v[224:225], off
	v_lshl_add_u64 v[224:225], s[20:21], 0, v[186:187]
	s_mov_b32 m0, s50
	s_nop 0
	global_load_lds_dwordx4 v[224:225], off
	s_waitcnt vmcnt(8)
	s_waitcnt lgkmcnt(0)
	s_barrier
	s_setprio 1
	s_waitcnt lgkmcnt(0)
	v_mfma_f32_16x16x32_bf16 v[124:127], v[128:131], v[160:163], v[124:127]
	v_mfma_f32_16x16x32_bf16 v[116:119], v[136:139], v[160:163], v[116:119]
	v_mfma_f32_16x16x32_bf16 v[108:111], v[128:131], v[168:171], v[108:111]
	v_mfma_f32_16x16x32_bf16 v[100:103], v[136:139], v[168:171], v[100:103]
	v_mfma_f32_16x16x32_bf16 v[92:95], v[128:131], v[196:199], v[92:95]
	v_mfma_f32_16x16x32_bf16 v[84:87], v[136:139], v[196:199], v[84:87]
	v_mfma_f32_16x16x32_bf16 v[76:79], v[128:131], v[204:207], v[76:79]
	v_mfma_f32_16x16x32_bf16 v[68:71], v[136:139], v[204:207], v[68:71]
	v_mfma_f32_16x16x32_bf16 v[124:127], v[132:135], v[164:167], v[124:127]
	v_mfma_f32_16x16x32_bf16 v[116:119], v[140:143], v[164:167], v[116:119]
	v_mfma_f32_16x16x32_bf16 v[108:111], v[132:135], v[172:175], v[108:111]
	v_mfma_f32_16x16x32_bf16 v[100:103], v[140:143], v[172:175], v[100:103]
	v_mfma_f32_16x16x32_bf16 v[92:95], v[132:135], v[200:203], v[92:95]
	v_mfma_f32_16x16x32_bf16 v[84:87], v[140:143], v[200:203], v[84:87]
	v_mfma_f32_16x16x32_bf16 v[76:79], v[132:135], v[208:211], v[76:79]
	v_mfma_f32_16x16x32_bf16 v[68:71], v[140:143], v[208:211], v[68:71]
	s_setprio 0
	s_setprio 1
	v_mfma_f32_16x16x32_bf16 v[120:123], v[144:147], v[160:163], v[120:123]
	v_mfma_f32_16x16x32_bf16 v[112:115], v[152:155], v[160:163], v[112:115]
	v_mfma_f32_16x16x32_bf16 v[104:107], v[144:147], v[168:171], v[104:107]
	v_mfma_f32_16x16x32_bf16 v[96:99], v[152:155], v[168:171], v[96:99]
	v_mfma_f32_16x16x32_bf16 v[88:91], v[144:147], v[196:199], v[88:91]
	v_mfma_f32_16x16x32_bf16 v[80:83], v[152:155], v[196:199], v[80:83]
	v_mfma_f32_16x16x32_bf16 v[72:75], v[144:147], v[204:207], v[72:75]
	v_mfma_f32_16x16x32_bf16 v[64:67], v[152:155], v[204:207], v[64:67]
	v_mfma_f32_16x16x32_bf16 v[120:123], v[148:151], v[164:167], v[120:123]
	v_mfma_f32_16x16x32_bf16 v[112:115], v[156:159], v[164:167], v[112:115]
	v_mfma_f32_16x16x32_bf16 v[104:107], v[148:151], v[172:175], v[104:107]
	v_mfma_f32_16x16x32_bf16 v[96:99], v[156:159], v[172:175], v[96:99]
	v_mfma_f32_16x16x32_bf16 v[88:91], v[148:151], v[200:203], v[88:91]
	v_mfma_f32_16x16x32_bf16 v[80:83], v[156:159], v[200:203], v[80:83]
	v_mfma_f32_16x16x32_bf16 v[72:75], v[148:151], v[208:211], v[72:75]
	v_mfma_f32_16x16x32_bf16 v[64:67], v[156:159], v[208:211], v[64:67]
	s_setprio 0
	s_barrier
; #define PG8_STAGE(bufoff, gbase, voff) do { _Pragma("unroll") for (int _i = 0; _i < 2; ++_i) \
;         __builtin_amdgcn_global_load_lds((const unsigned*)((const char*)(gbase) + (voff)[_i]), (LAS unsigned*)(lds + (bufoff) + ldsw + _i * 8192), 16, 0, 0); } while (0)
; #define PG8_LDA(dst, b, h) do { _Pragma("unroll") for (int m = 0; m < 4; ++m) _Pragma("unroll") for (int k = 0; k < 2; ++k) dst[m][k] = *(const LAS bf16x8*)(lds + PG8_SA(b, h) + aoff + m * 2048 + k * 1024); } while (0)
; #define PG8_MMA(ai, bj, At, Bt) do { __builtin_amdgcn_s_setprio(1); _Pragma("unroll") for (int m = 0; m < 4; ++m) _Pragma("unroll") for (int n = 0; n < 2; ++n) _Pragma("unroll") for (int k = 0; k < 2; ++k) \
;         acc[ai][bj][m][n] = __builtin_amdgcn_mfma_f32_16x16x32_bf16(Bt[n][k], At[m][k], acc[ai][bj][m][n], 0, 0, 0); __builtin_amdgcn_s_setprio(0); } while (0)
; #define PG8_WAIT_V(n) asm volatile("s_waitcnt vmcnt(" #n ")" ::: "memory")
; #define PG8_WAIT_L(n) asm volatile("s_waitcnt lgkmcnt(" #n ")" ::: "memory")
; #define PG8_BAR __builtin_amdgcn_s_barrier()
; #define PG8_SCHED __builtin_amdgcn_sched_barrier(0)
; template <class Epi, bool ALIGN_EPI = PG8_ALIGN>
; __device__ __forceinline__ void gemm_phase(LAS unsigned char* lds, const Gemm g, const StaticOrder& S, const Epi& E) {
;     ...
;             PG8_LDA(At, 1, 1); PG8_STAGE(PG8_SB(1, 0), b3, voffB); PG8_STAGE(PG8_SB(1, 1), b3 + hstepB, voffB); PG8_STAGE(PG8_SA(1, 0), a3, voffA);
;             PG8_WAIT_V(8); PG8_WAIT_L(0); PG8_BAR; PG8_MMA(1, 0, At, B0); PG8_MMA(1, 1, At, B1); PG8_BAR; PG8_SCHED;
;         }
	s_add_i32 s20, s22, s46
	v_lshl_add_u64 v[180:181], v[180:181], 0, s[0:1]
	s_mov_b32 m0, s20
	ds_read_b128 v[160:163], v223 offset:49152
	ds_read_b128 v[164:167], v223 offset:50176
	ds_read_b128 v[168:171], v223 offset:51200
	ds_read_b128 v[172:175], v223 offset:52224
	ds_read_b128 v[196:199], v223 offset:53248
	ds_read_b128 v[200:203], v223 offset:54272
	ds_read_b128 v[204:207], v223 offset:55296
	ds_read_b128 v[208:211], v223 offset:56320
	global_load_lds_dwordx4 v[180:181], off
	v_lshl_add_u64 v[180:181], v[182:183], 0, s[0:1]
	s_add_i32 m0, s20, 0x2000
	s_add_i32 s20, s23, s46
	global_load_lds_dwordx4 v[180:181], off
	v_lshl_add_u64 v[180:181], v[212:213], 0, s[0:1]
	s_mov_b32 m0, s20
	s_nop 0
	global_load_lds_dwordx4 v[180:181], off
	v_lshl_add_u64 v[180:181], v[214:215], 0, s[0:1]
	s_add_i32 m0, s20, 0x2000
	s_nop 0
	global_load_lds_dwordx4 v[180:181], off
	v_lshl_add_u64 v[180:181], v[216:217], 0, s[0:1]
	s_mov_b32 m0, s18
	s_nop 0
	global_load_lds_dwordx4 v[180:181], off
	v_lshl_add_u64 v[180:181], v[218:219], 0, s[0:1]
	s_mov_b32 m0, s51
	s_nop 0
	global_load_lds_dwordx4 v[180:181], off
	s_nop 15
	s_nop 15
	s_waitcnt vmcnt(8)
	s_waitcnt lgkmcnt(0)
	s_barrier
	s_setprio 1
	s_waitcnt lgkmcnt(0)
	v_mfma_f32_16x16x32_bf16 v[60:63], v[128:131], v[160:163], v[60:63]
	v_mfma_f32_16x16x32_bf16 v[52:55], v[136:139], v[160:163], v[52:55]
	v_mfma_f32_16x16x32_bf16 v[44:47], v[128:131], v[168:171], v[44:47]
	v_mfma_f32_16x16x32_bf16 v[36:39], v[136:139], v[168:171], v[36:39]
	v_mfma_f32_16x16x32_bf16 v[28:31], v[128:131], v[196:199], v[28:31]
	v_mfma_f32_16x16x32_bf16 v[20:23], v[136:139], v[196:199], v[20:23]
	v_mfma_f32_16x16x32_bf16 v[12:15], v[128:131], v[204:207], v[12:15]
	v_mfma_f32_16x16x32_bf16 v[4:7], v[136:139], v[204:207], v[4:7]
	v_mfma_f32_16x16x32_bf16 v[60:63], v[132:135], v[164:167], v[60:63]
	v_mfma_f32_16x16x32_bf16 v[52:55], v[140:143], v[164:167], v[52:55]
	v_mfma_f32_16x16x32_bf16 v[44:47], v[132:135], v[172:175], v[44:47]
	v_mfma_f32_16x16x32_bf16 v[36:39], v[140:143], v[172:175], v[36:39]
	v_mfma_f32_16x16x32_bf16 v[28:31], v[132:135], v[200:203], v[28:31]
	v_mfma_f32_16x16x32_bf16 v[20:23], v[140:143], v[200:203], v[20:23]
	v_mfma_f32_16x16x32_bf16 v[12:15], v[132:135], v[208:211], v[12:15]
	v_mfma_f32_16x16x32_bf16 v[4:7], v[140:143], v[208:211], v[4:7]
	s_setprio 0
	s_setprio 1
	v_mfma_f32_16x16x32_bf16 v[56:59], v[144:147], v[160:163], v[56:59]
	v_mfma_f32_16x16x32_bf16 v[48:51], v[152:155], v[160:163], v[48:51]
	v_mfma_f32_16x16x32_bf16 v[40:43], v[144:147], v[168:171], v[40:43]
	v_mfma_f32_16x16x32_bf16 v[32:35], v[152:155], v[168:171], v[32:35]
	v_mfma_f32_16x16x32_bf16 v[24:27], v[144:147], v[196:199], v[24:27]
	v_mfma_f32_16x16x32_bf16 v[16:19], v[152:155], v[196:199], v[16:19]
	v_mfma_f32_16x16x32_bf16 v[8:11], v[144:147], v[204:207], v[8:11]
	v_mfma_f32_16x16x32_bf16 v[0:3], v[152:155], v[204:207], v[0:3]
	v_mfma_f32_16x16x32_bf16 v[56:59], v[148:151], v[164:167], v[56:59]
	v_mfma_f32_16x16x32_bf16 v[48:51], v[156:159], v[164:167], v[48:51]
	v_mfma_f32_16x16x32_bf16 v[40:43], v[148:151], v[172:175], v[40:43]
	v_mfma_f32_16x16x32_bf16 v[32:35], v[156:159], v[172:175], v[32:35]
	v_mfma_f32_16x16x32_bf16 v[24:27], v[148:151], v[200:203], v[24:27]
	v_mfma_f32_16x16x32_bf16 v[16:19], v[156:159], v[200:203], v[16:19]
	v_mfma_f32_16x16x32_bf16 v[8:11], v[148:151], v[208:211], v[8:11]
	v_mfma_f32_16x16x32_bf16 v[0:3], v[156:159], v[208:211], v[0:3]
	s_setprio 0
	s_barrier
	s_add_u32 s2, s2, 0x100
	s_addc_u32 s3, s3, 0
	s_add_u32 s29, s29, 0x100
	s_addc_u32 s30, s30, 0
	s_cmp_ge_i32 s31, s52
	s_mov_b32 s24, s31
	s_cbranch_scc0 .LBB0_1028

; #define PG8_STAGE(bufoff, gbase, voff) do { _Pragma("unroll") for (int _i = 0; _i < 2; ++_i) \
;         __builtin_amdgcn_global_load_lds((const unsigned*)((const char*)(gbase) + (voff)[_i]), (LAS unsigned*)(lds + (bufoff) + ldsw + _i * 8192), 16, 0, 0); } while (0)
; #define PG8_LDA(dst, b, h) do { _Pragma("unroll") for (int m = 0; m < 4; ++m) _Pragma("unroll") for (int k = 0; k < 2; ++k) dst[m][k] = *(const LAS bf16x8*)(lds + PG8_SA(b, h) + aoff + m * 2048 + k * 1024); } while (0)
; #define PG8_LDB(dst, b, h) do { _Pragma("unroll") for (int n = 0; n < 2; ++n) _Pragma("unroll") for (int k = 0; k < 2; ++k) dst[n][k] = *(const LAS bf16x8*)(lds + PG8_SB(b, h) + boff + n * 2048 + k * 1024); } while (0)
; #define PG8_MMA(ai, bj, At, Bt) do { __builtin_amdgcn_s_setprio(1); _Pragma("unroll") for (int m = 0; m < 4; ++m) _Pragma("unroll") for (int n = 0; n < 2; ++n) _Pragma("unroll") for (int k = 0; k < 2; ++k) \
;         acc[ai][bj][m][n] = __builtin_amdgcn_mfma_f32_16x16x32_bf16(Bt[n][k], At[m][k], acc[ai][bj][m][n], 0, 0, 0); __builtin_amdgcn_s_setprio(0); } while (0)
; #define PG8_WAIT_V(n) asm volatile("s_waitcnt vmcnt(" #n ")" ::: "memory")
; #define PG8_WAIT_L(n) asm volatile("s_waitcnt lgkmcnt(" #n ")" ::: "memory")
; #define PG8_BAR __builtin_amdgcn_s_barrier()
; #define PG8_SCHED __builtin_amdgcn_sched_barrier(0)
; template <class Epi, bool ALIGN_EPI = PG8_ALIGN>
; __device__ __forceinline__ void gemm_phase(LAS unsigned char* lds, const Gemm g, const StaticOrder& S, const Epi& E) {
;     ...
;         for (int t = 0; t < nt; t += 2) {
;             const bool last = (t == nt - 2);
;             const char* a1 = cA + (size_t)(t + 1) * kstep;
;             const char* a2 = last ? nA : cA + (size_t)(t + 2) * kstep; const char* b2 = last ? nB : cB + (size_t)(t + 2) * kstep;
;             const char* a3 = a2 + kstep; const char* b3 = b2 + kstep;
;             PG8_LDB(B0, 0, 0); PG8_LDB(B1, 0, 1); PG8_SCHED; PG8_LDA(At, 0, 0); PG8_STAGE(PG8_SA(1, 1), a1 + hstepA, voffA);
;             PG8_WAIT_V(8); PG8_WAIT_L(0); PG8_BAR; PG8_MMA(0, 0, At, B0); PG8_MMA(0, 1, At, B1); PG8_BAR; PG8_SCHED;
;             PG8_LDA(At, 0, 1); PG8_STAGE(PG8_SB(0, 0), b2, voffB); PG8_STAGE(PG8_SB(0, 1), b2 + hstepB, voffB); PG8_STAGE(PG8_SA(0, 0), a2, voffA);
;             PG8_WAIT_V(8); PG8_WAIT_L(0); PG8_BAR; PG8_MMA(1, 0, At, B0); PG8_MMA(1, 1, At, B1); PG8_BAR; PG8_SCHED;
.LBB0_1108:
	s_add_i32 s53, s40, 2
	s_add_u32 s36, s24, 0x100
	s_addc_u32 s37, s25, 0
	s_add_i32 s22, 16, 0x10000
	s_cmp_eq_u32 s27, s40
	s_cselect_b32 s41, s3, s37
	s_cselect_b32 s40, s2, s36
	s_cselect_b32 s21, s17, s52
	s_cselect_b32 s20, s16, s51
	s_add_i32 s23, 16, 0x14000
	v_add_u32_e32 v154, s22, v147
	v_add_u32_e32 v170, s23, v147
	ds_read_b128 v[138:141], v154
	ds_read_b128 v[142:145], v154 offset:1024
	ds_read_b128 v[150:153], v154 offset:2048
	ds_read_b128 v[154:157], v154 offset:3072
	ds_read_b128 v[158:161], v170
	ds_read_b128 v[162:165], v170 offset:1024
	ds_read_b128 v[166:169], v170 offset:2048
	ds_read_b128 v[170:173], v170 offset:3072
	v_lshl_add_u64 v[174:175], s[24:25], 0, v[134:135]
	s_add_i32 m0, s31, 0xc000
	ds_read_b128 v[184:187], v149
	ds_read_b128 v[188:191], v149 offset:1024
	ds_read_b128 v[192:195], v149 offset:2048
	ds_read_b128 v[196:199], v149 offset:3072
	ds_read_b128 v[200:203], v149 offset:4096
	ds_read_b128 v[204:207], v149 offset:5120
	ds_read_b128 v[208:211], v149 offset:6144
	ds_read_b128 v[212:215], v149 offset:7168
	global_load_lds_dwordx4 v[174:175], off
	v_lshl_add_u64 v[174:175], s[24:25], 0, v[136:137]
	s_add_i32 m0, s31, 0xe000
	s_nop 0
	global_load_lds_dwordx4 v[174:175], off
	s_waitcnt vmcnt(8)
	s_waitcnt lgkmcnt(0)
	s_barrier
	s_setprio 1
	s_waitcnt lgkmcnt(0)
	v_mfma_f32_16x16x32_bf16 v[124:127], v[138:141], v[184:187], v[124:127]
	v_mfma_f32_16x16x32_bf16 v[120:123], v[150:153], v[184:187], v[120:123]
	v_mfma_f32_16x16x32_bf16 v[116:119], v[138:141], v[192:195], v[116:119]
	v_mfma_f32_16x16x32_bf16 v[112:115], v[150:153], v[192:195], v[112:115]
	v_mfma_f32_16x16x32_bf16 v[104:107], v[138:141], v[200:203], v[104:107]
	v_mfma_f32_16x16x32_bf16 v[96:99], v[150:153], v[200:203], v[96:99]
	v_mfma_f32_16x16x32_bf16 v[88:91], v[138:141], v[208:211], v[88:91]
	v_mfma_f32_16x16x32_bf16 v[80:83], v[150:153], v[208:211], v[80:83]
	v_mfma_f32_16x16x32_bf16 v[124:127], v[142:145], v[188:191], v[124:127]
	v_mfma_f32_16x16x32_bf16 v[120:123], v[154:157], v[188:191], v[120:123]
	v_mfma_f32_16x16x32_bf16 v[116:119], v[142:145], v[196:199], v[116:119]
	v_mfma_f32_16x16x32_bf16 v[112:115], v[154:157], v[196:199], v[112:115]
	v_mfma_f32_16x16x32_bf16 v[104:107], v[142:145], v[204:207], v[104:107]
	v_mfma_f32_16x16x32_bf16 v[96:99], v[154:157], v[204:207], v[96:99]
	v_mfma_f32_16x16x32_bf16 v[88:91], v[142:145], v[212:215], v[88:91]
	v_mfma_f32_16x16x32_bf16 v[80:83], v[154:157], v[212:215], v[80:83]
	s_setprio 0
	s_setprio 1
	v_mfma_f32_16x16x32_bf16 v[108:111], v[158:161], v[184:187], v[108:111]
	v_mfma_f32_16x16x32_bf16 v[100:103], v[166:169], v[184:187], v[100:103]
	v_mfma_f32_16x16x32_bf16 v[92:95], v[158:161], v[192:195], v[92:95]
	v_mfma_f32_16x16x32_bf16 v[84:87], v[166:169], v[192:195], v[84:87]
	v_mfma_f32_16x16x32_bf16 v[76:79], v[158:161], v[200:203], v[76:79]
	v_mfma_f32_16x16x32_bf16 v[72:75], v[166:169], v[200:203], v[72:75]
	v_mfma_f32_16x16x32_bf16 v[68:71], v[158:161], v[208:211], v[68:71]
	v_mfma_f32_16x16x32_bf16 v[64:67], v[166:169], v[208:211], v[64:67]
	v_mfma_f32_16x16x32_bf16 v[108:111], v[162:165], v[188:191], v[108:111]
	v_mfma_f32_16x16x32_bf16 v[100:103], v[170:173], v[188:191], v[100:103]
	v_mfma_f32_16x16x32_bf16 v[92:95], v[162:165], v[196:199], v[92:95]
	v_mfma_f32_16x16x32_bf16 v[84:87], v[170:173], v[196:199], v[84:87]
	v_mfma_f32_16x16x32_bf16 v[76:79], v[162:165], v[204:207], v[76:79]
	v_mfma_f32_16x16x32_bf16 v[72:75], v[170:173], v[204:207], v[72:75]
	v_mfma_f32_16x16x32_bf16 v[68:71], v[162:165], v[212:215], v[68:71]
	v_mfma_f32_16x16x32_bf16 v[64:67], v[170:173], v[212:215], v[64:67]
	s_setprio 0
	s_barrier
	s_add_i32 s22, s22, s18
	v_lshl_add_u64 v[174:175], s[20:21], 0, v[176:177]
	s_mov_b32 m0, s22
	ds_read_b128 v[184:187], v149 offset:16384
	ds_read_b128 v[188:191], v149 offset:17408
	ds_read_b128 v[192:195], v149 offset:18432
	ds_read_b128 v[196:199], v149 offset:19456
	ds_read_b128 v[200:203], v149 offset:20480
	ds_read_b128 v[204:207], v149 offset:21504
	ds_read_b128 v[208:211], v149 offset:22528
	ds_read_b128 v[212:215], v149 offset:23552
	global_load_lds_dwordx4 v[174:175], off
	s_add_i32 m0, s22, 0x2000
	v_lshl_add_u64 v[180:181], s[20:21], 0, v[128:129]
	s_add_u32 s20, s20, s6
	s_addc_u32 s21, s21, s7
	s_add_i32 s22, s23, s18
	global_load_lds_dwordx4 v[180:181], off
	v_lshl_add_u64 v[182:183], s[20:21], 0, v[176:177]
	s_mov_b32 m0, s22
	v_lshl_add_u64 v[216:217], s[20:21], 0, v[128:129]
	global_load_lds_dwordx4 v[182:183], off
	s_add_i32 m0, s22, 0x2000
	v_lshl_add_u64 v[218:219], s[40:41], 0, v[132:133]
	global_load_lds_dwordx4 v[216:217], off
	s_mov_b32 m0, s31
	v_lshl_add_u64 v[220:221], s[40:41], 0, v[130:131]
	global_load_lds_dwordx4 v[218:219], off
	s_mov_b32 m0, s42
	s_nop 0
	global_load_lds_dwordx4 v[220:221], off
	s_nop 15
	s_nop 15
	s_waitcnt vmcnt(8)
	s_waitcnt lgkmcnt(0)
	s_barrier
; #define PG8_STAGE(bufoff, gbase, voff) do { _Pragma("unroll") for (int _i = 0; _i < 2; ++_i) \
;         __builtin_amdgcn_global_load_lds((const unsigned*)((const char*)(gbase) + (voff)[_i]), (LAS unsigned*)(lds + (bufoff) + ldsw + _i * 8192), 16, 0, 0); } while (0)
; #define PG8_LDA(dst, b, h) do { _Pragma("unroll") for (int m = 0; m < 4; ++m) _Pragma("unroll") for (int k = 0; k < 2; ++k) dst[m][k] = *(const LAS bf16x8*)(lds + PG8_SA(b, h) + aoff + m * 2048 + k * 1024); } while (0)
; #define PG8_LDB(dst, b, h) do { _Pragma("unroll") for (int n = 0; n < 2; ++n) _Pragma("unroll") for (int k = 0; k < 2; ++k) dst[n][k] = *(const LAS bf16x8*)(lds + PG8_SB(b, h) + boff + n * 2048 + k * 1024); } while (0)
; #define PG8_MMA(ai, bj, At, Bt) do { __builtin_amdgcn_s_setprio(1); _Pragma("unroll") for (int m = 0; m < 4; ++m) _Pragma("unroll") for (int n = 0; n < 2; ++n) _Pragma("unroll") for (int k = 0; k < 2; ++k) \
;         acc[ai][bj][m][n] = __builtin_amdgcn_mfma_f32_16x16x32_bf16(Bt[n][k], At[m][k], acc[ai][bj][m][n], 0, 0, 0); __builtin_amdgcn_s_setprio(0); } while (0)
; #define PG8_WAIT_V(n) asm volatile("s_waitcnt vmcnt(" #n ")" ::: "memory")
; #define PG8_WAIT_L(n) asm volatile("s_waitcnt lgkmcnt(" #n ")" ::: "memory")
; #define PG8_BAR __builtin_amdgcn_s_barrier()
; #define PG8_SCHED __builtin_amdgcn_sched_barrier(0)
; template <class Epi, bool ALIGN_EPI = PG8_ALIGN>
; __device__ __forceinline__ void gemm_phase(LAS unsigned char* lds, const Gemm g, const StaticOrder& S, const Epi& E) {
;     ...
;             PG8_WAIT_V(8); PG8_WAIT_L(0); PG8_BAR; PG8_MMA(1, 0, At, B0); PG8_MMA(1, 1, At, B1); PG8_BAR; PG8_SCHED;
;             PG8_LDB(B0, 1, 0); PG8_LDB(B1, 1, 1); PG8_SCHED; PG8_LDA(At, 1, 0); PG8_STAGE(PG8_SA(0, 1), a2 + hstepA, voffA);
;             PG8_WAIT_V(8); PG8_WAIT_L(0); PG8_BAR; PG8_MMA(0, 0, At, B0); PG8_MMA(0, 1, At, B1); PG8_BAR; PG8_SCHED;
	s_setprio 1
	s_waitcnt lgkmcnt(0)
	v_mfma_f32_16x16x32_bf16 v[60:63], v[138:141], v[184:187], v[60:63]
	v_mfma_f32_16x16x32_bf16 v[56:59], v[150:153], v[184:187], v[56:59]
	v_mfma_f32_16x16x32_bf16 v[52:55], v[138:141], v[192:195], v[52:55]
	v_mfma_f32_16x16x32_bf16 v[48:51], v[150:153], v[192:195], v[48:51]
	v_mfma_f32_16x16x32_bf16 v[40:43], v[138:141], v[200:203], v[40:43]
	v_mfma_f32_16x16x32_bf16 v[32:35], v[150:153], v[200:203], v[32:35]
	v_mfma_f32_16x16x32_bf16 v[24:27], v[138:141], v[208:211], v[24:27]
	v_mfma_f32_16x16x32_bf16 v[16:19], v[150:153], v[208:211], v[16:19]
	v_mfma_f32_16x16x32_bf16 v[60:63], v[142:145], v[188:191], v[60:63]
	v_mfma_f32_16x16x32_bf16 v[56:59], v[154:157], v[188:191], v[56:59]
	v_mfma_f32_16x16x32_bf16 v[52:55], v[142:145], v[196:199], v[52:55]
	v_mfma_f32_16x16x32_bf16 v[48:51], v[154:157], v[196:199], v[48:51]
	v_mfma_f32_16x16x32_bf16 v[40:43], v[142:145], v[204:207], v[40:43]
	v_mfma_f32_16x16x32_bf16 v[32:35], v[154:157], v[204:207], v[32:35]
	v_mfma_f32_16x16x32_bf16 v[24:27], v[142:145], v[212:215], v[24:27]
	v_mfma_f32_16x16x32_bf16 v[16:19], v[154:157], v[212:215], v[16:19]
	s_setprio 0
	s_setprio 1
	v_mfma_f32_16x16x32_bf16 v[44:47], v[158:161], v[184:187], v[44:47]
	v_mfma_f32_16x16x32_bf16 v[36:39], v[166:169], v[184:187], v[36:39]
	v_mfma_f32_16x16x32_bf16 v[28:31], v[158:161], v[192:195], v[28:31]
	v_mfma_f32_16x16x32_bf16 v[20:23], v[166:169], v[192:195], v[20:23]
	v_mfma_f32_16x16x32_bf16 v[12:15], v[158:161], v[200:203], v[12:15]
	v_mfma_f32_16x16x32_bf16 v[8:11], v[166:169], v[200:203], v[8:11]
	v_mfma_f32_16x16x32_bf16 v[4:7], v[158:161], v[208:211], v[4:7]
	v_mfma_f32_16x16x32_bf16 v[0:3], v[166:169], v[208:211], v[0:3]
	v_mfma_f32_16x16x32_bf16 v[44:47], v[162:165], v[188:191], v[44:47]
	v_mfma_f32_16x16x32_bf16 v[36:39], v[170:173], v[188:191], v[36:39]
	v_mfma_f32_16x16x32_bf16 v[28:31], v[162:165], v[196:199], v[28:31]
	v_mfma_f32_16x16x32_bf16 v[20:23], v[170:173], v[196:199], v[20:23]
	v_mfma_f32_16x16x32_bf16 v[12:15], v[162:165], v[204:207], v[12:15]
	v_mfma_f32_16x16x32_bf16 v[8:11], v[170:173], v[204:207], v[8:11]
	v_mfma_f32_16x16x32_bf16 v[4:7], v[162:165], v[212:215], v[4:7]
	v_mfma_f32_16x16x32_bf16 v[0:3], v[170:173], v[212:215], v[0:3]
	s_setprio 0
	s_barrier
	s_add_i32 s22, 16, 0x18000
	s_add_i32 s23, 16, 0x1c000
	v_add_u32_e32 v154, s22, v147
	v_add_u32_e32 v170, s23, v147
	ds_read_b128 v[138:141], v154
	ds_read_b128 v[142:145], v154 offset:1024
	ds_read_b128 v[150:153], v154 offset:2048
	ds_read_b128 v[154:157], v154 offset:3072
	ds_read_b128 v[158:161], v170
	ds_read_b128 v[162:165], v170 offset:1024
	ds_read_b128 v[166:169], v170 offset:2048
	ds_read_b128 v[170:173], v170 offset:3072
	s_add_u32 s20, s40, 0x160000
	s_addc_u32 s21, s41, 0
	s_mov_b32 m0, s43
	v_lshl_add_u64 v[222:223], s[20:21], 0, v[132:133]
	ds_read_b128 v[184:187], v149 offset:32768
	ds_read_b128 v[188:191], v149 offset:33792
	ds_read_b128 v[192:195], v149 offset:34816
	ds_read_b128 v[196:199], v149 offset:35840
	ds_read_b128 v[200:203], v149 offset:36864
	ds_read_b128 v[204:207], v149 offset:37888
	ds_read_b128 v[208:211], v149 offset:38912
	ds_read_b128 v[212:215], v149 offset:39936
	global_load_lds_dwordx4 v[222:223], off
	v_lshl_add_u64 v[222:223], s[20:21], 0, v[130:131]
	s_mov_b32 m0, s44
	s_nop 0
	global_load_lds_dwordx4 v[222:223], off
	s_waitcnt vmcnt(8)
	s_waitcnt lgkmcnt(0)
	s_barrier
	s_setprio 1
	s_waitcnt lgkmcnt(0)
	v_mfma_f32_16x16x32_bf16 v[124:127], v[138:141], v[184:187], v[124:127]
	v_mfma_f32_16x16x32_bf16 v[120:123], v[150:153], v[184:187], v[120:123]
	v_mfma_f32_16x16x32_bf16 v[116:119], v[138:141], v[192:195], v[116:119]
	v_mfma_f32_16x16x32_bf16 v[112:115], v[150:153], v[192:195], v[112:115]
	v_mfma_f32_16x16x32_bf16 v[104:107], v[138:141], v[200:203], v[104:107]
	v_mfma_f32_16x16x32_bf16 v[96:99], v[150:153], v[200:203], v[96:99]
	v_mfma_f32_16x16x32_bf16 v[88:91], v[138:141], v[208:211], v[88:91]
	v_mfma_f32_16x16x32_bf16 v[80:83], v[150:153], v[208:211], v[80:83]
	v_mfma_f32_16x16x32_bf16 v[124:127], v[142:145], v[188:191], v[124:127]
	v_mfma_f32_16x16x32_bf16 v[120:123], v[154:157], v[188:191], v[120:123]
	v_mfma_f32_16x16x32_bf16 v[116:119], v[142:145], v[196:199], v[116:119]
	v_mfma_f32_16x16x32_bf16 v[112:115], v[154:157], v[196:199], v[112:115]
	v_mfma_f32_16x16x32_bf16 v[104:107], v[142:145], v[204:207], v[104:107]
	v_mfma_f32_16x16x32_bf16 v[96:99], v[154:157], v[204:207], v[96:99]
	v_mfma_f32_16x16x32_bf16 v[88:91], v[142:145], v[212:215], v[88:91]
	v_mfma_f32_16x16x32_bf16 v[80:83], v[154:157], v[212:215], v[80:83]
	s_setprio 0
	s_setprio 1
	v_mfma_f32_16x16x32_bf16 v[108:111], v[158:161], v[184:187], v[108:111]
	v_mfma_f32_16x16x32_bf16 v[100:103], v[166:169], v[184:187], v[100:103]
	v_mfma_f32_16x16x32_bf16 v[92:95], v[158:161], v[192:195], v[92:95]
	v_mfma_f32_16x16x32_bf16 v[84:87], v[166:169], v[192:195], v[84:87]
	v_mfma_f32_16x16x32_bf16 v[76:79], v[158:161], v[200:203], v[76:79]
	v_mfma_f32_16x16x32_bf16 v[72:75], v[166:169], v[200:203], v[72:75]
	v_mfma_f32_16x16x32_bf16 v[68:71], v[158:161], v[208:211], v[68:71]
	v_mfma_f32_16x16x32_bf16 v[64:67], v[166:169], v[208:211], v[64:67]
	v_mfma_f32_16x16x32_bf16 v[108:111], v[162:165], v[188:191], v[108:111]
	v_mfma_f32_16x16x32_bf16 v[100:103], v[170:173], v[188:191], v[100:103]
	v_mfma_f32_16x16x32_bf16 v[92:95], v[162:165], v[196:199], v[92:95]
	v_mfma_f32_16x16x32_bf16 v[84:87], v[170:173], v[196:199], v[84:87]
	v_mfma_f32_16x16x32_bf16 v[76:79], v[162:165], v[204:207], v[76:79]
	v_mfma_f32_16x16x32_bf16 v[72:75], v[170:173], v[204:207], v[72:75]
	v_mfma_f32_16x16x32_bf16 v[68:71], v[162:165], v[212:215], v[68:71]
	v_mfma_f32_16x16x32_bf16 v[64:67], v[170:173], v[212:215], v[64:67]
	s_setprio 0
	s_barrier
; #define PG8_STAGE(bufoff, gbase, voff) do { _Pragma("unroll") for (int _i = 0; _i < 2; ++_i) \
;         __builtin_amdgcn_global_load_lds((const unsigned*)((const char*)(gbase) + (voff)[_i]), (LAS unsigned*)(lds + (bufoff) + ldsw + _i * 8192), 16, 0, 0); } while (0)
; #define PG8_LDA(dst, b, h) do { _Pragma("unroll") for (int m = 0; m < 4; ++m) _Pragma("unroll") for (int k = 0; k < 2; ++k) dst[m][k] = *(const LAS bf16x8*)(lds + PG8_SA(b, h) + aoff + m * 2048 + k * 1024); } while (0)
; #define PG8_MMA(ai, bj, At, Bt) do { __builtin_amdgcn_s_setprio(1); _Pragma("unroll") for (int m = 0; m < 4; ++m) _Pragma("unroll") for (int n = 0; n < 2; ++n) _Pragma("unroll") for (int k = 0; k < 2; ++k) \
;         acc[ai][bj][m][n] = __builtin_amdgcn_mfma_f32_16x16x32_bf16(Bt[n][k], At[m][k], acc[ai][bj][m][n], 0, 0, 0); __builtin_amdgcn_s_setprio(0); } while (0)
; #define PG8_WAIT_V(n) asm volatile("s_waitcnt vmcnt(" #n ")" ::: "memory")
; #define PG8_WAIT_L(n) asm volatile("s_waitcnt lgkmcnt(" #n ")" ::: "memory")
; #define PG8_BAR __builtin_amdgcn_s_barrier()
; #define PG8_SCHED __builtin_amdgcn_sched_barrier(0)
; template <class Epi, bool ALIGN_EPI = PG8_ALIGN>
; __device__ __forceinline__ void gemm_phase(LAS unsigned char* lds, const Gemm g, const StaticOrder& S, const Epi& E) {
;     ...
;             PG8_LDA(At, 1, 1); PG8_STAGE(PG8_SB(1, 0), b3, voffB); PG8_STAGE(PG8_SB(1, 1), b3 + hstepB, voffB); PG8_STAGE(PG8_SA(1, 0), a3, voffA);
;             PG8_WAIT_V(8); PG8_WAIT_L(0); PG8_BAR; PG8_MMA(1, 0, At, B0); PG8_MMA(1, 1, At, B1); PG8_BAR; PG8_SCHED;
;         }
	s_add_i32 s20, s22, s18
	v_lshl_add_u64 v[174:175], v[174:175], 0, s[0:1]
	s_mov_b32 m0, s20
	ds_read_b128 v[184:187], v149 offset:49152
	ds_read_b128 v[188:191], v149 offset:50176
	ds_read_b128 v[192:195], v149 offset:51200
	ds_read_b128 v[196:199], v149 offset:52224
	ds_read_b128 v[200:203], v149 offset:53248
	ds_read_b128 v[204:207], v149 offset:54272
	ds_read_b128 v[208:211], v149 offset:55296
	ds_read_b128 v[212:215], v149 offset:56320
	global_load_lds_dwordx4 v[174:175], off
	v_lshl_add_u64 v[174:175], v[180:181], 0, s[0:1]
	s_add_i32 m0, s20, 0x2000
	s_add_i32 s20, s23, s18
	global_load_lds_dwordx4 v[174:175], off
	v_lshl_add_u64 v[174:175], v[182:183], 0, s[0:1]
	s_mov_b32 m0, s20
	s_nop 0
	global_load_lds_dwordx4 v[174:175], off
	v_lshl_add_u64 v[174:175], v[216:217], 0, s[0:1]
	s_add_i32 m0, s20, 0x2000
	s_nop 0
	global_load_lds_dwordx4 v[174:175], off
	v_lshl_add_u64 v[174:175], v[218:219], 0, s[0:1]
	s_mov_b32 m0, s45
	s_nop 0
	global_load_lds_dwordx4 v[174:175], off
	v_lshl_add_u64 v[174:175], v[220:221], 0, s[0:1]
	s_mov_b32 m0, s46
	s_nop 0
	global_load_lds_dwordx4 v[174:175], off
	s_nop 15
	s_nop 15
	s_waitcnt vmcnt(8)
	s_waitcnt lgkmcnt(0)
	s_barrier
	s_setprio 1
	s_waitcnt lgkmcnt(0)
	v_mfma_f32_16x16x32_bf16 v[60:63], v[138:141], v[184:187], v[60:63]
	v_mfma_f32_16x16x32_bf16 v[56:59], v[150:153], v[184:187], v[56:59]
	v_mfma_f32_16x16x32_bf16 v[52:55], v[138:141], v[192:195], v[52:55]
	v_mfma_f32_16x16x32_bf16 v[48:51], v[150:153], v[192:195], v[48:51]
	v_mfma_f32_16x16x32_bf16 v[40:43], v[138:141], v[200:203], v[40:43]
	v_mfma_f32_16x16x32_bf16 v[32:35], v[150:153], v[200:203], v[32:35]
	v_mfma_f32_16x16x32_bf16 v[24:27], v[138:141], v[208:211], v[24:27]
	v_mfma_f32_16x16x32_bf16 v[16:19], v[150:153], v[208:211], v[16:19]
	v_mfma_f32_16x16x32_bf16 v[60:63], v[142:145], v[188:191], v[60:63]
	v_mfma_f32_16x16x32_bf16 v[56:59], v[154:157], v[188:191], v[56:59]
	v_mfma_f32_16x16x32_bf16 v[52:55], v[142:145], v[196:199], v[52:55]
	v_mfma_f32_16x16x32_bf16 v[48:51], v[154:157], v[196:199], v[48:51]
	v_mfma_f32_16x16x32_bf16 v[40:43], v[142:145], v[204:207], v[40:43]
	v_mfma_f32_16x16x32_bf16 v[32:35], v[154:157], v[204:207], v[32:35]
	v_mfma_f32_16x16x32_bf16 v[24:27], v[142:145], v[212:215], v[24:27]
	v_mfma_f32_16x16x32_bf16 v[16:19], v[154:157], v[212:215], v[16:19]
	s_setprio 0
	s_setprio 1
	v_mfma_f32_16x16x32_bf16 v[44:47], v[158:161], v[184:187], v[44:47]
	v_mfma_f32_16x16x32_bf16 v[36:39], v[166:169], v[184:187], v[36:39]
	v_mfma_f32_16x16x32_bf16 v[28:31], v[158:161], v[192:195], v[28:31]
	v_mfma_f32_16x16x32_bf16 v[20:23], v[166:169], v[192:195], v[20:23]
	v_mfma_f32_16x16x32_bf16 v[12:15], v[158:161], v[200:203], v[12:15]
	v_mfma_f32_16x16x32_bf16 v[8:11], v[166:169], v[200:203], v[8:11]
	v_mfma_f32_16x16x32_bf16 v[4:7], v[158:161], v[208:211], v[4:7]
	v_mfma_f32_16x16x32_bf16 v[0:3], v[166:169], v[208:211], v[0:3]
	v_mfma_f32_16x16x32_bf16 v[44:47], v[162:165], v[188:191], v[44:47]
	v_mfma_f32_16x16x32_bf16 v[36:39], v[170:173], v[188:191], v[36:39]
	v_mfma_f32_16x16x32_bf16 v[28:31], v[162:165], v[196:199], v[28:31]
	v_mfma_f32_16x16x32_bf16 v[20:23], v[170:173], v[196:199], v[20:23]
	v_mfma_f32_16x16x32_bf16 v[12:15], v[162:165], v[204:207], v[12:15]
	v_mfma_f32_16x16x32_bf16 v[8:11], v[170:173], v[204:207], v[8:11]
	v_mfma_f32_16x16x32_bf16 v[4:7], v[162:165], v[212:215], v[4:7]
	v_mfma_f32_16x16x32_bf16 v[0:3], v[170:173], v[212:215], v[0:3]
	s_setprio 0
	s_barrier
	s_add_u32 s51, s51, 0x100
	s_addc_u32 s52, s52, 0
	s_cmp_ge_i32 s53, s26
	s_mov_b64 s[24:25], s[36:37]
	s_mov_b32 s40, s53
	s_cbranch_scc0 .LBB0_1108
; __device__ __forceinline__ unsigned cvt_pk(float lo, float hi) { f32x2_t v = {lo, hi}; bf16x2_t b = __builtin_convertvector(v, bf16x2_t); return __builtin_bit_cast(unsigned, b); }
;     __device__ __forceinline__ void operator()(const f32x4 (&acc)[2][2][4][2], const Unit& u, int wr, int wc, int fr, int fq) const {
;     ...
;                 const int row = row0 + ai * HALF + m * 16; const float sc = scv[ai][m];
;                 bf16_t* rowp = O + (size_t)row * ldc + col0;
; #pragma unroll
;                 for (int bj = 0; bj < 2; ++bj) { const f32x4 v0 = acc[ai][bj][m][0] * sc, v1 = acc[ai][bj][m][1] * sc;
;                     u32x4 w; w.x = cvt_pk(v0[0], v0[1]); w.y = cvt_pk(v0[2], v0[3]); w.z = cvt_pk(v1[0], v1[1]); w.w = cvt_pk(v1[2], v1[3]);
;                     *(u32x4*)(rowp + bj * HALF) = w; }
	v_pk_mul_f32 v[126:127], v[126:127], 0.5 op_sel_hi:[1,0]
	v_pk_mul_f32 v[124:125], v[124:125], 0.5 op_sel_hi:[1,0]
	v_pk_mul_f32 v[122:123], v[122:123], 0.5 op_sel_hi:[1,0]
	v_pk_mul_f32 v[120:121], v[120:121], 0.5 op_sel_hi:[1,0]
	v_pk_mul_f32 v[138:139], v[110:111], 0.5 op_sel_hi:[1,0]
	v_pk_mul_f32 v[140:141], v[108:109], 0.5 op_sel_hi:[1,0]
	v_pk_mul_f32 v[142:143], v[102:103], 0.5 op_sel_hi:[1,0]
	v_pk_mul_f32 v[144:145], v[100:101], 0.5 op_sel_hi:[1,0]
	v_pk_mul_f32 v[100:101], v[118:119], 0.5 op_sel_hi:[1,0]
	v_pk_mul_f32 v[102:103], v[116:117], 0.5 op_sel_hi:[1,0]
	v_pk_mul_f32 v[108:109], v[114:115], 0.5 op_sel_hi:[1,0]
	v_pk_mul_f32 v[110:111], v[112:113], 0.5 op_sel_hi:[1,0]
	v_pk_mul_f32 v[112:113], v[94:95], 0.5 op_sel_hi:[1,0]
	v_pk_mul_f32 v[114:115], v[92:93], 0.5 op_sel_hi:[1,0]
	v_pk_mul_f32 v[116:117], v[86:87], 0.5 op_sel_hi:[1,0]
	v_pk_mul_f32 v[118:119], v[84:85], 0.5 op_sel_hi:[1,0]
	v_pk_mul_f32 v[84:85], v[106:107], 0.5 op_sel_hi:[1,0]
	v_pk_mul_f32 v[86:87], v[104:105], 0.5 op_sel_hi:[1,0]
	v_pk_mul_f32 v[92:93], v[98:99], 0.5 op_sel_hi:[1,0]
	v_pk_mul_f32 v[94:95], v[96:97], 0.5 op_sel_hi:[1,0]
	v_pk_mul_f32 v[96:97], v[78:79], 0.5 op_sel_hi:[1,0]
	v_pk_mul_f32 v[98:99], v[76:77], 0.5 op_sel_hi:[1,0]
	v_pk_mul_f32 v[104:105], v[74:75], 0.5 op_sel_hi:[1,0]
	v_pk_mul_f32 v[106:107], v[72:73], 0.5 op_sel_hi:[1,0]
	v_pk_mul_f32 v[72:73], v[90:91], 0.5 op_sel_hi:[1,0]
	v_pk_mul_f32 v[74:75], v[88:89], 0.5 op_sel_hi:[1,0]
	v_pk_mul_f32 v[76:77], v[82:83], 0.5 op_sel_hi:[1,0]
	v_pk_mul_f32 v[78:79], v[80:81], 0.5 op_sel_hi:[1,0]
	v_pk_mul_f32 v[70:71], v[70:71], 0.5 op_sel_hi:[1,0]
	v_pk_mul_f32 v[68:69], v[68:69], 0.5 op_sel_hi:[1,0]
	v_pk_mul_f32 v[66:67], v[66:67], 0.5 op_sel_hi:[1,0]
	v_pk_mul_f32 v[64:65], v[64:65], 0.5 op_sel_hi:[1,0]
	v_pk_mul_f32 v[62:63], v[62:63], 0.5 op_sel_hi:[1,0]
	v_pk_mul_f32 v[60:61], v[60:61], 0.5 op_sel_hi:[1,0]
	v_pk_mul_f32 v[58:59], v[58:59], 0.5 op_sel_hi:[1,0]
	v_pk_mul_f32 v[56:57], v[56:57], 0.5 op_sel_hi:[1,0]
	v_pk_mul_f32 v[80:81], v[46:47], 0.5 op_sel_hi:[1,0]
	v_pk_mul_f32 v[82:83], v[44:45], 0.5 op_sel_hi:[1,0]
	v_pk_mul_f32 v[88:89], v[38:39], 0.5 op_sel_hi:[1,0]
	v_pk_mul_f32 v[90:91], v[36:37], 0.5 op_sel_hi:[1,0]
	v_pk_mul_f32 v[36:37], v[54:55], 0.5 op_sel_hi:[1,0]
	v_pk_mul_f32 v[38:39], v[52:53], 0.5 op_sel_hi:[1,0]
	v_pk_mul_f32 v[44:45], v[50:51], 0.5 op_sel_hi:[1,0]
	v_pk_mul_f32 v[46:47], v[48:49], 0.5 op_sel_hi:[1,0]
	v_pk_mul_f32 v[48:49], v[30:31], 0.5 op_sel_hi:[1,0]
	v_pk_mul_f32 v[50:51], v[28:29], 0.5 op_sel_hi:[1,0]
	v_pk_mul_f32 v[52:53], v[22:23], 0.5 op_sel_hi:[1,0]
	v_pk_mul_f32 v[54:55], v[20:21], 0.5 op_sel_hi:[1,0]
	v_pk_mul_f32 v[20:21], v[42:43], 0.5 op_sel_hi:[1,0]
	v_pk_mul_f32 v[22:23], v[40:41], 0.5 op_sel_hi:[1,0]
	v_pk_mul_f32 v[28:29], v[34:35], 0.5 op_sel_hi:[1,0]
	v_pk_mul_f32 v[30:31], v[32:33], 0.5 op_sel_hi:[1,0]
	v_pk_mul_f32 v[32:33], v[14:15], 0.5 op_sel_hi:[1,0]
	v_pk_mul_f32 v[34:35], v[12:13], 0.5 op_sel_hi:[1,0]
	v_pk_mul_f32 v[40:41], v[10:11], 0.5 op_sel_hi:[1,0]
	v_pk_mul_f32 v[42:43], v[8:9], 0.5 op_sel_hi:[1,0]
	v_pk_mul_f32 v[8:9], v[26:27], 0.5 op_sel_hi:[1,0]
	v_pk_mul_f32 v[10:11], v[24:25], 0.5 op_sel_hi:[1,0]
	v_pk_mul_f32 v[12:13], v[18:19], 0.5 op_sel_hi:[1,0]
	v_pk_mul_f32 v[14:15], v[16:17], 0.5 op_sel_hi:[1,0]
	v_pk_mul_f32 v[6:7], v[6:7], 0.5 op_sel_hi:[1,0]
	v_pk_mul_f32 v[4:5], v[4:5], 0.5 op_sel_hi:[1,0]
	v_pk_mul_f32 v[2:3], v[2:3], 0.5 op_sel_hi:[1,0]
	v_pk_mul_f32 v[0:1], v[0:1], 0.5 op_sel_hi:[1,0]

; template <int PHM, int MIXM>
; __global__ void __launch_bounds__(512, 2) mega(Args Aval) {
	.amdhsa_kernel _Z4megaILi65535ELi15EEv4Args
		.amdhsa_group_segment_fixed_size 16
		.amdhsa_private_segment_fixed_size 0
		.amdhsa_kernarg_size 600
		.amdhsa_user_sgpr_count 2
		.amdhsa_user_sgpr_dispatch_ptr 0
		.amdhsa_user_sgpr_queue_ptr 0
		.amdhsa_user_sgpr_kernarg_segment_ptr 1
		.amdhsa_user_sgpr_dispatch_id 0
		.amdhsa_user_sgpr_kernarg_preload_length 0
		.amdhsa_user_sgpr_kernarg_preload_offset 0
		.amdhsa_user_sgpr_private_segment_size 0
		.amdhsa_uses_dynamic_stack 0
		.amdhsa_enable_private_segment 0
		.amdhsa_system_sgpr_workgroup_id_x 1
		.amdhsa_system_sgpr_workgroup_id_y 0
		.amdhsa_system_sgpr_workgroup_id_z 0
		.amdhsa_system_sgpr_workgroup_info 0
		.amdhsa_system_vgpr_workitem_id 2
		.amdhsa_next_free_vgpr 256
		.amdhsa_next_free_sgpr 100
		.amdhsa_accum_offset 256
		.amdhsa_reserve_vcc 1
		.amdhsa_float_round_mode_32 0
		.amdhsa_float_round_mode_16_64 0
		.amdhsa_float_denorm_mode_32 3
		.amdhsa_float_denorm_mode_16_64 3
		.amdhsa_dx10_clamp 1
		.amdhsa_ieee_mode 1
		.amdhsa_fp16_overflow 0
		.amdhsa_tg_split 0
		.amdhsa_exception_fp_ieee_invalid_op 0
		.amdhsa_exception_fp_denorm_src 0
		.amdhsa_exception_fp_ieee_div_zero 0
		.amdhsa_exception_fp_ieee_overflow 0
		.amdhsa_exception_fp_ieee_underflow 0
		.amdhsa_exception_fp_ieee_inexact 0
		.amdhsa_exception_int_div_zero 0
	.end_amdhsa_kernel

; template <int PHM, int MIXM>
; __global__ void __launch_bounds__(512, 2) mega(Args Aval) {
amdhsa.kernels:
  - .agpr_count:     0
    .args:
      - .offset:         0
        .size:           344
        .value_kind:     by_value
      - .offset:         344
        .size:           4
        .value_kind:     hidden_block_count_x
      - .offset:         348
        .size:           4
        .value_kind:     hidden_block_count_y
      - .offset:         352
        .size:           4
        .value_kind:     hidden_block_count_z
      - .offset:         356
        .size:           2
        .value_kind:     hidden_group_size_x
      - .offset:         358
        .size:           2
        .value_kind:     hidden_group_size_y
      - .offset:         360
        .size:           2
        .value_kind:     hidden_group_size_z
      - .offset:         362
        .size:           2
        .value_kind:     hidden_remainder_x
      - .offset:         364
        .size:           2
        .value_kind:     hidden_remainder_y
      - .offset:         366
        .size:           2
        .value_kind:     hidden_remainder_z
      - .offset:         384
        .size:           8
        .value_kind:     hidden_global_offset_x
      - .offset:         392
        .size:           8
        .value_kind:     hidden_global_offset_y
      - .offset:         400
        .size:           8
        .value_kind:     hidden_global_offset_z
      - .offset:         408
        .size:           2
        .value_kind:     hidden_grid_dims
      - .offset:         432
        .size:           8
        .value_kind:     hidden_multigrid_sync_arg
      - .offset:         464
        .size:           4
        .value_kind:     hidden_dynamic_lds_size
    .group_segment_fixed_size: 16
    .kernarg_segment_align: 8
    .kernarg_segment_size: 600
    .language:       OpenCL C
    .language_version:
      - 2
      - 0
    .max_flat_workgroup_size: 512
    .name:           _Z4megaILi65535ELi15EEv4Args
    .private_segment_fixed_size: 0
    .sgpr_count:     106
    .sgpr_spill_count: 230
    .symbol:         _Z4megaILi65535ELi15EEv4Args.kd
    .uniform_work_group_size: 1
    .uses_dynamic_stack: false
    .vgpr_count:     256
    .vgpr_spill_count: 0
    .wavefront_size: 64
